# GEMM K-loops: removed the compiler's duplicate lgkmcnt(0) after each s_setprio 1 (60 sites)
# speedup vs baseline: 1.0057x; 1.0057x over previous
; #define PG8_STAGE(bufoff, gbase) do { _Pragma("unroll") for (int _i = 0; _i < 2; ++_i) \
;         __builtin_amdgcn_global_load_lds((const unsigned*)((const char*)(gbase) + voff[_i]), (LAS unsigned*)(lds + (bufoff) + ldsw + _i * 8192), 16, 0, 0); } while (0)
; #define PG8_LDA(dst, b, h) do { _Pragma("unroll") for (int m = 0; m < 4; ++m) _Pragma("unroll") for (int k = 0; k < 2; ++k) dst[m][k] = *(const LAS bf16x8*)(lds + PG8_SA(b, h) + aoff + m * 2048 + k * 1024); } while (0)
; #define PG8_LDB(dst, b, h) do { _Pragma("unroll") for (int n = 0; n < 2; ++n) _Pragma("unroll") for (int k = 0; k < 2; ++k) dst[n][k] = *(const LAS bf16x8*)(lds + PG8_SB(b, h) + boff + n * 2048 + k * 1024); } while (0)
; #define PG8_WAIT_L(n) asm volatile("s_waitcnt lgkmcnt(" #n ")" ::: "memory")
; #define PG8_BAR __builtin_amdgcn_s_barrier()
; #define PG8_SCHED __builtin_amdgcn_sched_barrier(0)
;     ...
;         for (int t = 0; t < nt; t += 2) {
;             const bool last = (t == nt - 2);
;             const char* a1 = cA + (size_t)(t + 1) * kstep;
;             const char* a2 = last ? nA : cA + (size_t)(t + 2) * kstep; const char* b2 = last ? nB : cB + (size_t)(t + 2) * kstep;
;             const char* a3 = a2 + kstep; const char* b3 = b2 + kstep;
;             PG8_LDB(B0, 0, 0); PG8_SCHED; PG8_LDA(At, 0, 0); PG8_STAGE(PG8_SA(1, 1), a1 + hstep);
;             PG8_WAIT_L(8); PG8_BAR; PG8_WAIT_L(0); PG8_MMA(0, 0, At, B0); PG8_BAR; PG8_SCHED;
;             PG8_LDB(B1, 0, 1); PG8_STAGE(PG8_SB(0, 0), b2);
;             PG8_BAR; PG8_WAIT_L(0); PG8_MMA(0, 1, At, B1); PG8_BAR;
;             PG8_LDA(At, 0, 1); PG8_STAGE(PG8_SA(0, 0), a2);
;             PG8_BAR; PG8_WAIT_L(0); PG8_MMA(1, 0, At, B0); PG8_BAR; PG8_SCHED;
.LBB0_161:
	s_add_u32 s0, s10, 0xfffc0080
	s_addc_u32 s1, s11, -1
	s_add_i32 s29, 0, 0x10000
	v_add_u32_e32 v162, s29, v1
	ds_read_b128 v[158:161], v162
	ds_read_b128 v[168:171], v162 offset:1024
	ds_read_b128 v[172:175], v162 offset:2048
	ds_read_b128 v[194:197], v162 offset:3072
	s_cmp_eq_u32 s28, 12
	s_cselect_b32 s15, s4, s1
	s_cselect_b32 s14, s7, s0
	s_cselect_b32 s13, s18, s23
	s_cselect_b32 s12, s19, s22
	v_lshl_add_u64 v[162:163], s[10:11], 0, v[154:155]
	s_add_i32 m0, s17, 0xc000
	ds_read_b128 v[198:201], v166
	ds_read_b128 v[202:205], v166 offset:1024
	ds_read_b128 v[206:209], v166 offset:2048
	ds_read_b128 v[210:213], v166 offset:3072
	ds_read_b128 v[214:217], v166 offset:4096
	ds_read_b128 v[218:221], v166 offset:5120
	ds_read_b128 v[222:225], v166 offset:6144
	ds_read_b128 v[226:229], v166 offset:7168
	global_load_lds_dwordx4 v[162:163], off
	v_lshl_add_u64 v[162:163], s[10:11], 0, v[156:157]
	s_add_i32 m0, s17, 0xe000
	s_nop 0
	global_load_lds_dwordx4 v[162:163], off
	s_waitcnt lgkmcnt(8)
	s_barrier
	s_waitcnt lgkmcnt(0)
	s_setprio 1
	v_mfma_f32_16x16x32_bf16 v[126:129], v[198:201], v[158:161], v[126:129]
	v_mfma_f32_16x16x32_bf16 v[110:113], v[198:201], v[172:175], v[110:113]
	v_mfma_f32_16x16x32_bf16 v[122:125], v[206:209], v[158:161], v[122:125]
	v_mfma_f32_16x16x32_bf16 v[106:109], v[206:209], v[172:175], v[106:109]
	v_mfma_f32_16x16x32_bf16 v[118:121], v[214:217], v[158:161], v[118:121]
	v_mfma_f32_16x16x32_bf16 v[102:105], v[214:217], v[172:175], v[102:105]
	v_mfma_f32_16x16x32_bf16 v[114:117], v[222:225], v[158:161], v[114:117]
	v_mfma_f32_16x16x32_bf16 v[94:97], v[222:225], v[172:175], v[94:97]
	v_mfma_f32_16x16x32_bf16 v[126:129], v[202:205], v[168:171], v[126:129]
	v_mfma_f32_16x16x32_bf16 v[110:113], v[202:205], v[194:197], v[110:113]
	v_mfma_f32_16x16x32_bf16 v[122:125], v[210:213], v[168:171], v[122:125]
	v_mfma_f32_16x16x32_bf16 v[106:109], v[210:213], v[194:197], v[106:109]
	v_mfma_f32_16x16x32_bf16 v[118:121], v[218:221], v[168:171], v[118:121]
	v_mfma_f32_16x16x32_bf16 v[102:105], v[218:221], v[194:197], v[102:105]
	v_mfma_f32_16x16x32_bf16 v[114:117], v[226:229], v[168:171], v[114:117]
	v_mfma_f32_16x16x32_bf16 v[94:97], v[226:229], v[194:197], v[94:97]
	s_setprio 0
	s_barrier
	s_add_i32 s0, 0, 0x14000
	v_add_u32_e32 v162, s0, v1
	s_add_i32 s1, s29, s16
	ds_read_b128 v[230:233], v162
	ds_read_b128 v[234:237], v162 offset:1024
	ds_read_b128 v[238:241], v162 offset:2048
	ds_read_b128 v[242:245], v162 offset:3072
	v_lshl_add_u64 v[162:163], s[12:13], 0, v[132:133]
	s_mov_b32 m0, s1
	v_lshl_add_u64 v[246:247], s[12:13], 0, v[130:131]
	global_load_lds_dwordx4 v[162:163], off
	s_add_i32 m0, s1, 0x2000
	s_nop 0
	global_load_lds_dwordx4 v[246:247], off
	s_barrier
	s_waitcnt lgkmcnt(0)
	s_setprio 1
	v_mfma_f32_16x16x32_bf16 v[82:85], v[198:201], v[230:233], v[82:85]
	v_mfma_f32_16x16x32_bf16 v[50:53], v[198:201], v[238:241], v[50:53]
	v_mfma_f32_16x16x32_bf16 v[74:77], v[206:209], v[230:233], v[74:77]
	v_mfma_f32_16x16x32_bf16 v[42:45], v[206:209], v[238:241], v[42:45]
	v_mfma_f32_16x16x32_bf16 v[66:69], v[214:217], v[230:233], v[66:69]
	v_mfma_f32_16x16x32_bf16 v[38:41], v[214:217], v[238:241], v[38:41]
	v_mfma_f32_16x16x32_bf16 v[58:61], v[222:225], v[230:233], v[58:61]
	v_mfma_f32_16x16x32_bf16 v[30:33], v[222:225], v[238:241], v[30:33]
	v_mfma_f32_16x16x32_bf16 v[82:85], v[202:205], v[234:237], v[82:85]
	v_mfma_f32_16x16x32_bf16 v[50:53], v[202:205], v[242:245], v[50:53]
	v_mfma_f32_16x16x32_bf16 v[74:77], v[210:213], v[234:237], v[74:77]
	v_mfma_f32_16x16x32_bf16 v[42:45], v[210:213], v[242:245], v[42:45]
	v_mfma_f32_16x16x32_bf16 v[66:69], v[218:221], v[234:237], v[66:69]
	v_mfma_f32_16x16x32_bf16 v[38:41], v[218:221], v[242:245], v[38:41]
	v_mfma_f32_16x16x32_bf16 v[58:61], v[226:229], v[234:237], v[58:61]
	v_mfma_f32_16x16x32_bf16 v[30:33], v[226:229], v[242:245], v[30:33]
	s_setprio 0
	s_mov_b32 m0, s17
	v_lshl_add_u64 v[248:249], s[14:15], 0, v[132:133]
	s_barrier
	ds_read_b128 v[198:201], v166 offset:16384
	ds_read_b128 v[202:205], v166 offset:17408
	ds_read_b128 v[206:209], v166 offset:18432
	ds_read_b128 v[210:213], v166 offset:19456
	ds_read_b128 v[214:217], v166 offset:20480
	ds_read_b128 v[218:221], v166 offset:21504
	ds_read_b128 v[222:225], v166 offset:22528
	ds_read_b128 v[226:229], v166 offset:23552
	global_load_lds_dwordx4 v[248:249], off
	v_lshl_add_u64 v[192:193], s[14:15], 0, v[130:131]
	s_mov_b32 m0, s20
	s_nop 0
	global_load_lds_dwordx4 v[192:193], off
	s_barrier
	s_waitcnt lgkmcnt(0)
	s_setprio 1
	v_mfma_f32_16x16x32_bf16 v[98:101], v[198:201], v[158:161], v[98:101]
	v_mfma_f32_16x16x32_bf16 v[70:73], v[198:201], v[172:175], v[70:73]
	v_mfma_f32_16x16x32_bf16 v[90:93], v[206:209], v[158:161], v[90:93]
	v_mfma_f32_16x16x32_bf16 v[62:65], v[206:209], v[172:175], v[62:65]
	v_mfma_f32_16x16x32_bf16 v[86:89], v[214:217], v[158:161], v[86:89]
	v_mfma_f32_16x16x32_bf16 v[54:57], v[214:217], v[172:175], v[54:57]
	v_mfma_f32_16x16x32_bf16 v[78:81], v[222:225], v[158:161], v[78:81]
	v_mfma_f32_16x16x32_bf16 v[46:49], v[222:225], v[172:175], v[46:49]
	v_mfma_f32_16x16x32_bf16 v[98:101], v[202:205], v[168:171], v[98:101]
	v_mfma_f32_16x16x32_bf16 v[70:73], v[202:205], v[194:197], v[70:73]
	v_mfma_f32_16x16x32_bf16 v[90:93], v[210:213], v[168:171], v[90:93]
	v_mfma_f32_16x16x32_bf16 v[62:65], v[210:213], v[194:197], v[62:65]
	v_mfma_f32_16x16x32_bf16 v[86:89], v[218:221], v[168:171], v[86:89]
	v_mfma_f32_16x16x32_bf16 v[54:57], v[218:221], v[194:197], v[54:57]
	v_mfma_f32_16x16x32_bf16 v[78:81], v[226:229], v[168:171], v[78:81]
	v_mfma_f32_16x16x32_bf16 v[46:49], v[226:229], v[194:197], v[46:49]
	s_setprio 0
	s_barrier
; #define PG8_STAGE(bufoff, gbase) do { _Pragma("unroll") for (int _i = 0; _i < 2; ++_i) \
;         __builtin_amdgcn_global_load_lds((const unsigned*)((const char*)(gbase) + voff[_i]), (LAS unsigned*)(lds + (bufoff) + ldsw + _i * 8192), 16, 0, 0); } while (0)
; #define PG8_LDA(dst, b, h) do { _Pragma("unroll") for (int m = 0; m < 4; ++m) _Pragma("unroll") for (int k = 0; k < 2; ++k) dst[m][k] = *(const LAS bf16x8*)(lds + PG8_SA(b, h) + aoff + m * 2048 + k * 1024); } while (0)
; #define PG8_LDB(dst, b, h) do { _Pragma("unroll") for (int n = 0; n < 2; ++n) _Pragma("unroll") for (int k = 0; k < 2; ++k) dst[n][k] = *(const LAS bf16x8*)(lds + PG8_SB(b, h) + boff + n * 2048 + k * 1024); } while (0)
; #define PG8_WAIT_V(n) asm volatile("s_waitcnt vmcnt(" #n ")" ::: "memory")
; #define PG8_WAIT_L(n) asm volatile("s_waitcnt lgkmcnt(" #n ")" ::: "memory")
; #define PG8_BAR __builtin_amdgcn_s_barrier()
; #define PG8_SCHED __builtin_amdgcn_sched_barrier(0)
;     ...
;             PG8_STAGE(PG8_SB(0, 1), b2 + hstep);
;             PG8_WAIT_V(6); PG8_BAR; PG8_MMA(1, 1, At, B1); PG8_BAR;
;             PG8_LDB(B0, 1, 0); PG8_SCHED; PG8_LDA(At, 1, 0); PG8_STAGE(PG8_SA(0, 1), a2 + hstep);
;             PG8_WAIT_L(8); PG8_BAR; PG8_WAIT_L(0); PG8_MMA(0, 0, At, B0); PG8_BAR; PG8_SCHED;
;             PG8_LDB(B1, 1, 1); PG8_STAGE(PG8_SB(1, 0), b3);
;             PG8_BAR; PG8_WAIT_L(0); PG8_MMA(0, 1, At, B1); PG8_BAR;
;             PG8_LDA(At, 1, 1); PG8_STAGE(PG8_SA(1, 0), a3);
	s_add_u32 s30, s12, 0x40000
	s_addc_u32 s31, s13, 0
	s_add_i32 s0, s0, s16
	v_lshl_add_u64 v[158:159], s[30:31], 0, v[132:133]
	s_mov_b32 m0, s0
	s_nop 0
	global_load_lds_dwordx4 v[158:159], off
	v_lshl_add_u64 v[158:159], s[30:31], 0, v[130:131]
	s_add_i32 m0, s0, 0x2000
	s_nop 0
	global_load_lds_dwordx4 v[158:159], off
	s_waitcnt vmcnt(6)
	s_barrier
	s_setprio 1
	v_mfma_f32_16x16x32_bf16 v[34:37], v[198:201], v[230:233], v[34:37]
	v_mfma_f32_16x16x32_bf16 v[14:17], v[198:201], v[238:241], v[14:17]
	v_mfma_f32_16x16x32_bf16 v[26:29], v[206:209], v[230:233], v[26:29]
	v_mfma_f32_16x16x32_bf16 v[10:13], v[206:209], v[238:241], v[10:13]
	v_mfma_f32_16x16x32_bf16 v[22:25], v[214:217], v[230:233], v[22:25]
	v_mfma_f32_16x16x32_bf16 v[6:9], v[214:217], v[238:241], v[6:9]
	v_mfma_f32_16x16x32_bf16 v[18:21], v[222:225], v[230:233], v[18:21]
	v_mfma_f32_16x16x32_bf16 v[2:5], v[222:225], v[238:241], v[2:5]
	v_mfma_f32_16x16x32_bf16 v[34:37], v[202:205], v[234:237], v[34:37]
	v_mfma_f32_16x16x32_bf16 v[14:17], v[202:205], v[242:245], v[14:17]
	v_mfma_f32_16x16x32_bf16 v[26:29], v[210:213], v[234:237], v[26:29]
	v_mfma_f32_16x16x32_bf16 v[10:13], v[210:213], v[242:245], v[10:13]
	v_mfma_f32_16x16x32_bf16 v[22:25], v[218:221], v[234:237], v[22:25]
	v_mfma_f32_16x16x32_bf16 v[6:9], v[218:221], v[242:245], v[6:9]
	v_mfma_f32_16x16x32_bf16 v[18:21], v[226:229], v[234:237], v[18:21]
	v_mfma_f32_16x16x32_bf16 v[2:5], v[226:229], v[242:245], v[2:5]
	s_setprio 0
	s_add_i32 s0, 0, 0x18000
	v_add_u32_e32 v194, s0, v1
	s_barrier
	ds_read_b128 v[158:161], v194
	ds_read_b128 v[168:171], v194 offset:1024
	ds_read_b128 v[172:175], v194 offset:2048
	ds_read_b128 v[194:197], v194 offset:3072
	s_add_u32 s14, s14, 0x40000
	s_addc_u32 s15, s15, 0
	s_mov_b32 m0, s40
	v_lshl_add_u64 v[230:231], s[14:15], 0, v[132:133]
	ds_read_b128 v[198:201], v166 offset:32768
	ds_read_b128 v[202:205], v166 offset:33792
	ds_read_b128 v[206:209], v166 offset:34816
	ds_read_b128 v[210:213], v166 offset:35840
	ds_read_b128 v[214:217], v166 offset:36864
	ds_read_b128 v[218:221], v166 offset:37888
	ds_read_b128 v[222:225], v166 offset:38912
	ds_read_b128 v[226:229], v166 offset:39936
	global_load_lds_dwordx4 v[230:231], off
	v_lshl_add_u64 v[230:231], s[14:15], 0, v[130:131]
	s_mov_b32 m0, s41
	s_nop 0
	global_load_lds_dwordx4 v[230:231], off
	s_waitcnt lgkmcnt(8)
	s_barrier
	s_waitcnt lgkmcnt(0)
	s_setprio 1
	v_mfma_f32_16x16x32_bf16 v[126:129], v[198:201], v[158:161], v[126:129]
	v_mfma_f32_16x16x32_bf16 v[110:113], v[198:201], v[172:175], v[110:113]
	v_mfma_f32_16x16x32_bf16 v[122:125], v[206:209], v[158:161], v[122:125]
	v_mfma_f32_16x16x32_bf16 v[106:109], v[206:209], v[172:175], v[106:109]
	v_mfma_f32_16x16x32_bf16 v[118:121], v[214:217], v[158:161], v[118:121]
	v_mfma_f32_16x16x32_bf16 v[102:105], v[214:217], v[172:175], v[102:105]
	v_mfma_f32_16x16x32_bf16 v[114:117], v[222:225], v[158:161], v[114:117]
	v_mfma_f32_16x16x32_bf16 v[94:97], v[222:225], v[172:175], v[94:97]
	v_mfma_f32_16x16x32_bf16 v[126:129], v[202:205], v[168:171], v[126:129]
	v_mfma_f32_16x16x32_bf16 v[110:113], v[202:205], v[194:197], v[110:113]
	v_mfma_f32_16x16x32_bf16 v[122:125], v[210:213], v[168:171], v[122:125]
	v_mfma_f32_16x16x32_bf16 v[106:109], v[210:213], v[194:197], v[106:109]
	v_mfma_f32_16x16x32_bf16 v[118:121], v[218:221], v[168:171], v[118:121]
	v_mfma_f32_16x16x32_bf16 v[102:105], v[218:221], v[194:197], v[102:105]
	v_mfma_f32_16x16x32_bf16 v[114:117], v[226:229], v[168:171], v[114:117]
	v_mfma_f32_16x16x32_bf16 v[94:97], v[226:229], v[194:197], v[94:97]
	s_setprio 0
	s_barrier
	s_add_i32 s1, 0, 0x1c000
	s_add_i32 s0, s0, s16
	v_add_u32_e32 v242, s1, v1
	v_lshl_add_u64 v[162:163], v[162:163], 0, s[88:89]
	s_mov_b32 m0, s0
	ds_read_b128 v[230:233], v242
	ds_read_b128 v[234:237], v242 offset:1024
	ds_read_b128 v[238:241], v242 offset:2048
	ds_read_b128 v[242:245], v242 offset:3072
	global_load_lds_dwordx4 v[162:163], off
	v_lshl_add_u64 v[162:163], v[246:247], 0, s[88:89]
	s_add_i32 m0, s0, 0x2000
	s_nop 0
	global_load_lds_dwordx4 v[162:163], off
	s_barrier
	s_waitcnt lgkmcnt(0)
	s_setprio 1
	v_mfma_f32_16x16x32_bf16 v[82:85], v[198:201], v[230:233], v[82:85]
	v_mfma_f32_16x16x32_bf16 v[50:53], v[198:201], v[238:241], v[50:53]
	v_mfma_f32_16x16x32_bf16 v[74:77], v[206:209], v[230:233], v[74:77]
	v_mfma_f32_16x16x32_bf16 v[42:45], v[206:209], v[238:241], v[42:45]
	v_mfma_f32_16x16x32_bf16 v[66:69], v[214:217], v[230:233], v[66:69]
	v_mfma_f32_16x16x32_bf16 v[38:41], v[214:217], v[238:241], v[38:41]
	v_mfma_f32_16x16x32_bf16 v[58:61], v[222:225], v[230:233], v[58:61]
	v_mfma_f32_16x16x32_bf16 v[30:33], v[222:225], v[238:241], v[30:33]
	v_mfma_f32_16x16x32_bf16 v[82:85], v[202:205], v[234:237], v[82:85]
	v_mfma_f32_16x16x32_bf16 v[50:53], v[202:205], v[242:245], v[50:53]
	v_mfma_f32_16x16x32_bf16 v[74:77], v[210:213], v[234:237], v[74:77]
	v_mfma_f32_16x16x32_bf16 v[42:45], v[210:213], v[242:245], v[42:45]
	v_mfma_f32_16x16x32_bf16 v[66:69], v[218:221], v[234:237], v[66:69]
	v_mfma_f32_16x16x32_bf16 v[38:41], v[218:221], v[242:245], v[38:41]
	v_mfma_f32_16x16x32_bf16 v[58:61], v[226:229], v[234:237], v[58:61]
	v_mfma_f32_16x16x32_bf16 v[30:33], v[226:229], v[242:245], v[30:33]
	s_setprio 0
	s_mov_b32 m0, s58
	v_lshl_add_u64 v[162:163], v[248:249], 0, s[88:89]
	s_barrier
	ds_read_b128 v[198:201], v166 offset:49152
	ds_read_b128 v[202:205], v166 offset:50176
	ds_read_b128 v[206:209], v166 offset:51200
	ds_read_b128 v[210:213], v166 offset:52224
	ds_read_b128 v[214:217], v166 offset:53248
	ds_read_b128 v[218:221], v166 offset:54272
	ds_read_b128 v[222:225], v166 offset:55296
	ds_read_b128 v[226:229], v166 offset:56320
	global_load_lds_dwordx4 v[162:163], off
	v_lshl_add_u64 v[162:163], v[192:193], 0, s[88:89]
	s_mov_b32 m0, s59
	s_nop 0
	global_load_lds_dwordx4 v[162:163], off
	s_barrier
; #define PG8_STAGE(bufoff, gbase) do { _Pragma("unroll") for (int _i = 0; _i < 2; ++_i) \
;         __builtin_amdgcn_global_load_lds((const unsigned*)((const char*)(gbase) + voff[_i]), (LAS unsigned*)(lds + (bufoff) + ldsw + _i * 8192), 16, 0, 0); } while (0)
; #define PG8_WAIT_V(n) asm volatile("s_waitcnt vmcnt(" #n ")" ::: "memory")
; #define PG8_WAIT_L(n) asm volatile("s_waitcnt lgkmcnt(" #n ")" ::: "memory")
; #define PG8_BAR __builtin_amdgcn_s_barrier()
; #define PG8_SCHED __builtin_amdgcn_sched_barrier(0)
;     ...
;             PG8_BAR; PG8_WAIT_L(0); PG8_MMA(1, 0, At, B0); PG8_BAR; PG8_SCHED;
;             PG8_STAGE(PG8_SB(1, 1), b3 + hstep);
;             PG8_WAIT_V(6); PG8_BAR; PG8_MMA(1, 1, At, B1); PG8_BAR;
;         }
;         E(acc, cur.pm + pm0, cur.pn, wr, wc, fr, fq);
;         if (!has_next) break;
;     __device__ __forceinline__ void operator()(Acc& acc, int pm, int pn, int wr, int wc, int fr, int fq) const {
;         if (pn >= 8) { store_vT(acc, vT, (pn - 8) * 256, pm, wr, wc, fr, fq); return; }
;         const int head = pn * 4 + wc;
;         const bool isk = head >= 16;
;         const float* g = isk ? kg : qg;
;         const float sc = isk ? 1.0f : 0.125f;
;         float gv[2][2];
; #pragma unroll
;         for (int bj = 0; bj < 2; ++bj)
; #pragma unroll
;             for (int n = 0; n < 2; ++n) gv[bj][n] = g[bj * 32 + n * 16 + fr] * sc;
; #pragma unroll
;         for (int ai = 0; ai < 2; ++ai)
; #pragma unroll
;             for (int m = 0; m < 4; ++m)
; #pragma unroll
;                 for (int j = 0; j < 4; ++j) {
;                     float ss = acc[ai][0][m][0][j] * acc[ai][0][m][0][j] + acc[ai][0][m][1][j] * acc[ai][0][m][1][j] +
;                                acc[ai][1][m][0][j] * acc[ai][1][m][0][j] + acc[ai][1][m][1][j] * acc[ai][1][m][1][j];
;                     ss += __shfl_xor(ss, 1); ss += __shfl_xor(ss, 2); ss += __shfl_xor(ss, 4); ss += __shfl_xor(ss, 8);
	s_waitcnt lgkmcnt(0)
	s_setprio 1
	v_mfma_f32_16x16x32_bf16 v[98:101], v[198:201], v[158:161], v[98:101]
	v_mfma_f32_16x16x32_bf16 v[70:73], v[198:201], v[172:175], v[70:73]
	v_mfma_f32_16x16x32_bf16 v[90:93], v[206:209], v[158:161], v[90:93]
	v_mfma_f32_16x16x32_bf16 v[62:65], v[206:209], v[172:175], v[62:65]
	v_mfma_f32_16x16x32_bf16 v[86:89], v[214:217], v[158:161], v[86:89]
	v_mfma_f32_16x16x32_bf16 v[54:57], v[214:217], v[172:175], v[54:57]
	v_mfma_f32_16x16x32_bf16 v[78:81], v[222:225], v[158:161], v[78:81]
	v_mfma_f32_16x16x32_bf16 v[46:49], v[222:225], v[172:175], v[46:49]
	v_mfma_f32_16x16x32_bf16 v[98:101], v[202:205], v[168:171], v[98:101]
	v_mfma_f32_16x16x32_bf16 v[70:73], v[202:205], v[194:197], v[70:73]
	v_mfma_f32_16x16x32_bf16 v[90:93], v[210:213], v[168:171], v[90:93]
	v_mfma_f32_16x16x32_bf16 v[62:65], v[210:213], v[194:197], v[62:65]
	v_mfma_f32_16x16x32_bf16 v[86:89], v[218:221], v[168:171], v[86:89]
	v_mfma_f32_16x16x32_bf16 v[54:57], v[218:221], v[194:197], v[54:57]
	v_mfma_f32_16x16x32_bf16 v[78:81], v[226:229], v[168:171], v[78:81]
	v_mfma_f32_16x16x32_bf16 v[46:49], v[226:229], v[194:197], v[46:49]
	s_setprio 0
	s_barrier
	s_add_u32 s12, s12, 0x40080
	s_addc_u32 s13, s13, 0
	s_add_i32 s0, s1, s16
	v_lshl_add_u64 v[158:159], s[12:13], 0, v[132:133]
	s_mov_b32 m0, s0
	s_nop 0
	global_load_lds_dwordx4 v[158:159], off
	v_lshl_add_u64 v[158:159], s[12:13], 0, v[130:131]
	s_add_i32 m0, s0, 0x2000
	s_nop 0
	global_load_lds_dwordx4 v[158:159], off
	s_waitcnt vmcnt(6)
	s_barrier
	s_setprio 1
	v_mfma_f32_16x16x32_bf16 v[34:37], v[198:201], v[230:233], v[34:37]
	v_mfma_f32_16x16x32_bf16 v[14:17], v[198:201], v[238:241], v[14:17]
	v_mfma_f32_16x16x32_bf16 v[26:29], v[206:209], v[230:233], v[26:29]
	v_mfma_f32_16x16x32_bf16 v[10:13], v[206:209], v[238:241], v[10:13]
	v_mfma_f32_16x16x32_bf16 v[22:25], v[214:217], v[230:233], v[22:25]
	v_mfma_f32_16x16x32_bf16 v[6:9], v[214:217], v[238:241], v[6:9]
	v_mfma_f32_16x16x32_bf16 v[18:21], v[222:225], v[230:233], v[18:21]
	v_mfma_f32_16x16x32_bf16 v[2:5], v[222:225], v[238:241], v[2:5]
	v_mfma_f32_16x16x32_bf16 v[34:37], v[202:205], v[234:237], v[34:37]
	v_mfma_f32_16x16x32_bf16 v[14:17], v[202:205], v[242:245], v[14:17]
	v_mfma_f32_16x16x32_bf16 v[26:29], v[210:213], v[234:237], v[26:29]
	v_mfma_f32_16x16x32_bf16 v[10:13], v[210:213], v[242:245], v[10:13]
	v_mfma_f32_16x16x32_bf16 v[22:25], v[218:221], v[234:237], v[22:25]
	v_mfma_f32_16x16x32_bf16 v[6:9], v[218:221], v[242:245], v[6:9]
	v_mfma_f32_16x16x32_bf16 v[18:21], v[226:229], v[234:237], v[18:21]
	v_mfma_f32_16x16x32_bf16 v[2:5], v[226:229], v[242:245], v[2:5]
	s_setprio 0
	s_add_i32 s28, s28, 2
	s_add_u32 s10, s10, 0x100
	s_addc_u32 s11, s11, 0
	s_add_u32 s22, s22, 0x100
	s_addc_u32 s23, s23, 0
	s_cmp_gt_u32 s28, 13
	s_barrier
	s_cbranch_scc0 .LBB0_161
	s_cmp_lt_i32 s95, 8
	s_mov_b64 s[10:11], -1
	s_cbranch_scc0 .LBB0_164
	s_lshl_b32 s0, s95, 2
	s_or_b32 s0, s0, s90
	s_cmp_gt_i32 s0, 15
	s_cselect_b64 s[10:11], -1, 0
	v_readlane_b32 s60, v254, 42
	v_cndmask_b32_e64 v158, v189, 1.0, s[10:11]
	s_and_b64 s[10:11], s[10:11], exec
	v_readlane_b32 s72, v254, 54
	v_readlane_b32 s73, v254, 55
	v_readlane_b32 s74, v254, 56
	v_readlane_b32 s75, v254, 57
	s_cselect_b32 s11, s75, s73
	s_cselect_b32 s10, s74, s72
	global_load_dword v159, v167, s[10:11]
	v_mov_b32_e32 v162, v126
	v_mov_b32_e32 v163, v110
	v_mov_b32_e32 v198, v127
	v_mov_b32_e32 v199, v111
	v_pk_mul_f32 v[162:163], v[162:163], v[162:163]
	v_mov_b32_e32 v194, v82
	v_mov_b32_e32 v195, v50
	v_pk_mul_f32 v[198:199], v[198:199], v[198:199]
	v_mov_b32_e32 v200, v83
	v_mov_b32_e32 v201, v51
	v_pk_mul_f32 v[194:195], v[194:195], v[194:195]
	v_pk_mul_f32 v[200:201], v[200:201], v[200:201]
	v_mov_b32_e32 v202, v198
	v_mov_b32_e32 v203, v162
	v_mov_b32_e32 v162, v199
	v_cmp_lt_i32_e32 vcc, v188, v182
	v_pk_add_f32 v[162:163], v[202:203], v[162:163]
	v_mov_b32_e32 v198, v200
	v_mov_b32_e32 v199, v194
	v_pk_add_f32 v[162:163], v[162:163], v[198:199]
	v_mov_b32_e32 v194, v201
	v_pk_add_f32 v[162:163], v[162:163], v[194:195]
	s_mov_b32 s4, 0x358637bd
	v_lshl_add_u32 v160, s5, 8, v164
	v_ashrrev_i32_e32 v161, 31, v160
	v_lshlrev_b64 v[196:197], 12, v[160:161]
	v_mov_b32_e32 v200, v129
	v_mov_b32_e32 v201, v113
	v_pk_mul_f32 v[200:201], v[200:201], v[200:201]
	v_mov_b32_e32 v202, v85
	v_mov_b32_e32 v203, v53
	v_pk_mul_f32 v[202:203], v[202:203], v[202:203]
	v_mov_b32_e32 v204, v200
	v_mov_b32_e32 v200, v202
	v_or_b32_e32 v198, 2, v160
	v_ashrrev_i32_e32 v199, 31, v198
	v_lshlrev_b64 v[198:199], 12, v[198:199]
	v_mov_b32_e32 v202, v75
	v_readlane_b32 s74, v255, 22
	v_readlane_b32 s61, v254, 43
	v_readlane_b32 s62, v254, 44
	v_readlane_b32 s63, v254, 45
	v_readlane_b32 s64, v254, 46
	v_readlane_b32 s65, v254, 47
	v_readlane_b32 s66, v254, 48
	v_readlane_b32 s67, v254, 49
	v_readlane_b32 s68, v254, 50
	v_readlane_b32 s69, v254, 51
	v_readlane_b32 s70, v254, 52
	v_readlane_b32 s71, v254, 53
	v_readlane_b32 s75, v255, 23
	s_waitcnt vmcnt(0)
	v_mul_f32_e32 v168, v158, v159
	global_load_dword v159, v167, s[10:11] offset:64
	s_waitcnt vmcnt(0)
	v_mul_f32_e32 v169, v158, v159
	global_load_dword v159, v167, s[10:11] offset:128
	s_waitcnt vmcnt(0)
	v_mul_f32_e32 v170, v158, v159
	global_load_dword v159, v167, s[10:11] offset:192
	s_lshl_b32 s10, s0, 6
	s_ashr_i32 s11, s10, 31
	s_waitcnt vmcnt(0)
	v_mul_f32_e32 v171, v158, v159
	v_cndmask_b32_e32 v158, v180, v188, vcc
	v_lshlrev_b32_e32 v175, 2, v158
	ds_bpermute_b32 v195, v175, v163
	ds_bpermute_b32 v194, v175, v162
	v_cmp_lt_i32_e32 vcc, v187, v182
	s_waitcnt lgkmcnt(0)
; __device__ __forceinline__ unsigned f2bf(float f) { const __bf16 b = (__bf16)f; return (unsigned)__builtin_bit_cast(unsigned short, b); }
;     __device__ __forceinline__ void operator()(Acc& acc, int pm, int pn, int wr, int wc, int fr, int fq) const {
;     ...
;         for (int ai = 0; ai < 2; ++ai)
; #pragma unroll
;             for (int m = 0; m < 4; ++m)
; #pragma unroll
;                 for (int j = 0; j < 4; ++j) {
;                     float ss = acc[ai][0][m][0][j] * acc[ai][0][m][0][j] + acc[ai][0][m][1][j] * acc[ai][0][m][1][j] +
;                                acc[ai][1][m][0][j] * acc[ai][1][m][0][j] + acc[ai][1][m][1][j] * acc[ai][1][m][1][j];
;                     ss += __shfl_xor(ss, 1); ss += __shfl_xor(ss, 2); ss += __shfl_xor(ss, 4); ss += __shfl_xor(ss, 8);
;                     const float rs = rsqrtf(ss * (1.0f / 64.0f) + EPSV);
;                     bf16_t* rp = qk + (size_t)(pm * 256 + ai * 128 + wr * 64 + m * 16 + fq * 4 + j) * 2048 + head * 64 + fr;
; #pragma unroll
;                     for (int bj = 0; bj < 2; ++bj)
; #pragma unroll
;                         for (int n = 0; n < 2; ++n) rp[bj * 32 + n * 16] = (bf16_t)f2bf(acc[ai][bj][m][n][j] * rs * gv[bj][n]);
;                 }
	v_pk_add_f32 v[162:163], v[162:163], v[194:195]
	v_cndmask_b32_e32 v158, v180, v187, vcc
	v_lshlrev_b32_e32 v174, 2, v158
	ds_bpermute_b32 v195, v174, v163
	ds_bpermute_b32 v194, v174, v162
	v_cmp_lt_i32_e32 vcc, v186, v182
	s_waitcnt lgkmcnt(0)
	v_pk_add_f32 v[162:163], v[162:163], v[194:195]
	v_cndmask_b32_e32 v158, v180, v186, vcc
	v_lshlrev_b32_e32 v173, 2, v158
	ds_bpermute_b32 v195, v173, v163
	ds_bpermute_b32 v194, v173, v162
	v_cmp_lt_i32_e32 vcc, v185, v182
	s_waitcnt lgkmcnt(0)
	v_pk_add_f32 v[162:163], v[162:163], v[194:195]
	v_cndmask_b32_e32 v158, v180, v185, vcc
	v_lshlrev_b32_e32 v172, 2, v158
	ds_bpermute_b32 v195, v172, v163
	ds_bpermute_b32 v194, v172, v162
	v_lshl_add_u64 v[158:159], s[10:11], 1, v[150:151]
	v_lshl_add_u64 v[196:197], v[158:159], 0, v[196:197]
	v_lshl_add_u64 v[198:199], v[158:159], 0, v[198:199]
	s_mov_b64 s[10:11], 0
	s_waitcnt lgkmcnt(0)
	v_pk_add_f32 v[194:195], v[162:163], v[194:195]
	v_mov_b64_e32 v[162:163], s[4:5]
	v_pk_fma_f32 v[194:195], v[194:195], s[8:9], v[162:163] op_sel_hi:[1,0,0]
	s_nop 0
	v_mul_f32_e32 v161, 0x4b800000, v195
	v_cmp_gt_f32_e64 s[46:47], s93, v195
	v_cmp_gt_f32_e32 vcc, s93, v194
	s_nop 0
	v_cndmask_b32_e64 v161, v195, v161, s[46:47]
	v_rsq_f32_e32 v161, v161
	s_nop 0
	v_mul_f32_e32 v192, 0x45800000, v161
	v_cndmask_b32_e64 v161, v161, v192, s[46:47]
	v_mul_f32_e32 v192, v126, v161
	v_mul_f32_e32 v192, v168, v192
	v_cvt_pk_bf16_f32 v192, v192, s0
	global_store_short v[196:197], v192, off
	v_mul_f32_e32 v192, v110, v161
	v_mul_f32_e32 v192, v169, v192
	v_cvt_pk_bf16_f32 v192, v192, s0
	global_store_short v[196:197], v192, off offset:32
	v_mul_f32_e32 v192, v82, v161
	v_mul_f32_e32 v161, v50, v161
	v_mul_f32_e32 v161, v171, v161
	v_cvt_pk_bf16_f32 v161, v161, s0
	global_store_short v[196:197], v161, off offset:96
	v_mul_f32_e32 v161, 0x4b800000, v194
	v_cndmask_b32_e32 v161, v194, v161, vcc
	v_rsq_f32_e32 v161, v161
	v_mul_f32_e32 v192, v170, v192
	v_cvt_pk_bf16_f32 v192, v192, s0
	global_store_short v[196:197], v192, off offset:64
	v_mul_f32_e32 v192, 0x45800000, v161
	v_cndmask_b32_e32 v161, v161, v192, vcc
	v_or_b32_e32 v194, 1, v160
	v_ashrrev_i32_e32 v195, 31, v194
	v_mul_f32_e32 v192, v127, v161
	v_lshlrev_b64 v[194:195], 12, v[194:195]
	v_mul_f32_e32 v192, v168, v192
	v_lshl_add_u64 v[194:195], v[158:159], 0, v[194:195]
	v_cvt_pk_bf16_f32 v192, v192, s0
	global_store_short v[194:195], v192, off
	v_mul_f32_e32 v192, v111, v161
	v_mul_f32_e32 v192, v169, v192
	v_cvt_pk_bf16_f32 v192, v192, s0
	global_store_short v[194:195], v192, off offset:32
	v_mul_f32_e32 v192, v83, v161
	v_mul_f32_e32 v161, v51, v161
	v_mul_f32_e32 v192, v170, v192
	v_mul_f32_e32 v161, v171, v161
	v_cvt_pk_bf16_f32 v192, v192, s0
	v_cvt_pk_bf16_f32 v161, v161, s0
	global_store_short v[194:195], v192, off offset:64
	global_store_short v[194:195], v161, off offset:96
	v_mov_b32_e32 v194, v128
	v_mov_b32_e32 v195, v112
	v_pk_mul_f32 v[194:195], v[194:195], v[194:195]
	v_mov_b32_e32 v196, v84
	v_mov_b32_e32 v197, v52
	v_pk_mul_f32 v[196:197], v[196:197], v[196:197]
	v_mov_b32_e32 v205, v194
	v_mov_b32_e32 v194, v201
	v_pk_add_f32 v[194:195], v[204:205], v[194:195]
	v_mov_b32_e32 v201, v196
	v_pk_add_f32 v[194:195], v[194:195], v[200:201]
	v_mov_b32_e32 v196, v203
	v_pk_add_f32 v[194:195], v[194:195], v[196:197]
	ds_bpermute_b32 v197, v175, v195
	ds_bpermute_b32 v196, v175, v194
	v_mov_b32_e32 v200, v123
	v_mov_b32_e32 v201, v107
	v_pk_mul_f32 v[200:201], v[200:201], v[200:201]
	v_mov_b32_e32 v203, v43
	s_waitcnt lgkmcnt(0)
	v_pk_add_f32 v[194:195], v[194:195], v[196:197]
	ds_bpermute_b32 v197, v174, v195
	ds_bpermute_b32 v196, v174, v194
	v_pk_mul_f32 v[202:203], v[202:203], v[202:203]
	v_mov_b32_e32 v204, v200
	v_mov_b32_e32 v200, v202
	v_mov_b32_e32 v202, v77
	s_waitcnt lgkmcnt(0)
	v_pk_add_f32 v[194:195], v[194:195], v[196:197]
	ds_bpermute_b32 v197, v173, v195
	ds_bpermute_b32 v196, v173, v194
	s_waitcnt lgkmcnt(0)
	v_pk_add_f32 v[194:195], v[194:195], v[196:197]
	ds_bpermute_b32 v197, v172, v195
	ds_bpermute_b32 v196, v172, v194
	s_waitcnt lgkmcnt(0)
	v_pk_add_f32 v[194:195], v[194:195], v[196:197]
	s_nop 0
	v_pk_fma_f32 v[194:195], v[194:195], s[8:9], v[162:163] op_sel_hi:[1,0,0]
	v_mov_b32_e32 v196, v122
	v_mul_f32_e32 v161, 0x4b800000, v195
	v_cmp_gt_f32_e64 s[46:47], s93, v195
	v_mov_b32_e32 v197, v106
	v_pk_mul_f32 v[196:197], v[196:197], v[196:197]
	v_cndmask_b32_e64 v161, v195, v161, s[46:47]
	v_rsq_f32_e32 v161, v161
	v_mov_b32_e32 v205, v196
	v_mov_b32_e32 v196, v201
	v_pk_add_f32 v[196:197], v[204:205], v[196:197]
	v_mul_f32_e32 v192, 0x45800000, v161
	v_cndmask_b32_e64 v161, v161, v192, s[46:47]
	v_mul_f32_e32 v192, v128, v161
	v_mul_f32_e32 v192, v168, v192
	v_cvt_pk_bf16_f32 v192, v192, s0
	global_store_short v[198:199], v192, off
	v_mul_f32_e32 v192, v112, v161
	v_mul_f32_e32 v192, v169, v192
	v_cvt_pk_bf16_f32 v192, v192, s0
	global_store_short v[198:199], v192, off offset:32
	v_mul_f32_e32 v192, v84, v161
	v_mul_f32_e32 v161, v52, v161
	v_mul_f32_e32 v192, v170, v192
	v_mul_f32_e32 v161, v171, v161
	v_cvt_pk_bf16_f32 v192, v192, s0
	v_cvt_pk_bf16_f32 v161, v161, s0
	global_store_short v[198:199], v192, off offset:64
	global_store_short v[198:199], v161, off offset:96
	v_mov_b32_e32 v198, v74
	v_mov_b32_e32 v199, v42
	v_pk_mul_f32 v[198:199], v[198:199], v[198:199]
	v_cmp_gt_f32_e32 vcc, s93, v194
	v_mov_b32_e32 v201, v198
	v_pk_add_f32 v[196:197], v[196:197], v[200:201]
	v_mov_b32_e32 v198, v203
	v_pk_add_f32 v[196:197], v[196:197], v[198:199]
	ds_bpermute_b32 v199, v175, v197
	ds_bpermute_b32 v198, v175, v196
	v_mul_f32_e32 v161, 0x4b800000, v194
	v_cndmask_b32_e32 v161, v194, v161, vcc
	v_rsq_f32_e32 v161, v161
	v_or_b32_e32 v194, 3, v160
	s_waitcnt lgkmcnt(0)
; __device__ __forceinline__ unsigned f2bf(float f) { const __bf16 b = (__bf16)f; return (unsigned)__builtin_bit_cast(unsigned short, b); }
;     __device__ __forceinline__ void operator()(Acc& acc, int pm, int pn, int wr, int wc, int fr, int fq) const {
;     ...
;         for (int ai = 0; ai < 2; ++ai)
; #pragma unroll
;             for (int m = 0; m < 4; ++m)
; #pragma unroll
;                 for (int j = 0; j < 4; ++j) {
;                     float ss = acc[ai][0][m][0][j] * acc[ai][0][m][0][j] + acc[ai][0][m][1][j] * acc[ai][0][m][1][j] +
;                                acc[ai][1][m][0][j] * acc[ai][1][m][0][j] + acc[ai][1][m][1][j] * acc[ai][1][m][1][j];
;                     ss += __shfl_xor(ss, 1); ss += __shfl_xor(ss, 2); ss += __shfl_xor(ss, 4); ss += __shfl_xor(ss, 8);
;                     const float rs = rsqrtf(ss * (1.0f / 64.0f) + EPSV);
;                     bf16_t* rp = qk + (size_t)(pm * 256 + ai * 128 + wr * 64 + m * 16 + fq * 4 + j) * 2048 + head * 64 + fr;
; #pragma unroll
;                     for (int bj = 0; bj < 2; ++bj)
; #pragma unroll
;                         for (int n = 0; n < 2; ++n) rp[bj * 32 + n * 16] = (bf16_t)f2bf(acc[ai][bj][m][n][j] * rs * gv[bj][n]);
;                 }
	v_pk_add_f32 v[196:197], v[196:197], v[198:199]
	ds_bpermute_b32 v199, v174, v197
	ds_bpermute_b32 v198, v174, v196
	v_mul_f32_e32 v192, 0x45800000, v161
	v_cndmask_b32_e32 v161, v161, v192, vcc
	v_ashrrev_i32_e32 v195, 31, v194
	v_mul_f32_e32 v192, v129, v161
	s_waitcnt lgkmcnt(0)
	v_pk_add_f32 v[196:197], v[196:197], v[198:199]
	ds_bpermute_b32 v199, v173, v197
	ds_bpermute_b32 v198, v173, v196
	v_lshlrev_b64 v[194:195], 12, v[194:195]
	v_mul_f32_e32 v192, v168, v192
	v_lshl_add_u64 v[194:195], v[158:159], 0, v[194:195]
	v_cvt_pk_bf16_f32 v192, v192, s0
	s_waitcnt lgkmcnt(0)
	v_pk_add_f32 v[196:197], v[196:197], v[198:199]
	ds_bpermute_b32 v199, v172, v197
	ds_bpermute_b32 v198, v172, v196
	global_store_short v[194:195], v192, off
	v_mul_f32_e32 v192, v113, v161
	v_mul_f32_e32 v192, v169, v192
	v_cvt_pk_bf16_f32 v192, v192, s0
	global_store_short v[194:195], v192, off offset:32
	v_mul_f32_e32 v192, v85, v161
	v_mul_f32_e32 v161, v53, v161
	v_mul_f32_e32 v161, v171, v161
	s_waitcnt lgkmcnt(0)
	v_pk_add_f32 v[196:197], v[196:197], v[198:199]
	v_cvt_pk_bf16_f32 v161, v161, s0
	v_pk_fma_f32 v[196:197], v[196:197], s[8:9], v[162:163] op_sel_hi:[1,0,0]
	global_store_short v[194:195], v161, off offset:96
	v_mul_f32_e32 v161, 0x4b800000, v197
	v_cmp_gt_f32_e64 s[46:47], s93, v197
	v_mul_f32_e32 v192, v170, v192
	v_cvt_pk_bf16_f32 v192, v192, s0
	v_cndmask_b32_e64 v161, v197, v161, s[46:47]
	v_rsq_f32_e32 v161, v161
	global_store_short v[194:195], v192, off offset:64
	v_or_b32_e32 v194, 16, v160
	v_ashrrev_i32_e32 v195, 31, v194
	v_mul_f32_e32 v192, 0x45800000, v161
	v_cndmask_b32_e64 v161, v161, v192, s[46:47]
	v_mul_f32_e32 v192, v122, v161
	v_lshlrev_b64 v[194:195], 12, v[194:195]
	v_mul_f32_e32 v192, v168, v192
	v_lshl_add_u64 v[194:195], v[158:159], 0, v[194:195]
	v_cvt_pk_bf16_f32 v192, v192, s0
	global_store_short v[194:195], v192, off
	v_mul_f32_e32 v192, v106, v161
	v_mul_f32_e32 v192, v169, v192
	v_cvt_pk_bf16_f32 v192, v192, s0
	global_store_short v[194:195], v192, off offset:32
	v_mul_f32_e32 v192, v74, v161
	v_mul_f32_e32 v161, v42, v161
	v_mul_f32_e32 v161, v171, v161
	v_cvt_pk_bf16_f32 v161, v161, s0
	v_cmp_gt_f32_e32 vcc, s93, v196
	global_store_short v[194:195], v161, off offset:96
	v_mul_f32_e32 v161, 0x4b800000, v196
	v_cndmask_b32_e32 v161, v196, v161, vcc
	v_rsq_f32_e32 v161, v161
	v_mul_f32_e32 v192, v170, v192
	v_cvt_pk_bf16_f32 v192, v192, s0
	global_store_short v[194:195], v192, off offset:64
	v_mul_f32_e32 v192, 0x45800000, v161
	v_cndmask_b32_e32 v161, v161, v192, vcc
	v_or_b32_e32 v194, 17, v160
	v_ashrrev_i32_e32 v195, 31, v194
	v_mul_f32_e32 v192, v123, v161
	v_lshlrev_b64 v[194:195], 12, v[194:195]
	v_mul_f32_e32 v192, v168, v192
	v_lshl_add_u64 v[194:195], v[158:159], 0, v[194:195]
	v_cvt_pk_bf16_f32 v192, v192, s0
	global_store_short v[194:195], v192, off
	v_mul_f32_e32 v192, v107, v161
	v_mul_f32_e32 v192, v169, v192
	v_cvt_pk_bf16_f32 v192, v192, s0
	global_store_short v[194:195], v192, off offset:32
	v_mul_f32_e32 v192, v75, v161
	v_mul_f32_e32 v161, v43, v161
	v_mul_f32_e32 v192, v170, v192
	v_mul_f32_e32 v161, v171, v161
	v_cvt_pk_bf16_f32 v192, v192, s0
	v_cvt_pk_bf16_f32 v161, v161, s0
	global_store_short v[194:195], v192, off offset:64
	global_store_short v[194:195], v161, off offset:96
	v_mov_b32_e32 v194, v124
	v_mov_b32_e32 v195, v108
	v_mov_b32_e32 v200, v125
	v_mov_b32_e32 v201, v109
	v_pk_mul_f32 v[194:195], v[194:195], v[194:195]
	v_mov_b32_e32 v196, v76
	v_mov_b32_e32 v197, v44
	v_pk_mul_f32 v[200:201], v[200:201], v[200:201]
	v_mov_b32_e32 v203, v45
	v_pk_mul_f32 v[196:197], v[196:197], v[196:197]
	v_pk_mul_f32 v[202:203], v[202:203], v[202:203]
	v_mov_b32_e32 v204, v200
	v_mov_b32_e32 v205, v194
	v_mov_b32_e32 v194, v201
	v_pk_add_f32 v[194:195], v[204:205], v[194:195]
	v_mov_b32_e32 v200, v202
	v_mov_b32_e32 v201, v196
	v_pk_add_f32 v[194:195], v[194:195], v[200:201]
	v_mov_b32_e32 v196, v203
	v_pk_add_f32 v[194:195], v[194:195], v[196:197]
	ds_bpermute_b32 v197, v175, v195
	ds_bpermute_b32 v196, v175, v194
	v_or_b32_e32 v198, 18, v160
	v_ashrrev_i32_e32 v199, 31, v198
	v_lshlrev_b64 v[198:199], 12, v[198:199]
	v_lshl_add_u64 v[198:199], v[158:159], 0, v[198:199]
	s_waitcnt lgkmcnt(0)
	v_pk_add_f32 v[194:195], v[194:195], v[196:197]
	ds_bpermute_b32 v197, v174, v195
	ds_bpermute_b32 v196, v174, v194
	v_mov_b32_e32 v200, v119
	v_mov_b32_e32 v201, v103
	v_pk_mul_f32 v[200:201], v[200:201], v[200:201]
	v_mov_b32_e32 v202, v67
	s_waitcnt lgkmcnt(0)
	v_pk_add_f32 v[194:195], v[194:195], v[196:197]
	ds_bpermute_b32 v197, v173, v195
	ds_bpermute_b32 v196, v173, v194
	v_mov_b32_e32 v203, v39
	v_pk_mul_f32 v[202:203], v[202:203], v[202:203]
	v_mov_b32_e32 v204, v200
	v_mov_b32_e32 v200, v202
	s_waitcnt lgkmcnt(0)
	v_pk_add_f32 v[194:195], v[194:195], v[196:197]
	ds_bpermute_b32 v197, v172, v195
	ds_bpermute_b32 v196, v172, v194
	v_mov_b32_e32 v202, v69
	s_waitcnt lgkmcnt(0)
; __device__ __forceinline__ unsigned f2bf(float f) { const __bf16 b = (__bf16)f; return (unsigned)__builtin_bit_cast(unsigned short, b); }
;     __device__ __forceinline__ void operator()(Acc& acc, int pm, int pn, int wr, int wc, int fr, int fq) const {
;     ...
;         for (int ai = 0; ai < 2; ++ai)
; #pragma unroll
;             for (int m = 0; m < 4; ++m)
; #pragma unroll
;                 for (int j = 0; j < 4; ++j) {
;                     float ss = acc[ai][0][m][0][j] * acc[ai][0][m][0][j] + acc[ai][0][m][1][j] * acc[ai][0][m][1][j] +
;                                acc[ai][1][m][0][j] * acc[ai][1][m][0][j] + acc[ai][1][m][1][j] * acc[ai][1][m][1][j];
;                     ss += __shfl_xor(ss, 1); ss += __shfl_xor(ss, 2); ss += __shfl_xor(ss, 4); ss += __shfl_xor(ss, 8);
;                     const float rs = rsqrtf(ss * (1.0f / 64.0f) + EPSV);
;                     bf16_t* rp = qk + (size_t)(pm * 256 + ai * 128 + wr * 64 + m * 16 + fq * 4 + j) * 2048 + head * 64 + fr;
; #pragma unroll
;                     for (int bj = 0; bj < 2; ++bj)
; #pragma unroll
;                         for (int n = 0; n < 2; ++n) rp[bj * 32 + n * 16] = (bf16_t)f2bf(acc[ai][bj][m][n][j] * rs * gv[bj][n]);
;                 }
	v_pk_add_f32 v[194:195], v[194:195], v[196:197]
	s_nop 0
	v_pk_fma_f32 v[194:195], v[194:195], s[8:9], v[162:163] op_sel_hi:[1,0,0]
	v_mov_b32_e32 v196, v118
	v_mul_f32_e32 v161, 0x4b800000, v195
	v_cmp_gt_f32_e64 s[46:47], s93, v195
	v_mov_b32_e32 v197, v102
	v_pk_mul_f32 v[196:197], v[196:197], v[196:197]
	v_cndmask_b32_e64 v161, v195, v161, s[46:47]
	v_rsq_f32_e32 v161, v161
	v_mov_b32_e32 v205, v196
	v_mov_b32_e32 v196, v201
	v_pk_add_f32 v[196:197], v[204:205], v[196:197]
	v_mul_f32_e32 v192, 0x45800000, v161
	v_cndmask_b32_e64 v161, v161, v192, s[46:47]
	v_mul_f32_e32 v192, v124, v161
	v_mul_f32_e32 v192, v168, v192
	v_cvt_pk_bf16_f32 v192, v192, s0
	global_store_short v[198:199], v192, off
	v_mul_f32_e32 v192, v108, v161
	v_mul_f32_e32 v192, v169, v192
	v_cvt_pk_bf16_f32 v192, v192, s0
	global_store_short v[198:199], v192, off offset:32
	v_mul_f32_e32 v192, v76, v161
	v_mul_f32_e32 v161, v44, v161
	v_mul_f32_e32 v192, v170, v192
	v_mul_f32_e32 v161, v171, v161
	v_cvt_pk_bf16_f32 v192, v192, s0
	v_cvt_pk_bf16_f32 v161, v161, s0
	global_store_short v[198:199], v192, off offset:64
	global_store_short v[198:199], v161, off offset:96
	v_mov_b32_e32 v198, v66
	v_mov_b32_e32 v199, v38
	v_pk_mul_f32 v[198:199], v[198:199], v[198:199]
	v_cmp_gt_f32_e32 vcc, s93, v194
	v_mov_b32_e32 v201, v198
	v_pk_add_f32 v[196:197], v[196:197], v[200:201]
	v_mov_b32_e32 v198, v203
	v_pk_add_f32 v[196:197], v[196:197], v[198:199]
	ds_bpermute_b32 v199, v175, v197
	ds_bpermute_b32 v198, v175, v196
	v_mul_f32_e32 v161, 0x4b800000, v194
	v_cndmask_b32_e32 v161, v194, v161, vcc
	v_rsq_f32_e32 v161, v161
	v_or_b32_e32 v194, 19, v160
	s_waitcnt lgkmcnt(0)
	v_pk_add_f32 v[196:197], v[196:197], v[198:199]
	ds_bpermute_b32 v199, v174, v197
	ds_bpermute_b32 v198, v174, v196
	v_mul_f32_e32 v192, 0x45800000, v161
	v_cndmask_b32_e32 v161, v161, v192, vcc
	v_ashrrev_i32_e32 v195, 31, v194
	v_mul_f32_e32 v192, v125, v161
	s_waitcnt lgkmcnt(0)
	v_pk_add_f32 v[196:197], v[196:197], v[198:199]
	ds_bpermute_b32 v199, v173, v197
	ds_bpermute_b32 v198, v173, v196
	v_lshlrev_b64 v[194:195], 12, v[194:195]
	v_mul_f32_e32 v192, v168, v192
	v_lshl_add_u64 v[194:195], v[158:159], 0, v[194:195]
	v_cvt_pk_bf16_f32 v192, v192, s0
	s_waitcnt lgkmcnt(0)
	v_pk_add_f32 v[196:197], v[196:197], v[198:199]
	ds_bpermute_b32 v199, v172, v197
	ds_bpermute_b32 v198, v172, v196
	global_store_short v[194:195], v192, off
	v_mul_f32_e32 v192, v109, v161
	v_mul_f32_e32 v192, v169, v192
	v_cvt_pk_bf16_f32 v192, v192, s0
	global_store_short v[194:195], v192, off offset:32
	v_mul_f32_e32 v192, v77, v161
	v_mul_f32_e32 v161, v45, v161
	v_mul_f32_e32 v161, v171, v161
	s_waitcnt lgkmcnt(0)
	v_pk_add_f32 v[196:197], v[196:197], v[198:199]
	v_cvt_pk_bf16_f32 v161, v161, s0
	v_pk_fma_f32 v[196:197], v[196:197], s[8:9], v[162:163] op_sel_hi:[1,0,0]
	global_store_short v[194:195], v161, off offset:96
	v_mul_f32_e32 v161, 0x4b800000, v197
	v_cmp_gt_f32_e64 s[46:47], s93, v197
	v_mul_f32_e32 v192, v170, v192
	v_cvt_pk_bf16_f32 v192, v192, s0
	v_cndmask_b32_e64 v161, v197, v161, s[46:47]
	v_rsq_f32_e32 v161, v161
	global_store_short v[194:195], v192, off offset:64
	v_or_b32_e32 v194, 32, v160
	v_ashrrev_i32_e32 v195, 31, v194
	v_mul_f32_e32 v192, 0x45800000, v161
	v_cndmask_b32_e64 v161, v161, v192, s[46:47]
	v_mul_f32_e32 v192, v118, v161
	v_lshlrev_b64 v[194:195], 12, v[194:195]
	v_mul_f32_e32 v192, v168, v192
	v_lshl_add_u64 v[194:195], v[158:159], 0, v[194:195]
	v_cvt_pk_bf16_f32 v192, v192, s0
	global_store_short v[194:195], v192, off
	v_mul_f32_e32 v192, v102, v161
	v_mul_f32_e32 v192, v169, v192
	v_cvt_pk_bf16_f32 v192, v192, s0
	global_store_short v[194:195], v192, off offset:32
	v_mul_f32_e32 v192, v66, v161
	v_mul_f32_e32 v161, v38, v161
	v_mul_f32_e32 v161, v171, v161
	v_cvt_pk_bf16_f32 v161, v161, s0
	v_cmp_gt_f32_e32 vcc, s93, v196
	global_store_short v[194:195], v161, off offset:96
	v_mul_f32_e32 v161, 0x4b800000, v196
	v_cndmask_b32_e32 v161, v196, v161, vcc
	v_rsq_f32_e32 v161, v161
	v_mul_f32_e32 v192, v170, v192
	v_cvt_pk_bf16_f32 v192, v192, s0
	global_store_short v[194:195], v192, off offset:64
	v_mul_f32_e32 v192, 0x45800000, v161
	v_cndmask_b32_e32 v161, v161, v192, vcc
	v_or_b32_e32 v194, 33, v160
	v_ashrrev_i32_e32 v195, 31, v194
	v_mul_f32_e32 v192, v119, v161
	v_lshlrev_b64 v[194:195], 12, v[194:195]
	v_mul_f32_e32 v192, v168, v192
	v_lshl_add_u64 v[194:195], v[158:159], 0, v[194:195]
	v_cvt_pk_bf16_f32 v192, v192, s0
	global_store_short v[194:195], v192, off
	v_mul_f32_e32 v192, v103, v161
	v_mul_f32_e32 v192, v169, v192
	v_cvt_pk_bf16_f32 v192, v192, s0
	global_store_short v[194:195], v192, off offset:32
	v_mul_f32_e32 v192, v67, v161
	v_mul_f32_e32 v161, v39, v161
	v_mul_f32_e32 v192, v170, v192
	v_mul_f32_e32 v161, v171, v161
	v_cvt_pk_bf16_f32 v192, v192, s0
	v_cvt_pk_bf16_f32 v161, v161, s0
	global_store_short v[194:195], v192, off offset:64
	global_store_short v[194:195], v161, off offset:96
	v_mov_b32_e32 v194, v120
	v_mov_b32_e32 v195, v104
	v_mov_b32_e32 v200, v121
	v_mov_b32_e32 v201, v105
	v_pk_mul_f32 v[194:195], v[194:195], v[194:195]
	v_mov_b32_e32 v196, v68
	v_mov_b32_e32 v197, v40
	v_pk_mul_f32 v[200:201], v[200:201], v[200:201]
	v_mov_b32_e32 v203, v41
	v_pk_mul_f32 v[196:197], v[196:197], v[196:197]
	v_pk_mul_f32 v[202:203], v[202:203], v[202:203]
	v_mov_b32_e32 v204, v200
	v_mov_b32_e32 v205, v194
	v_mov_b32_e32 v194, v201
	v_pk_add_f32 v[194:195], v[204:205], v[194:195]
	v_mov_b32_e32 v200, v202
	v_mov_b32_e32 v201, v196
	v_pk_add_f32 v[194:195], v[194:195], v[200:201]
	v_mov_b32_e32 v196, v203
	v_pk_add_f32 v[194:195], v[194:195], v[196:197]
	ds_bpermute_b32 v197, v175, v195
	ds_bpermute_b32 v196, v175, v194
	v_or_b32_e32 v198, 34, v160
	v_ashrrev_i32_e32 v199, 31, v198
	v_lshlrev_b64 v[198:199], 12, v[198:199]
	v_lshl_add_u64 v[198:199], v[158:159], 0, v[198:199]
	s_waitcnt lgkmcnt(0)
; __device__ __forceinline__ unsigned f2bf(float f) { const __bf16 b = (__bf16)f; return (unsigned)__builtin_bit_cast(unsigned short, b); }
;     __device__ __forceinline__ void operator()(Acc& acc, int pm, int pn, int wr, int wc, int fr, int fq) const {
;     ...
;         for (int ai = 0; ai < 2; ++ai)
; #pragma unroll
;             for (int m = 0; m < 4; ++m)
; #pragma unroll
;                 for (int j = 0; j < 4; ++j) {
;                     float ss = acc[ai][0][m][0][j] * acc[ai][0][m][0][j] + acc[ai][0][m][1][j] * acc[ai][0][m][1][j] +
;                                acc[ai][1][m][0][j] * acc[ai][1][m][0][j] + acc[ai][1][m][1][j] * acc[ai][1][m][1][j];
;                     ss += __shfl_xor(ss, 1); ss += __shfl_xor(ss, 2); ss += __shfl_xor(ss, 4); ss += __shfl_xor(ss, 8);
;                     const float rs = rsqrtf(ss * (1.0f / 64.0f) + EPSV);
;                     bf16_t* rp = qk + (size_t)(pm * 256 + ai * 128 + wr * 64 + m * 16 + fq * 4 + j) * 2048 + head * 64 + fr;
; #pragma unroll
;                     for (int bj = 0; bj < 2; ++bj)
; #pragma unroll
;                         for (int n = 0; n < 2; ++n) rp[bj * 32 + n * 16] = (bf16_t)f2bf(acc[ai][bj][m][n][j] * rs * gv[bj][n]);
;                 }
	v_pk_add_f32 v[194:195], v[194:195], v[196:197]
	ds_bpermute_b32 v197, v174, v195
	ds_bpermute_b32 v196, v174, v194
	v_mov_b32_e32 v200, v115
	v_mov_b32_e32 v201, v95
	v_pk_mul_f32 v[200:201], v[200:201], v[200:201]
	v_mov_b32_e32 v202, v59
	s_waitcnt lgkmcnt(0)
	v_pk_add_f32 v[194:195], v[194:195], v[196:197]
	ds_bpermute_b32 v197, v173, v195
	ds_bpermute_b32 v196, v173, v194
	v_mov_b32_e32 v203, v31
	v_pk_mul_f32 v[202:203], v[202:203], v[202:203]
	v_mov_b32_e32 v204, v200
	v_mov_b32_e32 v200, v202
	s_waitcnt lgkmcnt(0)
	v_pk_add_f32 v[194:195], v[194:195], v[196:197]
	ds_bpermute_b32 v197, v172, v195
	ds_bpermute_b32 v196, v172, v194
	v_mov_b32_e32 v202, v61
	s_waitcnt lgkmcnt(0)
	v_pk_add_f32 v[194:195], v[194:195], v[196:197]
	s_nop 0
	v_pk_fma_f32 v[194:195], v[194:195], s[8:9], v[162:163] op_sel_hi:[1,0,0]
	v_mov_b32_e32 v196, v114
	v_mul_f32_e32 v161, 0x4b800000, v195
	v_cmp_gt_f32_e64 s[46:47], s93, v195
	v_mov_b32_e32 v197, v94
	v_pk_mul_f32 v[196:197], v[196:197], v[196:197]
	v_cndmask_b32_e64 v161, v195, v161, s[46:47]
	v_rsq_f32_e32 v161, v161
	v_mov_b32_e32 v205, v196
	v_mov_b32_e32 v196, v201
	v_pk_add_f32 v[196:197], v[204:205], v[196:197]
	v_mul_f32_e32 v192, 0x45800000, v161
	v_cndmask_b32_e64 v161, v161, v192, s[46:47]
	v_mul_f32_e32 v192, v120, v161
	v_mul_f32_e32 v192, v168, v192
	v_cvt_pk_bf16_f32 v192, v192, s0
	global_store_short v[198:199], v192, off
	v_mul_f32_e32 v192, v104, v161
	v_mul_f32_e32 v192, v169, v192
	v_cvt_pk_bf16_f32 v192, v192, s0
	global_store_short v[198:199], v192, off offset:32
	v_mul_f32_e32 v192, v68, v161
	v_mul_f32_e32 v161, v40, v161
	v_mul_f32_e32 v192, v170, v192
	v_mul_f32_e32 v161, v171, v161
	v_cvt_pk_bf16_f32 v192, v192, s0
	v_cvt_pk_bf16_f32 v161, v161, s0
	global_store_short v[198:199], v192, off offset:64
	global_store_short v[198:199], v161, off offset:96
	v_mov_b32_e32 v198, v58
	v_mov_b32_e32 v199, v30
	v_pk_mul_f32 v[198:199], v[198:199], v[198:199]
	v_cmp_gt_f32_e32 vcc, s93, v194
	v_mov_b32_e32 v201, v198
	v_pk_add_f32 v[196:197], v[196:197], v[200:201]
	v_mov_b32_e32 v198, v203
	v_pk_add_f32 v[196:197], v[196:197], v[198:199]
	ds_bpermute_b32 v199, v175, v197
	ds_bpermute_b32 v198, v175, v196
	v_mul_f32_e32 v161, 0x4b800000, v194
	v_cndmask_b32_e32 v161, v194, v161, vcc
	v_rsq_f32_e32 v161, v161
	v_or_b32_e32 v194, 35, v160
	s_waitcnt lgkmcnt(0)
	v_pk_add_f32 v[196:197], v[196:197], v[198:199]
	ds_bpermute_b32 v199, v174, v197
	ds_bpermute_b32 v198, v174, v196
	v_mul_f32_e32 v192, 0x45800000, v161
	v_cndmask_b32_e32 v161, v161, v192, vcc
	v_ashrrev_i32_e32 v195, 31, v194
	v_mul_f32_e32 v192, v121, v161
	s_waitcnt lgkmcnt(0)
	v_pk_add_f32 v[196:197], v[196:197], v[198:199]
	ds_bpermute_b32 v199, v173, v197
	ds_bpermute_b32 v198, v173, v196
	v_lshlrev_b64 v[194:195], 12, v[194:195]
	v_mul_f32_e32 v192, v168, v192
	v_lshl_add_u64 v[194:195], v[158:159], 0, v[194:195]
	v_cvt_pk_bf16_f32 v192, v192, s0
	s_waitcnt lgkmcnt(0)
	v_pk_add_f32 v[196:197], v[196:197], v[198:199]
	ds_bpermute_b32 v199, v172, v197
	ds_bpermute_b32 v198, v172, v196
	global_store_short v[194:195], v192, off
	v_mul_f32_e32 v192, v105, v161
	v_mul_f32_e32 v192, v169, v192
	v_cvt_pk_bf16_f32 v192, v192, s0
	global_store_short v[194:195], v192, off offset:32
	v_mul_f32_e32 v192, v69, v161
	v_mul_f32_e32 v161, v41, v161
	v_mul_f32_e32 v161, v171, v161
	s_waitcnt lgkmcnt(0)
	v_pk_add_f32 v[196:197], v[196:197], v[198:199]
	v_cvt_pk_bf16_f32 v161, v161, s0
	v_pk_fma_f32 v[196:197], v[196:197], s[8:9], v[162:163] op_sel_hi:[1,0,0]
	global_store_short v[194:195], v161, off offset:96
	v_mul_f32_e32 v161, 0x4b800000, v197
	v_cmp_gt_f32_e64 s[46:47], s93, v197
	v_mul_f32_e32 v192, v170, v192
	v_cvt_pk_bf16_f32 v192, v192, s0
	v_cndmask_b32_e64 v161, v197, v161, s[46:47]
	v_rsq_f32_e32 v161, v161
	global_store_short v[194:195], v192, off offset:64
	v_or_b32_e32 v194, 48, v160
	v_ashrrev_i32_e32 v195, 31, v194
	v_mul_f32_e32 v192, 0x45800000, v161
	v_cndmask_b32_e64 v161, v161, v192, s[46:47]
	v_mul_f32_e32 v192, v114, v161
	v_lshlrev_b64 v[194:195], 12, v[194:195]
	v_mul_f32_e32 v192, v168, v192
	v_lshl_add_u64 v[194:195], v[158:159], 0, v[194:195]
	v_cvt_pk_bf16_f32 v192, v192, s0
	global_store_short v[194:195], v192, off
	v_mul_f32_e32 v192, v94, v161
	v_mul_f32_e32 v192, v169, v192
	v_cvt_pk_bf16_f32 v192, v192, s0
	global_store_short v[194:195], v192, off offset:32
	v_mul_f32_e32 v192, v58, v161
	v_mul_f32_e32 v161, v30, v161
	v_mul_f32_e32 v161, v171, v161
	v_cvt_pk_bf16_f32 v161, v161, s0
	v_cmp_gt_f32_e32 vcc, s93, v196
	global_store_short v[194:195], v161, off offset:96
	v_mul_f32_e32 v161, 0x4b800000, v196
	v_cndmask_b32_e32 v161, v196, v161, vcc
	v_rsq_f32_e32 v161, v161
	v_mul_f32_e32 v192, v170, v192
	v_cvt_pk_bf16_f32 v192, v192, s0
	global_store_short v[194:195], v192, off offset:64
	v_mul_f32_e32 v192, 0x45800000, v161
	v_cndmask_b32_e32 v161, v161, v192, vcc
	v_or_b32_e32 v194, 49, v160
	v_ashrrev_i32_e32 v195, 31, v194
	v_mul_f32_e32 v192, v115, v161
	v_lshlrev_b64 v[194:195], 12, v[194:195]
	v_mul_f32_e32 v192, v168, v192
	v_lshl_add_u64 v[194:195], v[158:159], 0, v[194:195]
	v_cvt_pk_bf16_f32 v192, v192, s0
	global_store_short v[194:195], v192, off
	v_mul_f32_e32 v192, v95, v161
	v_mul_f32_e32 v192, v169, v192
	v_cvt_pk_bf16_f32 v192, v192, s0
	global_store_short v[194:195], v192, off offset:32
	v_mul_f32_e32 v192, v59, v161
	v_mul_f32_e32 v161, v31, v161
	v_mul_f32_e32 v192, v170, v192
	v_mul_f32_e32 v161, v171, v161
	v_cvt_pk_bf16_f32 v192, v192, s0
	v_cvt_pk_bf16_f32 v161, v161, s0
	global_store_short v[194:195], v192, off offset:64
	global_store_short v[194:195], v161, off offset:96
	v_mov_b32_e32 v194, v116
	v_mov_b32_e32 v195, v96
	v_mov_b32_e32 v200, v117
	v_mov_b32_e32 v201, v97
	v_pk_mul_f32 v[194:195], v[194:195], v[194:195]
	v_mov_b32_e32 v196, v60
	v_mov_b32_e32 v197, v32
	v_pk_mul_f32 v[200:201], v[200:201], v[200:201]
	v_mov_b32_e32 v203, v33
	v_pk_mul_f32 v[196:197], v[196:197], v[196:197]
	v_pk_mul_f32 v[202:203], v[202:203], v[202:203]
	v_mov_b32_e32 v204, v200
	v_mov_b32_e32 v205, v194
	v_mov_b32_e32 v194, v201
	v_pk_add_f32 v[194:195], v[204:205], v[194:195]
	v_mov_b32_e32 v200, v202
	v_mov_b32_e32 v201, v196
	v_pk_add_f32 v[194:195], v[194:195], v[200:201]
	v_mov_b32_e32 v196, v203
	v_pk_add_f32 v[194:195], v[194:195], v[196:197]
	ds_bpermute_b32 v197, v175, v195
	ds_bpermute_b32 v196, v175, v194
	v_or_b32_e32 v198, 50, v160
	v_ashrrev_i32_e32 v199, 31, v198
	v_lshlrev_b64 v[198:199], 12, v[198:199]
	v_lshl_add_u64 v[198:199], v[158:159], 0, v[198:199]
	s_waitcnt lgkmcnt(0)
; __device__ __forceinline__ unsigned f2bf(float f) { const __bf16 b = (__bf16)f; return (unsigned)__builtin_bit_cast(unsigned short, b); }
;     __device__ __forceinline__ void operator()(Acc& acc, int pm, int pn, int wr, int wc, int fr, int fq) const {
;     ...
;         for (int ai = 0; ai < 2; ++ai)
; #pragma unroll
;             for (int m = 0; m < 4; ++m)
; #pragma unroll
;                 for (int j = 0; j < 4; ++j) {
;                     float ss = acc[ai][0][m][0][j] * acc[ai][0][m][0][j] + acc[ai][0][m][1][j] * acc[ai][0][m][1][j] +
;                                acc[ai][1][m][0][j] * acc[ai][1][m][0][j] + acc[ai][1][m][1][j] * acc[ai][1][m][1][j];
;                     ss += __shfl_xor(ss, 1); ss += __shfl_xor(ss, 2); ss += __shfl_xor(ss, 4); ss += __shfl_xor(ss, 8);
;                     const float rs = rsqrtf(ss * (1.0f / 64.0f) + EPSV);
;                     bf16_t* rp = qk + (size_t)(pm * 256 + ai * 128 + wr * 64 + m * 16 + fq * 4 + j) * 2048 + head * 64 + fr;
; #pragma unroll
;                     for (int bj = 0; bj < 2; ++bj)
; #pragma unroll
;                         for (int n = 0; n < 2; ++n) rp[bj * 32 + n * 16] = (bf16_t)f2bf(acc[ai][bj][m][n][j] * rs * gv[bj][n]);
;                 }
	v_pk_add_f32 v[194:195], v[194:195], v[196:197]
	ds_bpermute_b32 v197, v174, v195
	ds_bpermute_b32 v196, v174, v194
	v_mov_b32_e32 v200, v99
	v_mov_b32_e32 v201, v71
	v_pk_mul_f32 v[200:201], v[200:201], v[200:201]
	v_mov_b32_e32 v202, v35
	s_waitcnt lgkmcnt(0)
	v_pk_add_f32 v[194:195], v[194:195], v[196:197]
	ds_bpermute_b32 v197, v173, v195
	ds_bpermute_b32 v196, v173, v194
	v_mov_b32_e32 v203, v15
	v_pk_mul_f32 v[202:203], v[202:203], v[202:203]
	v_mov_b32_e32 v204, v200
	v_mov_b32_e32 v200, v202
	s_waitcnt lgkmcnt(0)
	v_pk_add_f32 v[194:195], v[194:195], v[196:197]
	ds_bpermute_b32 v197, v172, v195
	ds_bpermute_b32 v196, v172, v194
	v_mov_b32_e32 v202, v37
	s_waitcnt lgkmcnt(0)
	v_pk_add_f32 v[194:195], v[194:195], v[196:197]
	s_nop 0
	v_pk_fma_f32 v[194:195], v[194:195], s[8:9], v[162:163] op_sel_hi:[1,0,0]
	v_mov_b32_e32 v196, v98
	v_mul_f32_e32 v161, 0x4b800000, v195
	v_cmp_gt_f32_e64 s[46:47], s93, v195
	v_mov_b32_e32 v197, v70
	v_pk_mul_f32 v[196:197], v[196:197], v[196:197]
	v_cndmask_b32_e64 v161, v195, v161, s[46:47]
	v_rsq_f32_e32 v161, v161
	v_mov_b32_e32 v205, v196
	v_mov_b32_e32 v196, v201
	v_pk_add_f32 v[196:197], v[204:205], v[196:197]
	v_mul_f32_e32 v192, 0x45800000, v161
	v_cndmask_b32_e64 v161, v161, v192, s[46:47]
	v_mul_f32_e32 v192, v116, v161
	v_mul_f32_e32 v192, v168, v192
	v_cvt_pk_bf16_f32 v192, v192, s0
	global_store_short v[198:199], v192, off
	v_mul_f32_e32 v192, v96, v161
	v_mul_f32_e32 v192, v169, v192
	v_cvt_pk_bf16_f32 v192, v192, s0
	global_store_short v[198:199], v192, off offset:32
	v_mul_f32_e32 v192, v60, v161
	v_mul_f32_e32 v161, v32, v161
	v_mul_f32_e32 v192, v170, v192
	v_mul_f32_e32 v161, v171, v161
	v_cvt_pk_bf16_f32 v192, v192, s0
	v_cvt_pk_bf16_f32 v161, v161, s0
	global_store_short v[198:199], v192, off offset:64
	global_store_short v[198:199], v161, off offset:96
	v_mov_b32_e32 v198, v34
	v_mov_b32_e32 v199, v14
	v_pk_mul_f32 v[198:199], v[198:199], v[198:199]
	v_cmp_gt_f32_e32 vcc, s93, v194
	v_mov_b32_e32 v201, v198
	v_pk_add_f32 v[196:197], v[196:197], v[200:201]
	v_mov_b32_e32 v198, v203
	v_pk_add_f32 v[196:197], v[196:197], v[198:199]
	ds_bpermute_b32 v199, v175, v197
	ds_bpermute_b32 v198, v175, v196
	v_mul_f32_e32 v161, 0x4b800000, v194
	v_cndmask_b32_e32 v161, v194, v161, vcc
	v_rsq_f32_e32 v161, v161
	v_or_b32_e32 v194, 51, v160
	s_waitcnt lgkmcnt(0)
	v_pk_add_f32 v[196:197], v[196:197], v[198:199]
	ds_bpermute_b32 v199, v174, v197
	ds_bpermute_b32 v198, v174, v196
	v_mul_f32_e32 v192, 0x45800000, v161
	v_cndmask_b32_e32 v161, v161, v192, vcc
	v_ashrrev_i32_e32 v195, 31, v194
	v_mul_f32_e32 v192, v117, v161
	s_waitcnt lgkmcnt(0)
	v_pk_add_f32 v[196:197], v[196:197], v[198:199]
	ds_bpermute_b32 v199, v173, v197
	ds_bpermute_b32 v198, v173, v196
	v_lshlrev_b64 v[194:195], 12, v[194:195]
	v_mul_f32_e32 v192, v168, v192
	v_lshl_add_u64 v[194:195], v[158:159], 0, v[194:195]
	v_cvt_pk_bf16_f32 v192, v192, s0
	s_waitcnt lgkmcnt(0)
	v_pk_add_f32 v[196:197], v[196:197], v[198:199]
	ds_bpermute_b32 v199, v172, v197
	ds_bpermute_b32 v198, v172, v196
	global_store_short v[194:195], v192, off
	v_mul_f32_e32 v192, v97, v161
	v_mul_f32_e32 v192, v169, v192
	v_cvt_pk_bf16_f32 v192, v192, s0
	global_store_short v[194:195], v192, off offset:32
	v_mul_f32_e32 v192, v61, v161
	v_mul_f32_e32 v161, v33, v161
	v_mul_f32_e32 v161, v171, v161
	s_waitcnt lgkmcnt(0)
	v_pk_add_f32 v[196:197], v[196:197], v[198:199]
	v_cvt_pk_bf16_f32 v161, v161, s0
	v_pk_fma_f32 v[196:197], v[196:197], s[8:9], v[162:163] op_sel_hi:[1,0,0]
	global_store_short v[194:195], v161, off offset:96
	v_mul_f32_e32 v161, 0x4b800000, v197
	v_cmp_gt_f32_e64 s[46:47], s93, v197
	v_mul_f32_e32 v192, v170, v192
	v_cvt_pk_bf16_f32 v192, v192, s0
	v_cndmask_b32_e64 v161, v197, v161, s[46:47]
	v_rsq_f32_e32 v161, v161
	global_store_short v[194:195], v192, off offset:64
	v_add_u32_e32 v194, 0x80, v160
	v_ashrrev_i32_e32 v195, 31, v194
	v_mul_f32_e32 v192, 0x45800000, v161
	v_cndmask_b32_e64 v161, v161, v192, s[46:47]
	v_mul_f32_e32 v192, v98, v161
	v_lshlrev_b64 v[194:195], 12, v[194:195]
	v_mul_f32_e32 v192, v168, v192
	v_lshl_add_u64 v[194:195], v[158:159], 0, v[194:195]
	v_cvt_pk_bf16_f32 v192, v192, s0
	global_store_short v[194:195], v192, off
	v_mul_f32_e32 v192, v70, v161
	v_mul_f32_e32 v192, v169, v192
	v_cvt_pk_bf16_f32 v192, v192, s0
	global_store_short v[194:195], v192, off offset:32
	v_mul_f32_e32 v192, v34, v161
	v_mul_f32_e32 v161, v14, v161
	v_mul_f32_e32 v161, v171, v161
	v_cvt_pk_bf16_f32 v161, v161, s0
	v_cmp_gt_f32_e32 vcc, s93, v196
	global_store_short v[194:195], v161, off offset:96
	v_mul_f32_e32 v161, 0x4b800000, v196
	v_cndmask_b32_e32 v161, v196, v161, vcc
	v_rsq_f32_e32 v161, v161
	v_mul_f32_e32 v192, v170, v192
	v_cvt_pk_bf16_f32 v192, v192, s0
	global_store_short v[194:195], v192, off offset:64
	v_mul_f32_e32 v192, 0x45800000, v161
	v_cndmask_b32_e32 v161, v161, v192, vcc
	v_add_u32_e32 v194, 0x81, v160
	v_ashrrev_i32_e32 v195, 31, v194
	v_mul_f32_e32 v192, v99, v161
	v_lshlrev_b64 v[194:195], 12, v[194:195]
	v_mul_f32_e32 v192, v168, v192
	v_lshl_add_u64 v[194:195], v[158:159], 0, v[194:195]
	v_cvt_pk_bf16_f32 v192, v192, s0
	global_store_short v[194:195], v192, off
	v_mul_f32_e32 v192, v71, v161
	v_mul_f32_e32 v192, v169, v192
	v_cvt_pk_bf16_f32 v192, v192, s0
	global_store_short v[194:195], v192, off offset:32
	v_mul_f32_e32 v192, v35, v161
	v_mul_f32_e32 v161, v15, v161
	v_mul_f32_e32 v192, v170, v192
	v_mul_f32_e32 v161, v171, v161
	v_cvt_pk_bf16_f32 v192, v192, s0
	v_cvt_pk_bf16_f32 v161, v161, s0
	global_store_short v[194:195], v192, off offset:64
	global_store_short v[194:195], v161, off offset:96
	v_mov_b32_e32 v194, v100
	v_mov_b32_e32 v195, v72
	v_mov_b32_e32 v200, v101
	v_mov_b32_e32 v201, v73
	v_pk_mul_f32 v[194:195], v[194:195], v[194:195]
	v_mov_b32_e32 v196, v36
	v_mov_b32_e32 v197, v16
	v_pk_mul_f32 v[200:201], v[200:201], v[200:201]
	v_mov_b32_e32 v203, v17
	v_pk_mul_f32 v[196:197], v[196:197], v[196:197]
	v_pk_mul_f32 v[202:203], v[202:203], v[202:203]
	v_mov_b32_e32 v204, v200
	v_mov_b32_e32 v205, v194
	v_mov_b32_e32 v194, v201
	v_pk_add_f32 v[194:195], v[204:205], v[194:195]
	v_mov_b32_e32 v200, v202
	v_mov_b32_e32 v201, v196
	v_pk_add_f32 v[194:195], v[194:195], v[200:201]
	v_mov_b32_e32 v196, v203
	v_pk_add_f32 v[194:195], v[194:195], v[196:197]
	ds_bpermute_b32 v197, v175, v195
	ds_bpermute_b32 v196, v175, v194
	v_add_u32_e32 v198, 0x82, v160
	v_ashrrev_i32_e32 v199, 31, v198
	v_lshlrev_b64 v[198:199], 12, v[198:199]
	v_lshl_add_u64 v[198:199], v[158:159], 0, v[198:199]
	s_waitcnt lgkmcnt(0)
; __device__ __forceinline__ unsigned f2bf(float f) { const __bf16 b = (__bf16)f; return (unsigned)__builtin_bit_cast(unsigned short, b); }
;     __device__ __forceinline__ void operator()(Acc& acc, int pm, int pn, int wr, int wc, int fr, int fq) const {
;     ...
;         for (int ai = 0; ai < 2; ++ai)
; #pragma unroll
;             for (int m = 0; m < 4; ++m)
; #pragma unroll
;                 for (int j = 0; j < 4; ++j) {
;                     float ss = acc[ai][0][m][0][j] * acc[ai][0][m][0][j] + acc[ai][0][m][1][j] * acc[ai][0][m][1][j] +
;                                acc[ai][1][m][0][j] * acc[ai][1][m][0][j] + acc[ai][1][m][1][j] * acc[ai][1][m][1][j];
;                     ss += __shfl_xor(ss, 1); ss += __shfl_xor(ss, 2); ss += __shfl_xor(ss, 4); ss += __shfl_xor(ss, 8);
;                     const float rs = rsqrtf(ss * (1.0f / 64.0f) + EPSV);
;                     bf16_t* rp = qk + (size_t)(pm * 256 + ai * 128 + wr * 64 + m * 16 + fq * 4 + j) * 2048 + head * 64 + fr;
; #pragma unroll
;                     for (int bj = 0; bj < 2; ++bj)
; #pragma unroll
;                         for (int n = 0; n < 2; ++n) rp[bj * 32 + n * 16] = (bf16_t)f2bf(acc[ai][bj][m][n][j] * rs * gv[bj][n]);
;                 }
	v_pk_add_f32 v[194:195], v[194:195], v[196:197]
	ds_bpermute_b32 v197, v174, v195
	ds_bpermute_b32 v196, v174, v194
	v_mov_b32_e32 v200, v91
	v_mov_b32_e32 v201, v63
	v_pk_mul_f32 v[200:201], v[200:201], v[200:201]
	v_mov_b32_e32 v202, v27
	s_waitcnt lgkmcnt(0)
	v_pk_add_f32 v[194:195], v[194:195], v[196:197]
	ds_bpermute_b32 v197, v173, v195
	ds_bpermute_b32 v196, v173, v194
	v_mov_b32_e32 v203, v11
	v_pk_mul_f32 v[202:203], v[202:203], v[202:203]
	v_mov_b32_e32 v204, v200
	v_mov_b32_e32 v200, v202
	s_waitcnt lgkmcnt(0)
	v_pk_add_f32 v[194:195], v[194:195], v[196:197]
	ds_bpermute_b32 v197, v172, v195
	ds_bpermute_b32 v196, v172, v194
	v_mov_b32_e32 v202, v29
	s_waitcnt lgkmcnt(0)
	v_pk_add_f32 v[194:195], v[194:195], v[196:197]
	s_nop 0
	v_pk_fma_f32 v[194:195], v[194:195], s[8:9], v[162:163] op_sel_hi:[1,0,0]
	v_mov_b32_e32 v196, v90
	v_mul_f32_e32 v161, 0x4b800000, v195
	v_cmp_gt_f32_e64 s[46:47], s93, v195
	v_mov_b32_e32 v197, v62
	v_pk_mul_f32 v[196:197], v[196:197], v[196:197]
	v_cndmask_b32_e64 v161, v195, v161, s[46:47]
	v_rsq_f32_e32 v161, v161
	v_mov_b32_e32 v205, v196
	v_mov_b32_e32 v196, v201
	v_pk_add_f32 v[196:197], v[204:205], v[196:197]
	v_mul_f32_e32 v192, 0x45800000, v161
	v_cndmask_b32_e64 v161, v161, v192, s[46:47]
	v_mul_f32_e32 v192, v100, v161
	v_mul_f32_e32 v192, v168, v192
	v_cvt_pk_bf16_f32 v192, v192, s0
	global_store_short v[198:199], v192, off
	v_mul_f32_e32 v192, v72, v161
	v_mul_f32_e32 v192, v169, v192
	v_cvt_pk_bf16_f32 v192, v192, s0
	global_store_short v[198:199], v192, off offset:32
	v_mul_f32_e32 v192, v36, v161
	v_mul_f32_e32 v161, v16, v161
	v_mul_f32_e32 v192, v170, v192
	v_mul_f32_e32 v161, v171, v161
	v_cvt_pk_bf16_f32 v192, v192, s0
	v_cvt_pk_bf16_f32 v161, v161, s0
	global_store_short v[198:199], v192, off offset:64
	global_store_short v[198:199], v161, off offset:96
	v_mov_b32_e32 v198, v26
	v_mov_b32_e32 v199, v10
	v_pk_mul_f32 v[198:199], v[198:199], v[198:199]
	v_cmp_gt_f32_e32 vcc, s93, v194
	v_mov_b32_e32 v201, v198
	v_pk_add_f32 v[196:197], v[196:197], v[200:201]
	v_mov_b32_e32 v198, v203
	v_pk_add_f32 v[196:197], v[196:197], v[198:199]
	ds_bpermute_b32 v199, v175, v197
	ds_bpermute_b32 v198, v175, v196
	v_mul_f32_e32 v161, 0x4b800000, v194
	v_cndmask_b32_e32 v161, v194, v161, vcc
	v_rsq_f32_e32 v161, v161
	v_add_u32_e32 v194, 0x83, v160
	s_waitcnt lgkmcnt(0)
	v_pk_add_f32 v[196:197], v[196:197], v[198:199]
	ds_bpermute_b32 v199, v174, v197
	ds_bpermute_b32 v198, v174, v196
	v_mul_f32_e32 v192, 0x45800000, v161
	v_cndmask_b32_e32 v161, v161, v192, vcc
	v_ashrrev_i32_e32 v195, 31, v194
	v_mul_f32_e32 v192, v101, v161
	s_waitcnt lgkmcnt(0)
	v_pk_add_f32 v[196:197], v[196:197], v[198:199]
	ds_bpermute_b32 v199, v173, v197
	ds_bpermute_b32 v198, v173, v196
	v_lshlrev_b64 v[194:195], 12, v[194:195]
	v_mul_f32_e32 v192, v168, v192
	v_lshl_add_u64 v[194:195], v[158:159], 0, v[194:195]
	v_cvt_pk_bf16_f32 v192, v192, s0
	s_waitcnt lgkmcnt(0)
	v_pk_add_f32 v[196:197], v[196:197], v[198:199]
	ds_bpermute_b32 v199, v172, v197
	ds_bpermute_b32 v198, v172, v196
	global_store_short v[194:195], v192, off
	v_mul_f32_e32 v192, v73, v161
	v_mul_f32_e32 v192, v169, v192
	v_cvt_pk_bf16_f32 v192, v192, s0
	global_store_short v[194:195], v192, off offset:32
	v_mul_f32_e32 v192, v37, v161
	v_mul_f32_e32 v161, v17, v161
	v_mul_f32_e32 v161, v171, v161
	s_waitcnt lgkmcnt(0)
	v_pk_add_f32 v[196:197], v[196:197], v[198:199]
	v_cvt_pk_bf16_f32 v161, v161, s0
	v_pk_fma_f32 v[196:197], v[196:197], s[8:9], v[162:163] op_sel_hi:[1,0,0]
	global_store_short v[194:195], v161, off offset:96
	v_mul_f32_e32 v161, 0x4b800000, v197
	v_cmp_gt_f32_e64 s[46:47], s93, v197
	v_mul_f32_e32 v192, v170, v192
	v_cvt_pk_bf16_f32 v192, v192, s0
	v_cndmask_b32_e64 v161, v197, v161, s[46:47]
	v_rsq_f32_e32 v161, v161
	global_store_short v[194:195], v192, off offset:64
	v_add_u32_e32 v194, 0x90, v160
	v_ashrrev_i32_e32 v195, 31, v194
	v_mul_f32_e32 v192, 0x45800000, v161
	v_cndmask_b32_e64 v161, v161, v192, s[46:47]
	v_mul_f32_e32 v192, v90, v161
	v_lshlrev_b64 v[194:195], 12, v[194:195]
	v_mul_f32_e32 v192, v168, v192
	v_lshl_add_u64 v[194:195], v[158:159], 0, v[194:195]
	v_cvt_pk_bf16_f32 v192, v192, s0
	global_store_short v[194:195], v192, off
	v_mul_f32_e32 v192, v62, v161
	v_mul_f32_e32 v192, v169, v192
	v_cvt_pk_bf16_f32 v192, v192, s0
	global_store_short v[194:195], v192, off offset:32
	v_mul_f32_e32 v192, v26, v161
	v_mul_f32_e32 v161, v10, v161
	v_mul_f32_e32 v161, v171, v161
	v_cvt_pk_bf16_f32 v161, v161, s0
	v_cmp_gt_f32_e32 vcc, s93, v196
	global_store_short v[194:195], v161, off offset:96
	v_mul_f32_e32 v161, 0x4b800000, v196
	v_cndmask_b32_e32 v161, v196, v161, vcc
	v_rsq_f32_e32 v161, v161
	v_mul_f32_e32 v192, v170, v192
	v_cvt_pk_bf16_f32 v192, v192, s0
	global_store_short v[194:195], v192, off offset:64
	v_mul_f32_e32 v192, 0x45800000, v161
	v_cndmask_b32_e32 v161, v161, v192, vcc
	v_add_u32_e32 v194, 0x91, v160
	v_ashrrev_i32_e32 v195, 31, v194
	v_mul_f32_e32 v192, v91, v161
	v_lshlrev_b64 v[194:195], 12, v[194:195]
	v_mul_f32_e32 v192, v168, v192
	v_lshl_add_u64 v[194:195], v[158:159], 0, v[194:195]
	v_cvt_pk_bf16_f32 v192, v192, s0
	global_store_short v[194:195], v192, off
	v_mul_f32_e32 v192, v63, v161
	v_mul_f32_e32 v192, v169, v192
	v_cvt_pk_bf16_f32 v192, v192, s0
	global_store_short v[194:195], v192, off offset:32
	v_mul_f32_e32 v192, v27, v161
	v_mul_f32_e32 v161, v11, v161
	v_mul_f32_e32 v192, v170, v192
	v_mul_f32_e32 v161, v171, v161
	v_cvt_pk_bf16_f32 v192, v192, s0
	v_cvt_pk_bf16_f32 v161, v161, s0
	global_store_short v[194:195], v192, off offset:64
	global_store_short v[194:195], v161, off offset:96
	v_mov_b32_e32 v194, v92
	v_mov_b32_e32 v195, v64
	v_mov_b32_e32 v200, v93
	v_mov_b32_e32 v201, v65
	v_pk_mul_f32 v[194:195], v[194:195], v[194:195]
	v_mov_b32_e32 v196, v28
	v_mov_b32_e32 v197, v12
	v_pk_mul_f32 v[200:201], v[200:201], v[200:201]
	v_mov_b32_e32 v203, v13
	v_pk_mul_f32 v[196:197], v[196:197], v[196:197]
	v_pk_mul_f32 v[202:203], v[202:203], v[202:203]
	v_mov_b32_e32 v204, v200
	v_mov_b32_e32 v205, v194
	v_mov_b32_e32 v194, v201
	v_pk_add_f32 v[194:195], v[204:205], v[194:195]
	v_mov_b32_e32 v200, v202
	v_mov_b32_e32 v201, v196
	v_pk_add_f32 v[194:195], v[194:195], v[200:201]
	v_mov_b32_e32 v196, v203
	v_pk_add_f32 v[194:195], v[194:195], v[196:197]
	ds_bpermute_b32 v197, v175, v195
	ds_bpermute_b32 v196, v175, v194
	v_add_u32_e32 v198, 0x92, v160
	v_ashrrev_i32_e32 v199, 31, v198
	v_lshlrev_b64 v[198:199], 12, v[198:199]
	v_lshl_add_u64 v[198:199], v[158:159], 0, v[198:199]
	s_waitcnt lgkmcnt(0)
; __device__ __forceinline__ unsigned f2bf(float f) { const __bf16 b = (__bf16)f; return (unsigned)__builtin_bit_cast(unsigned short, b); }
;     __device__ __forceinline__ void operator()(Acc& acc, int pm, int pn, int wr, int wc, int fr, int fq) const {
;     ...
;         for (int ai = 0; ai < 2; ++ai)
; #pragma unroll
;             for (int m = 0; m < 4; ++m)
; #pragma unroll
;                 for (int j = 0; j < 4; ++j) {
;                     float ss = acc[ai][0][m][0][j] * acc[ai][0][m][0][j] + acc[ai][0][m][1][j] * acc[ai][0][m][1][j] +
;                                acc[ai][1][m][0][j] * acc[ai][1][m][0][j] + acc[ai][1][m][1][j] * acc[ai][1][m][1][j];
;                     ss += __shfl_xor(ss, 1); ss += __shfl_xor(ss, 2); ss += __shfl_xor(ss, 4); ss += __shfl_xor(ss, 8);
;                     const float rs = rsqrtf(ss * (1.0f / 64.0f) + EPSV);
;                     bf16_t* rp = qk + (size_t)(pm * 256 + ai * 128 + wr * 64 + m * 16 + fq * 4 + j) * 2048 + head * 64 + fr;
; #pragma unroll
;                     for (int bj = 0; bj < 2; ++bj)
; #pragma unroll
;                         for (int n = 0; n < 2; ++n) rp[bj * 32 + n * 16] = (bf16_t)f2bf(acc[ai][bj][m][n][j] * rs * gv[bj][n]);
;                 }
	v_pk_add_f32 v[194:195], v[194:195], v[196:197]
	ds_bpermute_b32 v197, v174, v195
	ds_bpermute_b32 v196, v174, v194
	v_mov_b32_e32 v200, v87
	v_mov_b32_e32 v201, v55
	v_pk_mul_f32 v[200:201], v[200:201], v[200:201]
	v_mov_b32_e32 v202, v23
	s_waitcnt lgkmcnt(0)
	v_pk_add_f32 v[194:195], v[194:195], v[196:197]
	ds_bpermute_b32 v197, v173, v195
	ds_bpermute_b32 v196, v173, v194
	v_mov_b32_e32 v203, v7
	v_pk_mul_f32 v[202:203], v[202:203], v[202:203]
	v_mov_b32_e32 v204, v200
	v_mov_b32_e32 v200, v202
	s_waitcnt lgkmcnt(0)
	v_pk_add_f32 v[194:195], v[194:195], v[196:197]
	ds_bpermute_b32 v197, v172, v195
	ds_bpermute_b32 v196, v172, v194
	v_mov_b32_e32 v202, v25
	s_waitcnt lgkmcnt(0)
	v_pk_add_f32 v[194:195], v[194:195], v[196:197]
	s_nop 0
	v_pk_fma_f32 v[194:195], v[194:195], s[8:9], v[162:163] op_sel_hi:[1,0,0]
	v_mov_b32_e32 v196, v86
	v_mul_f32_e32 v161, 0x4b800000, v195
	v_cmp_gt_f32_e64 s[46:47], s93, v195
	v_mov_b32_e32 v197, v54
	v_pk_mul_f32 v[196:197], v[196:197], v[196:197]
	v_cndmask_b32_e64 v161, v195, v161, s[46:47]
	v_rsq_f32_e32 v161, v161
	v_mov_b32_e32 v205, v196
	v_mov_b32_e32 v196, v201
	v_pk_add_f32 v[196:197], v[204:205], v[196:197]
	v_mul_f32_e32 v192, 0x45800000, v161
	v_cndmask_b32_e64 v161, v161, v192, s[46:47]
	v_mul_f32_e32 v192, v92, v161
	v_mul_f32_e32 v192, v168, v192
	v_cvt_pk_bf16_f32 v192, v192, s0
	global_store_short v[198:199], v192, off
	v_mul_f32_e32 v192, v64, v161
	v_mul_f32_e32 v192, v169, v192
	v_cvt_pk_bf16_f32 v192, v192, s0
	global_store_short v[198:199], v192, off offset:32
	v_mul_f32_e32 v192, v28, v161
	v_mul_f32_e32 v161, v12, v161
	v_mul_f32_e32 v192, v170, v192
	v_mul_f32_e32 v161, v171, v161
	v_cvt_pk_bf16_f32 v192, v192, s0
	v_cvt_pk_bf16_f32 v161, v161, s0
	global_store_short v[198:199], v192, off offset:64
	global_store_short v[198:199], v161, off offset:96
	v_mov_b32_e32 v198, v22
	v_mov_b32_e32 v199, v6
	v_pk_mul_f32 v[198:199], v[198:199], v[198:199]
	v_cmp_gt_f32_e32 vcc, s93, v194
	v_mov_b32_e32 v201, v198
	v_pk_add_f32 v[196:197], v[196:197], v[200:201]
	v_mov_b32_e32 v198, v203
	v_pk_add_f32 v[196:197], v[196:197], v[198:199]
	ds_bpermute_b32 v199, v175, v197
	ds_bpermute_b32 v198, v175, v196
	v_mul_f32_e32 v161, 0x4b800000, v194
	v_cndmask_b32_e32 v161, v194, v161, vcc
	v_rsq_f32_e32 v161, v161
	v_add_u32_e32 v194, 0x93, v160
	s_waitcnt lgkmcnt(0)
	v_pk_add_f32 v[196:197], v[196:197], v[198:199]
	ds_bpermute_b32 v199, v174, v197
	ds_bpermute_b32 v198, v174, v196
	v_mul_f32_e32 v192, 0x45800000, v161
	v_cndmask_b32_e32 v161, v161, v192, vcc
	v_ashrrev_i32_e32 v195, 31, v194
	v_mul_f32_e32 v192, v93, v161
	s_waitcnt lgkmcnt(0)
	v_pk_add_f32 v[196:197], v[196:197], v[198:199]
	ds_bpermute_b32 v199, v173, v197
	ds_bpermute_b32 v198, v173, v196
	v_lshlrev_b64 v[194:195], 12, v[194:195]
	v_mul_f32_e32 v192, v168, v192
	v_lshl_add_u64 v[194:195], v[158:159], 0, v[194:195]
	v_cvt_pk_bf16_f32 v192, v192, s0
	s_waitcnt lgkmcnt(0)
	v_pk_add_f32 v[196:197], v[196:197], v[198:199]
	ds_bpermute_b32 v199, v172, v197
	ds_bpermute_b32 v198, v172, v196
	global_store_short v[194:195], v192, off
	v_mul_f32_e32 v192, v65, v161
	v_mul_f32_e32 v192, v169, v192
	v_cvt_pk_bf16_f32 v192, v192, s0
	global_store_short v[194:195], v192, off offset:32
	v_mul_f32_e32 v192, v29, v161
	v_mul_f32_e32 v161, v13, v161
	v_mul_f32_e32 v161, v171, v161
	s_waitcnt lgkmcnt(0)
	v_pk_add_f32 v[196:197], v[196:197], v[198:199]
	v_cvt_pk_bf16_f32 v161, v161, s0
	v_pk_fma_f32 v[196:197], v[196:197], s[8:9], v[162:163] op_sel_hi:[1,0,0]
	global_store_short v[194:195], v161, off offset:96
	v_mul_f32_e32 v161, 0x4b800000, v197
	v_cmp_gt_f32_e64 s[46:47], s93, v197
	v_mul_f32_e32 v192, v170, v192
	v_cvt_pk_bf16_f32 v192, v192, s0
	v_cndmask_b32_e64 v161, v197, v161, s[46:47]
	v_rsq_f32_e32 v161, v161
	global_store_short v[194:195], v192, off offset:64
	v_add_u32_e32 v194, 0xa0, v160
	v_ashrrev_i32_e32 v195, 31, v194
	v_mul_f32_e32 v192, 0x45800000, v161
	v_cndmask_b32_e64 v161, v161, v192, s[46:47]
	v_mul_f32_e32 v192, v86, v161
	v_lshlrev_b64 v[194:195], 12, v[194:195]
	v_mul_f32_e32 v192, v168, v192
	v_lshl_add_u64 v[194:195], v[158:159], 0, v[194:195]
	v_cvt_pk_bf16_f32 v192, v192, s0
	global_store_short v[194:195], v192, off
	v_mul_f32_e32 v192, v54, v161
	v_mul_f32_e32 v192, v169, v192
	v_cvt_pk_bf16_f32 v192, v192, s0
	global_store_short v[194:195], v192, off offset:32
	v_mul_f32_e32 v192, v22, v161
	v_mul_f32_e32 v161, v6, v161
	v_mul_f32_e32 v161, v171, v161
	v_cvt_pk_bf16_f32 v161, v161, s0
	v_cmp_gt_f32_e32 vcc, s93, v196
	global_store_short v[194:195], v161, off offset:96
	v_mul_f32_e32 v161, 0x4b800000, v196
	v_cndmask_b32_e32 v161, v196, v161, vcc
	v_rsq_f32_e32 v161, v161
	v_mul_f32_e32 v192, v170, v192
	v_cvt_pk_bf16_f32 v192, v192, s0
	global_store_short v[194:195], v192, off offset:64
	v_mul_f32_e32 v192, 0x45800000, v161
	v_cndmask_b32_e32 v161, v161, v192, vcc
	v_add_u32_e32 v194, 0xa1, v160
	v_ashrrev_i32_e32 v195, 31, v194
	v_mul_f32_e32 v192, v87, v161
	v_lshlrev_b64 v[194:195], 12, v[194:195]
	v_mul_f32_e32 v192, v168, v192
	v_lshl_add_u64 v[194:195], v[158:159], 0, v[194:195]
	v_cvt_pk_bf16_f32 v192, v192, s0
	global_store_short v[194:195], v192, off
	v_mul_f32_e32 v192, v55, v161
	v_mul_f32_e32 v192, v169, v192
	v_cvt_pk_bf16_f32 v192, v192, s0
	global_store_short v[194:195], v192, off offset:32
	v_mul_f32_e32 v192, v23, v161
	v_mul_f32_e32 v161, v7, v161
	v_mul_f32_e32 v192, v170, v192
	v_mul_f32_e32 v161, v171, v161
	v_cvt_pk_bf16_f32 v192, v192, s0
	v_cvt_pk_bf16_f32 v161, v161, s0
	global_store_short v[194:195], v192, off offset:64
	global_store_short v[194:195], v161, off offset:96
	v_mov_b32_e32 v194, v88
	v_mov_b32_e32 v195, v56
	v_mov_b32_e32 v200, v89
	v_mov_b32_e32 v201, v57
	v_pk_mul_f32 v[194:195], v[194:195], v[194:195]
	v_mov_b32_e32 v196, v24
	v_mov_b32_e32 v197, v8
	v_pk_mul_f32 v[200:201], v[200:201], v[200:201]
	v_mov_b32_e32 v203, v9
	v_pk_mul_f32 v[196:197], v[196:197], v[196:197]
	v_pk_mul_f32 v[202:203], v[202:203], v[202:203]
	v_mov_b32_e32 v204, v200
	v_mov_b32_e32 v205, v194
	v_mov_b32_e32 v194, v201
	v_pk_add_f32 v[194:195], v[204:205], v[194:195]
	v_mov_b32_e32 v200, v202
	v_mov_b32_e32 v201, v196
	v_pk_add_f32 v[194:195], v[194:195], v[200:201]
	v_mov_b32_e32 v196, v203
	v_pk_add_f32 v[194:195], v[194:195], v[196:197]
	ds_bpermute_b32 v197, v175, v195
	ds_bpermute_b32 v196, v175, v194
	v_add_u32_e32 v198, 0xa2, v160
	v_ashrrev_i32_e32 v199, 31, v198
	v_lshlrev_b64 v[198:199], 12, v[198:199]
	v_lshl_add_u64 v[198:199], v[158:159], 0, v[198:199]
	s_waitcnt lgkmcnt(0)
; __device__ __forceinline__ unsigned f2bf(float f) { const __bf16 b = (__bf16)f; return (unsigned)__builtin_bit_cast(unsigned short, b); }
;     __device__ __forceinline__ void operator()(Acc& acc, int pm, int pn, int wr, int wc, int fr, int fq) const {
;     ...
;         for (int ai = 0; ai < 2; ++ai)
; #pragma unroll
;             for (int m = 0; m < 4; ++m)
; #pragma unroll
;                 for (int j = 0; j < 4; ++j) {
;                     float ss = acc[ai][0][m][0][j] * acc[ai][0][m][0][j] + acc[ai][0][m][1][j] * acc[ai][0][m][1][j] +
;                                acc[ai][1][m][0][j] * acc[ai][1][m][0][j] + acc[ai][1][m][1][j] * acc[ai][1][m][1][j];
;                     ss += __shfl_xor(ss, 1); ss += __shfl_xor(ss, 2); ss += __shfl_xor(ss, 4); ss += __shfl_xor(ss, 8);
;                     const float rs = rsqrtf(ss * (1.0f / 64.0f) + EPSV);
;                     bf16_t* rp = qk + (size_t)(pm * 256 + ai * 128 + wr * 64 + m * 16 + fq * 4 + j) * 2048 + head * 64 + fr;
; #pragma unroll
;                     for (int bj = 0; bj < 2; ++bj)
; #pragma unroll
;                         for (int n = 0; n < 2; ++n) rp[bj * 32 + n * 16] = (bf16_t)f2bf(acc[ai][bj][m][n][j] * rs * gv[bj][n]);
;                 }
	v_pk_add_f32 v[194:195], v[194:195], v[196:197]
	ds_bpermute_b32 v197, v174, v195
	ds_bpermute_b32 v196, v174, v194
	v_mov_b32_e32 v200, v79
	v_mov_b32_e32 v201, v47
	v_pk_mul_f32 v[200:201], v[200:201], v[200:201]
	v_mov_b32_e32 v202, v19
	s_waitcnt lgkmcnt(0)
	v_pk_add_f32 v[194:195], v[194:195], v[196:197]
	ds_bpermute_b32 v197, v173, v195
	ds_bpermute_b32 v196, v173, v194
	v_mov_b32_e32 v203, v3
	v_pk_mul_f32 v[202:203], v[202:203], v[202:203]
	v_mov_b32_e32 v204, v200
	v_mov_b32_e32 v200, v202
	s_waitcnt lgkmcnt(0)
	v_pk_add_f32 v[194:195], v[194:195], v[196:197]
	ds_bpermute_b32 v197, v172, v195
	ds_bpermute_b32 v196, v172, v194
	v_mov_b32_e32 v202, v21
	s_waitcnt lgkmcnt(0)
	v_pk_add_f32 v[194:195], v[194:195], v[196:197]
	s_nop 0
	v_pk_fma_f32 v[194:195], v[194:195], s[8:9], v[162:163] op_sel_hi:[1,0,0]
	v_mov_b32_e32 v196, v78
	v_mul_f32_e32 v161, 0x4b800000, v195
	v_cmp_gt_f32_e64 s[46:47], s93, v195
	v_mov_b32_e32 v197, v46
	v_pk_mul_f32 v[196:197], v[196:197], v[196:197]
	v_cndmask_b32_e64 v161, v195, v161, s[46:47]
	v_rsq_f32_e32 v161, v161
	v_mov_b32_e32 v205, v196
	v_mov_b32_e32 v196, v201
	v_pk_add_f32 v[196:197], v[204:205], v[196:197]
	v_mul_f32_e32 v192, 0x45800000, v161
	v_cndmask_b32_e64 v161, v161, v192, s[46:47]
	v_mul_f32_e32 v192, v88, v161
	v_mul_f32_e32 v192, v168, v192
	v_cvt_pk_bf16_f32 v192, v192, s0
	global_store_short v[198:199], v192, off
	v_mul_f32_e32 v192, v56, v161
	v_mul_f32_e32 v192, v169, v192
	v_cvt_pk_bf16_f32 v192, v192, s0
	global_store_short v[198:199], v192, off offset:32
	v_mul_f32_e32 v192, v24, v161
	v_mul_f32_e32 v161, v8, v161
	v_mul_f32_e32 v192, v170, v192
	v_mul_f32_e32 v161, v171, v161
	v_cvt_pk_bf16_f32 v192, v192, s0
	v_cvt_pk_bf16_f32 v161, v161, s0
	global_store_short v[198:199], v192, off offset:64
	global_store_short v[198:199], v161, off offset:96
	v_mov_b32_e32 v198, v18
	v_mov_b32_e32 v199, v2
	v_pk_mul_f32 v[198:199], v[198:199], v[198:199]
	v_cmp_gt_f32_e32 vcc, s93, v194
	v_mov_b32_e32 v201, v198
	v_pk_add_f32 v[196:197], v[196:197], v[200:201]
	v_mov_b32_e32 v198, v203
	v_pk_add_f32 v[196:197], v[196:197], v[198:199]
	ds_bpermute_b32 v199, v175, v197
	ds_bpermute_b32 v198, v175, v196
	v_mul_f32_e32 v161, 0x4b800000, v194
	v_cndmask_b32_e32 v161, v194, v161, vcc
	v_rsq_f32_e32 v161, v161
	v_add_u32_e32 v194, 0xa3, v160
	s_waitcnt lgkmcnt(0)
	v_pk_add_f32 v[196:197], v[196:197], v[198:199]
	ds_bpermute_b32 v199, v174, v197
	ds_bpermute_b32 v198, v174, v196
	v_mul_f32_e32 v192, 0x45800000, v161
	v_cndmask_b32_e32 v161, v161, v192, vcc
	v_ashrrev_i32_e32 v195, 31, v194
	v_mul_f32_e32 v192, v89, v161
	s_waitcnt lgkmcnt(0)
	v_pk_add_f32 v[196:197], v[196:197], v[198:199]
	ds_bpermute_b32 v199, v173, v197
	ds_bpermute_b32 v198, v173, v196
	v_lshlrev_b64 v[194:195], 12, v[194:195]
	v_mul_f32_e32 v192, v168, v192
	v_lshl_add_u64 v[194:195], v[158:159], 0, v[194:195]
	v_cvt_pk_bf16_f32 v192, v192, s0
	s_waitcnt lgkmcnt(0)
	v_pk_add_f32 v[196:197], v[196:197], v[198:199]
	ds_bpermute_b32 v199, v172, v197
	ds_bpermute_b32 v198, v172, v196
	global_store_short v[194:195], v192, off
	v_mul_f32_e32 v192, v57, v161
	v_mul_f32_e32 v192, v169, v192
	v_cvt_pk_bf16_f32 v192, v192, s0
	global_store_short v[194:195], v192, off offset:32
	v_mul_f32_e32 v192, v25, v161
	v_mul_f32_e32 v161, v9, v161
	v_mul_f32_e32 v161, v171, v161
	s_waitcnt lgkmcnt(0)
; __device__ __forceinline__ unsigned f2bf(float f) { const __bf16 b = (__bf16)f; return (unsigned)__builtin_bit_cast(unsigned short, b); }
;     __device__ __forceinline__ void operator()(Acc& acc, int pm, int pn, int wr, int wc, int fr, int fq) const {
;     ...
;                     float ss = acc[ai][0][m][0][j] * acc[ai][0][m][0][j] + acc[ai][0][m][1][j] * acc[ai][0][m][1][j] +
;                                acc[ai][1][m][0][j] * acc[ai][1][m][0][j] + acc[ai][1][m][1][j] * acc[ai][1][m][1][j];
;                     ss += __shfl_xor(ss, 1); ss += __shfl_xor(ss, 2); ss += __shfl_xor(ss, 4); ss += __shfl_xor(ss, 8);
;                     const float rs = rsqrtf(ss * (1.0f / 64.0f) + EPSV);
;                     bf16_t* rp = qk + (size_t)(pm * 256 + ai * 128 + wr * 64 + m * 16 + fq * 4 + j) * 2048 + head * 64 + fr;
; #pragma unroll
;                     for (int bj = 0; bj < 2; ++bj)
; #pragma unroll
;                         for (int n = 0; n < 2; ++n) rp[bj * 32 + n * 16] = (bf16_t)f2bf(acc[ai][bj][m][n][j] * rs * gv[bj][n]);
	v_pk_add_f32 v[196:197], v[196:197], v[198:199]
	v_cvt_pk_bf16_f32 v161, v161, s0
	v_pk_fma_f32 v[196:197], v[196:197], s[8:9], v[162:163] op_sel_hi:[1,0,0]
	global_store_short v[194:195], v161, off offset:96
	v_mul_f32_e32 v161, 0x4b800000, v197
	v_cmp_gt_f32_e64 s[46:47], s93, v197
	v_mul_f32_e32 v192, v170, v192
	v_cvt_pk_bf16_f32 v192, v192, s0
	v_cndmask_b32_e64 v161, v197, v161, s[46:47]
	v_rsq_f32_e32 v161, v161
	global_store_short v[194:195], v192, off offset:64
	v_add_u32_e32 v194, 0xb0, v160
	v_ashrrev_i32_e32 v195, 31, v194
	v_mul_f32_e32 v192, 0x45800000, v161
	v_cndmask_b32_e64 v161, v161, v192, s[46:47]
	v_mul_f32_e32 v192, v78, v161
	v_lshlrev_b64 v[194:195], 12, v[194:195]
	v_mul_f32_e32 v192, v168, v192
	v_lshl_add_u64 v[194:195], v[158:159], 0, v[194:195]
	v_cvt_pk_bf16_f32 v192, v192, s0
	global_store_short v[194:195], v192, off
	v_mul_f32_e32 v192, v46, v161
	v_mul_f32_e32 v192, v169, v192
	v_cvt_pk_bf16_f32 v192, v192, s0
	global_store_short v[194:195], v192, off offset:32
	v_mul_f32_e32 v192, v18, v161
	v_mul_f32_e32 v161, v2, v161
	v_mul_f32_e32 v161, v171, v161
	v_cvt_pk_bf16_f32 v161, v161, s0
	v_cmp_gt_f32_e32 vcc, s93, v196
	global_store_short v[194:195], v161, off offset:96
	v_mul_f32_e32 v161, 0x4b800000, v196
	v_cndmask_b32_e32 v161, v196, v161, vcc
	v_rsq_f32_e32 v161, v161
	v_mul_f32_e32 v192, v170, v192
	v_cvt_pk_bf16_f32 v192, v192, s0
	global_store_short v[194:195], v192, off offset:64
	v_mul_f32_e32 v192, 0x45800000, v161
	v_cndmask_b32_e32 v161, v161, v192, vcc
	v_add_u32_e32 v194, 0xb1, v160
	v_ashrrev_i32_e32 v195, 31, v194
	v_mul_f32_e32 v192, v79, v161
	v_lshlrev_b64 v[194:195], 12, v[194:195]
	v_mul_f32_e32 v192, v168, v192
	v_lshl_add_u64 v[194:195], v[158:159], 0, v[194:195]
	v_cvt_pk_bf16_f32 v192, v192, s0
	global_store_short v[194:195], v192, off
	v_mul_f32_e32 v192, v47, v161
	v_mul_f32_e32 v192, v169, v192
	v_cvt_pk_bf16_f32 v192, v192, s0
	global_store_short v[194:195], v192, off offset:32
	v_mul_f32_e32 v192, v19, v161
	v_mul_f32_e32 v161, v3, v161
	v_mul_f32_e32 v192, v170, v192
	v_mul_f32_e32 v161, v171, v161
	v_cvt_pk_bf16_f32 v192, v192, s0
	v_cvt_pk_bf16_f32 v161, v161, s0
	global_store_short v[194:195], v192, off offset:64
	global_store_short v[194:195], v161, off offset:96
	v_mov_b32_e32 v194, v80
	v_mov_b32_e32 v195, v48
	v_mov_b32_e32 v200, v81
	v_mov_b32_e32 v201, v49
	v_pk_mul_f32 v[194:195], v[194:195], v[194:195]
	v_mov_b32_e32 v196, v20
	v_mov_b32_e32 v197, v4
	v_pk_mul_f32 v[200:201], v[200:201], v[200:201]
	v_mov_b32_e32 v203, v5
	v_pk_mul_f32 v[196:197], v[196:197], v[196:197]
	v_pk_mul_f32 v[202:203], v[202:203], v[202:203]
	v_mov_b32_e32 v204, v200
	v_mov_b32_e32 v205, v194
	v_mov_b32_e32 v194, v201
	v_pk_add_f32 v[194:195], v[204:205], v[194:195]
	v_mov_b32_e32 v200, v202
	v_mov_b32_e32 v201, v196
	v_pk_add_f32 v[194:195], v[194:195], v[200:201]
	v_mov_b32_e32 v196, v203
	v_pk_add_f32 v[194:195], v[194:195], v[196:197]
	ds_bpermute_b32 v197, v175, v195
	ds_bpermute_b32 v196, v175, v194
	v_add_u32_e32 v198, 0xb2, v160
	v_ashrrev_i32_e32 v199, 31, v198
	v_lshlrev_b64 v[198:199], 12, v[198:199]
	v_lshl_add_u64 v[198:199], v[158:159], 0, v[198:199]
	s_waitcnt lgkmcnt(0)
	v_pk_add_f32 v[194:195], v[194:195], v[196:197]
	ds_bpermute_b32 v175, v174, v195
	ds_bpermute_b32 v174, v174, v194
	v_add_u32_e32 v160, 0xb3, v160
	s_waitcnt lgkmcnt(0)
	v_pk_add_f32 v[174:175], v[194:195], v[174:175]
	ds_bpermute_b32 v195, v173, v175
	ds_bpermute_b32 v194, v173, v174
	s_waitcnt lgkmcnt(0)
	v_pk_add_f32 v[174:175], v[174:175], v[194:195]
	ds_bpermute_b32 v173, v172, v175
	ds_bpermute_b32 v172, v172, v174
	s_waitcnt lgkmcnt(0)
	v_pk_add_f32 v[172:173], v[174:175], v[172:173]
	s_nop 0
	v_pk_fma_f32 v[162:163], v[172:173], s[8:9], v[162:163] op_sel_hi:[1,0,0]
	s_nop 0
	v_mul_f32_e32 v161, 0x4b800000, v163
	v_cmp_gt_f32_e64 s[46:47], s93, v163
	v_cmp_gt_f32_e32 vcc, s93, v162
	s_nop 0
	v_cndmask_b32_e64 v161, v163, v161, s[46:47]
	v_rsq_f32_e32 v161, v161
	s_nop 0
	v_mul_f32_e32 v163, 0x45800000, v161
	v_cndmask_b32_e64 v161, v161, v163, s[46:47]
	v_mul_f32_e32 v163, v80, v161
	v_mul_f32_e32 v163, v168, v163
	v_cvt_pk_bf16_f32 v163, v163, s0
	global_store_short v[198:199], v163, off
	v_mul_f32_e32 v163, v48, v161
	v_mul_f32_e32 v163, v169, v163
	v_cvt_pk_bf16_f32 v163, v163, s0
	global_store_short v[198:199], v163, off offset:32
	v_mul_f32_e32 v163, v20, v161
	v_mul_f32_e32 v161, v4, v161
	v_mul_f32_e32 v161, v171, v161
	v_cvt_pk_bf16_f32 v161, v161, s0
	global_store_short v[198:199], v161, off offset:96
	v_mul_f32_e32 v161, 0x4b800000, v162
	v_cndmask_b32_e32 v161, v162, v161, vcc
	v_rsq_f32_e32 v161, v161
	v_mul_f32_e32 v163, v170, v163
	v_cvt_pk_bf16_f32 v163, v163, s0
	global_store_short v[198:199], v163, off offset:64
	v_mul_f32_e32 v162, 0x45800000, v161
	v_cndmask_b32_e32 v162, v161, v162, vcc
	v_ashrrev_i32_e32 v161, 31, v160
	v_lshlrev_b64 v[160:161], 12, v[160:161]
	v_lshl_add_u64 v[158:159], v[158:159], 0, v[160:161]
	v_mul_f32_e32 v160, v81, v162
	v_mul_f32_e32 v160, v168, v160
	v_cvt_pk_bf16_f32 v160, v160, s0
	global_store_short v[158:159], v160, off
	v_mul_f32_e32 v160, v49, v162
	v_mul_f32_e32 v160, v169, v160
	v_cvt_pk_bf16_f32 v160, v160, s0
	global_store_short v[158:159], v160, off offset:32
	v_mul_f32_e32 v160, v21, v162
	v_mul_f32_e32 v160, v170, v160
	v_cvt_pk_bf16_f32 v160, v160, s0
	global_store_short v[158:159], v160, off offset:64
	v_mul_f32_e32 v160, v5, v162
	v_mul_f32_e32 v160, v171, v160
	v_cvt_pk_bf16_f32 v160, v160, s0
	global_store_short v[158:159], v160, off offset:96

; #define PG8_STAGE(bufoff, gbase) do { _Pragma("unroll") for (int _i = 0; _i < 2; ++_i) \
;         __builtin_amdgcn_global_load_lds((const unsigned*)((const char*)(gbase) + voff[_i]), (LAS unsigned*)(lds + (bufoff) + ldsw + _i * 8192), 16, 0, 0); } while (0)
; #define PG8_LDA(dst, b, h) do { _Pragma("unroll") for (int m = 0; m < 4; ++m) _Pragma("unroll") for (int k = 0; k < 2; ++k) dst[m][k] = *(const LAS bf16x8*)(lds + PG8_SA(b, h) + aoff + m * 2048 + k * 1024); } while (0)
; #define PG8_LDB(dst, b, h) do { _Pragma("unroll") for (int n = 0; n < 2; ++n) _Pragma("unroll") for (int k = 0; k < 2; ++k) dst[n][k] = *(const LAS bf16x8*)(lds + PG8_SB(b, h) + boff + n * 2048 + k * 1024); } while (0)
; #define PG8_WAIT_V(n) asm volatile("s_waitcnt vmcnt(" #n ")" ::: "memory")
; #define PG8_WAIT_L(n) asm volatile("s_waitcnt lgkmcnt(" #n ")" ::: "memory")
; #define PG8_BAR __builtin_amdgcn_s_barrier()
; #define PG8_SCHED __builtin_amdgcn_sched_barrier(0)
;     ...
;             PG8_LDB(B0, 0, 0); PG8_SCHED; PG8_LDA(At, 0, 0); PG8_STAGE(PG8_SA(1, 1), a1 + hstep);
;             PG8_WAIT_L(8); PG8_BAR; PG8_WAIT_L(0); PG8_MMA(0, 0, At, B0); PG8_BAR; PG8_SCHED;
;             PG8_LDB(B1, 0, 1); PG8_STAGE(PG8_SB(0, 0), b2);
;             PG8_BAR; PG8_WAIT_L(0); PG8_MMA(0, 1, At, B1); PG8_BAR;
;             PG8_LDA(At, 0, 1); PG8_STAGE(PG8_SA(0, 0), a2);
;             PG8_BAR; PG8_WAIT_L(0); PG8_MMA(1, 0, At, B0); PG8_BAR; PG8_SCHED;
;             PG8_STAGE(PG8_SB(0, 1), b2 + hstep);
;             PG8_WAIT_V(6); PG8_BAR; PG8_MMA(1, 1, At, B1); PG8_BAR;
;             PG8_LDB(B0, 1, 0); PG8_SCHED; PG8_LDA(At, 1, 0); PG8_STAGE(PG8_SA(0, 1), a2 + hstep);
;             PG8_WAIT_L(8); PG8_BAR; PG8_WAIT_L(0); PG8_MMA(0, 0, At, B0); PG8_BAR; PG8_SCHED;
;             PG8_LDB(B1, 1, 1); PG8_STAGE(PG8_SB(1, 0), b3);
;             PG8_BAR; PG8_WAIT_L(0); PG8_MMA(0, 1, At, B1); PG8_BAR;
.LBB0_482:
	s_add_u32 s0, s10, 0xfffc0080
	s_addc_u32 s1, s11, -1
	s_add_i32 s29, 0, 0x10000
	v_add_u32_e32 v169, s29, v164
	ds_read_b128 v[156:159], v169
	ds_read_b128 v[160:163], v169 offset:1024
	ds_read_b128 v[170:173], v169 offset:2048
	ds_read_b128 v[194:197], v169 offset:3072
	s_cmp_eq_u32 s28, 12
	s_cselect_b32 s15, s4, s1
	s_cselect_b32 s14, s7, s0
	s_cselect_b32 s13, s18, s23
	s_cselect_b32 s12, s19, s22
	v_lshl_add_u64 v[174:175], s[10:11], 0, v[152:153]
	s_add_i32 m0, s41, 0xc000
	ds_read_b128 v[198:201], v168
	ds_read_b128 v[202:205], v168 offset:1024
	ds_read_b128 v[206:209], v168 offset:2048
	ds_read_b128 v[210:213], v168 offset:3072
	ds_read_b128 v[214:217], v168 offset:4096
	ds_read_b128 v[218:221], v168 offset:5120
	ds_read_b128 v[222:225], v168 offset:6144
	ds_read_b128 v[226:229], v168 offset:7168
	global_load_lds_dwordx4 v[174:175], off
	v_lshl_add_u64 v[174:175], s[10:11], 0, v[154:155]
	s_add_i32 m0, s41, 0xe000
	s_nop 0
	global_load_lds_dwordx4 v[174:175], off
	s_waitcnt lgkmcnt(8)
	s_barrier
	s_waitcnt lgkmcnt(0)
	s_setprio 1
	v_mfma_f32_16x16x32_bf16 v[126:129], v[198:201], v[156:159], v[126:129]
	v_mfma_f32_16x16x32_bf16 v[110:113], v[198:201], v[170:173], v[110:113]
	v_mfma_f32_16x16x32_bf16 v[122:125], v[206:209], v[156:159], v[122:125]
	v_mfma_f32_16x16x32_bf16 v[106:109], v[206:209], v[170:173], v[106:109]
	v_mfma_f32_16x16x32_bf16 v[118:121], v[214:217], v[156:159], v[118:121]
	v_mfma_f32_16x16x32_bf16 v[102:105], v[214:217], v[170:173], v[102:105]
	v_mfma_f32_16x16x32_bf16 v[114:117], v[222:225], v[156:159], v[114:117]
	v_mfma_f32_16x16x32_bf16 v[94:97], v[222:225], v[170:173], v[94:97]
	v_mfma_f32_16x16x32_bf16 v[126:129], v[202:205], v[160:163], v[126:129]
	v_mfma_f32_16x16x32_bf16 v[110:113], v[202:205], v[194:197], v[110:113]
	v_mfma_f32_16x16x32_bf16 v[122:125], v[210:213], v[160:163], v[122:125]
	v_mfma_f32_16x16x32_bf16 v[106:109], v[210:213], v[194:197], v[106:109]
	v_mfma_f32_16x16x32_bf16 v[118:121], v[218:221], v[160:163], v[118:121]
	v_mfma_f32_16x16x32_bf16 v[102:105], v[218:221], v[194:197], v[102:105]
	v_mfma_f32_16x16x32_bf16 v[114:117], v[226:229], v[160:163], v[114:117]
	v_mfma_f32_16x16x32_bf16 v[94:97], v[226:229], v[194:197], v[94:97]
	s_setprio 0
	s_barrier
	s_add_i32 s0, 0, 0x14000
	s_add_i32 s1, s29, s40
	v_add_u32_e32 v169, s0, v164
	v_lshl_add_u64 v[174:175], s[12:13], 0, v[132:133]
	s_mov_b32 m0, s1
	ds_read_b128 v[230:233], v169
	ds_read_b128 v[234:237], v169 offset:1024
	ds_read_b128 v[238:241], v169 offset:2048
	ds_read_b128 v[242:245], v169 offset:3072
	global_load_lds_dwordx4 v[174:175], off
	v_lshl_add_u64 v[192:193], s[12:13], 0, v[130:131]
	s_add_i32 m0, s1, 0x2000
	s_nop 0
	global_load_lds_dwordx4 v[192:193], off
	s_barrier
	s_waitcnt lgkmcnt(0)
	s_setprio 1
	v_mfma_f32_16x16x32_bf16 v[82:85], v[198:201], v[230:233], v[82:85]
	v_mfma_f32_16x16x32_bf16 v[50:53], v[198:201], v[238:241], v[50:53]
	v_mfma_f32_16x16x32_bf16 v[74:77], v[206:209], v[230:233], v[74:77]
	v_mfma_f32_16x16x32_bf16 v[42:45], v[206:209], v[238:241], v[42:45]
	v_mfma_f32_16x16x32_bf16 v[66:69], v[214:217], v[230:233], v[66:69]
	v_mfma_f32_16x16x32_bf16 v[38:41], v[214:217], v[238:241], v[38:41]
	v_mfma_f32_16x16x32_bf16 v[58:61], v[222:225], v[230:233], v[58:61]
	v_mfma_f32_16x16x32_bf16 v[30:33], v[222:225], v[238:241], v[30:33]
	v_mfma_f32_16x16x32_bf16 v[82:85], v[202:205], v[234:237], v[82:85]
	v_mfma_f32_16x16x32_bf16 v[50:53], v[202:205], v[242:245], v[50:53]
	v_mfma_f32_16x16x32_bf16 v[74:77], v[210:213], v[234:237], v[74:77]
	v_mfma_f32_16x16x32_bf16 v[42:45], v[210:213], v[242:245], v[42:45]
	v_mfma_f32_16x16x32_bf16 v[66:69], v[218:221], v[234:237], v[66:69]
	v_mfma_f32_16x16x32_bf16 v[38:41], v[218:221], v[242:245], v[38:41]
	v_mfma_f32_16x16x32_bf16 v[58:61], v[226:229], v[234:237], v[58:61]
	v_mfma_f32_16x16x32_bf16 v[30:33], v[226:229], v[242:245], v[30:33]
	s_setprio 0
	s_mov_b32 m0, s41
	v_lshl_add_u64 v[246:247], s[14:15], 0, v[132:133]
	s_barrier
	ds_read_b128 v[198:201], v168 offset:16384
	ds_read_b128 v[202:205], v168 offset:17408
	ds_read_b128 v[206:209], v168 offset:18432
	ds_read_b128 v[210:213], v168 offset:19456
	ds_read_b128 v[214:217], v168 offset:20480
	ds_read_b128 v[218:221], v168 offset:21504
	ds_read_b128 v[222:225], v168 offset:22528
	ds_read_b128 v[226:229], v168 offset:23552
	global_load_lds_dwordx4 v[246:247], off
	v_lshl_add_u64 v[248:249], s[14:15], 0, v[130:131]
	s_mov_b32 m0, s64
	s_nop 0
	global_load_lds_dwordx4 v[248:249], off
	s_barrier
	s_waitcnt lgkmcnt(0)
	s_setprio 1
	v_mfma_f32_16x16x32_bf16 v[98:101], v[198:201], v[156:159], v[98:101]
	v_mfma_f32_16x16x32_bf16 v[70:73], v[198:201], v[170:173], v[70:73]
	v_mfma_f32_16x16x32_bf16 v[90:93], v[206:209], v[156:159], v[90:93]
	v_mfma_f32_16x16x32_bf16 v[62:65], v[206:209], v[170:173], v[62:65]
	v_mfma_f32_16x16x32_bf16 v[86:89], v[214:217], v[156:159], v[86:89]
	v_mfma_f32_16x16x32_bf16 v[54:57], v[214:217], v[170:173], v[54:57]
	v_mfma_f32_16x16x32_bf16 v[78:81], v[222:225], v[156:159], v[78:81]
	v_mfma_f32_16x16x32_bf16 v[46:49], v[222:225], v[170:173], v[46:49]
	v_mfma_f32_16x16x32_bf16 v[98:101], v[202:205], v[160:163], v[98:101]
	v_mfma_f32_16x16x32_bf16 v[70:73], v[202:205], v[194:197], v[70:73]
	v_mfma_f32_16x16x32_bf16 v[90:93], v[210:213], v[160:163], v[90:93]
	v_mfma_f32_16x16x32_bf16 v[62:65], v[210:213], v[194:197], v[62:65]
	v_mfma_f32_16x16x32_bf16 v[86:89], v[218:221], v[160:163], v[86:89]
	v_mfma_f32_16x16x32_bf16 v[54:57], v[218:221], v[194:197], v[54:57]
	v_mfma_f32_16x16x32_bf16 v[78:81], v[226:229], v[160:163], v[78:81]
	v_mfma_f32_16x16x32_bf16 v[46:49], v[226:229], v[194:197], v[46:49]
	s_setprio 0
	s_barrier
; #define PG8_STAGE(bufoff, gbase) do { _Pragma("unroll") for (int _i = 0; _i < 2; ++_i) \
;         __builtin_amdgcn_global_load_lds((const unsigned*)((const char*)(gbase) + voff[_i]), (LAS unsigned*)(lds + (bufoff) + ldsw + _i * 8192), 16, 0, 0); } while (0)
; #define PG8_LDA(dst, b, h) do { _Pragma("unroll") for (int m = 0; m < 4; ++m) _Pragma("unroll") for (int k = 0; k < 2; ++k) dst[m][k] = *(const LAS bf16x8*)(lds + PG8_SA(b, h) + aoff + m * 2048 + k * 1024); } while (0)
; #define PG8_LDB(dst, b, h) do { _Pragma("unroll") for (int n = 0; n < 2; ++n) _Pragma("unroll") for (int k = 0; k < 2; ++k) dst[n][k] = *(const LAS bf16x8*)(lds + PG8_SB(b, h) + boff + n * 2048 + k * 1024); } while (0)
; #define PG8_WAIT_V(n) asm volatile("s_waitcnt vmcnt(" #n ")" ::: "memory")
; #define PG8_WAIT_L(n) asm volatile("s_waitcnt lgkmcnt(" #n ")" ::: "memory")
; #define PG8_BAR __builtin_amdgcn_s_barrier()
; #define PG8_SCHED __builtin_amdgcn_sched_barrier(0)
;     ...
;             PG8_STAGE(PG8_SB(0, 1), b2 + hstep);
;             PG8_WAIT_V(6); PG8_BAR; PG8_MMA(1, 1, At, B1); PG8_BAR;
;             PG8_LDB(B0, 1, 0); PG8_SCHED; PG8_LDA(At, 1, 0); PG8_STAGE(PG8_SA(0, 1), a2 + hstep);
;             PG8_WAIT_L(8); PG8_BAR; PG8_WAIT_L(0); PG8_MMA(0, 0, At, B0); PG8_BAR; PG8_SCHED;
;             PG8_LDB(B1, 1, 1); PG8_STAGE(PG8_SB(1, 0), b3);
;             PG8_BAR; PG8_WAIT_L(0); PG8_MMA(0, 1, At, B1); PG8_BAR;
;             PG8_LDA(At, 1, 1); PG8_STAGE(PG8_SA(1, 0), a3);
;             PG8_BAR; PG8_WAIT_L(0); PG8_MMA(1, 0, At, B0); PG8_BAR; PG8_SCHED;
	s_add_u32 s30, s12, 0x40000
	s_addc_u32 s31, s13, 0
	s_add_i32 s0, s0, s40
	v_lshl_add_u64 v[156:157], s[30:31], 0, v[132:133]
	s_mov_b32 m0, s0
	s_nop 0
	global_load_lds_dwordx4 v[156:157], off
	v_lshl_add_u64 v[156:157], s[30:31], 0, v[130:131]
	s_add_i32 m0, s0, 0x2000
	s_nop 0
	global_load_lds_dwordx4 v[156:157], off
	s_waitcnt vmcnt(6)
	s_barrier
	s_setprio 1
	v_mfma_f32_16x16x32_bf16 v[34:37], v[198:201], v[230:233], v[34:37]
	v_mfma_f32_16x16x32_bf16 v[14:17], v[198:201], v[238:241], v[14:17]
	v_mfma_f32_16x16x32_bf16 v[26:29], v[206:209], v[230:233], v[26:29]
	v_mfma_f32_16x16x32_bf16 v[10:13], v[206:209], v[238:241], v[10:13]
	v_mfma_f32_16x16x32_bf16 v[22:25], v[214:217], v[230:233], v[22:25]
	v_mfma_f32_16x16x32_bf16 v[6:9], v[214:217], v[238:241], v[6:9]
	v_mfma_f32_16x16x32_bf16 v[18:21], v[222:225], v[230:233], v[18:21]
	v_mfma_f32_16x16x32_bf16 v[2:5], v[222:225], v[238:241], v[2:5]
	v_mfma_f32_16x16x32_bf16 v[34:37], v[202:205], v[234:237], v[34:37]
	v_mfma_f32_16x16x32_bf16 v[14:17], v[202:205], v[242:245], v[14:17]
	v_mfma_f32_16x16x32_bf16 v[26:29], v[210:213], v[234:237], v[26:29]
	v_mfma_f32_16x16x32_bf16 v[10:13], v[210:213], v[242:245], v[10:13]
	v_mfma_f32_16x16x32_bf16 v[22:25], v[218:221], v[234:237], v[22:25]
	v_mfma_f32_16x16x32_bf16 v[6:9], v[218:221], v[242:245], v[6:9]
	v_mfma_f32_16x16x32_bf16 v[18:21], v[226:229], v[234:237], v[18:21]
	v_mfma_f32_16x16x32_bf16 v[2:5], v[226:229], v[242:245], v[2:5]
	s_setprio 0
	s_add_i32 s0, 0, 0x18000
	v_add_u32_e32 v169, s0, v164
	s_barrier
	ds_read_b128 v[156:159], v169
	ds_read_b128 v[160:163], v169 offset:1024
	ds_read_b128 v[170:173], v169 offset:2048
	ds_read_b128 v[194:197], v169 offset:3072
	s_add_u32 s14, s14, 0x40000
	s_addc_u32 s15, s15, 0
	s_mov_b32 m0, s65
	v_lshl_add_u64 v[230:231], s[14:15], 0, v[132:133]
	ds_read_b128 v[198:201], v168 offset:32768
	ds_read_b128 v[202:205], v168 offset:33792
	ds_read_b128 v[206:209], v168 offset:34816
	ds_read_b128 v[210:213], v168 offset:35840
	ds_read_b128 v[214:217], v168 offset:36864
	ds_read_b128 v[218:221], v168 offset:37888
	ds_read_b128 v[222:225], v168 offset:38912
	ds_read_b128 v[226:229], v168 offset:39936
	global_load_lds_dwordx4 v[230:231], off
	v_lshl_add_u64 v[230:231], s[14:15], 0, v[130:131]
	s_mov_b32 m0, s66
	s_nop 0
	global_load_lds_dwordx4 v[230:231], off
	s_waitcnt lgkmcnt(8)
	s_barrier
	s_waitcnt lgkmcnt(0)
	s_setprio 1
	v_mfma_f32_16x16x32_bf16 v[126:129], v[198:201], v[156:159], v[126:129]
	v_mfma_f32_16x16x32_bf16 v[110:113], v[198:201], v[170:173], v[110:113]
	v_mfma_f32_16x16x32_bf16 v[122:125], v[206:209], v[156:159], v[122:125]
	v_mfma_f32_16x16x32_bf16 v[106:109], v[206:209], v[170:173], v[106:109]
	v_mfma_f32_16x16x32_bf16 v[118:121], v[214:217], v[156:159], v[118:121]
	v_mfma_f32_16x16x32_bf16 v[102:105], v[214:217], v[170:173], v[102:105]
	v_mfma_f32_16x16x32_bf16 v[114:117], v[222:225], v[156:159], v[114:117]
	v_mfma_f32_16x16x32_bf16 v[94:97], v[222:225], v[170:173], v[94:97]
	v_mfma_f32_16x16x32_bf16 v[126:129], v[202:205], v[160:163], v[126:129]
	v_mfma_f32_16x16x32_bf16 v[110:113], v[202:205], v[194:197], v[110:113]
	v_mfma_f32_16x16x32_bf16 v[122:125], v[210:213], v[160:163], v[122:125]
	v_mfma_f32_16x16x32_bf16 v[106:109], v[210:213], v[194:197], v[106:109]
	v_mfma_f32_16x16x32_bf16 v[118:121], v[218:221], v[160:163], v[118:121]
	v_mfma_f32_16x16x32_bf16 v[102:105], v[218:221], v[194:197], v[102:105]
	v_mfma_f32_16x16x32_bf16 v[114:117], v[226:229], v[160:163], v[114:117]
	v_mfma_f32_16x16x32_bf16 v[94:97], v[226:229], v[194:197], v[94:97]
	s_setprio 0
	s_barrier
	s_add_i32 s1, 0, 0x1c000
	s_add_i32 s0, s0, s40
	v_add_u32_e32 v169, s1, v164
	v_lshl_add_u64 v[174:175], v[174:175], 0, s[88:89]
	s_mov_b32 m0, s0
	ds_read_b128 v[230:233], v169
	ds_read_b128 v[234:237], v169 offset:1024
	ds_read_b128 v[238:241], v169 offset:2048
	ds_read_b128 v[242:245], v169 offset:3072
	global_load_lds_dwordx4 v[174:175], off
	v_lshl_add_u64 v[174:175], v[192:193], 0, s[88:89]
	s_add_i32 m0, s0, 0x2000
	s_nop 0
	global_load_lds_dwordx4 v[174:175], off
	s_barrier
	s_waitcnt lgkmcnt(0)
	s_setprio 1
	v_mfma_f32_16x16x32_bf16 v[82:85], v[198:201], v[230:233], v[82:85]
	v_mfma_f32_16x16x32_bf16 v[50:53], v[198:201], v[238:241], v[50:53]
	v_mfma_f32_16x16x32_bf16 v[74:77], v[206:209], v[230:233], v[74:77]
	v_mfma_f32_16x16x32_bf16 v[42:45], v[206:209], v[238:241], v[42:45]
	v_mfma_f32_16x16x32_bf16 v[66:69], v[214:217], v[230:233], v[66:69]
	v_mfma_f32_16x16x32_bf16 v[38:41], v[214:217], v[238:241], v[38:41]
	v_mfma_f32_16x16x32_bf16 v[58:61], v[222:225], v[230:233], v[58:61]
	v_mfma_f32_16x16x32_bf16 v[30:33], v[222:225], v[238:241], v[30:33]
	v_mfma_f32_16x16x32_bf16 v[82:85], v[202:205], v[234:237], v[82:85]
	v_mfma_f32_16x16x32_bf16 v[50:53], v[202:205], v[242:245], v[50:53]
	v_mfma_f32_16x16x32_bf16 v[74:77], v[210:213], v[234:237], v[74:77]
	v_mfma_f32_16x16x32_bf16 v[42:45], v[210:213], v[242:245], v[42:45]
	v_mfma_f32_16x16x32_bf16 v[66:69], v[218:221], v[234:237], v[66:69]
	v_mfma_f32_16x16x32_bf16 v[38:41], v[218:221], v[242:245], v[38:41]
	v_mfma_f32_16x16x32_bf16 v[58:61], v[226:229], v[234:237], v[58:61]
	v_mfma_f32_16x16x32_bf16 v[30:33], v[226:229], v[242:245], v[30:33]
	s_setprio 0
	s_mov_b32 m0, s67
	v_lshl_add_u64 v[174:175], v[246:247], 0, s[88:89]
	s_barrier
	ds_read_b128 v[198:201], v168 offset:49152
	ds_read_b128 v[202:205], v168 offset:50176
	ds_read_b128 v[206:209], v168 offset:51200
	ds_read_b128 v[210:213], v168 offset:52224
	ds_read_b128 v[214:217], v168 offset:53248
	ds_read_b128 v[218:221], v168 offset:54272
	ds_read_b128 v[222:225], v168 offset:55296
	ds_read_b128 v[226:229], v168 offset:56320
	global_load_lds_dwordx4 v[174:175], off
	v_lshl_add_u64 v[174:175], v[248:249], 0, s[88:89]
	s_mov_b32 m0, s68
	s_nop 0
	global_load_lds_dwordx4 v[174:175], off
	s_barrier
; __device__ __forceinline__ float frcp(float x) { return __builtin_amdgcn_rcpf(x); }
; __device__ __forceinline__ float fexp(float x) { return __builtin_amdgcn_exp2f(x * 1.4426950408889634f); }
; #define PG8_STAGE(bufoff, gbase) do { _Pragma("unroll") for (int _i = 0; _i < 2; ++_i) \
;         __builtin_amdgcn_global_load_lds((const unsigned*)((const char*)(gbase) + voff[_i]), (LAS unsigned*)(lds + (bufoff) + ldsw + _i * 8192), 16, 0, 0); } while (0)
; #define PG8_WAIT_V(n) asm volatile("s_waitcnt vmcnt(" #n ")" ::: "memory")
; #define PG8_WAIT_L(n) asm volatile("s_waitcnt lgkmcnt(" #n ")" ::: "memory")
; #define PG8_BAR __builtin_amdgcn_s_barrier()
; #define PG8_SCHED __builtin_amdgcn_sched_barrier(0)
;     ...
;             PG8_BAR; PG8_WAIT_L(0); PG8_MMA(1, 0, At, B0); PG8_BAR; PG8_SCHED;
;             PG8_STAGE(PG8_SB(1, 1), b3 + hstep);
;             PG8_WAIT_V(6); PG8_BAR; PG8_MMA(1, 1, At, B1); PG8_BAR;
;     __device__ __forceinline__ void operator()(Acc& acc, int pm, int pn, int wr, int wc, int fr, int fq) const {
;     ...
;         const int chl = pn * 64 + wc * 16 + fr, chg = half * 512 + chl;
;         const float lb = lbv[chg], oml = 1.f - lb;
; #pragma unroll
;         for (int ai = 0; ai < 2; ++ai) {
;             const int row0 = pm * 256 + ai * 128 + wr * 64;
;             float totb = 1.f;
; #pragma unroll
;             for (int mt = 0; mt < 4; ++mt)
; #pragma unroll
;                 for (int j = 0; j < 4; ++j) {
;                     const float sb = frcp(1.f + fexp(-acc[ai][1][mt][0][j]));
;                     acc[ai][1][mt][0][j] = sb;
;                     totb *= lb + oml * sb;
;                 }
	s_waitcnt lgkmcnt(0)
	s_setprio 1
	v_mfma_f32_16x16x32_bf16 v[98:101], v[198:201], v[156:159], v[98:101]
	v_mfma_f32_16x16x32_bf16 v[70:73], v[198:201], v[170:173], v[70:73]
	v_mfma_f32_16x16x32_bf16 v[90:93], v[206:209], v[156:159], v[90:93]
	v_mfma_f32_16x16x32_bf16 v[62:65], v[206:209], v[170:173], v[62:65]
	v_mfma_f32_16x16x32_bf16 v[86:89], v[214:217], v[156:159], v[86:89]
	v_mfma_f32_16x16x32_bf16 v[54:57], v[214:217], v[170:173], v[54:57]
	v_mfma_f32_16x16x32_bf16 v[78:81], v[222:225], v[156:159], v[78:81]
	v_mfma_f32_16x16x32_bf16 v[46:49], v[222:225], v[170:173], v[46:49]
	v_mfma_f32_16x16x32_bf16 v[98:101], v[202:205], v[160:163], v[98:101]
	v_mfma_f32_16x16x32_bf16 v[70:73], v[202:205], v[194:197], v[70:73]
	v_mfma_f32_16x16x32_bf16 v[90:93], v[210:213], v[160:163], v[90:93]
	v_mfma_f32_16x16x32_bf16 v[62:65], v[210:213], v[194:197], v[62:65]
	v_mfma_f32_16x16x32_bf16 v[86:89], v[218:221], v[160:163], v[86:89]
	v_mfma_f32_16x16x32_bf16 v[54:57], v[218:221], v[194:197], v[54:57]
	v_mfma_f32_16x16x32_bf16 v[78:81], v[226:229], v[160:163], v[78:81]
	v_mfma_f32_16x16x32_bf16 v[46:49], v[226:229], v[194:197], v[46:49]
	s_setprio 0
	s_barrier
	s_add_u32 s12, s12, 0x40080
	s_addc_u32 s13, s13, 0
	s_add_i32 s0, s1, s40
	v_lshl_add_u64 v[156:157], s[12:13], 0, v[132:133]
	s_mov_b32 m0, s0
	s_nop 0
	global_load_lds_dwordx4 v[156:157], off
	v_lshl_add_u64 v[156:157], s[12:13], 0, v[130:131]
	s_add_i32 m0, s0, 0x2000
	s_nop 0
	global_load_lds_dwordx4 v[156:157], off
	s_waitcnt vmcnt(6)
	s_barrier
	s_setprio 1
	v_mfma_f32_16x16x32_bf16 v[34:37], v[198:201], v[230:233], v[34:37]
	v_mfma_f32_16x16x32_bf16 v[14:17], v[198:201], v[238:241], v[14:17]
	v_mfma_f32_16x16x32_bf16 v[26:29], v[206:209], v[230:233], v[26:29]
	v_mfma_f32_16x16x32_bf16 v[10:13], v[206:209], v[238:241], v[10:13]
	v_mfma_f32_16x16x32_bf16 v[22:25], v[214:217], v[230:233], v[22:25]
	v_mfma_f32_16x16x32_bf16 v[6:9], v[214:217], v[238:241], v[6:9]
	v_mfma_f32_16x16x32_bf16 v[18:21], v[222:225], v[230:233], v[18:21]
	v_mfma_f32_16x16x32_bf16 v[2:5], v[222:225], v[238:241], v[2:5]
	v_mfma_f32_16x16x32_bf16 v[34:37], v[202:205], v[234:237], v[34:37]
	v_mfma_f32_16x16x32_bf16 v[14:17], v[202:205], v[242:245], v[14:17]
	v_mfma_f32_16x16x32_bf16 v[26:29], v[210:213], v[234:237], v[26:29]
	v_mfma_f32_16x16x32_bf16 v[10:13], v[210:213], v[242:245], v[10:13]
	v_mfma_f32_16x16x32_bf16 v[22:25], v[218:221], v[234:237], v[22:25]
	v_mfma_f32_16x16x32_bf16 v[6:9], v[218:221], v[242:245], v[6:9]
	v_mfma_f32_16x16x32_bf16 v[18:21], v[226:229], v[234:237], v[18:21]
	v_mfma_f32_16x16x32_bf16 v[2:5], v[226:229], v[242:245], v[2:5]
	s_setprio 0
	s_add_i32 s28, s28, 2
	s_add_u32 s10, s10, 0x100
	s_addc_u32 s11, s11, 0
	s_add_u32 s22, s22, 0x100
	s_addc_u32 s23, s23, 0
	s_cmp_gt_u32 s28, 13
	s_barrier
	s_cbranch_scc0 .LBB0_482
	s_cmp_lt_i32 s70, 8
	s_mov_b64 s[10:11], -1
	s_cbranch_scc0 .LBB0_489
	v_lshl_or_b32 v156, s70, 6, v167
	v_add_u32_e32 v158, s55, v156
	v_readlane_b32 s12, v253, 28
	v_ashrrev_i32_e32 v159, 31, v158
	v_readlane_b32 s13, v253, 29
	v_cmp_lt_i32_e32 vcc, v184, v182
	v_mul_f32_e32 v162, 0xbfb8aa3b, v84
	v_lshl_add_u64 v[160:161], v[158:159], 2, s[12:13]
	global_load_dword v169, v[160:161], off
	v_cndmask_b32_e32 v157, v180, v184, vcc
	v_mul_f32_e32 v160, 0xbfb8aa3b, v82
	v_mul_f32_e32 v161, 0xbfb8aa3b, v83
	v_lshlrev_b32_e32 v172, 2, v157
	v_exp_f32_e32 v157, v160
	v_exp_f32_e32 v160, v161
	v_mul_f32_e32 v163, 0xbfb8aa3b, v85
	v_exp_f32_e32 v161, v162
	v_mul_f32_e32 v170, 0xbfb8aa3b, v74
	v_mul_f32_e32 v171, 0xbfb8aa3b, v75
	v_exp_f32_e32 v162, v163
	v_mul_f32_e32 v173, 0xbfb8aa3b, v76
	v_mul_f32_e32 v174, 0xbfb8aa3b, v77
	v_mul_f32_e32 v175, 0xbfb8aa3b, v66
	v_mul_f32_e32 v192, 0xbfb8aa3b, v67
	v_mul_f32_e32 v193, 0xbfb8aa3b, v68
	v_exp_f32_e32 v163, v170
	v_exp_f32_e32 v170, v171
	v_exp_f32_e32 v171, v173
	v_exp_f32_e32 v173, v174
	v_exp_f32_e32 v174, v175
	v_exp_f32_e32 v175, v192
	v_exp_f32_e32 v192, v193
	v_add_f32_e32 v157, 1.0, v157
	v_add_f32_e32 v160, 1.0, v160
	v_add_f32_e32 v161, 1.0, v161
	v_rcp_f32_e32 v210, v157
	v_rcp_f32_e32 v211, v160
	v_add_f32_e32 v162, 1.0, v162
	v_rcp_f32_e32 v213, v161
	v_add_f32_e32 v163, 1.0, v163
	v_add_f32_e32 v170, 1.0, v170
	v_rcp_f32_e32 v214, v162
	v_add_f32_e32 v192, 1.0, v192
	v_rcp_f32_e32 v222, v163
	v_rcp_f32_e32 v223, v170
	v_mul_f32_e32 v194, 0xbfb8aa3b, v69
	v_add_f32_e32 v171, 1.0, v171
	v_rcp_f32_e32 v205, v192
	v_mul_f32_e32 v195, 0xbfb8aa3b, v58
	v_exp_f32_e32 v193, v194
	v_add_f32_e32 v173, 1.0, v173
	v_rcp_f32_e32 v224, v171
	v_mul_f32_e32 v196, 0xbfb8aa3b, v59
	v_exp_f32_e32 v194, v195
	v_add_f32_e32 v174, 1.0, v174
	v_rcp_f32_e32 v225, v173
	v_mul_f32_e32 v197, 0xbfb8aa3b, v60
	v_exp_f32_e32 v195, v196
	v_add_f32_e32 v175, 1.0, v175
	v_rcp_f32_e32 v207, v174
	v_mul_f32_e32 v198, 0xbfb8aa3b, v61
	v_exp_f32_e32 v196, v197
	v_rcp_f32_e32 v206, v175
	v_exp_f32_e32 v197, v198
	v_add_f32_e32 v193, 1.0, v193
	v_add_f32_e32 v194, 1.0, v194
	v_rcp_f32_e32 v204, v193
	v_add_f32_e32 v195, 1.0, v195
	v_rcp_f32_e32 v199, v194
	v_add_f32_e32 v198, 1.0, v196
	v_rcp_f32_e32 v196, v195
	v_rcp_f32_e32 v198, v198
	v_add_f32_e32 v160, 1.0, v197
	v_rcp_f32_e32 v197, v160
	v_mul_f32_e32 v216, 0xbfb8aa3b, v111
	v_exp_f32_e32 v216, v216
	v_cmp_lt_i32_e32 vcc, v183, v182
	s_lshl_b32 s4, s71, 8
	s_add_i32 s4, s4, s54
	v_add_f32_e32 v216, 1.0, v216
	v_rcp_f32_e32 v216, v216
	v_cndmask_b32_e32 v161, v180, v183, vcc
	v_lshlrev_b32_e32 v173, 2, v161
	v_or_b32_e32 v161, v181, v1
	v_lshlrev_b32_e32 v171, 2, v161
	s_mov_b64 s[10:11], 0x1100000
	v_lshl_add_u64 v[158:159], v[158:159], 1, s[8:9]
	v_readlane_b32 s14, v253, 30
	s_waitcnt vmcnt(0)
;     __device__ __forceinline__ void operator()(Acc& acc, int pm, int pn, int wr, int wc, int fr, int fq) const {
;     ...
;                     const float sb = frcp(1.f + fexp(-acc[ai][1][mt][0][j]));
;                     acc[ai][1][mt][0][j] = sb;
;                     totb *= lb + oml * sb;
;                 }
;             totb *= __shfl_xor(totb, 16);
;             totb *= __shfl_xor(totb, 32);
;             float offf = 1.f, offb = 1.f;
; #pragma unroll
;             for (int mt = 0; mt < 4; ++mt) {
;                 float cf[4], cb[4], kf[4], kb[4], fbw[4];
;                 float rf = 1.f, rb = 1.f;
; #pragma unroll
;                 for (int j = 0; j < 4; ++j) {
;                     const float sf = frcp(1.f + fexp(-acc[ai][0][mt][1][j])), sb = acc[ai][1][mt][0][j];
;                     const float ff = lb + oml * sf, fb = lb + oml * sb;
;                     kf[j] = oml * (1.f - sf); kb[j] = oml * (1.f - sb);
;                     rf *= ff; rb *= fb; cf[j] = rf; cb[j] = rb; fbw[j] = fb;
;                 }
;                 const float a0 = __shfl(rf, fr), a1 = __shfl(rf, fr + 16), a2 = __shfl(rf, fr + 32), a3 = __shfl(rf, fr + 48);
;                 const float b0 = __shfl(rb, fr), b1 = __shfl(rb, fr + 16), b2 = __shfl(rb, fr + 32), b3 = __shfl(rb, fr + 48);
;                 const float pf = offf * (fq > 0 ? a0 : 1.f) * (fq > 1 ? a1 : 1.f) * (fq > 2 ? a2 : 1.f);
;                 const float pb = offb * (fq > 0 ? b0 : 1.f) * (fq > 1 ? b1 : 1.f) * (fq > 2 ? b2 : 1.f);
;                 offf *= (a0 * a1) * (a2 * a3);
;                 offb *= (b0 * b1) * (b2 * b3);
; #pragma unroll
;                 for (int j = 0; j < 4; ++j) {
;                     const int row = row0 + mt * 16 + fq * 4 + j;
;                     const float Pf = pf * cf[j];
;                     const float Pb = totb * fbw[j] * frcp(pb * cb[j]);
;                     const float qs = siluf_(acc[ai][0][mt][0][j]);
;                     const size_t o0 = ((size_t)row) * 512 + chl, o1 = ((size_t)T_ALL + row) * 512 + chl;
;                     qt[o0] = (bf16_t)f2bf(qs * Pf);
;                     qt[o1] = (bf16_t)f2bf(qs * Pb);
;                     kt[o0] = (bf16_t)f2bf(kf[j] * frcp(Pf));
;                     kt[o1] = (bf16_t)f2bf(kb[j] * frcp(Pb));
;                     sg[(size_t)row * DM + chg] = (bf16_t)f2bf(siluf_(acc[ai][1][mt][1][j]));
	v_sub_f32_e32 v170, 1.0, v169
	v_fma_f32 v163, v210, v170, v169
	v_fma_f32 v192, v211, v170, v169
	v_fma_f32 v226, v213, v170, v169
	v_mul_f32_e32 v220, v163, v192
	v_fma_f32 v227, v214, v170, v169
	v_mul_f32_e32 v229, v226, v220
	v_fma_f32 v228, v222, v170, v169
	v_mul_f32_e32 v230, v227, v229
	v_fma_f32 v212, v223, v170, v169
	v_mul_f32_e32 v157, v228, v230
	v_fma_f32 v209, v224, v170, v169
	v_mul_f32_e32 v157, v212, v157
	v_fma_f32 v208, v225, v170, v169
	v_mul_f32_e32 v157, v209, v157
	v_fma_f32 v203, v207, v170, v169
	v_mul_f32_e32 v157, v208, v157
	v_fma_f32 v202, v206, v170, v169
	v_mul_f32_e32 v157, v203, v157
	v_fma_f32 v201, v205, v170, v169
	v_mul_f32_e32 v157, v202, v157
	v_fma_f32 v200, v204, v170, v169
	v_mul_f32_e32 v157, v201, v157
	v_fma_f32 v195, v199, v170, v169
	v_mul_f32_e32 v157, v200, v157
	v_fma_f32 v194, v196, v170, v169
	v_mul_f32_e32 v157, v195, v157
	v_mul_f32_e32 v157, v194, v157
	v_fma_f32 v193, v198, v170, v169
	v_mul_f32_e32 v157, v193, v157
	v_fma_f32 v175, v197, v170, v169
	v_mul_f32_e32 v157, v175, v157
	ds_bpermute_b32 v160, v172, v157
	v_sub_f32_e32 v210, 1.0, v210
	v_mul_f32_e32 v231, v210, v170
	v_fma_f32 v210, v216, v170, v169
	v_sub_f32_e32 v211, 1.0, v211
	s_waitcnt lgkmcnt(0)
	v_mul_f32_e32 v162, v157, v160
	v_mul_f32_e32 v160, 0xbfb8aa3b, v110
	v_exp_f32_e32 v215, v160
	v_mul_f32_e32 v233, v211, v170
	ds_bpermute_b32 v218, v171, v230 offset:64
	ds_bpermute_b32 v219, v171, v230 offset:128
	v_add_f32_e32 v215, 1.0, v215
	v_rcp_f32_e32 v215, v215
	ds_bpermute_b32 v240, v171, v230 offset:192
	s_waitcnt lgkmcnt(2)
	v_cndmask_b32_e64 v243, 1.0, v218, s[46:47]
	ds_bpermute_b32 v174, v173, v162
	v_fma_f32 v217, v215, v170, v169
	v_sub_f32_e32 v215, 1.0, v215
	v_mul_f32_e32 v221, v215, v170
	v_sub_f32_e32 v215, 1.0, v216
	v_mul_f32_e32 v216, 0xbfb8aa3b, v112
	v_exp_f32_e32 v216, v216
	v_mul_f32_e32 v234, v217, v210
	v_mul_f32_e32 v210, 0xbfb8aa3b, v113
	v_exp_f32_e32 v210, v210
	v_add_f32_e32 v211, 1.0, v216
	v_rcp_f32_e32 v211, v211
	v_mul_f32_e32 v232, v215, v170
	v_add_f32_e32 v210, 1.0, v210
	v_rcp_f32_e32 v210, v210
	v_fma_f32 v215, v211, v170, v169
	v_sub_f32_e32 v211, 1.0, v211
	v_mul_f32_e32 v235, v211, v170
	v_sub_f32_e32 v211, 1.0, v213
	v_mul_f32_e32 v213, v211, v170
	v_mul_f32_e32 v236, v215, v234
	v_fma_f32 v211, v210, v170, v169
	v_sub_f32_e32 v210, 1.0, v210
	v_mul_f32_e32 v237, v210, v170
	v_sub_f32_e32 v210, 1.0, v214
	v_mul_f32_e32 v239, v211, v236
	v_mul_f32_e32 v238, v210, v170
	ds_bpermute_b32 v210, v171, v239
	ds_bpermute_b32 v211, v171, v239 offset:64
	ds_bpermute_b32 v214, v171, v239 offset:128
	ds_bpermute_b32 v215, v171, v239 offset:192
	ds_bpermute_b32 v216, v171, v230
	s_waitcnt lgkmcnt(4)
	v_cndmask_b32_e64 v241, v210, 1.0, s[44:45]
	s_waitcnt lgkmcnt(3)
	v_cndmask_b32_e64 v242, 1.0, v211, s[46:47]
	v_mul_f32_e32 v241, v241, v242
	s_waitcnt lgkmcnt(2)
	v_cndmask_b32_e64 v242, 1.0, v214, s[48:49]
	v_mul_f32_e32 v210, v210, v211
	s_waitcnt lgkmcnt(1)
	v_mul_f32_e32 v211, v214, v215
	v_mul_f32_e32 v215, 0xbfb8aa3b, v126
	v_mul_f32_e32 v241, v241, v242
	s_waitcnt lgkmcnt(0)
	v_cndmask_b32_e64 v242, v216, 1.0, s[44:45]
	v_exp_f32_e32 v215, v215
	v_mul_f32_e32 v242, v242, v243
	v_cndmask_b32_e64 v243, 1.0, v219, s[48:49]
	v_mul_f32_e32 v242, v242, v243
	v_mul_f32_e32 v210, v210, v211
	v_mul_f32_e32 v211, v216, v218
	v_mul_f32_e32 v214, v219, v240
	v_mul_f32_e32 v211, v211, v214
	v_mul_f32_e32 v214, v163, v242
	v_rcp_f32_e32 v214, v214
	v_add_f32_e32 v215, 1.0, v215
	v_rcp_f32_e32 v215, v215
	v_mul_f32_e32 v174, v162, v174
	v_or_b32_e32 v162, s4, v165
	v_mul_f32_e32 v163, v163, v174
	v_mul_f32_e32 v243, v214, v163
	v_ashrrev_i32_e32 v163, 31, v162
	v_ashrrev_i32_e32 v157, 31, v156
	v_mul_f32_e32 v244, v126, v215
	v_lshlrev_b64 v[214:215], 9, v[162:163]
	v_mul_f32_e32 v240, v217, v241
	v_lshl_add_u64 v[216:217], v[214:215], 0, v[156:157]
	v_lshl_add_u64 v[160:161], v[156:157], 0, s[10:11]
	v_mul_f32_e32 v218, v244, v240
	v_lshlrev_b64 v[216:217], 1, v[216:217]
	v_rcp_f32_e32 v240, v240
	v_lshl_add_u64 v[214:215], v[214:215], 0, v[160:161]
	v_cvt_pk_bf16_f32 v245, v218, s0
	v_lshl_add_u64 v[218:219], s[26:27], 0, v[216:217]
	global_store_short v[218:219], v245, off
	v_mul_f32_e32 v218, v244, v243
	v_lshlrev_b64 v[214:215], 1, v[214:215]
	v_cvt_pk_bf16_f32 v244, v218, s0
	v_lshl_add_u64 v[218:219], s[26:27], 0, v[214:215]
	global_store_short v[218:219], v244, off
	v_mul_f32_e32 v218, v221, v240
	v_mul_f32_e32 v221, 0xbfb8aa3b, v50
	v_exp_f32_e32 v221, v221
	v_cvt_pk_bf16_f32 v218, v218, s0
	v_rcp_f32_e32 v219, v243
	v_lshl_add_u64 v[216:217], s[86:87], 0, v[216:217]
	global_store_short v[216:217], v218, off
	v_add_f32_e32 v217, 1.0, v221
	v_rcp_f32_e32 v217, v217
	v_mul_f32_e32 v216, v231, v219
	v_cvt_pk_bf16_f32 v216, v216, s0
	v_lshl_add_u64 v[214:215], s[86:87], 0, v[214:215]
	global_store_short v[214:215], v216, off
	v_mul_f32_e32 v214, v50, v217
	v_cvt_pk_bf16_f32 v216, v214, s0
	v_lshlrev_b64 v[214:215], 11, v[162:163]
	v_mul_f32_e32 v163, 0xbfb8aa3b, v127
	v_exp_f32_e32 v163, v163
	v_lshl_add_u64 v[214:215], v[158:159], 0, v[214:215]
	global_store_short v[214:215], v216, off
	v_mul_f32_e32 v215, v220, v242
	v_rcp_f32_e32 v215, v215
	v_add_f32_e32 v163, 1.0, v163
	v_rcp_f32_e32 v163, v163
	v_or_b32_e32 v214, 1, v162
	v_mul_f32_e32 v192, v192, v174
	v_mul_f32_e32 v192, v215, v192
	v_ashrrev_i32_e32 v215, 31, v214
	v_lshlrev_b64 v[216:217], 9, v[214:215]
	v_mul_f32_e32 v231, v234, v241
	v_mul_f32_e32 v163, v127, v163
	v_lshl_add_u64 v[218:219], v[216:217], 0, v[156:157]
	v_lshl_add_u64 v[216:217], v[216:217], 0, v[160:161]
	v_mul_f32_e32 v220, v163, v231
	v_lshlrev_b64 v[218:219], 1, v[218:219]
; __device__ __forceinline__ unsigned f2bf(float f) { const __bf16 b = (__bf16)f; return (unsigned)__builtin_bit_cast(unsigned short, b); }
; __device__ __forceinline__ float frcp(float x) { return __builtin_amdgcn_rcpf(x); }
; __device__ __forceinline__ float siluf_(float x) { return x * frcp(1.0f + fexp(-x)); }
;     __device__ __forceinline__ void operator()(Acc& acc, int pm, int pn, int wr, int wc, int fr, int fq) const {
;     ...
;                 for (int j = 0; j < 4; ++j) {
;                     const int row = row0 + mt * 16 + fq * 4 + j;
;                     const float Pf = pf * cf[j];
;                     const float Pb = totb * fbw[j] * frcp(pb * cb[j]);
;                     const float qs = siluf_(acc[ai][0][mt][0][j]);
;                     const size_t o0 = ((size_t)row) * 512 + chl, o1 = ((size_t)T_ALL + row) * 512 + chl;
;                     qt[o0] = (bf16_t)f2bf(qs * Pf);
;                     qt[o1] = (bf16_t)f2bf(qs * Pb);
;                     kt[o0] = (bf16_t)f2bf(kf[j] * frcp(Pf));
;                     kt[o1] = (bf16_t)f2bf(kb[j] * frcp(Pb));
;                     sg[(size_t)row * DM + chg] = (bf16_t)f2bf(siluf_(acc[ai][1][mt][1][j]));
	v_cvt_pk_bf16_f32 v234, v220, s0
	v_lshl_add_u64 v[220:221], s[26:27], 0, v[218:219]
	v_mul_f32_e32 v163, v163, v192
	v_lshlrev_b64 v[216:217], 1, v[216:217]
	global_store_short v[220:221], v234, off
	v_cvt_pk_bf16_f32 v163, v163, s0
	v_rcp_f32_e32 v231, v231
	v_lshl_add_u64 v[220:221], s[26:27], 0, v[216:217]
	global_store_short v[220:221], v163, off
	v_mul_f32_e32 v220, 0xbfb8aa3b, v51
	v_rcp_f32_e32 v192, v192
	v_exp_f32_e32 v220, v220
	v_mul_f32_e32 v163, v232, v231
	v_cvt_pk_bf16_f32 v163, v163, s0
	v_lshl_add_u64 v[218:219], s[86:87], 0, v[218:219]
	global_store_short v[218:219], v163, off
	v_mul_f32_e32 v163, v233, v192
	v_add_f32_e32 v192, 1.0, v220
	v_rcp_f32_e32 v192, v192
	v_cvt_pk_bf16_f32 v163, v163, s0
	v_lshl_add_u64 v[216:217], s[86:87], 0, v[216:217]
	global_store_short v[216:217], v163, off
	v_mul_f32_e32 v163, v51, v192
	v_lshlrev_b64 v[214:215], 11, v[214:215]
	v_cvt_pk_bf16_f32 v163, v163, s0
	v_lshl_add_u64 v[214:215], v[158:159], 0, v[214:215]
	global_store_short v[214:215], v163, off
	v_mul_f32_e32 v163, 0xbfb8aa3b, v128
	v_exp_f32_e32 v163, v163
	v_mul_f32_e32 v192, v229, v242
	v_rcp_f32_e32 v192, v192
	v_or_b32_e32 v214, 2, v162
	v_add_f32_e32 v163, 1.0, v163
	v_rcp_f32_e32 v163, v163
	v_mul_f32_e32 v215, v226, v174
	v_mul_f32_e32 v192, v192, v215
	v_ashrrev_i32_e32 v215, 31, v214
	v_lshlrev_b64 v[216:217], 9, v[214:215]
	v_mul_f32_e32 v229, v236, v241
	v_mul_f32_e32 v163, v128, v163
	v_lshl_add_u64 v[218:219], v[216:217], 0, v[156:157]
	v_lshl_add_u64 v[216:217], v[216:217], 0, v[160:161]
	v_mul_f32_e32 v220, v163, v229
	v_lshlrev_b64 v[218:219], 1, v[218:219]
	v_cvt_pk_bf16_f32 v226, v220, s0
	v_lshl_add_u64 v[220:221], s[26:27], 0, v[218:219]
	v_mul_f32_e32 v163, v163, v192
	v_lshlrev_b64 v[216:217], 1, v[216:217]
	global_store_short v[220:221], v226, off
	v_cvt_pk_bf16_f32 v163, v163, s0
	v_rcp_f32_e32 v226, v229
	v_lshl_add_u64 v[220:221], s[26:27], 0, v[216:217]
	global_store_short v[220:221], v163, off
	v_mul_f32_e32 v220, 0xbfb8aa3b, v52
	v_rcp_f32_e32 v192, v192
	v_exp_f32_e32 v220, v220
	v_mul_f32_e32 v163, v235, v226
	v_cvt_pk_bf16_f32 v163, v163, s0
	v_lshl_add_u64 v[218:219], s[86:87], 0, v[218:219]
	global_store_short v[218:219], v163, off
	v_mul_f32_e32 v163, v213, v192
	v_add_f32_e32 v192, 1.0, v220
	v_rcp_f32_e32 v192, v192
	v_cvt_pk_bf16_f32 v163, v163, s0
	v_lshl_add_u64 v[216:217], s[86:87], 0, v[216:217]
	global_store_short v[216:217], v163, off
	v_mul_f32_e32 v163, v52, v192
	v_lshlrev_b64 v[214:215], 11, v[214:215]
	v_cvt_pk_bf16_f32 v163, v163, s0
	v_lshl_add_u64 v[214:215], v[158:159], 0, v[214:215]
	global_store_short v[214:215], v163, off
	v_mul_f32_e32 v163, 0xbfb8aa3b, v129
	v_exp_f32_e32 v163, v163
	v_mul_f32_e32 v192, v230, v242
	v_rcp_f32_e32 v192, v192
	v_or_b32_e32 v214, 3, v162
	v_add_f32_e32 v163, 1.0, v163
	v_rcp_f32_e32 v163, v163
	v_mul_f32_e32 v215, v227, v174
	v_mul_f32_e32 v192, v192, v215
	v_ashrrev_i32_e32 v215, 31, v214
	v_mul_f32_e32 v213, v239, v241
	v_mul_f32_e32 v163, v129, v163
	v_lshlrev_b64 v[216:217], 9, v[214:215]
	v_lshl_add_u64 v[218:219], v[216:217], 0, v[156:157]
	v_mul_f32_e32 v220, v163, v213
	v_rcp_f32_e32 v213, v213
	v_lshl_add_u64 v[216:217], v[216:217], 0, v[160:161]
	v_lshlrev_b64 v[218:219], 1, v[218:219]
	v_cvt_pk_bf16_f32 v226, v220, s0
	v_lshl_add_u64 v[220:221], s[26:27], 0, v[218:219]
	v_mul_f32_e32 v163, v163, v192
	v_lshlrev_b64 v[216:217], 1, v[216:217]
	global_store_short v[220:221], v226, off
	v_cvt_pk_bf16_f32 v163, v163, s0
	v_lshl_add_u64 v[220:221], s[26:27], 0, v[216:217]
	global_store_short v[220:221], v163, off
	v_mul_f32_e32 v163, v237, v213
	v_mul_f32_e32 v213, 0xbfb8aa3b, v53
	v_rcp_f32_e32 v192, v192
	v_exp_f32_e32 v213, v213
	v_cvt_pk_bf16_f32 v163, v163, s0
	v_lshl_add_u64 v[218:219], s[86:87], 0, v[218:219]
	global_store_short v[218:219], v163, off
	v_mul_f32_e32 v163, v238, v192
	v_add_f32_e32 v192, 1.0, v213
	v_rcp_f32_e32 v192, v192
	v_cvt_pk_bf16_f32 v163, v163, s0
	v_lshl_add_u64 v[216:217], s[86:87], 0, v[216:217]
	global_store_short v[216:217], v163, off
	v_mul_f32_e32 v163, v53, v192
	v_lshlrev_b64 v[214:215], 11, v[214:215]
	v_mul_f32_e32 v213, 0xbfb8aa3b, v107
	v_mul_f32_e32 v192, 0xbfb8aa3b, v106
	v_cvt_pk_bf16_f32 v163, v163, s0
	v_lshl_add_u64 v[214:215], v[158:159], 0, v[214:215]
	v_exp_f32_e32 v213, v213
	v_exp_f32_e32 v192, v192
	global_store_short v[214:215], v163, off
	v_mul_f32_e32 v215, 0xbfb8aa3b, v108
	v_exp_f32_e32 v215, v215
	v_mul_f32_e32 v216, 0xbfb8aa3b, v109
	v_exp_f32_e32 v216, v216
	v_add_f32_e32 v213, 1.0, v213
	v_add_f32_e32 v192, 1.0, v192
	v_rcp_f32_e32 v213, v213
	v_rcp_f32_e32 v192, v192
	v_add_f32_e32 v215, 1.0, v215
	v_rcp_f32_e32 v215, v215
	v_add_f32_e32 v216, 1.0, v216
	v_sub_f32_e32 v214, 1.0, v222
	v_rcp_f32_e32 v216, v216
	v_mul_f32_e32 v222, v214, v170
	v_fma_f32 v214, v213, v170, v169
	v_sub_f32_e32 v213, 1.0, v213
	v_fma_f32 v163, v192, v170, v169
	v_mul_f32_e32 v226, v213, v170
	v_sub_f32_e32 v213, 1.0, v223
	v_mul_f32_e32 v223, v213, v170
	v_mul_f32_e32 v213, v163, v214
	v_fma_f32 v214, v215, v170, v169
	v_sub_f32_e32 v215, 1.0, v215
	v_mul_f32_e32 v229, v215, v170
	v_sub_f32_e32 v215, 1.0, v224
	v_mul_f32_e32 v230, v214, v213
	v_fma_f32 v214, v216, v170, v169
	v_mul_f32_e32 v224, v215, v170
	v_sub_f32_e32 v215, 1.0, v216
	v_mul_f32_e32 v233, v214, v230
	v_mul_f32_e32 v227, v228, v212
	v_mul_f32_e32 v232, v215, v170
	v_sub_f32_e32 v215, 1.0, v225
	ds_bpermute_b32 v214, v171, v233
	v_mul_f32_e32 v231, v209, v227
	v_mul_f32_e32 v225, v215, v170
	ds_bpermute_b32 v215, v171, v233 offset:64
	v_mul_f32_e32 v234, v208, v231
	ds_bpermute_b32 v216, v171, v233 offset:128
	ds_bpermute_b32 v218, v171, v234
	ds_bpermute_b32 v219, v171, v234 offset:64
	ds_bpermute_b32 v217, v171, v233 offset:192
	ds_bpermute_b32 v220, v171, v234 offset:128
	s_waitcnt lgkmcnt(6)
; __device__ __forceinline__ unsigned f2bf(float f) { const __bf16 b = (__bf16)f; return (unsigned)__builtin_bit_cast(unsigned short, b); }
; __device__ __forceinline__ float frcp(float x) { return __builtin_amdgcn_rcpf(x); }
; __device__ __forceinline__ float siluf_(float x) { return x * frcp(1.0f + fexp(-x)); }
;     __device__ __forceinline__ void operator()(Acc& acc, int pm, int pn, int wr, int wc, int fr, int fq) const {
;     ...
;                 const float a0 = __shfl(rf, fr), a1 = __shfl(rf, fr + 16), a2 = __shfl(rf, fr + 32), a3 = __shfl(rf, fr + 48);
;                 const float b0 = __shfl(rb, fr), b1 = __shfl(rb, fr + 16), b2 = __shfl(rb, fr + 32), b3 = __shfl(rb, fr + 48);
;                 const float pf = offf * (fq > 0 ? a0 : 1.f) * (fq > 1 ? a1 : 1.f) * (fq > 2 ? a2 : 1.f);
;                 const float pb = offb * (fq > 0 ? b0 : 1.f) * (fq > 1 ? b1 : 1.f) * (fq > 2 ? b2 : 1.f);
;                 offf *= (a0 * a1) * (a2 * a3);
;                 offb *= (b0 * b1) * (b2 * b3);
; #pragma unroll
;                 for (int j = 0; j < 4; ++j) {
;                     const int row = row0 + mt * 16 + fq * 4 + j;
;                     const float Pf = pf * cf[j];
;                     const float Pb = totb * fbw[j] * frcp(pb * cb[j]);
;                     const float qs = siluf_(acc[ai][0][mt][0][j]);
;                     const size_t o0 = ((size_t)row) * 512 + chl, o1 = ((size_t)T_ALL + row) * 512 + chl;
;                     qt[o0] = (bf16_t)f2bf(qs * Pf);
;                     qt[o1] = (bf16_t)f2bf(qs * Pb);
;                     kt[o0] = (bf16_t)f2bf(kf[j] * frcp(Pf));
;                     kt[o1] = (bf16_t)f2bf(kb[j] * frcp(Pb));
;                     sg[(size_t)row * DM + chg] = (bf16_t)f2bf(siluf_(acc[ai][1][mt][1][j]));
	v_cndmask_b32_e64 v235, v214, 1.0, s[44:45]
	ds_bpermute_b32 v221, v171, v234 offset:192
	v_mul_f32_e32 v235, v210, v235
	s_waitcnt lgkmcnt(6)
	v_cndmask_b32_e64 v236, 1.0, v215, s[46:47]
	v_mul_f32_e32 v235, v235, v236
	s_waitcnt lgkmcnt(5)
	v_cndmask_b32_e64 v236, 1.0, v216, s[48:49]
	v_mul_f32_e32 v235, v235, v236
	s_waitcnt lgkmcnt(4)
	v_cndmask_b32_e64 v236, v218, 1.0, s[44:45]
	v_mul_f32_e32 v236, v211, v236
	s_waitcnt lgkmcnt(3)
	v_cndmask_b32_e64 v237, 1.0, v219, s[46:47]
	v_mul_f32_e32 v236, v236, v237
	s_waitcnt lgkmcnt(1)
	v_cndmask_b32_e64 v237, 1.0, v220, s[48:49]
	v_mul_f32_e32 v214, v214, v215
	v_mul_f32_e32 v215, v216, v217
	v_mul_f32_e32 v236, v236, v237
	v_mul_f32_e32 v237, v214, v215
	v_mul_f32_e32 v214, v218, v219
	s_waitcnt lgkmcnt(0)
	v_mul_f32_e32 v215, v220, v221
	v_mul_f32_e32 v238, v214, v215
	v_mul_f32_e32 v214, 0xbfb8aa3b, v122
	v_exp_f32_e32 v215, v214
	v_mul_f32_e32 v216, v228, v236
	v_rcp_f32_e32 v216, v216
	v_or_b32_e32 v214, 16, v162
	v_add_f32_e32 v215, 1.0, v215
	v_rcp_f32_e32 v215, v215
	v_mul_f32_e32 v217, v228, v174
	v_mul_f32_e32 v228, v217, v216
	v_mul_f32_e32 v163, v163, v235
	v_mul_f32_e32 v239, v122, v215
	v_ashrrev_i32_e32 v215, 31, v214
	v_lshlrev_b64 v[216:217], 9, v[214:215]
	v_lshl_add_u64 v[218:219], v[216:217], 0, v[156:157]
	v_mul_f32_e32 v220, v239, v163
	v_lshlrev_b64 v[218:219], 1, v[218:219]
	v_lshl_add_u64 v[216:217], v[216:217], 0, v[160:161]
	v_cvt_pk_bf16_f32 v240, v220, s0
	v_lshl_add_u64 v[220:221], s[26:27], 0, v[218:219]
	v_rcp_f32_e32 v163, v163
	global_store_short v[220:221], v240, off
	v_mul_f32_e32 v220, v239, v228
	v_lshlrev_b64 v[216:217], 1, v[216:217]
	v_sub_f32_e32 v192, 1.0, v192
	v_cvt_pk_bf16_f32 v239, v220, s0
	v_lshl_add_u64 v[220:221], s[26:27], 0, v[216:217]
	v_mul_f32_e32 v192, v192, v170
	global_store_short v[220:221], v239, off
	v_mul_f32_e32 v220, 0xbfb8aa3b, v42
	v_mul_f32_e32 v163, v192, v163
	v_rcp_f32_e32 v192, v228
	v_exp_f32_e32 v220, v220
	v_cvt_pk_bf16_f32 v163, v163, s0
	v_lshl_add_u64 v[218:219], s[86:87], 0, v[218:219]
	global_store_short v[218:219], v163, off
	v_mul_f32_e32 v163, v222, v192
	v_add_f32_e32 v192, 1.0, v220
	v_rcp_f32_e32 v192, v192
	v_cvt_pk_bf16_f32 v163, v163, s0
	v_lshl_add_u64 v[216:217], s[86:87], 0, v[216:217]
	global_store_short v[216:217], v163, off
	v_mul_f32_e32 v163, v42, v192
	v_lshlrev_b64 v[214:215], 11, v[214:215]
	v_cvt_pk_bf16_f32 v163, v163, s0
	v_lshl_add_u64 v[214:215], v[158:159], 0, v[214:215]
	global_store_short v[214:215], v163, off
	v_mul_f32_e32 v163, 0xbfb8aa3b, v123
	v_exp_f32_e32 v163, v163
	v_mul_f32_e32 v192, v227, v236
	v_rcp_f32_e32 v192, v192
	v_or_b32_e32 v214, 17, v162
	v_add_f32_e32 v163, 1.0, v163
	v_rcp_f32_e32 v163, v163
	v_mul_f32_e32 v212, v212, v174
	v_ashrrev_i32_e32 v215, 31, v214
	v_mul_f32_e32 v220, v213, v235
	v_mul_f32_e32 v192, v212, v192
	v_lshlrev_b64 v[212:213], 9, v[214:215]
	v_mul_f32_e32 v163, v123, v163
	v_lshl_add_u64 v[216:217], v[212:213], 0, v[156:157]
	v_lshl_add_u64 v[212:213], v[212:213], 0, v[160:161]
	v_mul_f32_e32 v218, v163, v220
	v_lshlrev_b64 v[216:217], 1, v[216:217]
	v_cvt_pk_bf16_f32 v221, v218, s0
	v_lshl_add_u64 v[218:219], s[26:27], 0, v[216:217]
	v_mul_f32_e32 v163, v163, v192
	v_lshlrev_b64 v[212:213], 1, v[212:213]
	global_store_short v[218:219], v221, off
	v_cvt_pk_bf16_f32 v163, v163, s0
	v_rcp_f32_e32 v220, v220
	v_lshl_add_u64 v[218:219], s[26:27], 0, v[212:213]
	global_store_short v[218:219], v163, off
	v_mul_f32_e32 v218, 0xbfb8aa3b, v43
	v_rcp_f32_e32 v192, v192
	v_exp_f32_e32 v218, v218
	v_mul_f32_e32 v163, v226, v220
	v_cvt_pk_bf16_f32 v163, v163, s0
	v_lshl_add_u64 v[216:217], s[86:87], 0, v[216:217]
	global_store_short v[216:217], v163, off
	v_mul_f32_e32 v163, v223, v192
	v_add_f32_e32 v192, 1.0, v218
	v_rcp_f32_e32 v192, v192
	v_cvt_pk_bf16_f32 v163, v163, s0
	v_lshl_add_u64 v[212:213], s[86:87], 0, v[212:213]
	global_store_short v[212:213], v163, off
	v_mul_f32_e32 v163, v43, v192
	v_lshlrev_b64 v[212:213], 11, v[214:215]
	v_cvt_pk_bf16_f32 v163, v163, s0
	v_lshl_add_u64 v[212:213], v[158:159], 0, v[212:213]
	global_store_short v[212:213], v163, off
	v_mul_f32_e32 v163, 0xbfb8aa3b, v124
	v_exp_f32_e32 v163, v163
	v_mul_f32_e32 v192, v231, v236
	v_or_b32_e32 v212, 18, v162
	v_rcp_f32_e32 v192, v192
	v_add_f32_e32 v163, 1.0, v163
	v_rcp_f32_e32 v163, v163
	v_ashrrev_i32_e32 v213, 31, v212
	v_lshlrev_b64 v[214:215], 9, v[212:213]
	v_mul_f32_e32 v220, v230, v235
	v_mul_f32_e32 v209, v209, v174
	v_mul_f32_e32 v163, v124, v163
	v_lshl_add_u64 v[216:217], v[214:215], 0, v[156:157]
	v_mul_f32_e32 v192, v209, v192
	v_mul_f32_e32 v209, v163, v220
	v_lshlrev_b64 v[216:217], 1, v[216:217]
	v_cvt_pk_bf16_f32 v209, v209, s0
	v_lshl_add_u64 v[218:219], s[26:27], 0, v[216:217]
	global_store_short v[218:219], v209, off
	v_rcp_f32_e32 v209, v220
	v_lshl_add_u64 v[214:215], v[214:215], 0, v[160:161]
	v_mul_f32_e32 v163, v163, v192
	v_lshlrev_b64 v[214:215], 1, v[214:215]
	v_cvt_pk_bf16_f32 v163, v163, s0
	v_lshl_add_u64 v[218:219], s[26:27], 0, v[214:215]
	global_store_short v[218:219], v163, off
	v_mul_f32_e32 v163, v229, v209
	v_mul_f32_e32 v209, 0xbfb8aa3b, v44
	v_rcp_f32_e32 v192, v192
	v_exp_f32_e32 v209, v209
	v_cvt_pk_bf16_f32 v163, v163, s0
	v_lshl_add_u64 v[216:217], s[86:87], 0, v[216:217]
	global_store_short v[216:217], v163, off
	v_mul_f32_e32 v163, v224, v192
	v_add_f32_e32 v192, 1.0, v209
	v_rcp_f32_e32 v192, v192
	v_cvt_pk_bf16_f32 v163, v163, s0
	v_lshl_add_u64 v[214:215], s[86:87], 0, v[214:215]
	global_store_short v[214:215], v163, off
	v_mul_f32_e32 v163, v44, v192
	v_lshlrev_b64 v[212:213], 11, v[212:213]
	v_cvt_pk_bf16_f32 v163, v163, s0
; __device__ __forceinline__ unsigned f2bf(float f) { const __bf16 b = (__bf16)f; return (unsigned)__builtin_bit_cast(unsigned short, b); }
; __device__ __forceinline__ float frcp(float x) { return __builtin_amdgcn_rcpf(x); }
; __device__ __forceinline__ float fexp(float x) { return __builtin_amdgcn_exp2f(x * 1.4426950408889634f); }
; __device__ __forceinline__ float siluf_(float x) { return x * frcp(1.0f + fexp(-x)); }
;     __device__ __forceinline__ void operator()(Acc& acc, int pm, int pn, int wr, int wc, int fr, int fq) const {
;     ...
;                     const float sf = frcp(1.f + fexp(-acc[ai][0][mt][1][j])), sb = acc[ai][1][mt][0][j];
;                     const float ff = lb + oml * sf, fb = lb + oml * sb;
;                     kf[j] = oml * (1.f - sf); kb[j] = oml * (1.f - sb);
;                     rf *= ff; rb *= fb; cf[j] = rf; cb[j] = rb; fbw[j] = fb;
;                 }
;                 const float a0 = __shfl(rf, fr), a1 = __shfl(rf, fr + 16), a2 = __shfl(rf, fr + 32), a3 = __shfl(rf, fr + 48);
;                 const float b0 = __shfl(rb, fr), b1 = __shfl(rb, fr + 16), b2 = __shfl(rb, fr + 32), b3 = __shfl(rb, fr + 48);
;                 const float pf = offf * (fq > 0 ? a0 : 1.f) * (fq > 1 ? a1 : 1.f) * (fq > 2 ? a2 : 1.f);
;                 const float pb = offb * (fq > 0 ? b0 : 1.f) * (fq > 1 ? b1 : 1.f) * (fq > 2 ? b2 : 1.f);
;                 offf *= (a0 * a1) * (a2 * a3);
;                 offb *= (b0 * b1) * (b2 * b3);
; #pragma unroll
;                 for (int j = 0; j < 4; ++j) {
;                     const int row = row0 + mt * 16 + fq * 4 + j;
;                     const float Pf = pf * cf[j];
;                     const float Pb = totb * fbw[j] * frcp(pb * cb[j]);
;                     const float qs = siluf_(acc[ai][0][mt][0][j]);
;                     const size_t o0 = ((size_t)row) * 512 + chl, o1 = ((size_t)T_ALL + row) * 512 + chl;
;                     qt[o0] = (bf16_t)f2bf(qs * Pf);
;                     qt[o1] = (bf16_t)f2bf(qs * Pb);
;                     kt[o0] = (bf16_t)f2bf(kf[j] * frcp(Pf));
;                     kt[o1] = (bf16_t)f2bf(kb[j] * frcp(Pb));
;                     sg[(size_t)row * DM + chg] = (bf16_t)f2bf(siluf_(acc[ai][1][mt][1][j]));
	v_lshl_add_u64 v[212:213], v[158:159], 0, v[212:213]
	global_store_short v[212:213], v163, off
	v_mul_f32_e32 v163, 0xbfb8aa3b, v125
	v_exp_f32_e32 v163, v163
	v_mul_f32_e32 v192, v234, v236
	v_rcp_f32_e32 v192, v192
	v_or_b32_e32 v212, 19, v162
	v_add_f32_e32 v163, 1.0, v163
	v_rcp_f32_e32 v163, v163
	v_mul_f32_e32 v208, v208, v174
	v_ashrrev_i32_e32 v213, 31, v212
	v_mul_f32_e32 v192, v208, v192
	v_lshlrev_b64 v[208:209], 9, v[212:213]
	v_mul_f32_e32 v218, v233, v235
	v_mul_f32_e32 v163, v125, v163
	v_lshl_add_u64 v[214:215], v[208:209], 0, v[156:157]
	v_lshl_add_u64 v[208:209], v[208:209], 0, v[160:161]
	v_mul_f32_e32 v216, v163, v218
	v_lshlrev_b64 v[214:215], 1, v[214:215]
	v_cvt_pk_bf16_f32 v219, v216, s0
	v_lshl_add_u64 v[216:217], s[26:27], 0, v[214:215]
	v_mul_f32_e32 v163, v163, v192
	v_lshlrev_b64 v[208:209], 1, v[208:209]
	global_store_short v[216:217], v219, off
	v_cvt_pk_bf16_f32 v163, v163, s0
	v_rcp_f32_e32 v218, v218
	v_lshl_add_u64 v[216:217], s[26:27], 0, v[208:209]
	global_store_short v[216:217], v163, off
	v_mul_f32_e32 v216, 0xbfb8aa3b, v45
	v_rcp_f32_e32 v192, v192
	v_exp_f32_e32 v216, v216
	v_mul_f32_e32 v163, v232, v218
	v_cvt_pk_bf16_f32 v163, v163, s0
	v_lshl_add_u64 v[214:215], s[86:87], 0, v[214:215]
	global_store_short v[214:215], v163, off
	v_mul_f32_e32 v163, v225, v192
	v_add_f32_e32 v192, 1.0, v216
	v_rcp_f32_e32 v192, v192
	v_cvt_pk_bf16_f32 v163, v163, s0
	v_lshl_add_u64 v[208:209], s[86:87], 0, v[208:209]
	global_store_short v[208:209], v163, off
	v_mul_f32_e32 v163, v45, v192
	v_lshlrev_b64 v[208:209], 11, v[212:213]
	v_cvt_pk_bf16_f32 v163, v163, s0
	v_lshl_add_u64 v[208:209], v[158:159], 0, v[208:209]
	v_mul_f32_e32 v192, 0xbfb8aa3b, v102
	global_store_short v[208:209], v163, off
	v_mul_f32_e32 v208, 0xbfb8aa3b, v103
	v_exp_f32_e32 v192, v192
	v_exp_f32_e32 v208, v208
	v_sub_f32_e32 v207, 1.0, v207
	v_mul_f32_e32 v163, v210, v237
	v_add_f32_e32 v192, 1.0, v192
	v_add_f32_e32 v208, 1.0, v208
	v_rcp_f32_e32 v192, v192
	v_rcp_f32_e32 v208, v208
	v_mul_f32_e32 v213, v207, v170
	v_mul_f32_e32 v210, 0xbfb8aa3b, v104
	v_fma_f32 v209, v192, v170, v169
	v_fma_f32 v207, v208, v170, v169
	v_exp_f32_e32 v210, v210
	v_mul_f32_e32 v216, v209, v207
	v_mul_f32_e32 v207, 0xbfb8aa3b, v105
	v_exp_f32_e32 v207, v207
	v_sub_f32_e32 v208, 1.0, v208
	v_mul_f32_e32 v214, v208, v170
	v_add_f32_e32 v208, 1.0, v210
	v_rcp_f32_e32 v208, v208
	v_add_f32_e32 v207, 1.0, v207
	v_rcp_f32_e32 v207, v207
	v_sub_f32_e32 v206, 1.0, v206
	v_mul_f32_e32 v215, v206, v170
	v_fma_f32 v206, v208, v170, v169
	v_sub_f32_e32 v205, 1.0, v205
	v_mul_f32_e32 v219, v205, v170
	v_mul_f32_e32 v220, v206, v216
	v_fma_f32 v205, v207, v170, v169
	v_sub_f32_e32 v204, 1.0, v204
	v_mul_f32_e32 v224, v205, v220
	v_mul_f32_e32 v217, v203, v202
	v_mul_f32_e32 v223, v204, v170
	ds_bpermute_b32 v204, v171, v224
	v_mul_f32_e32 v221, v201, v217
	v_sub_f32_e32 v206, 1.0, v207
	ds_bpermute_b32 v205, v171, v224 offset:64
	v_sub_f32_e32 v208, 1.0, v208
	v_mul_f32_e32 v222, v206, v170
	v_mul_f32_e32 v225, v200, v221
	ds_bpermute_b32 v206, v171, v224 offset:128
	v_mul_f32_e32 v218, v208, v170
	ds_bpermute_b32 v208, v171, v225
	ds_bpermute_b32 v210, v171, v225 offset:64
	v_mul_f32_e32 v212, v211, v238
	ds_bpermute_b32 v207, v171, v224 offset:192
	ds_bpermute_b32 v211, v171, v225 offset:128
	s_waitcnt lgkmcnt(6)
	v_cndmask_b32_e64 v227, v204, 1.0, s[44:45]
	ds_bpermute_b32 v226, v171, v225 offset:192
	v_mul_f32_e32 v227, v163, v227
	s_waitcnt lgkmcnt(6)
	v_cndmask_b32_e64 v228, 1.0, v205, s[46:47]
	v_mul_f32_e32 v227, v227, v228
	s_waitcnt lgkmcnt(5)
	v_cndmask_b32_e64 v228, 1.0, v206, s[48:49]
	v_mul_f32_e32 v227, v227, v228
	s_waitcnt lgkmcnt(4)
	v_cndmask_b32_e64 v228, v208, 1.0, s[44:45]
	v_mul_f32_e32 v228, v212, v228
	s_waitcnt lgkmcnt(3)
	v_cndmask_b32_e64 v229, 1.0, v210, s[46:47]
	v_mul_f32_e32 v228, v228, v229
	s_waitcnt lgkmcnt(1)
	v_cndmask_b32_e64 v229, 1.0, v211, s[48:49]
	v_mul_f32_e32 v204, v204, v205
	v_mul_f32_e32 v205, v206, v207
	v_mul_f32_e32 v228, v228, v229
	v_mul_f32_e32 v229, v204, v205
	v_mul_f32_e32 v204, v208, v210
	s_waitcnt lgkmcnt(0)
	v_mul_f32_e32 v205, v211, v226
	v_mul_f32_e32 v226, v204, v205
	v_mul_f32_e32 v204, 0xbfb8aa3b, v118
	v_exp_f32_e32 v205, v204
	v_mul_f32_e32 v206, v203, v228
	v_rcp_f32_e32 v206, v206
	v_or_b32_e32 v204, 32, v162
	v_add_f32_e32 v205, 1.0, v205
	v_rcp_f32_e32 v205, v205
	v_mul_f32_e32 v203, v203, v174
	v_mul_f32_e32 v203, v203, v206
	v_mul_f32_e32 v230, v209, v227
	v_mul_f32_e32 v231, v118, v205
	v_ashrrev_i32_e32 v205, 31, v204
	v_lshlrev_b64 v[206:207], 9, v[204:205]
	v_lshl_add_u64 v[208:209], v[206:207], 0, v[156:157]
	v_mul_f32_e32 v210, v231, v230
	v_lshlrev_b64 v[208:209], 1, v[208:209]
	v_lshl_add_u64 v[206:207], v[206:207], 0, v[160:161]
	v_cvt_pk_bf16_f32 v232, v210, s0
	v_lshl_add_u64 v[210:211], s[26:27], 0, v[208:209]
	global_store_short v[210:211], v232, off
	v_mul_f32_e32 v210, v231, v203
	v_lshlrev_b64 v[206:207], 1, v[206:207]
	v_cvt_pk_bf16_f32 v231, v210, s0
	v_rcp_f32_e32 v230, v230
	v_lshl_add_u64 v[210:211], s[26:27], 0, v[206:207]
	global_store_short v[210:211], v231, off
	v_mul_f32_e32 v210, 0xbfb8aa3b, v38
	v_sub_f32_e32 v192, 1.0, v192
	v_rcp_f32_e32 v203, v203
	v_exp_f32_e32 v210, v210
	v_mul_f32_e32 v192, v192, v170
	v_mul_f32_e32 v192, v192, v230
	v_cvt_pk_bf16_f32 v192, v192, s0
	v_lshl_add_u64 v[208:209], s[86:87], 0, v[208:209]
	global_store_short v[208:209], v192, off
	v_mul_f32_e32 v192, v213, v203
	v_add_f32_e32 v203, 1.0, v210
	v_rcp_f32_e32 v203, v203
	v_cvt_pk_bf16_f32 v192, v192, s0
	v_lshl_add_u64 v[206:207], s[86:87], 0, v[206:207]
	global_store_short v[206:207], v192, off
; __device__ __forceinline__ unsigned f2bf(float f) { const __bf16 b = (__bf16)f; return (unsigned)__builtin_bit_cast(unsigned short, b); }
; __device__ __forceinline__ float frcp(float x) { return __builtin_amdgcn_rcpf(x); }
; __device__ __forceinline__ float fexp(float x) { return __builtin_amdgcn_exp2f(x * 1.4426950408889634f); }
; __device__ __forceinline__ float siluf_(float x) { return x * frcp(1.0f + fexp(-x)); }
;     __device__ __forceinline__ void operator()(Acc& acc, int pm, int pn, int wr, int wc, int fr, int fq) const {
;     ...
;                     const float sf = frcp(1.f + fexp(-acc[ai][0][mt][1][j])), sb = acc[ai][1][mt][0][j];
;                     const float ff = lb + oml * sf, fb = lb + oml * sb;
;                     kf[j] = oml * (1.f - sf); kb[j] = oml * (1.f - sb);
;                     rf *= ff; rb *= fb; cf[j] = rf; cb[j] = rb; fbw[j] = fb;
;                 }
;                 const float a0 = __shfl(rf, fr), a1 = __shfl(rf, fr + 16), a2 = __shfl(rf, fr + 32), a3 = __shfl(rf, fr + 48);
;                 const float b0 = __shfl(rb, fr), b1 = __shfl(rb, fr + 16), b2 = __shfl(rb, fr + 32), b3 = __shfl(rb, fr + 48);
;                 const float pf = offf * (fq > 0 ? a0 : 1.f) * (fq > 1 ? a1 : 1.f) * (fq > 2 ? a2 : 1.f);
;                 const float pb = offb * (fq > 0 ? b0 : 1.f) * (fq > 1 ? b1 : 1.f) * (fq > 2 ? b2 : 1.f);
;                 offf *= (a0 * a1) * (a2 * a3);
;                 offb *= (b0 * b1) * (b2 * b3);
; #pragma unroll
;                 for (int j = 0; j < 4; ++j) {
;                     const int row = row0 + mt * 16 + fq * 4 + j;
;                     const float Pf = pf * cf[j];
;                     const float Pb = totb * fbw[j] * frcp(pb * cb[j]);
;                     const float qs = siluf_(acc[ai][0][mt][0][j]);
;                     const size_t o0 = ((size_t)row) * 512 + chl, o1 = ((size_t)T_ALL + row) * 512 + chl;
;                     qt[o0] = (bf16_t)f2bf(qs * Pf);
;                     qt[o1] = (bf16_t)f2bf(qs * Pb);
;                     kt[o0] = (bf16_t)f2bf(kf[j] * frcp(Pf));
;                     kt[o1] = (bf16_t)f2bf(kb[j] * frcp(Pb));
;                     sg[(size_t)row * DM + chg] = (bf16_t)f2bf(siluf_(acc[ai][1][mt][1][j]));
	v_mul_f32_e32 v192, v38, v203
	v_lshlrev_b64 v[204:205], 11, v[204:205]
	v_cvt_pk_bf16_f32 v192, v192, s0
	v_lshl_add_u64 v[204:205], v[158:159], 0, v[204:205]
	global_store_short v[204:205], v192, off
	v_mul_f32_e32 v192, 0xbfb8aa3b, v119
	v_exp_f32_e32 v192, v192
	v_mul_f32_e32 v203, v217, v228
	v_rcp_f32_e32 v203, v203
	v_or_b32_e32 v204, 33, v162
	v_add_f32_e32 v192, 1.0, v192
	v_rcp_f32_e32 v192, v192
	v_mul_f32_e32 v202, v202, v174
	v_ashrrev_i32_e32 v205, 31, v204
	v_mul_f32_e32 v211, v202, v203
	v_lshlrev_b64 v[202:203], 9, v[204:205]
	v_mul_f32_e32 v210, v216, v227
	v_mul_f32_e32 v192, v119, v192
	v_lshl_add_u64 v[206:207], v[202:203], 0, v[156:157]
	v_lshl_add_u64 v[202:203], v[202:203], 0, v[160:161]
	v_mul_f32_e32 v208, v192, v210
	v_lshlrev_b64 v[206:207], 1, v[206:207]
	v_cvt_pk_bf16_f32 v213, v208, s0
	v_lshl_add_u64 v[208:209], s[26:27], 0, v[206:207]
	v_mul_f32_e32 v192, v192, v211
	v_lshlrev_b64 v[202:203], 1, v[202:203]
	global_store_short v[208:209], v213, off
	v_cvt_pk_bf16_f32 v192, v192, s0
	v_rcp_f32_e32 v210, v210
	v_lshl_add_u64 v[208:209], s[26:27], 0, v[202:203]
	global_store_short v[208:209], v192, off
	v_mul_f32_e32 v209, 0xbfb8aa3b, v39
	v_exp_f32_e32 v209, v209
	v_mul_f32_e32 v192, v214, v210
	v_cvt_pk_bf16_f32 v192, v192, s0
	v_rcp_f32_e32 v208, v211
	v_lshl_add_u64 v[206:207], s[86:87], 0, v[206:207]
	global_store_short v[206:207], v192, off
	v_add_f32_e32 v206, 1.0, v209
	v_rcp_f32_e32 v206, v206
	v_mul_f32_e32 v192, v215, v208
	v_cvt_pk_bf16_f32 v192, v192, s0
	v_lshl_add_u64 v[202:203], s[86:87], 0, v[202:203]
	global_store_short v[202:203], v192, off
	v_mul_f32_e32 v192, v39, v206
	v_lshlrev_b64 v[202:203], 11, v[204:205]
	v_cvt_pk_bf16_f32 v192, v192, s0
	v_lshl_add_u64 v[202:203], v[158:159], 0, v[202:203]
	global_store_short v[202:203], v192, off
	v_mul_f32_e32 v192, 0xbfb8aa3b, v120
	v_exp_f32_e32 v192, v192
	v_mul_f32_e32 v203, v221, v228
	v_rcp_f32_e32 v203, v203
	v_or_b32_e32 v202, 34, v162
	v_add_f32_e32 v192, 1.0, v192
	v_rcp_f32_e32 v192, v192
	v_mul_f32_e32 v201, v201, v174
	v_mul_f32_e32 v201, v201, v203
	v_ashrrev_i32_e32 v203, 31, v202
	v_lshlrev_b64 v[204:205], 9, v[202:203]
	v_mul_f32_e32 v210, v220, v227
	v_mul_f32_e32 v192, v120, v192
	v_lshl_add_u64 v[206:207], v[204:205], 0, v[156:157]
	v_lshl_add_u64 v[204:205], v[204:205], 0, v[160:161]
	v_mul_f32_e32 v208, v192, v210
	v_lshlrev_b64 v[206:207], 1, v[206:207]
	v_cvt_pk_bf16_f32 v211, v208, s0
	v_lshl_add_u64 v[208:209], s[26:27], 0, v[206:207]
	v_mul_f32_e32 v192, v192, v201
	v_lshlrev_b64 v[204:205], 1, v[204:205]
	global_store_short v[208:209], v211, off
	v_cvt_pk_bf16_f32 v192, v192, s0
	v_rcp_f32_e32 v210, v210
	v_lshl_add_u64 v[208:209], s[26:27], 0, v[204:205]
	global_store_short v[208:209], v192, off
	v_mul_f32_e32 v208, 0xbfb8aa3b, v40
	v_rcp_f32_e32 v201, v201
	v_exp_f32_e32 v208, v208
	v_mul_f32_e32 v192, v218, v210
	v_cvt_pk_bf16_f32 v192, v192, s0
	v_lshl_add_u64 v[206:207], s[86:87], 0, v[206:207]
	global_store_short v[206:207], v192, off
	v_mul_f32_e32 v192, v219, v201
	v_add_f32_e32 v201, 1.0, v208
	v_rcp_f32_e32 v201, v201
	v_cvt_pk_bf16_f32 v192, v192, s0
	v_lshl_add_u64 v[204:205], s[86:87], 0, v[204:205]
	global_store_short v[204:205], v192, off
	v_mul_f32_e32 v192, v40, v201
	v_lshlrev_b64 v[202:203], 11, v[202:203]
	v_cvt_pk_bf16_f32 v192, v192, s0
	v_lshl_add_u64 v[202:203], v[158:159], 0, v[202:203]
	global_store_short v[202:203], v192, off
	v_mul_f32_e32 v192, 0xbfb8aa3b, v121
	v_exp_f32_e32 v192, v192
	v_mul_f32_e32 v201, v225, v228
	v_rcp_f32_e32 v201, v201
	v_or_b32_e32 v202, 35, v162
	v_add_f32_e32 v192, 1.0, v192
	v_rcp_f32_e32 v192, v192
	v_mul_f32_e32 v200, v200, v174
	v_ashrrev_i32_e32 v203, 31, v202
	v_mul_f32_e32 v209, v200, v201
	v_lshlrev_b64 v[200:201], 9, v[202:203]
	v_mul_f32_e32 v208, v224, v227
	v_mul_f32_e32 v192, v121, v192
	v_lshl_add_u64 v[204:205], v[200:201], 0, v[156:157]
	v_lshl_add_u64 v[200:201], v[200:201], 0, v[160:161]
	v_mul_f32_e32 v206, v192, v208
	v_lshlrev_b64 v[204:205], 1, v[204:205]
	v_cvt_pk_bf16_f32 v210, v206, s0
	v_lshl_add_u64 v[206:207], s[26:27], 0, v[204:205]
	v_mul_f32_e32 v192, v192, v209
	v_lshlrev_b64 v[200:201], 1, v[200:201]
	global_store_short v[206:207], v210, off
	v_cvt_pk_bf16_f32 v192, v192, s0
	v_rcp_f32_e32 v208, v208
	v_lshl_add_u64 v[206:207], s[26:27], 0, v[200:201]
	global_store_short v[206:207], v192, off
	v_mul_f32_e32 v207, 0xbfb8aa3b, v41
	v_exp_f32_e32 v207, v207
	v_mul_f32_e32 v192, v222, v208
	v_cvt_pk_bf16_f32 v192, v192, s0
	v_rcp_f32_e32 v206, v209
	v_lshl_add_u64 v[204:205], s[86:87], 0, v[204:205]
	global_store_short v[204:205], v192, off
	v_add_f32_e32 v204, 1.0, v207
	v_rcp_f32_e32 v204, v204
	v_mul_f32_e32 v192, v223, v206
	v_cvt_pk_bf16_f32 v192, v192, s0
	v_lshl_add_u64 v[200:201], s[86:87], 0, v[200:201]
	global_store_short v[200:201], v192, off
	v_mul_f32_e32 v192, v41, v204
	v_lshlrev_b64 v[200:201], 11, v[202:203]
	v_cvt_pk_bf16_f32 v192, v192, s0
	v_lshl_add_u64 v[200:201], v[158:159], 0, v[200:201]
	global_store_short v[200:201], v192, off
	v_mul_f32_e32 v200, 0xbfb8aa3b, v95
	v_exp_f32_e32 v200, v200
	v_mul_f32_e32 v202, 0xbfb8aa3b, v94
	v_exp_f32_e32 v202, v202
	v_mul_f32_e32 v203, 0xbfb8aa3b, v96
	v_add_f32_e32 v200, 1.0, v200
	v_rcp_f32_e32 v200, v200
	v_exp_f32_e32 v203, v203
	v_add_f32_e32 v192, 1.0, v202
	v_sub_f32_e32 v199, 1.0, v199
	v_rcp_f32_e32 v192, v192
	v_mul_f32_e32 v208, v199, v170
	v_fma_f32 v199, v200, v170, v169
	v_sub_f32_e32 v200, 1.0, v200
	v_mul_f32_e32 v209, v200, v170
	v_add_f32_e32 v200, 1.0, v203
	v_rcp_f32_e32 v200, v200
	v_mul_f32_e32 v201, v212, v226
	v_fma_f32 v202, v192, v170, v169
	v_mul_f32_e32 v212, v195, v194
	v_sub_f32_e32 v196, 1.0, v196
	v_mul_f32_e32 v211, v202, v199
	v_mul_f32_e32 v199, 0xbfb8aa3b, v97
	v_mul_f32_e32 v216, v193, v212
	v_mul_f32_e32 v210, v196, v170
	v_fma_f32 v196, v200, v170, v169
	v_exp_f32_e32 v199, v199
	v_sub_f32_e32 v200, 1.0, v200
	v_mul_f32_e32 v220, v175, v216
	v_mul_f32_e32 v213, v200, v170
	ds_bpermute_b32 v200, v171, v220
	ds_bpermute_b32 v203, v171, v220 offset:64
	ds_bpermute_b32 v204, v171, v220 offset:128
	v_add_f32_e32 v199, 1.0, v199
	v_rcp_f32_e32 v199, v199
	s_waitcnt lgkmcnt(2)
; __device__ __forceinline__ unsigned f2bf(float f) { const __bf16 b = (__bf16)f; return (unsigned)__builtin_bit_cast(unsigned short, b); }
; __device__ __forceinline__ float frcp(float x) { return __builtin_amdgcn_rcpf(x); }
; __device__ __forceinline__ float siluf_(float x) { return x * frcp(1.0f + fexp(-x)); }
;     __device__ __forceinline__ void operator()(Acc& acc, int pm, int pn, int wr, int wc, int fr, int fq) const {
;     ...
;                 const float a0 = __shfl(rf, fr), a1 = __shfl(rf, fr + 16), a2 = __shfl(rf, fr + 32), a3 = __shfl(rf, fr + 48);
;                 const float b0 = __shfl(rb, fr), b1 = __shfl(rb, fr + 16), b2 = __shfl(rb, fr + 32), b3 = __shfl(rb, fr + 48);
;                 const float pf = offf * (fq > 0 ? a0 : 1.f) * (fq > 1 ? a1 : 1.f) * (fq > 2 ? a2 : 1.f);
;                 const float pb = offb * (fq > 0 ? b0 : 1.f) * (fq > 1 ? b1 : 1.f) * (fq > 2 ? b2 : 1.f);
;                 offf *= (a0 * a1) * (a2 * a3);
;                 offb *= (b0 * b1) * (b2 * b3);
; #pragma unroll
;                 for (int j = 0; j < 4; ++j) {
;                     const int row = row0 + mt * 16 + fq * 4 + j;
;                     const float Pf = pf * cf[j];
;                     const float Pb = totb * fbw[j] * frcp(pb * cb[j]);
;                     const float qs = siluf_(acc[ai][0][mt][0][j]);
;                     const size_t o0 = ((size_t)row) * 512 + chl, o1 = ((size_t)T_ALL + row) * 512 + chl;
;                     qt[o0] = (bf16_t)f2bf(qs * Pf);
;                     qt[o1] = (bf16_t)f2bf(qs * Pb);
;                     kt[o0] = (bf16_t)f2bf(kf[j] * frcp(Pf));
;                     kt[o1] = (bf16_t)f2bf(kb[j] * frcp(Pb));
;                     sg[(size_t)row * DM + chg] = (bf16_t)f2bf(siluf_(acc[ai][1][mt][1][j]));
	v_cndmask_b32_e64 v200, v200, 1.0, s[44:45]
	v_mul_f32_e32 v200, v201, v200
	s_waitcnt lgkmcnt(1)
	v_cndmask_b32_e64 v201, 1.0, v203, s[46:47]
	v_mul_f32_e32 v200, v200, v201
	s_waitcnt lgkmcnt(0)
	v_cndmask_b32_e64 v201, 1.0, v204, s[48:49]
	v_mul_f32_e32 v215, v196, v211
	v_fma_f32 v196, v199, v170, v169
	v_mul_f32_e32 v222, v200, v201
	v_mul_f32_e32 v200, 0xbfb8aa3b, v114
	v_mul_f32_e32 v219, v196, v215
	v_exp_f32_e32 v201, v200
	v_sub_f32_e32 v198, 1.0, v198
	v_sub_f32_e32 v197, 1.0, v197
	ds_bpermute_b32 v196, v171, v219
	v_mul_f32_e32 v214, v198, v170
	v_sub_f32_e32 v198, 1.0, v199
	v_mul_f32_e32 v218, v197, v170
	ds_bpermute_b32 v197, v171, v219 offset:64
	v_mul_f32_e32 v217, v198, v170
	ds_bpermute_b32 v198, v171, v219 offset:128
	v_add_f32_e32 v201, 1.0, v201
	v_mul_f32_e32 v203, v195, v222
	v_rcp_f32_e32 v201, v201
	v_mul_f32_e32 v163, v163, v229
	s_waitcnt lgkmcnt(2)
	v_cndmask_b32_e64 v205, v196, 1.0, s[44:45]
	v_rcp_f32_e32 v203, v203
	v_mul_f32_e32 v205, v163, v205
	s_waitcnt lgkmcnt(1)
	v_cndmask_b32_e64 v206, 1.0, v197, s[46:47]
	v_mul_f32_e32 v205, v205, v206
	s_waitcnt lgkmcnt(0)
	v_cndmask_b32_e64 v206, 1.0, v198, s[48:49]
	v_or_b32_e32 v200, 48, v162
	v_mul_f32_e32 v221, v205, v206
	v_mul_f32_e32 v195, v195, v174
	v_mul_f32_e32 v224, v114, v201
	v_ashrrev_i32_e32 v201, 31, v200
	v_mul_f32_e32 v223, v202, v221
	v_mul_f32_e32 v195, v195, v203
	v_lshlrev_b64 v[202:203], 9, v[200:201]
	v_lshl_add_u64 v[204:205], v[202:203], 0, v[156:157]
	v_mul_f32_e32 v206, v224, v223
	v_lshlrev_b64 v[204:205], 1, v[204:205]
	v_lshl_add_u64 v[202:203], v[202:203], 0, v[160:161]
	v_cvt_pk_bf16_f32 v225, v206, s0
	v_lshl_add_u64 v[206:207], s[26:27], 0, v[204:205]
	global_store_short v[206:207], v225, off
	v_mul_f32_e32 v206, v224, v195
	v_lshlrev_b64 v[202:203], 1, v[202:203]
	v_cvt_pk_bf16_f32 v224, v206, s0
	v_rcp_f32_e32 v223, v223
	v_lshl_add_u64 v[206:207], s[26:27], 0, v[202:203]
	global_store_short v[206:207], v224, off
	v_mul_f32_e32 v206, 0xbfb8aa3b, v30
	v_sub_f32_e32 v192, 1.0, v192
	v_rcp_f32_e32 v195, v195
	v_exp_f32_e32 v206, v206
	v_mul_f32_e32 v192, v192, v170
	v_mul_f32_e32 v192, v192, v223
	v_cvt_pk_bf16_f32 v192, v192, s0
	v_lshl_add_u64 v[204:205], s[86:87], 0, v[204:205]
	global_store_short v[204:205], v192, off
	v_mul_f32_e32 v192, v208, v195
	v_add_f32_e32 v195, 1.0, v206
	v_rcp_f32_e32 v195, v195
	v_cvt_pk_bf16_f32 v192, v192, s0
	v_lshl_add_u64 v[202:203], s[86:87], 0, v[202:203]
	global_store_short v[202:203], v192, off
	v_mul_f32_e32 v192, v30, v195
	v_lshlrev_b64 v[200:201], 11, v[200:201]
	v_cvt_pk_bf16_f32 v192, v192, s0
	v_lshl_add_u64 v[200:201], v[158:159], 0, v[200:201]
	global_store_short v[200:201], v192, off
	v_mul_f32_e32 v192, 0xbfb8aa3b, v115
	v_exp_f32_e32 v192, v192
	v_mul_f32_e32 v195, v212, v222
	v_rcp_f32_e32 v195, v195
	v_or_b32_e32 v200, 49, v162
	v_add_f32_e32 v192, 1.0, v192
	v_rcp_f32_e32 v192, v192
	v_mul_f32_e32 v194, v194, v174
	v_ashrrev_i32_e32 v201, 31, v200
	v_mul_f32_e32 v207, v194, v195
	v_lshlrev_b64 v[194:195], 9, v[200:201]
	v_mul_f32_e32 v206, v211, v221
	v_mul_f32_e32 v192, v115, v192
	v_lshl_add_u64 v[202:203], v[194:195], 0, v[156:157]
	v_lshl_add_u64 v[194:195], v[194:195], 0, v[160:161]
	v_mul_f32_e32 v204, v192, v206
	v_lshlrev_b64 v[202:203], 1, v[202:203]
	v_cvt_pk_bf16_f32 v208, v204, s0
	v_lshl_add_u64 v[204:205], s[26:27], 0, v[202:203]
	v_mul_f32_e32 v192, v192, v207
	v_lshlrev_b64 v[194:195], 1, v[194:195]
	global_store_short v[204:205], v208, off
	v_cvt_pk_bf16_f32 v192, v192, s0
	v_rcp_f32_e32 v206, v206
	v_lshl_add_u64 v[204:205], s[26:27], 0, v[194:195]
	global_store_short v[204:205], v192, off
	v_mul_f32_e32 v205, 0xbfb8aa3b, v31
	v_exp_f32_e32 v205, v205
	v_mul_f32_e32 v192, v209, v206
	v_cvt_pk_bf16_f32 v192, v192, s0
	v_rcp_f32_e32 v204, v207
	v_lshl_add_u64 v[202:203], s[86:87], 0, v[202:203]
	global_store_short v[202:203], v192, off
	v_add_f32_e32 v202, 1.0, v205
	v_rcp_f32_e32 v202, v202
	v_mul_f32_e32 v192, v210, v204
	v_cvt_pk_bf16_f32 v192, v192, s0
	v_lshl_add_u64 v[194:195], s[86:87], 0, v[194:195]
	global_store_short v[194:195], v192, off
	v_mul_f32_e32 v192, v31, v202
	v_lshlrev_b64 v[194:195], 11, v[200:201]
; __device__ __forceinline__ unsigned f2bf(float f) { const __bf16 b = (__bf16)f; return (unsigned)__builtin_bit_cast(unsigned short, b); }
; __device__ __forceinline__ float frcp(float x) { return __builtin_amdgcn_rcpf(x); }
; __device__ __forceinline__ float siluf_(float x) { return x * frcp(1.0f + fexp(-x)); }
;     __device__ __forceinline__ void operator()(Acc& acc, int pm, int pn, int wr, int wc, int fr, int fq) const {
;     ...
;                 for (int j = 0; j < 4; ++j) {
;                     const int row = row0 + mt * 16 + fq * 4 + j;
;                     const float Pf = pf * cf[j];
;                     const float Pb = totb * fbw[j] * frcp(pb * cb[j]);
;                     const float qs = siluf_(acc[ai][0][mt][0][j]);
;                     const size_t o0 = ((size_t)row) * 512 + chl, o1 = ((size_t)T_ALL + row) * 512 + chl;
;                     qt[o0] = (bf16_t)f2bf(qs * Pf);
;                     qt[o1] = (bf16_t)f2bf(qs * Pb);
;                     kt[o0] = (bf16_t)f2bf(kf[j] * frcp(Pf));
;                     kt[o1] = (bf16_t)f2bf(kb[j] * frcp(Pb));
;                     sg[(size_t)row * DM + chg] = (bf16_t)f2bf(siluf_(acc[ai][1][mt][1][j]));
;                 }
;             }
;             const int chunk = row0 >> 6;
;             if (fq == 0) {
;                 dend[((size_t)0 * 544 + chunk) * 512 + chl] = offf;
;                 dend[((size_t)1 * 544 + chunk) * 512 + chl] = totb;
;             }
	v_cvt_pk_bf16_f32 v192, v192, s0
	v_lshl_add_u64 v[194:195], v[158:159], 0, v[194:195]
	global_store_short v[194:195], v192, off
	v_mul_f32_e32 v192, 0xbfb8aa3b, v116
	v_exp_f32_e32 v194, v192
	v_mul_f32_e32 v195, v216, v222
	v_rcp_f32_e32 v195, v195
	v_or_b32_e32 v192, 50, v162
	v_add_f32_e32 v194, 1.0, v194
	v_rcp_f32_e32 v194, v194
	v_mul_f32_e32 v193, v193, v174
	v_mul_f32_e32 v205, v193, v195
	v_ashrrev_i32_e32 v193, 31, v192
	v_mul_f32_e32 v206, v116, v194
	v_lshlrev_b64 v[194:195], 9, v[192:193]
	v_mul_f32_e32 v204, v215, v221
	v_lshl_add_u64 v[200:201], v[194:195], 0, v[156:157]
	v_mul_f32_e32 v202, v206, v204
	v_lshlrev_b64 v[200:201], 1, v[200:201]
	v_rcp_f32_e32 v204, v204
	v_lshl_add_u64 v[194:195], v[194:195], 0, v[160:161]
	v_cvt_pk_bf16_f32 v207, v202, s0
	v_lshl_add_u64 v[202:203], s[26:27], 0, v[200:201]
	global_store_short v[202:203], v207, off
	v_mul_f32_e32 v202, v206, v205
	v_lshlrev_b64 v[194:195], 1, v[194:195]
	v_cvt_pk_bf16_f32 v206, v202, s0
	v_lshl_add_u64 v[202:203], s[26:27], 0, v[194:195]
	global_store_short v[202:203], v206, off
	v_mul_f32_e32 v202, v213, v204
	v_mul_f32_e32 v204, 0xbfb8aa3b, v32
	v_exp_f32_e32 v204, v204
	v_cvt_pk_bf16_f32 v202, v202, s0
	v_rcp_f32_e32 v203, v205
	v_lshl_add_u64 v[200:201], s[86:87], 0, v[200:201]
	global_store_short v[200:201], v202, off
	v_add_f32_e32 v201, 1.0, v204
	v_rcp_f32_e32 v201, v201
	v_mul_f32_e32 v200, v214, v203
	v_cvt_pk_bf16_f32 v200, v200, s0
	v_lshl_add_u64 v[194:195], s[86:87], 0, v[194:195]
	global_store_short v[194:195], v200, off
	v_mul_f32_e32 v194, v32, v201
	v_lshlrev_b64 v[192:193], 11, v[192:193]
	v_cvt_pk_bf16_f32 v194, v194, s0
	v_lshl_add_u64 v[192:193], v[158:159], 0, v[192:193]
	global_store_short v[192:193], v194, off
	v_mul_f32_e32 v192, 0xbfb8aa3b, v117
	v_exp_f32_e32 v193, v192
	v_or_b32_e32 v192, 51, v162
	v_mul_f32_e32 v162, v220, v222
	v_rcp_f32_e32 v162, v162
	v_add_f32_e32 v193, 1.0, v193
	v_rcp_f32_e32 v193, v193
	v_mul_f32_e32 v175, v175, v174
	v_mul_f32_e32 v162, v175, v162
	v_mul_f32_e32 v204, v219, v221
	v_mul_f32_e32 v175, v117, v193
	v_ashrrev_i32_e32 v193, 31, v192
	v_lshlrev_b64 v[194:195], 9, v[192:193]
	v_lshl_add_u64 v[200:201], v[194:195], 0, v[156:157]
	v_lshl_add_u64 v[194:195], v[194:195], 0, v[160:161]
	v_mul_f32_e32 v202, v175, v204
	v_lshlrev_b64 v[200:201], 1, v[200:201]
	v_cvt_pk_bf16_f32 v205, v202, s0
	v_lshl_add_u64 v[202:203], s[26:27], 0, v[200:201]
	v_mul_f32_e32 v175, v175, v162
	v_lshlrev_b64 v[194:195], 1, v[194:195]
	global_store_short v[202:203], v205, off
	v_cvt_pk_bf16_f32 v175, v175, s0
	v_rcp_f32_e32 v204, v204
	v_lshl_add_u64 v[202:203], s[26:27], 0, v[194:195]
	global_store_short v[202:203], v175, off
	v_mul_f32_e32 v202, 0xbfb8aa3b, v33
	v_exp_f32_e32 v202, v202
	v_mul_f32_e32 v175, v217, v204
	v_cvt_pk_bf16_f32 v175, v175, s0
	v_rcp_f32_e32 v162, v162
	v_lshl_add_u64 v[200:201], s[86:87], 0, v[200:201]
	global_store_short v[200:201], v175, off
	v_add_f32_e32 v175, 1.0, v202
	v_rcp_f32_e32 v175, v175
	ds_bpermute_b32 v199, v171, v219 offset:192
	v_mul_f32_e32 v162, v218, v162
	v_cvt_pk_bf16_f32 v162, v162, s0
	v_lshl_add_u64 v[194:195], s[86:87], 0, v[194:195]
	global_store_short v[194:195], v162, off
	v_mul_f32_e32 v162, v33, v175
	v_lshlrev_b64 v[192:193], 11, v[192:193]
	v_cvt_pk_bf16_f32 v162, v162, s0
	v_lshl_add_u64 v[192:193], v[158:159], 0, v[192:193]
	v_readlane_b32 s15, v253, 31
	global_store_short v[192:193], v162, off
	s_and_saveexec_b64 s[10:11], s[44:45]
	s_cbranch_execz .LBB0_486
	s_ashr_i32 s12, s4, 6
	s_ashr_i32 s13, s12, 31
	v_readlane_b32 s28, v253, 28
	s_lshl_b64 s[12:13], s[12:13], 11
	v_readlane_b32 s30, v253, 30
	v_mul_f32_e32 v162, v196, v197
	s_waitcnt lgkmcnt(0)
	v_mul_f32_e32 v175, v198, v199
	v_readlane_b32 s31, v253, 31
	s_add_u32 s12, s30, s12
	v_mul_f32_e32 v162, v162, v175
	s_addc_u32 s13, s31, s13
	v_mul_f32_e32 v175, v163, v162
	v_lshl_add_u64 v[162:163], v[156:157], 2, s[12:13]
	global_store_dword v[162:163], v175, off
	v_add_co_u32_e32 v162, vcc, 0x110000, v162
	v_readlane_b32 s29, v253, 29
	s_nop 0
	v_addc_co_u32_e32 v163, vcc, 0, v163, vcc
	global_store_dword v[162:163], v174, off

; #define PG8_STAGE(bufoff, gbase) do { _Pragma("unroll") for (int _i = 0; _i < 2; ++_i) \
;         __builtin_amdgcn_global_load_lds((const unsigned*)((const char*)(gbase) + voff[_i]), (LAS unsigned*)(lds + (bufoff) + ldsw + _i * 8192), 16, 0, 0); } while (0)
; #define PG8_LDA(dst, b, h) do { _Pragma("unroll") for (int m = 0; m < 4; ++m) _Pragma("unroll") for (int k = 0; k < 2; ++k) dst[m][k] = *(const LAS bf16x8*)(lds + PG8_SA(b, h) + aoff + m * 2048 + k * 1024); } while (0)
; #define PG8_LDB(dst, b, h) do { _Pragma("unroll") for (int n = 0; n < 2; ++n) _Pragma("unroll") for (int k = 0; k < 2; ++k) dst[n][k] = *(const LAS bf16x8*)(lds + PG8_SB(b, h) + boff + n * 2048 + k * 1024); } while (0)
; #define PG8_WAIT_V(n) asm volatile("s_waitcnt vmcnt(" #n ")" ::: "memory")
; #define PG8_WAIT_L(n) asm volatile("s_waitcnt lgkmcnt(" #n ")" ::: "memory")
; #define PG8_BAR __builtin_amdgcn_s_barrier()
; #define PG8_SCHED __builtin_amdgcn_sched_barrier(0)
;     ...
;             PG8_LDB(B0, 0, 0); PG8_SCHED; PG8_LDA(At, 0, 0); PG8_STAGE(PG8_SA(1, 1), a1 + hstep);
;             PG8_WAIT_L(8); PG8_BAR; PG8_WAIT_L(0); PG8_MMA(0, 0, At, B0); PG8_BAR; PG8_SCHED;
;             PG8_LDB(B1, 0, 1); PG8_STAGE(PG8_SB(0, 0), b2);
;             PG8_BAR; PG8_WAIT_L(0); PG8_MMA(0, 1, At, B1); PG8_BAR;
;             PG8_LDA(At, 0, 1); PG8_STAGE(PG8_SA(0, 0), a2);
;             PG8_BAR; PG8_WAIT_L(0); PG8_MMA(1, 0, At, B0); PG8_BAR; PG8_SCHED;
;             PG8_STAGE(PG8_SB(0, 1), b2 + hstep);
;             PG8_WAIT_V(6); PG8_BAR; PG8_MMA(1, 1, At, B1); PG8_BAR;
;             PG8_LDB(B0, 1, 0); PG8_SCHED; PG8_LDA(At, 1, 0); PG8_STAGE(PG8_SA(0, 1), a2 + hstep);
;             PG8_WAIT_L(8); PG8_BAR; PG8_WAIT_L(0); PG8_MMA(0, 0, At, B0); PG8_BAR; PG8_SCHED;
;             PG8_LDB(B1, 1, 1); PG8_STAGE(PG8_SB(1, 0), b3);
;             PG8_BAR; PG8_WAIT_L(0); PG8_MMA(0, 1, At, B1); PG8_BAR;
.LBB0_759:
	s_add_u32 s0, s10, 0xfffc0080
	s_addc_u32 s1, s11, -1
	s_add_i32 s31, 0, 0x10000
	v_add_u32_e32 v161, s31, v158
	ds_read_b128 v[154:157], v161
	ds_read_b128 v[162:165], v161 offset:1024
	ds_read_b128 v[166:169], v161 offset:2048
	ds_read_b128 v[170:173], v161 offset:3072
	s_cmp_eq_u32 s30, 12
	s_cselect_b32 s15, s18, s1
	s_cselect_b32 s14, s19, s0
	s_cselect_b32 s13, s22, s29
	s_cselect_b32 s12, s23, s28
	v_lshl_add_u64 v[174:175], s[10:11], 0, v[150:151]
	s_add_i32 m0, s17, 0xc000
	ds_read_b128 v[194:197], v160
	ds_read_b128 v[198:201], v160 offset:1024
	ds_read_b128 v[202:205], v160 offset:2048
	ds_read_b128 v[206:209], v160 offset:3072
	ds_read_b128 v[210:213], v160 offset:4096
	ds_read_b128 v[214:217], v160 offset:5120
	ds_read_b128 v[218:221], v160 offset:6144
	ds_read_b128 v[222:225], v160 offset:7168
	global_load_lds_dwordx4 v[174:175], off
	v_lshl_add_u64 v[174:175], s[10:11], 0, v[152:153]
	s_add_i32 m0, s17, 0xe000
	s_nop 0
	global_load_lds_dwordx4 v[174:175], off
	s_waitcnt lgkmcnt(8)
	s_barrier
	s_waitcnt lgkmcnt(0)
	s_setprio 1
	v_mfma_f32_16x16x32_bf16 v[126:129], v[154:157], v[194:197], v[126:129]
	v_mfma_f32_16x16x32_bf16 v[122:125], v[166:169], v[194:197], v[122:125]
	v_mfma_f32_16x16x32_bf16 v[110:113], v[154:157], v[202:205], v[110:113]
	v_mfma_f32_16x16x32_bf16 v[106:109], v[166:169], v[202:205], v[106:109]
	v_mfma_f32_16x16x32_bf16 v[94:97], v[154:157], v[210:213], v[94:97]
	v_mfma_f32_16x16x32_bf16 v[90:93], v[166:169], v[210:213], v[90:93]
	v_mfma_f32_16x16x32_bf16 v[78:81], v[154:157], v[218:221], v[78:81]
	v_mfma_f32_16x16x32_bf16 v[74:77], v[166:169], v[218:221], v[74:77]
	v_mfma_f32_16x16x32_bf16 v[126:129], v[162:165], v[198:201], v[126:129]
	v_mfma_f32_16x16x32_bf16 v[122:125], v[170:173], v[198:201], v[122:125]
	v_mfma_f32_16x16x32_bf16 v[110:113], v[162:165], v[206:209], v[110:113]
	v_mfma_f32_16x16x32_bf16 v[106:109], v[170:173], v[206:209], v[106:109]
	v_mfma_f32_16x16x32_bf16 v[94:97], v[162:165], v[214:217], v[94:97]
	v_mfma_f32_16x16x32_bf16 v[90:93], v[170:173], v[214:217], v[90:93]
	v_mfma_f32_16x16x32_bf16 v[78:81], v[162:165], v[222:225], v[78:81]
	v_mfma_f32_16x16x32_bf16 v[74:77], v[170:173], v[222:225], v[74:77]
	s_setprio 0
	s_barrier
	s_add_i32 s0, 0, 0x14000
	s_add_i32 s1, s31, s16
	v_add_u32_e32 v161, s0, v158
	v_lshl_add_u64 v[174:175], s[12:13], 0, v[132:133]
	s_mov_b32 m0, s1
	ds_read_b128 v[226:229], v161
	ds_read_b128 v[230:233], v161 offset:1024
	ds_read_b128 v[234:237], v161 offset:2048
	ds_read_b128 v[238:241], v161 offset:3072
	global_load_lds_dwordx4 v[174:175], off
	v_lshl_add_u64 v[242:243], s[12:13], 0, v[130:131]
	s_add_i32 m0, s1, 0x2000
	s_nop 0
	global_load_lds_dwordx4 v[242:243], off
	s_barrier
	s_waitcnt lgkmcnt(0)
	s_setprio 1
	v_mfma_f32_16x16x32_bf16 v[118:121], v[226:229], v[194:197], v[118:121]
	v_mfma_f32_16x16x32_bf16 v[114:117], v[234:237], v[194:197], v[114:117]
	v_mfma_f32_16x16x32_bf16 v[102:105], v[226:229], v[202:205], v[102:105]
	v_mfma_f32_16x16x32_bf16 v[98:101], v[234:237], v[202:205], v[98:101]
	v_mfma_f32_16x16x32_bf16 v[86:89], v[226:229], v[210:213], v[86:89]
	v_mfma_f32_16x16x32_bf16 v[82:85], v[234:237], v[210:213], v[82:85]
	v_mfma_f32_16x16x32_bf16 v[70:73], v[226:229], v[218:221], v[70:73]
	v_mfma_f32_16x16x32_bf16 v[66:69], v[234:237], v[218:221], v[66:69]
	v_mfma_f32_16x16x32_bf16 v[118:121], v[230:233], v[198:201], v[118:121]
	v_mfma_f32_16x16x32_bf16 v[114:117], v[238:241], v[198:201], v[114:117]
	v_mfma_f32_16x16x32_bf16 v[102:105], v[230:233], v[206:209], v[102:105]
	v_mfma_f32_16x16x32_bf16 v[98:101], v[238:241], v[206:209], v[98:101]
	v_mfma_f32_16x16x32_bf16 v[86:89], v[230:233], v[214:217], v[86:89]
	v_mfma_f32_16x16x32_bf16 v[82:85], v[238:241], v[214:217], v[82:85]
	v_mfma_f32_16x16x32_bf16 v[70:73], v[230:233], v[222:225], v[70:73]
	v_mfma_f32_16x16x32_bf16 v[66:69], v[238:241], v[222:225], v[66:69]
	s_setprio 0
	s_mov_b32 m0, s17
	v_lshl_add_u64 v[244:245], s[14:15], 0, v[132:133]
	s_barrier
	ds_read_b128 v[194:197], v160 offset:16384
	ds_read_b128 v[198:201], v160 offset:17408
	ds_read_b128 v[202:205], v160 offset:18432
	ds_read_b128 v[206:209], v160 offset:19456
	ds_read_b128 v[210:213], v160 offset:20480
	ds_read_b128 v[214:217], v160 offset:21504
	ds_read_b128 v[218:221], v160 offset:22528
	ds_read_b128 v[222:225], v160 offset:23552
	global_load_lds_dwordx4 v[244:245], off
	v_lshl_add_u64 v[246:247], s[14:15], 0, v[130:131]
	s_mov_b32 m0, s20
	s_nop 0
	global_load_lds_dwordx4 v[246:247], off
	s_barrier
	s_waitcnt lgkmcnt(0)
	s_setprio 1
	v_mfma_f32_16x16x32_bf16 v[62:65], v[154:157], v[194:197], v[62:65]
	v_mfma_f32_16x16x32_bf16 v[58:61], v[166:169], v[194:197], v[58:61]
	v_mfma_f32_16x16x32_bf16 v[46:49], v[154:157], v[202:205], v[46:49]
	v_mfma_f32_16x16x32_bf16 v[42:45], v[166:169], v[202:205], v[42:45]
	v_mfma_f32_16x16x32_bf16 v[30:33], v[154:157], v[210:213], v[30:33]
	v_mfma_f32_16x16x32_bf16 v[26:29], v[166:169], v[210:213], v[26:29]
	v_mfma_f32_16x16x32_bf16 v[14:17], v[154:157], v[218:221], v[14:17]
	v_mfma_f32_16x16x32_bf16 v[10:13], v[166:169], v[218:221], v[10:13]
	v_mfma_f32_16x16x32_bf16 v[62:65], v[162:165], v[198:201], v[62:65]
	v_mfma_f32_16x16x32_bf16 v[58:61], v[170:173], v[198:201], v[58:61]
	v_mfma_f32_16x16x32_bf16 v[46:49], v[162:165], v[206:209], v[46:49]
	v_mfma_f32_16x16x32_bf16 v[42:45], v[170:173], v[206:209], v[42:45]
	v_mfma_f32_16x16x32_bf16 v[30:33], v[162:165], v[214:217], v[30:33]
	v_mfma_f32_16x16x32_bf16 v[26:29], v[170:173], v[214:217], v[26:29]
	v_mfma_f32_16x16x32_bf16 v[14:17], v[162:165], v[222:225], v[14:17]
	v_mfma_f32_16x16x32_bf16 v[10:13], v[170:173], v[222:225], v[10:13]
	s_setprio 0
	s_barrier
; #define PG8_STAGE(bufoff, gbase) do { _Pragma("unroll") for (int _i = 0; _i < 2; ++_i) \
;         __builtin_amdgcn_global_load_lds((const unsigned*)((const char*)(gbase) + voff[_i]), (LAS unsigned*)(lds + (bufoff) + ldsw + _i * 8192), 16, 0, 0); } while (0)
; #define PG8_LDA(dst, b, h) do { _Pragma("unroll") for (int m = 0; m < 4; ++m) _Pragma("unroll") for (int k = 0; k < 2; ++k) dst[m][k] = *(const LAS bf16x8*)(lds + PG8_SA(b, h) + aoff + m * 2048 + k * 1024); } while (0)
; #define PG8_LDB(dst, b, h) do { _Pragma("unroll") for (int n = 0; n < 2; ++n) _Pragma("unroll") for (int k = 0; k < 2; ++k) dst[n][k] = *(const LAS bf16x8*)(lds + PG8_SB(b, h) + boff + n * 2048 + k * 1024); } while (0)
; #define PG8_WAIT_V(n) asm volatile("s_waitcnt vmcnt(" #n ")" ::: "memory")
; #define PG8_WAIT_L(n) asm volatile("s_waitcnt lgkmcnt(" #n ")" ::: "memory")
; #define PG8_BAR __builtin_amdgcn_s_barrier()
; #define PG8_SCHED __builtin_amdgcn_sched_barrier(0)
;     ...
;             PG8_STAGE(PG8_SB(0, 1), b2 + hstep);
;             PG8_WAIT_V(6); PG8_BAR; PG8_MMA(1, 1, At, B1); PG8_BAR;
;             PG8_LDB(B0, 1, 0); PG8_SCHED; PG8_LDA(At, 1, 0); PG8_STAGE(PG8_SA(0, 1), a2 + hstep);
;             PG8_WAIT_L(8); PG8_BAR; PG8_WAIT_L(0); PG8_MMA(0, 0, At, B0); PG8_BAR; PG8_SCHED;
;             PG8_LDB(B1, 1, 1); PG8_STAGE(PG8_SB(1, 0), b3);
;             PG8_BAR; PG8_WAIT_L(0); PG8_MMA(0, 1, At, B1); PG8_BAR;
;             PG8_LDA(At, 1, 1); PG8_STAGE(PG8_SA(1, 0), a3);
;             PG8_BAR; PG8_WAIT_L(0); PG8_MMA(1, 0, At, B0); PG8_BAR; PG8_SCHED;
	s_add_u32 s46, s12, 0x40000
	s_addc_u32 s47, s13, 0
	s_add_i32 s0, s0, s16
	v_lshl_add_u64 v[154:155], s[46:47], 0, v[132:133]
	s_mov_b32 m0, s0
	s_nop 0
	global_load_lds_dwordx4 v[154:155], off
	v_lshl_add_u64 v[154:155], s[46:47], 0, v[130:131]
	s_add_i32 m0, s0, 0x2000
	s_nop 0
	global_load_lds_dwordx4 v[154:155], off
	s_waitcnt vmcnt(6)
	s_barrier
	s_setprio 1
	v_mfma_f32_16x16x32_bf16 v[54:57], v[226:229], v[194:197], v[54:57]
	v_mfma_f32_16x16x32_bf16 v[50:53], v[234:237], v[194:197], v[50:53]
	v_mfma_f32_16x16x32_bf16 v[38:41], v[226:229], v[202:205], v[38:41]
	v_mfma_f32_16x16x32_bf16 v[34:37], v[234:237], v[202:205], v[34:37]
	v_mfma_f32_16x16x32_bf16 v[22:25], v[226:229], v[210:213], v[22:25]
	v_mfma_f32_16x16x32_bf16 v[18:21], v[234:237], v[210:213], v[18:21]
	v_mfma_f32_16x16x32_bf16 v[6:9], v[226:229], v[218:221], v[6:9]
	v_mfma_f32_16x16x32_bf16 v[2:5], v[234:237], v[218:221], v[2:5]
	v_mfma_f32_16x16x32_bf16 v[54:57], v[230:233], v[198:201], v[54:57]
	v_mfma_f32_16x16x32_bf16 v[50:53], v[238:241], v[198:201], v[50:53]
	v_mfma_f32_16x16x32_bf16 v[38:41], v[230:233], v[206:209], v[38:41]
	v_mfma_f32_16x16x32_bf16 v[34:37], v[238:241], v[206:209], v[34:37]
	v_mfma_f32_16x16x32_bf16 v[22:25], v[230:233], v[214:217], v[22:25]
	v_mfma_f32_16x16x32_bf16 v[18:21], v[238:241], v[214:217], v[18:21]
	v_mfma_f32_16x16x32_bf16 v[6:9], v[230:233], v[222:225], v[6:9]
	v_mfma_f32_16x16x32_bf16 v[2:5], v[238:241], v[222:225], v[2:5]
	s_setprio 0
	s_add_i32 s0, 0, 0x18000
	v_add_u32_e32 v161, s0, v158
	s_barrier
	ds_read_b128 v[154:157], v161
	ds_read_b128 v[162:165], v161 offset:1024
	ds_read_b128 v[166:169], v161 offset:2048
	ds_read_b128 v[170:173], v161 offset:3072
	s_add_u32 s14, s14, 0x40000
	s_addc_u32 s15, s15, 0
	s_mov_b32 m0, s40
	v_lshl_add_u64 v[226:227], s[14:15], 0, v[132:133]
	ds_read_b128 v[194:197], v160 offset:32768
	ds_read_b128 v[198:201], v160 offset:33792
	ds_read_b128 v[202:205], v160 offset:34816
	ds_read_b128 v[206:209], v160 offset:35840
	ds_read_b128 v[210:213], v160 offset:36864
	ds_read_b128 v[214:217], v160 offset:37888
	ds_read_b128 v[218:221], v160 offset:38912
	ds_read_b128 v[222:225], v160 offset:39936
	global_load_lds_dwordx4 v[226:227], off
	v_lshl_add_u64 v[226:227], s[14:15], 0, v[130:131]
	s_mov_b32 m0, s41
	s_nop 0
	global_load_lds_dwordx4 v[226:227], off
	s_waitcnt lgkmcnt(8)
	s_barrier
	s_waitcnt lgkmcnt(0)
	s_setprio 1
	v_mfma_f32_16x16x32_bf16 v[126:129], v[154:157], v[194:197], v[126:129]
	v_mfma_f32_16x16x32_bf16 v[122:125], v[166:169], v[194:197], v[122:125]
	v_mfma_f32_16x16x32_bf16 v[110:113], v[154:157], v[202:205], v[110:113]
	v_mfma_f32_16x16x32_bf16 v[106:109], v[166:169], v[202:205], v[106:109]
	v_mfma_f32_16x16x32_bf16 v[94:97], v[154:157], v[210:213], v[94:97]
	v_mfma_f32_16x16x32_bf16 v[90:93], v[166:169], v[210:213], v[90:93]
	v_mfma_f32_16x16x32_bf16 v[78:81], v[154:157], v[218:221], v[78:81]
	v_mfma_f32_16x16x32_bf16 v[74:77], v[166:169], v[218:221], v[74:77]
	v_mfma_f32_16x16x32_bf16 v[126:129], v[162:165], v[198:201], v[126:129]
	v_mfma_f32_16x16x32_bf16 v[122:125], v[170:173], v[198:201], v[122:125]
	v_mfma_f32_16x16x32_bf16 v[110:113], v[162:165], v[206:209], v[110:113]
	v_mfma_f32_16x16x32_bf16 v[106:109], v[170:173], v[206:209], v[106:109]
	v_mfma_f32_16x16x32_bf16 v[94:97], v[162:165], v[214:217], v[94:97]
	v_mfma_f32_16x16x32_bf16 v[90:93], v[170:173], v[214:217], v[90:93]
	v_mfma_f32_16x16x32_bf16 v[78:81], v[162:165], v[222:225], v[78:81]
	v_mfma_f32_16x16x32_bf16 v[74:77], v[170:173], v[222:225], v[74:77]
	s_setprio 0
	s_barrier
	s_add_i32 s1, 0, 0x1c000
	s_add_i32 s0, s0, s16
	v_add_u32_e32 v161, s1, v158
	v_lshl_add_u64 v[174:175], v[174:175], 0, s[88:89]
	s_mov_b32 m0, s0
	ds_read_b128 v[226:229], v161
	ds_read_b128 v[230:233], v161 offset:1024
	ds_read_b128 v[234:237], v161 offset:2048
	ds_read_b128 v[238:241], v161 offset:3072
	global_load_lds_dwordx4 v[174:175], off
	v_lshl_add_u64 v[174:175], v[242:243], 0, s[88:89]
	s_add_i32 m0, s0, 0x2000
	s_nop 0
	global_load_lds_dwordx4 v[174:175], off
	s_barrier
	s_waitcnt lgkmcnt(0)
	s_setprio 1
	v_mfma_f32_16x16x32_bf16 v[118:121], v[226:229], v[194:197], v[118:121]
	v_mfma_f32_16x16x32_bf16 v[114:117], v[234:237], v[194:197], v[114:117]
	v_mfma_f32_16x16x32_bf16 v[102:105], v[226:229], v[202:205], v[102:105]
	v_mfma_f32_16x16x32_bf16 v[98:101], v[234:237], v[202:205], v[98:101]
	v_mfma_f32_16x16x32_bf16 v[86:89], v[226:229], v[210:213], v[86:89]
	v_mfma_f32_16x16x32_bf16 v[82:85], v[234:237], v[210:213], v[82:85]
	v_mfma_f32_16x16x32_bf16 v[70:73], v[226:229], v[218:221], v[70:73]
	v_mfma_f32_16x16x32_bf16 v[66:69], v[234:237], v[218:221], v[66:69]
	v_mfma_f32_16x16x32_bf16 v[118:121], v[230:233], v[198:201], v[118:121]
	v_mfma_f32_16x16x32_bf16 v[114:117], v[238:241], v[198:201], v[114:117]
	v_mfma_f32_16x16x32_bf16 v[102:105], v[230:233], v[206:209], v[102:105]
	v_mfma_f32_16x16x32_bf16 v[98:101], v[238:241], v[206:209], v[98:101]
	v_mfma_f32_16x16x32_bf16 v[86:89], v[230:233], v[214:217], v[86:89]
	v_mfma_f32_16x16x32_bf16 v[82:85], v[238:241], v[214:217], v[82:85]
	v_mfma_f32_16x16x32_bf16 v[70:73], v[230:233], v[222:225], v[70:73]
	v_mfma_f32_16x16x32_bf16 v[66:69], v[238:241], v[222:225], v[66:69]
	s_setprio 0
	s_mov_b32 m0, s70
	v_lshl_add_u64 v[174:175], v[244:245], 0, s[88:89]
	s_barrier
; #define PG8_STAGE(bufoff, gbase) do { _Pragma("unroll") for (int _i = 0; _i < 2; ++_i) \
;         __builtin_amdgcn_global_load_lds((const unsigned*)((const char*)(gbase) + voff[_i]), (LAS unsigned*)(lds + (bufoff) + ldsw + _i * 8192), 16, 0, 0); } while (0)
; #define PG8_WAIT_V(n) asm volatile("s_waitcnt vmcnt(" #n ")" ::: "memory")
; #define PG8_WAIT_L(n) asm volatile("s_waitcnt lgkmcnt(" #n ")" ::: "memory")
; #define PG8_BAR __builtin_amdgcn_s_barrier()
; #define PG8_SCHED __builtin_amdgcn_sched_barrier(0)
;     ...
;             PG8_BAR; PG8_WAIT_L(0); PG8_MMA(1, 0, At, B0); PG8_BAR; PG8_SCHED;
;             PG8_STAGE(PG8_SB(1, 1), b3 + hstep);
;             PG8_WAIT_V(6); PG8_BAR; PG8_MMA(1, 1, At, B1); PG8_BAR;
;     __device__ __forceinline__ void operator()(Acc& acc, int pm, int pn, int wr, int wc, int fr, int fq) const {
;         const bool isg = mode == 0 ? (pn < 5) : (mode == 1);
;         bf16_t* base = isg ? gbuf : upre;
;         const int cb = ((mode == 0 && !isg) ? pn * 256 - DRNN : pn * 256) + wc * 32 + fq * 4;
; #pragma unroll
;         for (int ai = 0; ai < 2; ++ai)
; #pragma unroll
;             for (int m = 0; m < 4; ++m) {
;                 const size_t ro = (size_t)(pm * 256 + ai * 128 + wr * 64 + m * 16 + fr) * DRNN + cb;
; #pragma unroll
;                 for (int bj = 0; bj < 2; ++bj)
; #pragma unroll
;                     for (int n = 0; n < 2; ++n) {
;                         f32x4 v = acc[ai][bj][m][n];
;                         if (isg) { v[0] = gelu_tanh(v[0]); v[1] = gelu_tanh(v[1]); v[2] = gelu_tanh(v[2]); v[3] = gelu_tanh(v[3]); }
	ds_read_b128 v[194:197], v160 offset:49152
	ds_read_b128 v[198:201], v160 offset:50176
	ds_read_b128 v[202:205], v160 offset:51200
	ds_read_b128 v[206:209], v160 offset:52224
	ds_read_b128 v[210:213], v160 offset:53248
	ds_read_b128 v[214:217], v160 offset:54272
	ds_read_b128 v[218:221], v160 offset:55296
	ds_read_b128 v[222:225], v160 offset:56320
	global_load_lds_dwordx4 v[174:175], off
	v_lshl_add_u64 v[174:175], v[246:247], 0, s[88:89]
	s_mov_b32 m0, s71
	s_nop 0
	global_load_lds_dwordx4 v[174:175], off
	s_barrier
	s_waitcnt lgkmcnt(0)
	s_setprio 1
	v_mfma_f32_16x16x32_bf16 v[62:65], v[154:157], v[194:197], v[62:65]
	v_mfma_f32_16x16x32_bf16 v[58:61], v[166:169], v[194:197], v[58:61]
	v_mfma_f32_16x16x32_bf16 v[46:49], v[154:157], v[202:205], v[46:49]
	v_mfma_f32_16x16x32_bf16 v[42:45], v[166:169], v[202:205], v[42:45]
	v_mfma_f32_16x16x32_bf16 v[30:33], v[154:157], v[210:213], v[30:33]
	v_mfma_f32_16x16x32_bf16 v[26:29], v[166:169], v[210:213], v[26:29]
	v_mfma_f32_16x16x32_bf16 v[14:17], v[154:157], v[218:221], v[14:17]
	v_mfma_f32_16x16x32_bf16 v[10:13], v[166:169], v[218:221], v[10:13]
	v_mfma_f32_16x16x32_bf16 v[62:65], v[162:165], v[198:201], v[62:65]
	v_mfma_f32_16x16x32_bf16 v[58:61], v[170:173], v[198:201], v[58:61]
	v_mfma_f32_16x16x32_bf16 v[46:49], v[162:165], v[206:209], v[46:49]
	v_mfma_f32_16x16x32_bf16 v[42:45], v[170:173], v[206:209], v[42:45]
	v_mfma_f32_16x16x32_bf16 v[30:33], v[162:165], v[214:217], v[30:33]
	v_mfma_f32_16x16x32_bf16 v[26:29], v[170:173], v[214:217], v[26:29]
	v_mfma_f32_16x16x32_bf16 v[14:17], v[162:165], v[222:225], v[14:17]
	v_mfma_f32_16x16x32_bf16 v[10:13], v[170:173], v[222:225], v[10:13]
	s_setprio 0
	s_barrier
	s_add_u32 s12, s12, 0x40080
	s_addc_u32 s13, s13, 0
	s_add_i32 s0, s1, s16
	v_lshl_add_u64 v[154:155], s[12:13], 0, v[132:133]
	s_mov_b32 m0, s0
	s_nop 0
	global_load_lds_dwordx4 v[154:155], off
	v_lshl_add_u64 v[154:155], s[12:13], 0, v[130:131]
	s_add_i32 m0, s0, 0x2000
	s_nop 0
	global_load_lds_dwordx4 v[154:155], off
	s_waitcnt vmcnt(6)
	s_barrier
	s_setprio 1
	v_mfma_f32_16x16x32_bf16 v[54:57], v[226:229], v[194:197], v[54:57]
	v_mfma_f32_16x16x32_bf16 v[50:53], v[234:237], v[194:197], v[50:53]
	v_mfma_f32_16x16x32_bf16 v[38:41], v[226:229], v[202:205], v[38:41]
	v_mfma_f32_16x16x32_bf16 v[34:37], v[234:237], v[202:205], v[34:37]
	v_mfma_f32_16x16x32_bf16 v[22:25], v[226:229], v[210:213], v[22:25]
	v_mfma_f32_16x16x32_bf16 v[18:21], v[234:237], v[210:213], v[18:21]
	v_mfma_f32_16x16x32_bf16 v[6:9], v[226:229], v[218:221], v[6:9]
	v_mfma_f32_16x16x32_bf16 v[2:5], v[234:237], v[218:221], v[2:5]
	v_mfma_f32_16x16x32_bf16 v[54:57], v[230:233], v[198:201], v[54:57]
	v_mfma_f32_16x16x32_bf16 v[50:53], v[238:241], v[198:201], v[50:53]
	v_mfma_f32_16x16x32_bf16 v[38:41], v[230:233], v[206:209], v[38:41]
	v_mfma_f32_16x16x32_bf16 v[34:37], v[238:241], v[206:209], v[34:37]
	v_mfma_f32_16x16x32_bf16 v[22:25], v[230:233], v[214:217], v[22:25]
	v_mfma_f32_16x16x32_bf16 v[18:21], v[238:241], v[214:217], v[18:21]
	v_mfma_f32_16x16x32_bf16 v[6:9], v[230:233], v[222:225], v[6:9]
	v_mfma_f32_16x16x32_bf16 v[2:5], v[238:241], v[222:225], v[2:5]
	s_setprio 0
	s_add_i32 s30, s30, 2
	s_add_u32 s10, s10, 0x100
	s_addc_u32 s11, s11, 0
	s_add_u32 s28, s28, 0x100
	s_addc_u32 s29, s29, 0
	s_cmp_gt_u32 s30, 13
	s_barrier
	s_cbranch_scc0 .LBB0_759
	s_cmp_lt_i32 s7, 5
	s_cselect_b64 s[10:11], -1, 0
	s_cmp_gt_i32 s7, 4
	s_cbranch_scc1 .LBB0_762
	v_mul_f32_e32 v154, 0x3d372713, v126
	v_mul_f32_e32 v155, 0x3d372713, v127
	v_mul_f32_e32 v156, 0x3d372713, v128
	v_mul_f32_e32 v157, 0x3d372713, v129
	v_mul_f32_e32 v154, v126, v154
	v_mul_f32_e32 v155, v127, v155
	v_mul_f32_e32 v156, v128, v156
	v_mul_f32_e32 v157, v129, v157
	v_fma_f32 v154, v126, v154, v126
	v_fma_f32 v155, v127, v155, v127
	v_fma_f32 v156, v128, v156, v128
	v_fma_f32 v157, v129, v157, v129
	v_mul_f32_e32 v154, 0xbfcc422a, v154
	v_mul_f32_e32 v155, 0xbfcc422a, v155
	v_mul_f32_e32 v156, 0xbfcc422a, v156
	v_mul_f32_e32 v157, 0xbfcc422a, v157
	v_mul_f32_e32 v154, 0x3fb8aa3b, v154
	v_mul_f32_e32 v155, 0x3fb8aa3b, v155
	v_mul_f32_e32 v156, 0x3fb8aa3b, v156
	v_mul_f32_e32 v157, 0x3fb8aa3b, v157
	v_exp_f32_e32 v154, v154
	v_exp_f32_e32 v155, v155
	v_exp_f32_e32 v156, v156
	v_exp_f32_e32 v157, v157
	v_add_f32_e32 v154, 1.0, v154
	v_add_f32_e32 v155, 1.0, v155
	v_add_f32_e32 v156, 1.0, v156
	v_add_f32_e32 v157, 1.0, v157
	v_rcp_f32_e32 v154, v154
	v_rcp_f32_e32 v156, v156
	v_rcp_f32_e32 v157, v157
	v_rcp_f32_e32 v155, v155
	v_pk_mul_f32 v[128:129], v[128:129], v[156:157]
	v_pk_mul_f32 v[126:127], v[126:127], v[154:155]

; #define PG8_STAGE(bufoff, gbase) do { _Pragma("unroll") for (int _i = 0; _i < 2; ++_i) \
;         __builtin_amdgcn_global_load_lds((const unsigned*)((const char*)(gbase) + voff[_i]), (LAS unsigned*)(lds + (bufoff) + ldsw + _i * 8192), 16, 0, 0); } while (0)
; #define PG8_LDA(dst, b, h) do { _Pragma("unroll") for (int m = 0; m < 4; ++m) _Pragma("unroll") for (int k = 0; k < 2; ++k) dst[m][k] = *(const LAS bf16x8*)(lds + PG8_SA(b, h) + aoff + m * 2048 + k * 1024); } while (0)
; #define PG8_LDB(dst, b, h) do { _Pragma("unroll") for (int n = 0; n < 2; ++n) _Pragma("unroll") for (int k = 0; k < 2; ++k) dst[n][k] = *(const LAS bf16x8*)(lds + PG8_SB(b, h) + boff + n * 2048 + k * 1024); } while (0)
; #define PG8_WAIT_V(n) asm volatile("s_waitcnt vmcnt(" #n ")" ::: "memory")
; #define PG8_WAIT_L(n) asm volatile("s_waitcnt lgkmcnt(" #n ")" ::: "memory")
; #define PG8_BAR __builtin_amdgcn_s_barrier()
; #define PG8_SCHED __builtin_amdgcn_sched_barrier(0)
;     ...
;             PG8_LDB(B0, 0, 0); PG8_SCHED; PG8_LDA(At, 0, 0); PG8_STAGE(PG8_SA(1, 1), a1 + hstep);
;             PG8_WAIT_L(8); PG8_BAR; PG8_WAIT_L(0); PG8_MMA(0, 0, At, B0); PG8_BAR; PG8_SCHED;
;             PG8_LDB(B1, 0, 1); PG8_STAGE(PG8_SB(0, 0), b2);
;             PG8_BAR; PG8_WAIT_L(0); PG8_MMA(0, 1, At, B1); PG8_BAR;
;             PG8_LDA(At, 0, 1); PG8_STAGE(PG8_SA(0, 0), a2);
;             PG8_BAR; PG8_WAIT_L(0); PG8_MMA(1, 0, At, B0); PG8_BAR; PG8_SCHED;
;             PG8_STAGE(PG8_SB(0, 1), b2 + hstep);
;             PG8_WAIT_V(6); PG8_BAR; PG8_MMA(1, 1, At, B1); PG8_BAR;
;             PG8_LDB(B0, 1, 0); PG8_SCHED; PG8_LDA(At, 1, 0); PG8_STAGE(PG8_SA(0, 1), a2 + hstep);
;             PG8_WAIT_L(8); PG8_BAR; PG8_WAIT_L(0); PG8_MMA(0, 0, At, B0); PG8_BAR; PG8_SCHED;
;             PG8_LDB(B1, 1, 1); PG8_STAGE(PG8_SB(1, 0), b3);
;             PG8_BAR; PG8_WAIT_L(0); PG8_MMA(0, 1, At, B1); PG8_BAR;
.LBB0_904:
	s_add_u32 s0, s54, 0xfffc0080
	s_addc_u32 s1, s55, -1
	s_add_i32 s63, 0, 0x10000
	v_add_u32_e32 v157, s63, v154
	ds_read_b128 v[158:161], v157
	ds_read_b128 v[162:165], v157 offset:1024
	ds_read_b128 v[166:169], v157 offset:2048
	ds_read_b128 v[170:173], v157 offset:3072
	s_cmp_eq_u32 s62, 12
	s_cselect_b32 s59, s15, s1
	s_cselect_b32 s58, s31, s0
	s_cselect_b32 s57, s13, s61
	s_cselect_b32 s56, s36, s60
	v_lshl_add_u64 v[174:175], s[54:55], 0, v[150:151]
	s_add_i32 m0, s17, 0xc000
	ds_read_b128 v[194:197], v156
	ds_read_b128 v[198:201], v156 offset:1024
	ds_read_b128 v[202:205], v156 offset:2048
	ds_read_b128 v[206:209], v156 offset:3072
	ds_read_b128 v[210:213], v156 offset:4096
	ds_read_b128 v[214:217], v156 offset:5120
	ds_read_b128 v[218:221], v156 offset:6144
	ds_read_b128 v[222:225], v156 offset:7168
	global_load_lds_dwordx4 v[174:175], off
	v_lshl_add_u64 v[174:175], s[54:55], 0, v[152:153]
	s_add_i32 m0, s17, 0xe000
	s_nop 0
	global_load_lds_dwordx4 v[174:175], off
	s_waitcnt lgkmcnt(8)
	s_barrier
	s_waitcnt lgkmcnt(0)
	s_setprio 1
	v_mfma_f32_16x16x32_bf16 v[126:129], v[158:161], v[194:197], v[126:129]
	v_mfma_f32_16x16x32_bf16 v[122:125], v[166:169], v[194:197], v[122:125]
	v_mfma_f32_16x16x32_bf16 v[118:121], v[158:161], v[202:205], v[118:121]
	v_mfma_f32_16x16x32_bf16 v[114:117], v[166:169], v[202:205], v[114:117]
	v_mfma_f32_16x16x32_bf16 v[102:105], v[158:161], v[210:213], v[102:105]
	v_mfma_f32_16x16x32_bf16 v[98:101], v[166:169], v[210:213], v[98:101]
	v_mfma_f32_16x16x32_bf16 v[86:89], v[158:161], v[218:221], v[86:89]
	v_mfma_f32_16x16x32_bf16 v[82:85], v[166:169], v[218:221], v[82:85]
	v_mfma_f32_16x16x32_bf16 v[126:129], v[162:165], v[198:201], v[126:129]
	v_mfma_f32_16x16x32_bf16 v[122:125], v[170:173], v[198:201], v[122:125]
	v_mfma_f32_16x16x32_bf16 v[118:121], v[162:165], v[206:209], v[118:121]
	v_mfma_f32_16x16x32_bf16 v[114:117], v[170:173], v[206:209], v[114:117]
	v_mfma_f32_16x16x32_bf16 v[102:105], v[162:165], v[214:217], v[102:105]
	v_mfma_f32_16x16x32_bf16 v[98:101], v[170:173], v[214:217], v[98:101]
	v_mfma_f32_16x16x32_bf16 v[86:89], v[162:165], v[222:225], v[86:89]
	v_mfma_f32_16x16x32_bf16 v[82:85], v[170:173], v[222:225], v[82:85]
	s_setprio 0
	s_barrier
	s_add_i32 s0, 0, 0x14000
	s_add_i32 s1, s63, s16
	v_add_u32_e32 v157, s0, v154
	v_lshl_add_u64 v[174:175], s[56:57], 0, v[132:133]
	s_mov_b32 m0, s1
	ds_read_b128 v[226:229], v157
	ds_read_b128 v[230:233], v157 offset:1024
	ds_read_b128 v[234:237], v157 offset:2048
	ds_read_b128 v[238:241], v157 offset:3072
	global_load_lds_dwordx4 v[174:175], off
	v_lshl_add_u64 v[242:243], s[56:57], 0, v[130:131]
	s_add_i32 m0, s1, 0x2000
	s_nop 0
	global_load_lds_dwordx4 v[242:243], off
	s_barrier
	s_waitcnt lgkmcnt(0)
	s_setprio 1
	v_mfma_f32_16x16x32_bf16 v[110:113], v[226:229], v[194:197], v[110:113]
	v_mfma_f32_16x16x32_bf16 v[106:109], v[234:237], v[194:197], v[106:109]
	v_mfma_f32_16x16x32_bf16 v[94:97], v[226:229], v[202:205], v[94:97]
	v_mfma_f32_16x16x32_bf16 v[90:93], v[234:237], v[202:205], v[90:93]
	v_mfma_f32_16x16x32_bf16 v[78:81], v[226:229], v[210:213], v[78:81]
	v_mfma_f32_16x16x32_bf16 v[74:77], v[234:237], v[210:213], v[74:77]
	v_mfma_f32_16x16x32_bf16 v[70:73], v[226:229], v[218:221], v[70:73]
	v_mfma_f32_16x16x32_bf16 v[66:69], v[234:237], v[218:221], v[66:69]
	v_mfma_f32_16x16x32_bf16 v[110:113], v[230:233], v[198:201], v[110:113]
	v_mfma_f32_16x16x32_bf16 v[106:109], v[238:241], v[198:201], v[106:109]
	v_mfma_f32_16x16x32_bf16 v[94:97], v[230:233], v[206:209], v[94:97]
	v_mfma_f32_16x16x32_bf16 v[90:93], v[238:241], v[206:209], v[90:93]
	v_mfma_f32_16x16x32_bf16 v[78:81], v[230:233], v[214:217], v[78:81]
	v_mfma_f32_16x16x32_bf16 v[74:77], v[238:241], v[214:217], v[74:77]
	v_mfma_f32_16x16x32_bf16 v[70:73], v[230:233], v[222:225], v[70:73]
	v_mfma_f32_16x16x32_bf16 v[66:69], v[238:241], v[222:225], v[66:69]
	s_setprio 0
	s_mov_b32 m0, s17
	v_lshl_add_u64 v[244:245], s[58:59], 0, v[132:133]
	s_barrier
	ds_read_b128 v[194:197], v156 offset:16384
	ds_read_b128 v[198:201], v156 offset:17408
	ds_read_b128 v[202:205], v156 offset:18432
	ds_read_b128 v[206:209], v156 offset:19456
	ds_read_b128 v[210:213], v156 offset:20480
	ds_read_b128 v[214:217], v156 offset:21504
	ds_read_b128 v[218:221], v156 offset:22528
	ds_read_b128 v[222:225], v156 offset:23552
	global_load_lds_dwordx4 v[244:245], off
	v_lshl_add_u64 v[246:247], s[58:59], 0, v[130:131]
	s_mov_b32 m0, s18
	s_nop 0
	global_load_lds_dwordx4 v[246:247], off
	s_barrier
	s_waitcnt lgkmcnt(0)
	s_setprio 1
	v_mfma_f32_16x16x32_bf16 v[62:65], v[158:161], v[194:197], v[62:65]
	v_mfma_f32_16x16x32_bf16 v[58:61], v[166:169], v[194:197], v[58:61]
	v_mfma_f32_16x16x32_bf16 v[54:57], v[158:161], v[202:205], v[54:57]
	v_mfma_f32_16x16x32_bf16 v[50:53], v[166:169], v[202:205], v[50:53]
	v_mfma_f32_16x16x32_bf16 v[38:41], v[158:161], v[210:213], v[38:41]
	v_mfma_f32_16x16x32_bf16 v[34:37], v[166:169], v[210:213], v[34:37]
	v_mfma_f32_16x16x32_bf16 v[22:25], v[158:161], v[218:221], v[22:25]
	v_mfma_f32_16x16x32_bf16 v[18:21], v[166:169], v[218:221], v[18:21]
	v_mfma_f32_16x16x32_bf16 v[62:65], v[162:165], v[198:201], v[62:65]
	v_mfma_f32_16x16x32_bf16 v[58:61], v[170:173], v[198:201], v[58:61]
	v_mfma_f32_16x16x32_bf16 v[54:57], v[162:165], v[206:209], v[54:57]
	v_mfma_f32_16x16x32_bf16 v[50:53], v[170:173], v[206:209], v[50:53]
	v_mfma_f32_16x16x32_bf16 v[38:41], v[162:165], v[214:217], v[38:41]
	v_mfma_f32_16x16x32_bf16 v[34:37], v[170:173], v[214:217], v[34:37]
	v_mfma_f32_16x16x32_bf16 v[22:25], v[162:165], v[222:225], v[22:25]
	v_mfma_f32_16x16x32_bf16 v[18:21], v[170:173], v[222:225], v[18:21]
	s_setprio 0
	s_barrier
; #define PG8_STAGE(bufoff, gbase) do { _Pragma("unroll") for (int _i = 0; _i < 2; ++_i) \
;         __builtin_amdgcn_global_load_lds((const unsigned*)((const char*)(gbase) + voff[_i]), (LAS unsigned*)(lds + (bufoff) + ldsw + _i * 8192), 16, 0, 0); } while (0)
; #define PG8_LDA(dst, b, h) do { _Pragma("unroll") for (int m = 0; m < 4; ++m) _Pragma("unroll") for (int k = 0; k < 2; ++k) dst[m][k] = *(const LAS bf16x8*)(lds + PG8_SA(b, h) + aoff + m * 2048 + k * 1024); } while (0)
; #define PG8_LDB(dst, b, h) do { _Pragma("unroll") for (int n = 0; n < 2; ++n) _Pragma("unroll") for (int k = 0; k < 2; ++k) dst[n][k] = *(const LAS bf16x8*)(lds + PG8_SB(b, h) + boff + n * 2048 + k * 1024); } while (0)
; #define PG8_WAIT_V(n) asm volatile("s_waitcnt vmcnt(" #n ")" ::: "memory")
; #define PG8_WAIT_L(n) asm volatile("s_waitcnt lgkmcnt(" #n ")" ::: "memory")
; #define PG8_BAR __builtin_amdgcn_s_barrier()
; #define PG8_SCHED __builtin_amdgcn_sched_barrier(0)
;     ...
;             PG8_STAGE(PG8_SB(0, 1), b2 + hstep);
;             PG8_WAIT_V(6); PG8_BAR; PG8_MMA(1, 1, At, B1); PG8_BAR;
;             PG8_LDB(B0, 1, 0); PG8_SCHED; PG8_LDA(At, 1, 0); PG8_STAGE(PG8_SA(0, 1), a2 + hstep);
;             PG8_WAIT_L(8); PG8_BAR; PG8_WAIT_L(0); PG8_MMA(0, 0, At, B0); PG8_BAR; PG8_SCHED;
;             PG8_LDB(B1, 1, 1); PG8_STAGE(PG8_SB(1, 0), b3);
;             PG8_BAR; PG8_WAIT_L(0); PG8_MMA(0, 1, At, B1); PG8_BAR;
;             PG8_LDA(At, 1, 1); PG8_STAGE(PG8_SA(1, 0), a3);
;             PG8_BAR; PG8_WAIT_L(0); PG8_MMA(1, 0, At, B0); PG8_BAR; PG8_SCHED;
	s_add_u32 s64, s56, 0x40000
	s_addc_u32 s65, s57, 0
	s_add_i32 s0, s0, s16
	v_lshl_add_u64 v[158:159], s[64:65], 0, v[132:133]
	s_mov_b32 m0, s0
	s_nop 0
	global_load_lds_dwordx4 v[158:159], off
	v_lshl_add_u64 v[158:159], s[64:65], 0, v[130:131]
	s_add_i32 m0, s0, 0x2000
	s_nop 0
	global_load_lds_dwordx4 v[158:159], off
	s_waitcnt vmcnt(6)
	s_barrier
	s_setprio 1
	v_mfma_f32_16x16x32_bf16 v[46:49], v[226:229], v[194:197], v[46:49]
	v_mfma_f32_16x16x32_bf16 v[42:45], v[234:237], v[194:197], v[42:45]
	v_mfma_f32_16x16x32_bf16 v[30:33], v[226:229], v[202:205], v[30:33]
	v_mfma_f32_16x16x32_bf16 v[26:29], v[234:237], v[202:205], v[26:29]
	v_mfma_f32_16x16x32_bf16 v[14:17], v[226:229], v[210:213], v[14:17]
	v_mfma_f32_16x16x32_bf16 v[10:13], v[234:237], v[210:213], v[10:13]
	v_mfma_f32_16x16x32_bf16 v[6:9], v[226:229], v[218:221], v[6:9]
	v_mfma_f32_16x16x32_bf16 v[2:5], v[234:237], v[218:221], v[2:5]
	v_mfma_f32_16x16x32_bf16 v[46:49], v[230:233], v[198:201], v[46:49]
	v_mfma_f32_16x16x32_bf16 v[42:45], v[238:241], v[198:201], v[42:45]
	v_mfma_f32_16x16x32_bf16 v[30:33], v[230:233], v[206:209], v[30:33]
	v_mfma_f32_16x16x32_bf16 v[26:29], v[238:241], v[206:209], v[26:29]
	v_mfma_f32_16x16x32_bf16 v[14:17], v[230:233], v[214:217], v[14:17]
	v_mfma_f32_16x16x32_bf16 v[10:13], v[238:241], v[214:217], v[10:13]
	v_mfma_f32_16x16x32_bf16 v[6:9], v[230:233], v[222:225], v[6:9]
	v_mfma_f32_16x16x32_bf16 v[2:5], v[238:241], v[222:225], v[2:5]
	s_setprio 0
	s_add_i32 s0, 0, 0x18000
	v_add_u32_e32 v157, s0, v154
	s_barrier
	ds_read_b128 v[158:161], v157
	ds_read_b128 v[162:165], v157 offset:1024
	ds_read_b128 v[166:169], v157 offset:2048
	ds_read_b128 v[170:173], v157 offset:3072
	s_add_u32 s58, s58, 0x40000
	s_addc_u32 s59, s59, 0
	s_mov_b32 m0, s19
	v_lshl_add_u64 v[226:227], s[58:59], 0, v[132:133]
	ds_read_b128 v[194:197], v156 offset:32768
	ds_read_b128 v[198:201], v156 offset:33792
	ds_read_b128 v[202:205], v156 offset:34816
	ds_read_b128 v[206:209], v156 offset:35840
	ds_read_b128 v[210:213], v156 offset:36864
	ds_read_b128 v[214:217], v156 offset:37888
	ds_read_b128 v[218:221], v156 offset:38912
	ds_read_b128 v[222:225], v156 offset:39936
	global_load_lds_dwordx4 v[226:227], off
	v_lshl_add_u64 v[226:227], s[58:59], 0, v[130:131]
	s_mov_b32 m0, s20
	s_nop 0
	global_load_lds_dwordx4 v[226:227], off
	s_waitcnt lgkmcnt(8)
	s_barrier
	s_waitcnt lgkmcnt(0)
	s_setprio 1
	v_mfma_f32_16x16x32_bf16 v[126:129], v[158:161], v[194:197], v[126:129]
	v_mfma_f32_16x16x32_bf16 v[122:125], v[166:169], v[194:197], v[122:125]
	v_mfma_f32_16x16x32_bf16 v[118:121], v[158:161], v[202:205], v[118:121]
	v_mfma_f32_16x16x32_bf16 v[114:117], v[166:169], v[202:205], v[114:117]
	v_mfma_f32_16x16x32_bf16 v[102:105], v[158:161], v[210:213], v[102:105]
	v_mfma_f32_16x16x32_bf16 v[98:101], v[166:169], v[210:213], v[98:101]
	v_mfma_f32_16x16x32_bf16 v[86:89], v[158:161], v[218:221], v[86:89]
	v_mfma_f32_16x16x32_bf16 v[82:85], v[166:169], v[218:221], v[82:85]
	v_mfma_f32_16x16x32_bf16 v[126:129], v[162:165], v[198:201], v[126:129]
	v_mfma_f32_16x16x32_bf16 v[122:125], v[170:173], v[198:201], v[122:125]
	v_mfma_f32_16x16x32_bf16 v[118:121], v[162:165], v[206:209], v[118:121]
	v_mfma_f32_16x16x32_bf16 v[114:117], v[170:173], v[206:209], v[114:117]
	v_mfma_f32_16x16x32_bf16 v[102:105], v[162:165], v[214:217], v[102:105]
	v_mfma_f32_16x16x32_bf16 v[98:101], v[170:173], v[214:217], v[98:101]
	v_mfma_f32_16x16x32_bf16 v[86:89], v[162:165], v[222:225], v[86:89]
	v_mfma_f32_16x16x32_bf16 v[82:85], v[170:173], v[222:225], v[82:85]
	s_setprio 0
	s_barrier
	s_add_i32 s1, 0, 0x1c000
	s_add_i32 s0, s0, s16
	v_add_u32_e32 v157, s1, v154
	v_lshl_add_u64 v[174:175], v[174:175], 0, s[88:89]
	s_mov_b32 m0, s0
	ds_read_b128 v[226:229], v157
	ds_read_b128 v[230:233], v157 offset:1024
	ds_read_b128 v[234:237], v157 offset:2048
	ds_read_b128 v[238:241], v157 offset:3072
	global_load_lds_dwordx4 v[174:175], off
	v_lshl_add_u64 v[174:175], v[242:243], 0, s[88:89]
	s_add_i32 m0, s0, 0x2000
	s_nop 0
	global_load_lds_dwordx4 v[174:175], off
	s_barrier
	s_waitcnt lgkmcnt(0)
	s_setprio 1
	v_mfma_f32_16x16x32_bf16 v[110:113], v[226:229], v[194:197], v[110:113]
	v_mfma_f32_16x16x32_bf16 v[106:109], v[234:237], v[194:197], v[106:109]
	v_mfma_f32_16x16x32_bf16 v[94:97], v[226:229], v[202:205], v[94:97]
	v_mfma_f32_16x16x32_bf16 v[90:93], v[234:237], v[202:205], v[90:93]
	v_mfma_f32_16x16x32_bf16 v[78:81], v[226:229], v[210:213], v[78:81]
	v_mfma_f32_16x16x32_bf16 v[74:77], v[234:237], v[210:213], v[74:77]
	v_mfma_f32_16x16x32_bf16 v[70:73], v[226:229], v[218:221], v[70:73]
	v_mfma_f32_16x16x32_bf16 v[66:69], v[234:237], v[218:221], v[66:69]
	v_mfma_f32_16x16x32_bf16 v[110:113], v[230:233], v[198:201], v[110:113]
	v_mfma_f32_16x16x32_bf16 v[106:109], v[238:241], v[198:201], v[106:109]
	v_mfma_f32_16x16x32_bf16 v[94:97], v[230:233], v[206:209], v[94:97]
	v_mfma_f32_16x16x32_bf16 v[90:93], v[238:241], v[206:209], v[90:93]
	v_mfma_f32_16x16x32_bf16 v[78:81], v[230:233], v[214:217], v[78:81]
	v_mfma_f32_16x16x32_bf16 v[74:77], v[238:241], v[214:217], v[74:77]
	v_mfma_f32_16x16x32_bf16 v[70:73], v[230:233], v[222:225], v[70:73]
	v_mfma_f32_16x16x32_bf16 v[66:69], v[238:241], v[222:225], v[66:69]
	s_setprio 0
	s_mov_b32 m0, s22
	v_lshl_add_u64 v[174:175], v[244:245], 0, s[88:89]
	s_barrier
	ds_read_b128 v[194:197], v156 offset:49152
	ds_read_b128 v[198:201], v156 offset:50176
	ds_read_b128 v[202:205], v156 offset:51200
	ds_read_b128 v[206:209], v156 offset:52224
	ds_read_b128 v[210:213], v156 offset:53248
	ds_read_b128 v[214:217], v156 offset:54272
	ds_read_b128 v[218:221], v156 offset:55296
	ds_read_b128 v[222:225], v156 offset:56320
	global_load_lds_dwordx4 v[174:175], off
	v_lshl_add_u64 v[174:175], v[246:247], 0, s[88:89]
	s_mov_b32 m0, s23
	s_nop 0
	global_load_lds_dwordx4 v[174:175], off
	s_barrier
; #define PG8_STAGE(bufoff, gbase) do { _Pragma("unroll") for (int _i = 0; _i < 2; ++_i) \
;         __builtin_amdgcn_global_load_lds((const unsigned*)((const char*)(gbase) + voff[_i]), (LAS unsigned*)(lds + (bufoff) + ldsw + _i * 8192), 16, 0, 0); } while (0)
; #define PG8_WAIT_V(n) asm volatile("s_waitcnt vmcnt(" #n ")" ::: "memory")
; #define PG8_WAIT_L(n) asm volatile("s_waitcnt lgkmcnt(" #n ")" ::: "memory")
; #define PG8_BAR __builtin_amdgcn_s_barrier()
; #define PG8_SCHED __builtin_amdgcn_sched_barrier(0)
;     ...
;             PG8_BAR; PG8_WAIT_L(0); PG8_MMA(1, 0, At, B0); PG8_BAR; PG8_SCHED;
;             PG8_STAGE(PG8_SB(1, 1), b3 + hstep);
;             PG8_WAIT_V(6); PG8_BAR; PG8_MMA(1, 1, At, B1); PG8_BAR;
	s_waitcnt lgkmcnt(0)
	s_setprio 1
	v_mfma_f32_16x16x32_bf16 v[62:65], v[158:161], v[194:197], v[62:65]
	v_mfma_f32_16x16x32_bf16 v[58:61], v[166:169], v[194:197], v[58:61]
	v_mfma_f32_16x16x32_bf16 v[54:57], v[158:161], v[202:205], v[54:57]
	v_mfma_f32_16x16x32_bf16 v[50:53], v[166:169], v[202:205], v[50:53]
	v_mfma_f32_16x16x32_bf16 v[38:41], v[158:161], v[210:213], v[38:41]
	v_mfma_f32_16x16x32_bf16 v[34:37], v[166:169], v[210:213], v[34:37]
	v_mfma_f32_16x16x32_bf16 v[22:25], v[158:161], v[218:221], v[22:25]
	v_mfma_f32_16x16x32_bf16 v[18:21], v[166:169], v[218:221], v[18:21]
	v_mfma_f32_16x16x32_bf16 v[62:65], v[162:165], v[198:201], v[62:65]
	v_mfma_f32_16x16x32_bf16 v[58:61], v[170:173], v[198:201], v[58:61]
	v_mfma_f32_16x16x32_bf16 v[54:57], v[162:165], v[206:209], v[54:57]
	v_mfma_f32_16x16x32_bf16 v[50:53], v[170:173], v[206:209], v[50:53]
	v_mfma_f32_16x16x32_bf16 v[38:41], v[162:165], v[214:217], v[38:41]
	v_mfma_f32_16x16x32_bf16 v[34:37], v[170:173], v[214:217], v[34:37]
	v_mfma_f32_16x16x32_bf16 v[22:25], v[162:165], v[222:225], v[22:25]
	v_mfma_f32_16x16x32_bf16 v[18:21], v[170:173], v[222:225], v[18:21]
	s_setprio 0
	s_barrier
	s_add_u32 s56, s56, 0x40080
	s_addc_u32 s57, s57, 0
	s_add_i32 s0, s1, s16
	v_lshl_add_u64 v[158:159], s[56:57], 0, v[132:133]
	s_mov_b32 m0, s0
	s_nop 0
	global_load_lds_dwordx4 v[158:159], off
	v_lshl_add_u64 v[158:159], s[56:57], 0, v[130:131]
	s_add_i32 m0, s0, 0x2000
	s_nop 0
	global_load_lds_dwordx4 v[158:159], off
	s_waitcnt vmcnt(6)
	s_barrier
	s_setprio 1
	v_mfma_f32_16x16x32_bf16 v[46:49], v[226:229], v[194:197], v[46:49]
	v_mfma_f32_16x16x32_bf16 v[42:45], v[234:237], v[194:197], v[42:45]
	v_mfma_f32_16x16x32_bf16 v[30:33], v[226:229], v[202:205], v[30:33]
	v_mfma_f32_16x16x32_bf16 v[26:29], v[234:237], v[202:205], v[26:29]
	v_mfma_f32_16x16x32_bf16 v[14:17], v[226:229], v[210:213], v[14:17]
	v_mfma_f32_16x16x32_bf16 v[10:13], v[234:237], v[210:213], v[10:13]
	v_mfma_f32_16x16x32_bf16 v[6:9], v[226:229], v[218:221], v[6:9]
	v_mfma_f32_16x16x32_bf16 v[2:5], v[234:237], v[218:221], v[2:5]
	v_mfma_f32_16x16x32_bf16 v[46:49], v[230:233], v[198:201], v[46:49]
	v_mfma_f32_16x16x32_bf16 v[42:45], v[238:241], v[198:201], v[42:45]
	v_mfma_f32_16x16x32_bf16 v[30:33], v[230:233], v[206:209], v[30:33]
	v_mfma_f32_16x16x32_bf16 v[26:29], v[238:241], v[206:209], v[26:29]
	v_mfma_f32_16x16x32_bf16 v[14:17], v[230:233], v[214:217], v[14:17]
	v_mfma_f32_16x16x32_bf16 v[10:13], v[238:241], v[214:217], v[10:13]
	v_mfma_f32_16x16x32_bf16 v[6:9], v[230:233], v[222:225], v[6:9]
	v_mfma_f32_16x16x32_bf16 v[2:5], v[238:241], v[222:225], v[2:5]
	s_setprio 0
	s_add_i32 s62, s62, 2
	s_add_u32 s54, s54, 0x100
	s_addc_u32 s55, s55, 0
	s_add_u32 s60, s60, 0x100
	s_addc_u32 s61, s61, 0
	s_cmp_gt_u32 s62, 13
	s_barrier
	s_cbranch_scc0 .LBB0_904
; #define PG8_WAIT_V(n) asm volatile("s_waitcnt vmcnt(" #n ")" ::: "memory")
; #define PG8_BAR __builtin_amdgcn_s_barrier()
;     ...
;     PG8_WAIT_V(0);
;     if (wr == 0) PG8_BAR;
;     PG8_BAR;
; __device__ __forceinline__ void store_vT(Acc& acc, bf16_t* vT, int chbase, int pm, int wr, int wc, int fr, int fq) {
; #pragma unroll
;     for (int bj = 0; bj < 2; ++bj)
; #pragma unroll
;         for (int n = 0; n < 2; ++n) {
;             bf16_t* rowp = vT + (size_t)(chbase + bj * 128 + wc * 32 + n * 16 + fr) * T_ALL + pm * 256 + wr * 64 + fq * 4;
; #pragma unroll
;             for (int ai = 0; ai < 2; ++ai)
; #pragma unroll
;                 for (int m = 0; m < 4; ++m) {
;                     const f32x4 v = acc[ai][bj][m][n];
;                     u32x2 o = {pack2(v[0], v[1]), pack2(v[2], v[3])};
;                     *reinterpret_cast<u32x2*>(rowp + ai * 128 + m * 16) = o;
;                 }
;         }
; }
	v_lshl_or_b32 v158, s29, 8, v155
	v_ashrrev_i32_e32 v159, 31, v158
	v_lshl_add_u32 v157, s30, 8, v1
	v_lshl_add_u64 v[158:159], v[158:159], 1, s[48:49]
	v_mad_i64_i32 v[160:161], s[30:31], v157, s73, v[158:159]
	v_cvt_pk_bf16_f32 v106, v106, v107
	v_cvt_pk_bf16_f32 v107, v108, v109
	global_store_dwordx2 v[160:161], v[106:107], off offset:288
	v_or_b32_e32 v106, 16, v157
	v_mad_i64_i32 v[106:107], s[30:31], v106, s73, v[158:159]
	v_cvt_pk_bf16_f32 v90, v90, v91
	v_cvt_pk_bf16_f32 v91, v92, v93
	global_store_dwordx2 v[106:107], v[90:91], off offset:288
	v_or_b32_e32 v90, 32, v157
	v_mad_i64_i32 v[90:91], s[30:31], v90, s73, v[158:159]
	v_cvt_pk_bf16_f32 v74, v74, v75
	v_cvt_pk_bf16_f32 v75, v76, v77
	global_store_dwordx2 v[90:91], v[74:75], off offset:288
	v_or_b32_e32 v74, 48, v157
	v_mad_i64_i32 v[74:75], s[30:31], v74, s73, v[158:159]
	v_cvt_pk_bf16_f32 v66, v66, v67
	v_cvt_pk_bf16_f32 v67, v68, v69
	global_store_dwordx2 v[74:75], v[66:67], off offset:288
	v_add_u32_e32 v66, 0x80, v157
	v_mad_i64_i32 v[66:67], s[30:31], v66, s73, v[158:159]
	v_cvt_pk_bf16_f32 v42, v42, v43
	v_cvt_pk_bf16_f32 v43, v44, v45
	global_store_dwordx2 v[66:67], v[42:43], off offset:288
	v_add_u32_e32 v42, 0x90, v157
	v_mad_i64_i32 v[42:43], s[30:31], v42, s73, v[158:159]
	v_cvt_pk_bf16_f32 v26, v26, v27
	v_cvt_pk_bf16_f32 v27, v28, v29
	global_store_dwordx2 v[42:43], v[26:27], off offset:288
	v_add_u32_e32 v26, 0xa0, v157
	v_mad_i64_i32 v[26:27], s[30:31], v26, s73, v[158:159]
	v_cvt_pk_bf16_f32 v10, v10, v11
	v_cvt_pk_bf16_f32 v11, v12, v13
	global_store_dwordx2 v[26:27], v[10:11], off offset:288
	v_add_u32_e32 v10, 0xb0, v157
	v_cvt_pk_bf16_f32 v108, v118, v119
	v_cvt_pk_bf16_f32 v109, v120, v121
	v_cvt_pk_bf16_f32 v92, v102, v103
	v_cvt_pk_bf16_f32 v93, v104, v105
	v_cvt_pk_bf16_f32 v76, v86, v87
	v_cvt_pk_bf16_f32 v77, v88, v89
	v_cvt_pk_bf16_f32 v44, v54, v55
	v_cvt_pk_bf16_f32 v45, v56, v57
	v_cvt_pk_bf16_f32 v28, v38, v39
	v_cvt_pk_bf16_f32 v29, v40, v41
	v_mad_i64_i32 v[10:11], s[30:31], v10, s73, v[158:159]
	v_cvt_pk_bf16_f32 v12, v22, v23
	v_cvt_pk_bf16_f32 v13, v24, v25
	v_cvt_pk_bf16_f32 v126, v126, v127
	v_cvt_pk_bf16_f32 v127, v128, v129
	v_cvt_pk_bf16_f32 v122, v122, v123
	v_cvt_pk_bf16_f32 v123, v124, v125
	v_cvt_pk_bf16_f32 v110, v110, v111
	v_cvt_pk_bf16_f32 v111, v112, v113
	global_store_dwordx2 v[106:107], v[108:109], off
	v_cvt_pk_bf16_f32 v108, v114, v115
	v_cvt_pk_bf16_f32 v109, v116, v117
	v_cvt_pk_bf16_f32 v94, v94, v95
	v_cvt_pk_bf16_f32 v95, v96, v97
	global_store_dwordx2 v[90:91], v[92:93], off
	v_cvt_pk_bf16_f32 v92, v98, v99
	v_cvt_pk_bf16_f32 v93, v100, v101
	v_cvt_pk_bf16_f32 v78, v78, v79
	v_cvt_pk_bf16_f32 v79, v80, v81
	global_store_dwordx2 v[74:75], v[76:77], off
	v_cvt_pk_bf16_f32 v76, v82, v83
	v_cvt_pk_bf16_f32 v77, v84, v85
	v_cvt_pk_bf16_f32 v70, v70, v71
	v_cvt_pk_bf16_f32 v71, v72, v73
	v_cvt_pk_bf16_f32 v62, v62, v63
	v_cvt_pk_bf16_f32 v63, v64, v65
	v_cvt_pk_bf16_f32 v58, v58, v59
	v_cvt_pk_bf16_f32 v59, v60, v61
	v_cvt_pk_bf16_f32 v46, v46, v47
	v_cvt_pk_bf16_f32 v47, v48, v49
	global_store_dwordx2 v[42:43], v[44:45], off
	v_cvt_pk_bf16_f32 v44, v50, v51
	v_cvt_pk_bf16_f32 v45, v52, v53
	v_cvt_pk_bf16_f32 v30, v30, v31
	v_cvt_pk_bf16_f32 v31, v32, v33
	global_store_dwordx2 v[26:27], v[28:29], off
	v_cvt_pk_bf16_f32 v28, v34, v35
	v_cvt_pk_bf16_f32 v29, v36, v37
	v_cvt_pk_bf16_f32 v14, v14, v15
	v_cvt_pk_bf16_f32 v15, v16, v17
	global_store_dwordx2 v[10:11], v[12:13], off
	v_cvt_pk_bf16_f32 v12, v18, v19
	v_cvt_pk_bf16_f32 v13, v20, v21
	v_cvt_pk_bf16_f32 v6, v6, v7
	v_cvt_pk_bf16_f32 v7, v8, v9
	v_cvt_pk_bf16_f32 v2, v2, v3
	v_cvt_pk_bf16_f32 v3, v4, v5
	s_and_b64 vcc, exec, s[44:45]
	s_mov_b32 s29, s12
	s_mov_b32 s30, s14
	s_mov_b64 s[56:57], s[46:47]
	s_mov_b64 s[54:55], s[40:41]
	global_store_dwordx2 v[160:161], v[126:127], off
	global_store_dwordx2 v[160:161], v[122:123], off offset:32
	global_store_dwordx2 v[160:161], v[110:111], off offset:256
	global_store_dwordx2 v[106:107], v[108:109], off offset:32
	global_store_dwordx2 v[106:107], v[94:95], off offset:256
	global_store_dwordx2 v[90:91], v[92:93], off offset:32
	global_store_dwordx2 v[90:91], v[78:79], off offset:256
	global_store_dwordx2 v[74:75], v[76:77], off offset:32
	global_store_dwordx2 v[74:75], v[70:71], off offset:256
	global_store_dwordx2 v[66:67], v[62:63], off
	global_store_dwordx2 v[66:67], v[58:59], off offset:32
	global_store_dwordx2 v[66:67], v[46:47], off offset:256
	global_store_dwordx2 v[42:43], v[44:45], off offset:32
	global_store_dwordx2 v[42:43], v[30:31], off offset:256
	global_store_dwordx2 v[26:27], v[28:29], off offset:32
	global_store_dwordx2 v[26:27], v[14:15], off offset:256
	global_store_dwordx2 v[10:11], v[12:13], off offset:32
	global_store_dwordx2 v[10:11], v[6:7], off offset:256
	global_store_dwordx2 v[10:11], v[2:3], off offset:288
	s_cbranch_vccz .LBB0_901
	s_waitcnt vmcnt(0)
	s_cmpk_gt_u32 s4, 0xff
	s_cbranch_scc1 .LBB0_908
	s_barrier

; #define PG8_STAGE(bufoff, gbase) do { _Pragma("unroll") for (int _i = 0; _i < 2; ++_i) \
;         __builtin_amdgcn_global_load_lds((const unsigned*)((const char*)(gbase) + voff[_i]), (LAS unsigned*)(lds + (bufoff) + ldsw + _i * 8192), 16, 0, 0); } while (0)
; #define PG8_LDA(dst, b, h) do { _Pragma("unroll") for (int m = 0; m < 4; ++m) _Pragma("unroll") for (int k = 0; k < 2; ++k) dst[m][k] = *(const LAS bf16x8*)(lds + PG8_SA(b, h) + aoff + m * 2048 + k * 1024); } while (0)
; #define PG8_LDB(dst, b, h) do { _Pragma("unroll") for (int n = 0; n < 2; ++n) _Pragma("unroll") for (int k = 0; k < 2; ++k) dst[n][k] = *(const LAS bf16x8*)(lds + PG8_SB(b, h) + boff + n * 2048 + k * 1024); } while (0)
; #define PG8_WAIT_V(n) asm volatile("s_waitcnt vmcnt(" #n ")" ::: "memory")
; #define PG8_WAIT_L(n) asm volatile("s_waitcnt lgkmcnt(" #n ")" ::: "memory")
; #define PG8_BAR __builtin_amdgcn_s_barrier()
; #define PG8_SCHED __builtin_amdgcn_sched_barrier(0)
;     ...
;             PG8_LDB(B0, 0, 0); PG8_SCHED; PG8_LDA(At, 0, 0); PG8_STAGE(PG8_SA(1, 1), a1 + hstep);
;             PG8_WAIT_L(8); PG8_BAR; PG8_WAIT_L(0); PG8_MMA(0, 0, At, B0); PG8_BAR; PG8_SCHED;
;             PG8_LDB(B1, 0, 1); PG8_STAGE(PG8_SB(0, 0), b2);
;             PG8_BAR; PG8_WAIT_L(0); PG8_MMA(0, 1, At, B1); PG8_BAR;
;             PG8_LDA(At, 0, 1); PG8_STAGE(PG8_SA(0, 0), a2);
;             PG8_BAR; PG8_WAIT_L(0); PG8_MMA(1, 0, At, B0); PG8_BAR; PG8_SCHED;
;             PG8_STAGE(PG8_SB(0, 1), b2 + hstep);
;             PG8_WAIT_V(6); PG8_BAR; PG8_MMA(1, 1, At, B1); PG8_BAR;
;             PG8_LDB(B0, 1, 0); PG8_SCHED; PG8_LDA(At, 1, 0); PG8_STAGE(PG8_SA(0, 1), a2 + hstep);
;             PG8_WAIT_L(8); PG8_BAR; PG8_WAIT_L(0); PG8_MMA(0, 0, At, B0); PG8_BAR; PG8_SCHED;
;             PG8_LDB(B1, 1, 1); PG8_STAGE(PG8_SB(1, 0), b3);
;             PG8_BAR; PG8_WAIT_L(0); PG8_MMA(0, 1, At, B1); PG8_BAR;
.LBB0_1051:
	s_add_u32 s0, s10, 0xfffc0080
	s_addc_u32 s1, s11, -1
	s_add_i32 s31, 0, 0x10000
	v_add_u32_e32 v161, s31, v158
	ds_read_b128 v[154:157], v161
	ds_read_b128 v[162:165], v161 offset:1024
	ds_read_b128 v[166:169], v161 offset:2048
	ds_read_b128 v[170:173], v161 offset:3072
	s_cmp_eq_u32 s30, 12
	s_cselect_b32 s15, s18, s1
	s_cselect_b32 s14, s19, s0
	s_cselect_b32 s13, s22, s29
	s_cselect_b32 s12, s23, s28
	v_lshl_add_u64 v[174:175], s[10:11], 0, v[150:151]
	s_add_i32 m0, s17, 0xc000
	ds_read_b128 v[194:197], v160
	ds_read_b128 v[198:201], v160 offset:1024
	ds_read_b128 v[202:205], v160 offset:2048
	ds_read_b128 v[206:209], v160 offset:3072
	ds_read_b128 v[210:213], v160 offset:4096
	ds_read_b128 v[214:217], v160 offset:5120
	ds_read_b128 v[218:221], v160 offset:6144
	ds_read_b128 v[222:225], v160 offset:7168
	global_load_lds_dwordx4 v[174:175], off
	v_lshl_add_u64 v[174:175], s[10:11], 0, v[152:153]
	s_add_i32 m0, s17, 0xe000
	s_nop 0
	global_load_lds_dwordx4 v[174:175], off
	s_waitcnt lgkmcnt(8)
	s_barrier
	s_waitcnt lgkmcnt(0)
	s_setprio 1
	v_mfma_f32_16x16x32_bf16 v[126:129], v[154:157], v[194:197], v[126:129]
	v_mfma_f32_16x16x32_bf16 v[122:125], v[166:169], v[194:197], v[122:125]
	v_mfma_f32_16x16x32_bf16 v[110:113], v[154:157], v[202:205], v[110:113]
	v_mfma_f32_16x16x32_bf16 v[106:109], v[166:169], v[202:205], v[106:109]
	v_mfma_f32_16x16x32_bf16 v[94:97], v[154:157], v[210:213], v[94:97]
	v_mfma_f32_16x16x32_bf16 v[90:93], v[166:169], v[210:213], v[90:93]
	v_mfma_f32_16x16x32_bf16 v[78:81], v[154:157], v[218:221], v[78:81]
	v_mfma_f32_16x16x32_bf16 v[74:77], v[166:169], v[218:221], v[74:77]
	v_mfma_f32_16x16x32_bf16 v[126:129], v[162:165], v[198:201], v[126:129]
	v_mfma_f32_16x16x32_bf16 v[122:125], v[170:173], v[198:201], v[122:125]
	v_mfma_f32_16x16x32_bf16 v[110:113], v[162:165], v[206:209], v[110:113]
	v_mfma_f32_16x16x32_bf16 v[106:109], v[170:173], v[206:209], v[106:109]
	v_mfma_f32_16x16x32_bf16 v[94:97], v[162:165], v[214:217], v[94:97]
	v_mfma_f32_16x16x32_bf16 v[90:93], v[170:173], v[214:217], v[90:93]
	v_mfma_f32_16x16x32_bf16 v[78:81], v[162:165], v[222:225], v[78:81]
	v_mfma_f32_16x16x32_bf16 v[74:77], v[170:173], v[222:225], v[74:77]
	s_setprio 0
	s_barrier
	s_add_i32 s0, 0, 0x14000
	s_add_i32 s1, s31, s16
	v_add_u32_e32 v161, s0, v158
	v_lshl_add_u64 v[174:175], s[12:13], 0, v[132:133]
	s_mov_b32 m0, s1
	ds_read_b128 v[226:229], v161
	ds_read_b128 v[230:233], v161 offset:1024
	ds_read_b128 v[234:237], v161 offset:2048
	ds_read_b128 v[238:241], v161 offset:3072
	global_load_lds_dwordx4 v[174:175], off
	v_lshl_add_u64 v[242:243], s[12:13], 0, v[130:131]
	s_add_i32 m0, s1, 0x2000
	s_nop 0
	global_load_lds_dwordx4 v[242:243], off
	s_barrier
	s_waitcnt lgkmcnt(0)
	s_setprio 1
	v_mfma_f32_16x16x32_bf16 v[118:121], v[226:229], v[194:197], v[118:121]
	v_mfma_f32_16x16x32_bf16 v[114:117], v[234:237], v[194:197], v[114:117]
	v_mfma_f32_16x16x32_bf16 v[102:105], v[226:229], v[202:205], v[102:105]
	v_mfma_f32_16x16x32_bf16 v[98:101], v[234:237], v[202:205], v[98:101]
	v_mfma_f32_16x16x32_bf16 v[86:89], v[226:229], v[210:213], v[86:89]
	v_mfma_f32_16x16x32_bf16 v[82:85], v[234:237], v[210:213], v[82:85]
	v_mfma_f32_16x16x32_bf16 v[70:73], v[226:229], v[218:221], v[70:73]
	v_mfma_f32_16x16x32_bf16 v[66:69], v[234:237], v[218:221], v[66:69]
	v_mfma_f32_16x16x32_bf16 v[118:121], v[230:233], v[198:201], v[118:121]
	v_mfma_f32_16x16x32_bf16 v[114:117], v[238:241], v[198:201], v[114:117]
	v_mfma_f32_16x16x32_bf16 v[102:105], v[230:233], v[206:209], v[102:105]
	v_mfma_f32_16x16x32_bf16 v[98:101], v[238:241], v[206:209], v[98:101]
	v_mfma_f32_16x16x32_bf16 v[86:89], v[230:233], v[214:217], v[86:89]
	v_mfma_f32_16x16x32_bf16 v[82:85], v[238:241], v[214:217], v[82:85]
	v_mfma_f32_16x16x32_bf16 v[70:73], v[230:233], v[222:225], v[70:73]
	v_mfma_f32_16x16x32_bf16 v[66:69], v[238:241], v[222:225], v[66:69]
	s_setprio 0
	s_mov_b32 m0, s17
	v_lshl_add_u64 v[244:245], s[14:15], 0, v[132:133]
	s_barrier
	ds_read_b128 v[194:197], v160 offset:16384
	ds_read_b128 v[198:201], v160 offset:17408
	ds_read_b128 v[202:205], v160 offset:18432
	ds_read_b128 v[206:209], v160 offset:19456
	ds_read_b128 v[210:213], v160 offset:20480
	ds_read_b128 v[214:217], v160 offset:21504
	ds_read_b128 v[218:221], v160 offset:22528
	ds_read_b128 v[222:225], v160 offset:23552
	global_load_lds_dwordx4 v[244:245], off
	v_lshl_add_u64 v[246:247], s[14:15], 0, v[130:131]
	s_mov_b32 m0, s40
	s_nop 0
	global_load_lds_dwordx4 v[246:247], off
	s_barrier
	s_waitcnt lgkmcnt(0)
	s_setprio 1
	v_mfma_f32_16x16x32_bf16 v[62:65], v[154:157], v[194:197], v[62:65]
	v_mfma_f32_16x16x32_bf16 v[58:61], v[166:169], v[194:197], v[58:61]
	v_mfma_f32_16x16x32_bf16 v[46:49], v[154:157], v[202:205], v[46:49]
	v_mfma_f32_16x16x32_bf16 v[42:45], v[166:169], v[202:205], v[42:45]
	v_mfma_f32_16x16x32_bf16 v[30:33], v[154:157], v[210:213], v[30:33]
	v_mfma_f32_16x16x32_bf16 v[26:29], v[166:169], v[210:213], v[26:29]
	v_mfma_f32_16x16x32_bf16 v[14:17], v[154:157], v[218:221], v[14:17]
	v_mfma_f32_16x16x32_bf16 v[10:13], v[166:169], v[218:221], v[10:13]
	v_mfma_f32_16x16x32_bf16 v[62:65], v[162:165], v[198:201], v[62:65]
	v_mfma_f32_16x16x32_bf16 v[58:61], v[170:173], v[198:201], v[58:61]
	v_mfma_f32_16x16x32_bf16 v[46:49], v[162:165], v[206:209], v[46:49]
	v_mfma_f32_16x16x32_bf16 v[42:45], v[170:173], v[206:209], v[42:45]
	v_mfma_f32_16x16x32_bf16 v[30:33], v[162:165], v[214:217], v[30:33]
	v_mfma_f32_16x16x32_bf16 v[26:29], v[170:173], v[214:217], v[26:29]
	v_mfma_f32_16x16x32_bf16 v[14:17], v[162:165], v[222:225], v[14:17]
	v_mfma_f32_16x16x32_bf16 v[10:13], v[170:173], v[222:225], v[10:13]
	s_setprio 0
	s_barrier
; #define PG8_STAGE(bufoff, gbase) do { _Pragma("unroll") for (int _i = 0; _i < 2; ++_i) \
;         __builtin_amdgcn_global_load_lds((const unsigned*)((const char*)(gbase) + voff[_i]), (LAS unsigned*)(lds + (bufoff) + ldsw + _i * 8192), 16, 0, 0); } while (0)
; #define PG8_LDA(dst, b, h) do { _Pragma("unroll") for (int m = 0; m < 4; ++m) _Pragma("unroll") for (int k = 0; k < 2; ++k) dst[m][k] = *(const LAS bf16x8*)(lds + PG8_SA(b, h) + aoff + m * 2048 + k * 1024); } while (0)
; #define PG8_LDB(dst, b, h) do { _Pragma("unroll") for (int n = 0; n < 2; ++n) _Pragma("unroll") for (int k = 0; k < 2; ++k) dst[n][k] = *(const LAS bf16x8*)(lds + PG8_SB(b, h) + boff + n * 2048 + k * 1024); } while (0)
; #define PG8_WAIT_V(n) asm volatile("s_waitcnt vmcnt(" #n ")" ::: "memory")
; #define PG8_WAIT_L(n) asm volatile("s_waitcnt lgkmcnt(" #n ")" ::: "memory")
; #define PG8_BAR __builtin_amdgcn_s_barrier()
; #define PG8_SCHED __builtin_amdgcn_sched_barrier(0)
;     ...
;             PG8_STAGE(PG8_SB(0, 1), b2 + hstep);
;             PG8_WAIT_V(6); PG8_BAR; PG8_MMA(1, 1, At, B1); PG8_BAR;
;             PG8_LDB(B0, 1, 0); PG8_SCHED; PG8_LDA(At, 1, 0); PG8_STAGE(PG8_SA(0, 1), a2 + hstep);
;             PG8_WAIT_L(8); PG8_BAR; PG8_WAIT_L(0); PG8_MMA(0, 0, At, B0); PG8_BAR; PG8_SCHED;
;             PG8_LDB(B1, 1, 1); PG8_STAGE(PG8_SB(1, 0), b3);
;             PG8_BAR; PG8_WAIT_L(0); PG8_MMA(0, 1, At, B1); PG8_BAR;
;             PG8_LDA(At, 1, 1); PG8_STAGE(PG8_SA(1, 0), a3);
;             PG8_BAR; PG8_WAIT_L(0); PG8_MMA(1, 0, At, B0); PG8_BAR; PG8_SCHED;
	s_add_u32 s70, s12, 0x40000
	s_addc_u32 s71, s13, 0
	s_add_i32 s0, s0, s16
	v_lshl_add_u64 v[154:155], s[70:71], 0, v[132:133]
	s_mov_b32 m0, s0
	s_nop 0
	global_load_lds_dwordx4 v[154:155], off
	v_lshl_add_u64 v[154:155], s[70:71], 0, v[130:131]
	s_add_i32 m0, s0, 0x2000
	s_nop 0
	global_load_lds_dwordx4 v[154:155], off
	s_waitcnt vmcnt(6)
	s_barrier
	s_setprio 1
	v_mfma_f32_16x16x32_bf16 v[54:57], v[226:229], v[194:197], v[54:57]
	v_mfma_f32_16x16x32_bf16 v[50:53], v[234:237], v[194:197], v[50:53]
	v_mfma_f32_16x16x32_bf16 v[38:41], v[226:229], v[202:205], v[38:41]
	v_mfma_f32_16x16x32_bf16 v[34:37], v[234:237], v[202:205], v[34:37]
	v_mfma_f32_16x16x32_bf16 v[22:25], v[226:229], v[210:213], v[22:25]
	v_mfma_f32_16x16x32_bf16 v[18:21], v[234:237], v[210:213], v[18:21]
	v_mfma_f32_16x16x32_bf16 v[6:9], v[226:229], v[218:221], v[6:9]
	v_mfma_f32_16x16x32_bf16 v[2:5], v[234:237], v[218:221], v[2:5]
	v_mfma_f32_16x16x32_bf16 v[54:57], v[230:233], v[198:201], v[54:57]
	v_mfma_f32_16x16x32_bf16 v[50:53], v[238:241], v[198:201], v[50:53]
	v_mfma_f32_16x16x32_bf16 v[38:41], v[230:233], v[206:209], v[38:41]
	v_mfma_f32_16x16x32_bf16 v[34:37], v[238:241], v[206:209], v[34:37]
	v_mfma_f32_16x16x32_bf16 v[22:25], v[230:233], v[214:217], v[22:25]
	v_mfma_f32_16x16x32_bf16 v[18:21], v[238:241], v[214:217], v[18:21]
	v_mfma_f32_16x16x32_bf16 v[6:9], v[230:233], v[222:225], v[6:9]
	v_mfma_f32_16x16x32_bf16 v[2:5], v[238:241], v[222:225], v[2:5]
	s_setprio 0
	s_add_i32 s0, 0, 0x18000
	v_add_u32_e32 v161, s0, v158
	s_barrier
	ds_read_b128 v[154:157], v161
	ds_read_b128 v[162:165], v161 offset:1024
	ds_read_b128 v[166:169], v161 offset:2048
	ds_read_b128 v[170:173], v161 offset:3072
	s_add_u32 s14, s14, 0x40000
	s_addc_u32 s15, s15, 0
	s_mov_b32 m0, s41
	v_lshl_add_u64 v[226:227], s[14:15], 0, v[132:133]
	ds_read_b128 v[194:197], v160 offset:32768
	ds_read_b128 v[198:201], v160 offset:33792
	ds_read_b128 v[202:205], v160 offset:34816
	ds_read_b128 v[206:209], v160 offset:35840
	ds_read_b128 v[210:213], v160 offset:36864
	ds_read_b128 v[214:217], v160 offset:37888
	ds_read_b128 v[218:221], v160 offset:38912
	ds_read_b128 v[222:225], v160 offset:39936
	global_load_lds_dwordx4 v[226:227], off
	v_lshl_add_u64 v[226:227], s[14:15], 0, v[130:131]
	s_mov_b32 m0, s66
	s_nop 0
	global_load_lds_dwordx4 v[226:227], off
	s_waitcnt lgkmcnt(8)
	s_barrier
	s_waitcnt lgkmcnt(0)
	s_setprio 1
	v_mfma_f32_16x16x32_bf16 v[126:129], v[154:157], v[194:197], v[126:129]
	v_mfma_f32_16x16x32_bf16 v[122:125], v[166:169], v[194:197], v[122:125]
	v_mfma_f32_16x16x32_bf16 v[110:113], v[154:157], v[202:205], v[110:113]
	v_mfma_f32_16x16x32_bf16 v[106:109], v[166:169], v[202:205], v[106:109]
	v_mfma_f32_16x16x32_bf16 v[94:97], v[154:157], v[210:213], v[94:97]
	v_mfma_f32_16x16x32_bf16 v[90:93], v[166:169], v[210:213], v[90:93]
	v_mfma_f32_16x16x32_bf16 v[78:81], v[154:157], v[218:221], v[78:81]
	v_mfma_f32_16x16x32_bf16 v[74:77], v[166:169], v[218:221], v[74:77]
	v_mfma_f32_16x16x32_bf16 v[126:129], v[162:165], v[198:201], v[126:129]
	v_mfma_f32_16x16x32_bf16 v[122:125], v[170:173], v[198:201], v[122:125]
	v_mfma_f32_16x16x32_bf16 v[110:113], v[162:165], v[206:209], v[110:113]
	v_mfma_f32_16x16x32_bf16 v[106:109], v[170:173], v[206:209], v[106:109]
	v_mfma_f32_16x16x32_bf16 v[94:97], v[162:165], v[214:217], v[94:97]
	v_mfma_f32_16x16x32_bf16 v[90:93], v[170:173], v[214:217], v[90:93]
	v_mfma_f32_16x16x32_bf16 v[78:81], v[162:165], v[222:225], v[78:81]
	v_mfma_f32_16x16x32_bf16 v[74:77], v[170:173], v[222:225], v[74:77]
	s_setprio 0
	s_barrier
	s_add_i32 s1, 0, 0x1c000
	s_add_i32 s0, s0, s16
	v_add_u32_e32 v161, s1, v158
	v_lshl_add_u64 v[174:175], v[174:175], 0, s[88:89]
	s_mov_b32 m0, s0
	ds_read_b128 v[226:229], v161
	ds_read_b128 v[230:233], v161 offset:1024
	ds_read_b128 v[234:237], v161 offset:2048
	ds_read_b128 v[238:241], v161 offset:3072
	global_load_lds_dwordx4 v[174:175], off
	v_lshl_add_u64 v[174:175], v[242:243], 0, s[88:89]
	s_add_i32 m0, s0, 0x2000
	s_nop 0
	global_load_lds_dwordx4 v[174:175], off
	s_barrier
	s_waitcnt lgkmcnt(0)
	s_setprio 1
	v_mfma_f32_16x16x32_bf16 v[118:121], v[226:229], v[194:197], v[118:121]
	v_mfma_f32_16x16x32_bf16 v[114:117], v[234:237], v[194:197], v[114:117]
	v_mfma_f32_16x16x32_bf16 v[102:105], v[226:229], v[202:205], v[102:105]
	v_mfma_f32_16x16x32_bf16 v[98:101], v[234:237], v[202:205], v[98:101]
	v_mfma_f32_16x16x32_bf16 v[86:89], v[226:229], v[210:213], v[86:89]
	v_mfma_f32_16x16x32_bf16 v[82:85], v[234:237], v[210:213], v[82:85]
	v_mfma_f32_16x16x32_bf16 v[70:73], v[226:229], v[218:221], v[70:73]
	v_mfma_f32_16x16x32_bf16 v[66:69], v[234:237], v[218:221], v[66:69]
	v_mfma_f32_16x16x32_bf16 v[118:121], v[230:233], v[198:201], v[118:121]
	v_mfma_f32_16x16x32_bf16 v[114:117], v[238:241], v[198:201], v[114:117]
	v_mfma_f32_16x16x32_bf16 v[102:105], v[230:233], v[206:209], v[102:105]
	v_mfma_f32_16x16x32_bf16 v[98:101], v[238:241], v[206:209], v[98:101]
	v_mfma_f32_16x16x32_bf16 v[86:89], v[230:233], v[214:217], v[86:89]
	v_mfma_f32_16x16x32_bf16 v[82:85], v[238:241], v[214:217], v[82:85]
	v_mfma_f32_16x16x32_bf16 v[70:73], v[230:233], v[222:225], v[70:73]
	v_mfma_f32_16x16x32_bf16 v[66:69], v[238:241], v[222:225], v[66:69]
	s_setprio 0
	s_mov_b32 m0, s67
	v_lshl_add_u64 v[174:175], v[244:245], 0, s[88:89]
	s_barrier
	ds_read_b128 v[194:197], v160 offset:49152
	ds_read_b128 v[198:201], v160 offset:50176
	ds_read_b128 v[202:205], v160 offset:51200
	ds_read_b128 v[206:209], v160 offset:52224
	ds_read_b128 v[210:213], v160 offset:53248
	ds_read_b128 v[214:217], v160 offset:54272
	ds_read_b128 v[218:221], v160 offset:55296
	ds_read_b128 v[222:225], v160 offset:56320
	global_load_lds_dwordx4 v[174:175], off
	v_lshl_add_u64 v[174:175], v[246:247], 0, s[88:89]
	s_mov_b32 m0, s68
	s_nop 0
	global_load_lds_dwordx4 v[174:175], off
	s_barrier
; #define PG8_STAGE(bufoff, gbase) do { _Pragma("unroll") for (int _i = 0; _i < 2; ++_i) \
;         __builtin_amdgcn_global_load_lds((const unsigned*)((const char*)(gbase) + voff[_i]), (LAS unsigned*)(lds + (bufoff) + ldsw + _i * 8192), 16, 0, 0); } while (0)
; #define PG8_WAIT_V(n) asm volatile("s_waitcnt vmcnt(" #n ")" ::: "memory")
; #define PG8_WAIT_L(n) asm volatile("s_waitcnt lgkmcnt(" #n ")" ::: "memory")
; #define PG8_BAR __builtin_amdgcn_s_barrier()
; #define PG8_SCHED __builtin_amdgcn_sched_barrier(0)
;     ...
;             PG8_BAR; PG8_WAIT_L(0); PG8_MMA(1, 0, At, B0); PG8_BAR; PG8_SCHED;
;             PG8_STAGE(PG8_SB(1, 1), b3 + hstep);
;             PG8_WAIT_V(6); PG8_BAR; PG8_MMA(1, 1, At, B1); PG8_BAR;
;     __device__ __forceinline__ void operator()(Acc& acc, int pm, int pn, int wr, int wc, int fr, int fq) const {
;     ...
;         for (int ai = 0; ai < 2; ++ai)
; #pragma unroll
;             for (int m = 0; m < 4; ++m) {
;                 const size_t ro = (size_t)(pm * 256 + ai * 128 + wr * 64 + m * 16 + fr) * DRNN + cb;
; #pragma unroll
;                 for (int bj = 0; bj < 2; ++bj)
; #pragma unroll
;                     for (int n = 0; n < 2; ++n) {
;                         f32x4 v = acc[ai][bj][m][n];
;                         if (isg) { v[0] = gelu_tanh(v[0]); v[1] = gelu_tanh(v[1]); v[2] = gelu_tanh(v[2]); v[3] = gelu_tanh(v[3]); }
;                         u32x2 o = {pack2(v[0], v[1]), pack2(v[2], v[3])};
;                         *reinterpret_cast<u32x2*>(base + ro + bj * 128 + n * 16) = o;
	s_waitcnt lgkmcnt(0)
	s_setprio 1
	v_mfma_f32_16x16x32_bf16 v[62:65], v[154:157], v[194:197], v[62:65]
	v_mfma_f32_16x16x32_bf16 v[58:61], v[166:169], v[194:197], v[58:61]
	v_mfma_f32_16x16x32_bf16 v[46:49], v[154:157], v[202:205], v[46:49]
	v_mfma_f32_16x16x32_bf16 v[42:45], v[166:169], v[202:205], v[42:45]
	v_mfma_f32_16x16x32_bf16 v[30:33], v[154:157], v[210:213], v[30:33]
	v_mfma_f32_16x16x32_bf16 v[26:29], v[166:169], v[210:213], v[26:29]
	v_mfma_f32_16x16x32_bf16 v[14:17], v[154:157], v[218:221], v[14:17]
	v_mfma_f32_16x16x32_bf16 v[10:13], v[166:169], v[218:221], v[10:13]
	v_mfma_f32_16x16x32_bf16 v[62:65], v[162:165], v[198:201], v[62:65]
	v_mfma_f32_16x16x32_bf16 v[58:61], v[170:173], v[198:201], v[58:61]
	v_mfma_f32_16x16x32_bf16 v[46:49], v[162:165], v[206:209], v[46:49]
	v_mfma_f32_16x16x32_bf16 v[42:45], v[170:173], v[206:209], v[42:45]
	v_mfma_f32_16x16x32_bf16 v[30:33], v[162:165], v[214:217], v[30:33]
	v_mfma_f32_16x16x32_bf16 v[26:29], v[170:173], v[214:217], v[26:29]
	v_mfma_f32_16x16x32_bf16 v[14:17], v[162:165], v[222:225], v[14:17]
	v_mfma_f32_16x16x32_bf16 v[10:13], v[170:173], v[222:225], v[10:13]
	s_setprio 0
	s_barrier
	s_add_u32 s12, s12, 0x40080
	s_addc_u32 s13, s13, 0
	s_add_i32 s0, s1, s16
	v_lshl_add_u64 v[154:155], s[12:13], 0, v[132:133]
	s_mov_b32 m0, s0
	s_nop 0
	global_load_lds_dwordx4 v[154:155], off
	v_lshl_add_u64 v[154:155], s[12:13], 0, v[130:131]
	s_add_i32 m0, s0, 0x2000
	s_nop 0
	global_load_lds_dwordx4 v[154:155], off
	s_waitcnt vmcnt(6)
	s_barrier
	s_setprio 1
	v_mfma_f32_16x16x32_bf16 v[54:57], v[226:229], v[194:197], v[54:57]
	v_mfma_f32_16x16x32_bf16 v[50:53], v[234:237], v[194:197], v[50:53]
	v_mfma_f32_16x16x32_bf16 v[38:41], v[226:229], v[202:205], v[38:41]
	v_mfma_f32_16x16x32_bf16 v[34:37], v[234:237], v[202:205], v[34:37]
	v_mfma_f32_16x16x32_bf16 v[22:25], v[226:229], v[210:213], v[22:25]
	v_mfma_f32_16x16x32_bf16 v[18:21], v[234:237], v[210:213], v[18:21]
	v_mfma_f32_16x16x32_bf16 v[6:9], v[226:229], v[218:221], v[6:9]
	v_mfma_f32_16x16x32_bf16 v[2:5], v[234:237], v[218:221], v[2:5]
	v_mfma_f32_16x16x32_bf16 v[54:57], v[230:233], v[198:201], v[54:57]
	v_mfma_f32_16x16x32_bf16 v[50:53], v[238:241], v[198:201], v[50:53]
	v_mfma_f32_16x16x32_bf16 v[38:41], v[230:233], v[206:209], v[38:41]
	v_mfma_f32_16x16x32_bf16 v[34:37], v[238:241], v[206:209], v[34:37]
	v_mfma_f32_16x16x32_bf16 v[22:25], v[230:233], v[214:217], v[22:25]
	v_mfma_f32_16x16x32_bf16 v[18:21], v[238:241], v[214:217], v[18:21]
	v_mfma_f32_16x16x32_bf16 v[6:9], v[230:233], v[222:225], v[6:9]
	v_mfma_f32_16x16x32_bf16 v[2:5], v[238:241], v[222:225], v[2:5]
	s_setprio 0
	s_add_i32 s30, s30, 2
	s_add_u32 s10, s10, 0x100
	s_addc_u32 s11, s11, 0
	s_add_u32 s28, s28, 0x100
	s_addc_u32 s29, s29, 0
	s_cmp_gt_u32 s30, 13
	s_barrier
	s_cbranch_scc0 .LBB0_1051
	v_mul_f32_e32 v162, 0x3d372713, v126
	v_mul_f32_e32 v162, v126, v162
	v_fma_f32 v162, v126, v162, v126
	v_mul_f32_e32 v162, 0xbfcc422a, v162
	v_mul_f32_e32 v162, 0x3fb8aa3b, v162
	v_exp_f32_e32 v162, v162
	v_lshl_or_b32 v154, s4, 8, v159
	v_ashrrev_i32_e32 v155, 31, v154
	v_lshl_add_u32 v161, s7, 8, v1
	v_add_f32_e32 v162, 1.0, v162
	v_rcp_f32_e32 v162, v162
	v_lshl_add_u64 v[154:155], v[154:155], 1, s[50:51]
	v_mad_i64_i32 v[156:157], s[10:11], v161, s73, v[154:155]
	v_mul_f32_e32 v126, v126, v162
	v_mul_f32_e32 v162, 0x3d372713, v127
	v_mul_f32_e32 v162, v127, v162
	v_fma_f32 v162, v127, v162, v127
	v_mul_f32_e32 v162, 0xbfcc422a, v162
	v_mul_f32_e32 v162, 0x3fb8aa3b, v162
	v_exp_f32_e32 v162, v162
	s_and_b64 vcc, exec, s[44:45]
	s_mov_b32 s4, s48
	s_mov_b32 s7, s60
	v_add_f32_e32 v162, 1.0, v162
	v_rcp_f32_e32 v162, v162
	s_mov_b64 s[12:13], s[64:65]
	v_mul_f32_e32 v127, v127, v162
	v_mul_f32_e32 v162, 0x3d372713, v128
	v_mul_f32_e32 v162, v128, v162
	v_fma_f32 v162, v128, v162, v128
	v_mul_f32_e32 v162, 0xbfcc422a, v162
	v_mul_f32_e32 v162, 0x3fb8aa3b, v162
	v_exp_f32_e32 v162, v162
	v_cvt_pk_bf16_f32 v126, v126, v127
	v_add_f32_e32 v162, 1.0, v162
	v_rcp_f32_e32 v162, v162
	s_nop 0
	v_mul_f32_e32 v128, v128, v162
	v_mul_f32_e32 v162, 0x3d372713, v129
	v_mul_f32_e32 v162, v129, v162
	v_fma_f32 v162, v129, v162, v129
	v_mul_f32_e32 v162, 0xbfcc422a, v162
	v_mul_f32_e32 v162, 0x3fb8aa3b, v162
	v_exp_f32_e32 v162, v162
	s_nop 0
	v_add_f32_e32 v162, 1.0, v162
	v_rcp_f32_e32 v162, v162
	s_nop 0
	v_mul_f32_e32 v129, v129, v162
	v_cvt_pk_bf16_f32 v127, v128, v129
	global_store_dwordx2 v[156:157], v[126:127], off
	v_mul_f32_e32 v126, 0x3d372713, v122
	v_mul_f32_e32 v126, v122, v126
	v_fma_f32 v126, v122, v126, v122
	v_mul_f32_e32 v126, 0xbfcc422a, v126
	v_mul_f32_e32 v126, 0x3fb8aa3b, v126
	v_exp_f32_e32 v126, v126
	s_nop 0
	v_add_f32_e32 v126, 1.0, v126
	v_rcp_f32_e32 v126, v126
	s_nop 0
	v_mul_f32_e32 v122, v122, v126
	v_mul_f32_e32 v126, 0x3d372713, v123
	v_mul_f32_e32 v126, v123, v126
	v_fma_f32 v126, v123, v126, v123
	v_mul_f32_e32 v126, 0xbfcc422a, v126
	v_mul_f32_e32 v126, 0x3fb8aa3b, v126
	v_exp_f32_e32 v126, v126
	s_nop 0
	v_add_f32_e32 v126, 1.0, v126
	v_rcp_f32_e32 v126, v126
	s_nop 0
	v_mul_f32_e32 v123, v123, v126
	v_mul_f32_e32 v126, 0x3d372713, v124
	v_mul_f32_e32 v126, v124, v126
	v_fma_f32 v126, v124, v126, v124
	v_mul_f32_e32 v126, 0xbfcc422a, v126
	v_mul_f32_e32 v126, 0x3fb8aa3b, v126
	v_exp_f32_e32 v126, v126
	v_cvt_pk_bf16_f32 v122, v122, v123
	v_add_f32_e32 v126, 1.0, v126
	v_rcp_f32_e32 v126, v126
	s_nop 0
	v_mul_f32_e32 v124, v124, v126
	v_mul_f32_e32 v126, 0x3d372713, v125
	v_mul_f32_e32 v126, v125, v126
	v_fma_f32 v126, v125, v126, v125
	v_mul_f32_e32 v126, 0xbfcc422a, v126
	v_mul_f32_e32 v126, 0x3fb8aa3b, v126
	v_exp_f32_e32 v126, v126
	s_nop 0
;     __device__ __forceinline__ void operator()(Acc& acc, int pm, int pn, int wr, int wc, int fr, int fq) const {
;     ...
;         for (int ai = 0; ai < 2; ++ai)
; #pragma unroll
;             for (int m = 0; m < 4; ++m) {
;                 const size_t ro = (size_t)(pm * 256 + ai * 128 + wr * 64 + m * 16 + fr) * DRNN + cb;
; #pragma unroll
;                 for (int bj = 0; bj < 2; ++bj)
; #pragma unroll
;                     for (int n = 0; n < 2; ++n) {
;                         f32x4 v = acc[ai][bj][m][n];
;                         if (isg) { v[0] = gelu_tanh(v[0]); v[1] = gelu_tanh(v[1]); v[2] = gelu_tanh(v[2]); v[3] = gelu_tanh(v[3]); }
;                         u32x2 o = {pack2(v[0], v[1]), pack2(v[2], v[3])};
;                         *reinterpret_cast<u32x2*>(base + ro + bj * 128 + n * 16) = o;
	v_add_f32_e32 v126, 1.0, v126
	v_rcp_f32_e32 v126, v126
	s_nop 0
	v_mul_f32_e32 v125, v125, v126
	v_cvt_pk_bf16_f32 v123, v124, v125
	global_store_dwordx2 v[156:157], v[122:123], off offset:32
	v_mul_f32_e32 v122, 0x3d372713, v118
	v_mul_f32_e32 v122, v118, v122
	v_fma_f32 v122, v118, v122, v118
	v_mul_f32_e32 v122, 0xbfcc422a, v122
	v_mul_f32_e32 v122, 0x3fb8aa3b, v122
	v_exp_f32_e32 v122, v122
	s_nop 0
	v_add_f32_e32 v122, 1.0, v122
	v_rcp_f32_e32 v122, v122
	s_nop 0
	v_mul_f32_e32 v118, v118, v122
	v_mul_f32_e32 v122, 0x3d372713, v119
	v_mul_f32_e32 v122, v119, v122
	v_fma_f32 v122, v119, v122, v119
	v_mul_f32_e32 v122, 0xbfcc422a, v122
	v_mul_f32_e32 v122, 0x3fb8aa3b, v122
	v_exp_f32_e32 v122, v122
	s_nop 0
	v_add_f32_e32 v122, 1.0, v122
	v_rcp_f32_e32 v122, v122
	s_nop 0
	v_mul_f32_e32 v119, v119, v122
	v_mul_f32_e32 v122, 0x3d372713, v120
	v_mul_f32_e32 v122, v120, v122
	v_fma_f32 v122, v120, v122, v120
	v_mul_f32_e32 v122, 0xbfcc422a, v122
	v_mul_f32_e32 v122, 0x3fb8aa3b, v122
	v_exp_f32_e32 v122, v122
	v_cvt_pk_bf16_f32 v118, v118, v119
	v_add_f32_e32 v122, 1.0, v122
	v_rcp_f32_e32 v122, v122
	s_nop 0
	v_mul_f32_e32 v120, v120, v122
	v_mul_f32_e32 v122, 0x3d372713, v121
	v_mul_f32_e32 v122, v121, v122
	v_fma_f32 v122, v121, v122, v121
	v_mul_f32_e32 v122, 0xbfcc422a, v122
	v_mul_f32_e32 v122, 0x3fb8aa3b, v122
	v_exp_f32_e32 v122, v122
	s_nop 0
	v_add_f32_e32 v122, 1.0, v122
	v_rcp_f32_e32 v122, v122
	s_nop 0
	v_mul_f32_e32 v121, v121, v122
	v_cvt_pk_bf16_f32 v119, v120, v121
	global_store_dwordx2 v[156:157], v[118:119], off offset:256
	v_mul_f32_e32 v118, 0x3d372713, v114
	v_mul_f32_e32 v118, v114, v118
	v_fma_f32 v118, v114, v118, v114
	v_mul_f32_e32 v118, 0xbfcc422a, v118
	v_mul_f32_e32 v118, 0x3fb8aa3b, v118
	v_exp_f32_e32 v118, v118
	s_nop 0
	v_add_f32_e32 v118, 1.0, v118
	v_rcp_f32_e32 v118, v118
	s_nop 0
	v_mul_f32_e32 v114, v114, v118
	v_mul_f32_e32 v118, 0x3d372713, v115
	v_mul_f32_e32 v118, v115, v118
	v_fma_f32 v118, v115, v118, v115
	v_mul_f32_e32 v118, 0xbfcc422a, v118
	v_mul_f32_e32 v118, 0x3fb8aa3b, v118
	v_exp_f32_e32 v118, v118
	s_nop 0
	v_add_f32_e32 v118, 1.0, v118
	v_rcp_f32_e32 v118, v118
	s_nop 0
	v_mul_f32_e32 v115, v115, v118
	v_mul_f32_e32 v118, 0x3d372713, v116
	v_mul_f32_e32 v118, v116, v118
	v_fma_f32 v118, v116, v118, v116
	v_mul_f32_e32 v118, 0xbfcc422a, v118
	v_mul_f32_e32 v118, 0x3fb8aa3b, v118
	v_exp_f32_e32 v118, v118
	v_cvt_pk_bf16_f32 v114, v114, v115
	v_add_f32_e32 v118, 1.0, v118
	v_rcp_f32_e32 v118, v118
	s_nop 0
	v_mul_f32_e32 v116, v116, v118
	v_mul_f32_e32 v118, 0x3d372713, v117
	v_mul_f32_e32 v118, v117, v118
	v_fma_f32 v118, v117, v118, v117
	v_mul_f32_e32 v118, 0xbfcc422a, v118
	v_mul_f32_e32 v118, 0x3fb8aa3b, v118
	v_exp_f32_e32 v118, v118
	s_nop 0
	v_add_f32_e32 v118, 1.0, v118
	v_rcp_f32_e32 v118, v118
	s_nop 0
	v_mul_f32_e32 v117, v117, v118
	v_cvt_pk_bf16_f32 v115, v116, v117
	v_mul_f32_e32 v116, 0x3d372713, v110
	v_mul_f32_e32 v116, v110, v116
	v_fma_f32 v116, v110, v116, v110
	v_mul_f32_e32 v116, 0xbfcc422a, v116
	v_mul_f32_e32 v116, 0x3fb8aa3b, v116
	v_exp_f32_e32 v116, v116
	global_store_dwordx2 v[156:157], v[114:115], off offset:288
	v_or_b32_e32 v114, 16, v161
	v_mad_i64_i32 v[114:115], s[10:11], v114, s73, v[154:155]
	v_add_f32_e32 v116, 1.0, v116
	v_rcp_f32_e32 v116, v116
	s_nop 0
	v_mul_f32_e32 v110, v110, v116
	v_mul_f32_e32 v116, 0x3d372713, v111
	v_mul_f32_e32 v116, v111, v116
	v_fma_f32 v116, v111, v116, v111
	v_mul_f32_e32 v116, 0xbfcc422a, v116
	v_mul_f32_e32 v116, 0x3fb8aa3b, v116
	v_exp_f32_e32 v116, v116
	s_nop 0
	v_add_f32_e32 v116, 1.0, v116
	v_rcp_f32_e32 v116, v116
	s_nop 0
	v_mul_f32_e32 v111, v111, v116
	v_mul_f32_e32 v116, 0x3d372713, v112
	v_mul_f32_e32 v116, v112, v116
	v_fma_f32 v116, v112, v116, v112
	v_mul_f32_e32 v116, 0xbfcc422a, v116
	v_mul_f32_e32 v116, 0x3fb8aa3b, v116
	v_exp_f32_e32 v116, v116
	v_cvt_pk_bf16_f32 v110, v110, v111
	v_add_f32_e32 v116, 1.0, v116
	v_rcp_f32_e32 v116, v116
	s_nop 0
	v_mul_f32_e32 v112, v112, v116
	v_mul_f32_e32 v116, 0x3d372713, v113
	v_mul_f32_e32 v116, v113, v116
	v_fma_f32 v116, v113, v116, v113
	v_mul_f32_e32 v116, 0xbfcc422a, v116
	v_mul_f32_e32 v116, 0x3fb8aa3b, v116
	v_exp_f32_e32 v116, v116
	s_nop 0
	v_add_f32_e32 v116, 1.0, v116
	v_rcp_f32_e32 v116, v116
	s_nop 0
	v_mul_f32_e32 v113, v113, v116
	v_cvt_pk_bf16_f32 v111, v112, v113
	global_store_dwordx2 v[114:115], v[110:111], off
	v_mul_f32_e32 v110, 0x3d372713, v106
	v_mul_f32_e32 v110, v106, v110
	v_fma_f32 v110, v106, v110, v106
	v_mul_f32_e32 v110, 0xbfcc422a, v110
	v_mul_f32_e32 v110, 0x3fb8aa3b, v110
	v_exp_f32_e32 v110, v110
	s_nop 0
	v_add_f32_e32 v110, 1.0, v110
	v_rcp_f32_e32 v110, v110
	s_nop 0
	v_mul_f32_e32 v106, v106, v110
	v_mul_f32_e32 v110, 0x3d372713, v107
	v_mul_f32_e32 v110, v107, v110
	v_fma_f32 v110, v107, v110, v107
	v_mul_f32_e32 v110, 0xbfcc422a, v110
	v_mul_f32_e32 v110, 0x3fb8aa3b, v110
	v_exp_f32_e32 v110, v110
	s_nop 0
	v_add_f32_e32 v110, 1.0, v110
	v_rcp_f32_e32 v110, v110
	s_nop 0
	v_mul_f32_e32 v107, v107, v110
	v_mul_f32_e32 v110, 0x3d372713, v108
	v_mul_f32_e32 v110, v108, v110
	v_fma_f32 v110, v108, v110, v108
	v_mul_f32_e32 v110, 0xbfcc422a, v110
	v_mul_f32_e32 v110, 0x3fb8aa3b, v110
	v_exp_f32_e32 v110, v110
	v_cvt_pk_bf16_f32 v106, v106, v107
	v_add_f32_e32 v110, 1.0, v110
	v_rcp_f32_e32 v110, v110
	s_nop 0
	v_mul_f32_e32 v108, v108, v110
	v_mul_f32_e32 v110, 0x3d372713, v109
	v_mul_f32_e32 v110, v109, v110
	v_fma_f32 v110, v109, v110, v109
	v_mul_f32_e32 v110, 0xbfcc422a, v110
	v_mul_f32_e32 v110, 0x3fb8aa3b, v110
	v_exp_f32_e32 v110, v110
	s_nop 0
	v_add_f32_e32 v110, 1.0, v110
	v_rcp_f32_e32 v110, v110
	s_nop 0
; __device__ __forceinline__ float frcp(float x) { return __builtin_amdgcn_rcpf(x); }
; __device__ __forceinline__ float fexp(float x) { return __builtin_amdgcn_exp2f(x * 1.4426950408889634f); }
; __device__ __forceinline__ float gelu_tanh(float x) {
;     float u = 1.5957691216057308f * (x + 0.044715f * x * x * x);
;     return x * frcp(1.0f + fexp(-u));
; }
;     __device__ __forceinline__ void operator()(Acc& acc, int pm, int pn, int wr, int wc, int fr, int fq) const {
;     ...
;         for (int ai = 0; ai < 2; ++ai)
; #pragma unroll
;             for (int m = 0; m < 4; ++m) {
;                 const size_t ro = (size_t)(pm * 256 + ai * 128 + wr * 64 + m * 16 + fr) * DRNN + cb;
; #pragma unroll
;                 for (int bj = 0; bj < 2; ++bj)
; #pragma unroll
;                     for (int n = 0; n < 2; ++n) {
;                         f32x4 v = acc[ai][bj][m][n];
;                         if (isg) { v[0] = gelu_tanh(v[0]); v[1] = gelu_tanh(v[1]); v[2] = gelu_tanh(v[2]); v[3] = gelu_tanh(v[3]); }
;                         u32x2 o = {pack2(v[0], v[1]), pack2(v[2], v[3])};
;                         *reinterpret_cast<u32x2*>(base + ro + bj * 128 + n * 16) = o;
;                     }
	v_mul_f32_e32 v109, v109, v110
	v_cvt_pk_bf16_f32 v107, v108, v109
	global_store_dwordx2 v[114:115], v[106:107], off offset:32
	v_mul_f32_e32 v106, 0x3d372713, v102
	v_mul_f32_e32 v106, v102, v106
	v_fma_f32 v106, v102, v106, v102
	v_mul_f32_e32 v106, 0xbfcc422a, v106
	v_mul_f32_e32 v106, 0x3fb8aa3b, v106
	v_exp_f32_e32 v106, v106
	s_nop 0
	v_add_f32_e32 v106, 1.0, v106
	v_rcp_f32_e32 v106, v106
	s_nop 0
	v_mul_f32_e32 v102, v102, v106
	v_mul_f32_e32 v106, 0x3d372713, v103
	v_mul_f32_e32 v106, v103, v106
	v_fma_f32 v106, v103, v106, v103
	v_mul_f32_e32 v106, 0xbfcc422a, v106
	v_mul_f32_e32 v106, 0x3fb8aa3b, v106
	v_exp_f32_e32 v106, v106
	s_nop 0
	v_add_f32_e32 v106, 1.0, v106
	v_rcp_f32_e32 v106, v106
	s_nop 0
	v_mul_f32_e32 v103, v103, v106
	v_mul_f32_e32 v106, 0x3d372713, v104
	v_mul_f32_e32 v106, v104, v106
	v_fma_f32 v106, v104, v106, v104
	v_mul_f32_e32 v106, 0xbfcc422a, v106
	v_mul_f32_e32 v106, 0x3fb8aa3b, v106
	v_exp_f32_e32 v106, v106
	v_cvt_pk_bf16_f32 v102, v102, v103
	v_add_f32_e32 v106, 1.0, v106
	v_rcp_f32_e32 v106, v106
	s_nop 0
	v_mul_f32_e32 v104, v104, v106
	v_mul_f32_e32 v106, 0x3d372713, v105
	v_mul_f32_e32 v106, v105, v106
	v_fma_f32 v106, v105, v106, v105
	v_mul_f32_e32 v106, 0xbfcc422a, v106
	v_mul_f32_e32 v106, 0x3fb8aa3b, v106
	v_exp_f32_e32 v106, v106
	s_nop 0
	v_add_f32_e32 v106, 1.0, v106
	v_rcp_f32_e32 v106, v106
	s_nop 0
	v_mul_f32_e32 v105, v105, v106
	v_cvt_pk_bf16_f32 v103, v104, v105
	global_store_dwordx2 v[114:115], v[102:103], off offset:256
	v_mul_f32_e32 v102, 0x3d372713, v98
	v_mul_f32_e32 v102, v98, v102
	v_fma_f32 v102, v98, v102, v98
	v_mul_f32_e32 v102, 0xbfcc422a, v102
	v_mul_f32_e32 v102, 0x3fb8aa3b, v102
	v_exp_f32_e32 v102, v102
	s_nop 0
	v_add_f32_e32 v102, 1.0, v102
	v_rcp_f32_e32 v102, v102
	s_nop 0
	v_mul_f32_e32 v98, v98, v102
	v_mul_f32_e32 v102, 0x3d372713, v99
	v_mul_f32_e32 v102, v99, v102
	v_fma_f32 v102, v99, v102, v99
	v_mul_f32_e32 v102, 0xbfcc422a, v102
	v_mul_f32_e32 v102, 0x3fb8aa3b, v102
	v_exp_f32_e32 v102, v102
	s_nop 0
	v_add_f32_e32 v102, 1.0, v102
	v_rcp_f32_e32 v102, v102
	s_nop 0
	v_mul_f32_e32 v99, v99, v102
	v_mul_f32_e32 v102, 0x3d372713, v100
	v_mul_f32_e32 v102, v100, v102
	v_fma_f32 v102, v100, v102, v100
	v_mul_f32_e32 v102, 0xbfcc422a, v102
	v_mul_f32_e32 v102, 0x3fb8aa3b, v102
	v_exp_f32_e32 v102, v102
	v_cvt_pk_bf16_f32 v98, v98, v99
	v_add_f32_e32 v102, 1.0, v102
	v_rcp_f32_e32 v102, v102
	s_nop 0
	v_mul_f32_e32 v100, v100, v102
	v_mul_f32_e32 v102, 0x3d372713, v101
	v_mul_f32_e32 v102, v101, v102
	v_fma_f32 v102, v101, v102, v101
	v_mul_f32_e32 v102, 0xbfcc422a, v102
	v_mul_f32_e32 v102, 0x3fb8aa3b, v102
	v_exp_f32_e32 v102, v102
	s_nop 0
	v_add_f32_e32 v102, 1.0, v102
	v_rcp_f32_e32 v102, v102
	s_nop 0
	v_mul_f32_e32 v101, v101, v102
	v_cvt_pk_bf16_f32 v99, v100, v101
	v_mul_f32_e32 v100, 0x3d372713, v94
	v_mul_f32_e32 v100, v94, v100
	v_fma_f32 v100, v94, v100, v94
	v_mul_f32_e32 v100, 0xbfcc422a, v100
	v_mul_f32_e32 v100, 0x3fb8aa3b, v100
	v_exp_f32_e32 v100, v100
	global_store_dwordx2 v[114:115], v[98:99], off offset:288
	v_or_b32_e32 v98, 32, v161
	v_mad_i64_i32 v[98:99], s[10:11], v98, s73, v[154:155]
	v_add_f32_e32 v100, 1.0, v100
	v_rcp_f32_e32 v100, v100
	s_nop 0
	v_mul_f32_e32 v94, v94, v100
	v_mul_f32_e32 v100, 0x3d372713, v95
	v_mul_f32_e32 v100, v95, v100
	v_fma_f32 v100, v95, v100, v95
	v_mul_f32_e32 v100, 0xbfcc422a, v100
	v_mul_f32_e32 v100, 0x3fb8aa3b, v100
	v_exp_f32_e32 v100, v100
	s_nop 0
	v_add_f32_e32 v100, 1.0, v100
	v_rcp_f32_e32 v100, v100
	s_nop 0
	v_mul_f32_e32 v95, v95, v100
	v_mul_f32_e32 v100, 0x3d372713, v96
	v_mul_f32_e32 v100, v96, v100
	v_fma_f32 v100, v96, v100, v96
	v_mul_f32_e32 v100, 0xbfcc422a, v100
	v_mul_f32_e32 v100, 0x3fb8aa3b, v100
	v_exp_f32_e32 v100, v100
	v_cvt_pk_bf16_f32 v94, v94, v95
	v_add_f32_e32 v100, 1.0, v100
	v_rcp_f32_e32 v100, v100
	s_nop 0
	v_mul_f32_e32 v96, v96, v100
	v_mul_f32_e32 v100, 0x3d372713, v97
	v_mul_f32_e32 v100, v97, v100
	v_fma_f32 v100, v97, v100, v97
	v_mul_f32_e32 v100, 0xbfcc422a, v100
	v_mul_f32_e32 v100, 0x3fb8aa3b, v100
	v_exp_f32_e32 v100, v100
	s_nop 0
	v_add_f32_e32 v100, 1.0, v100
	v_rcp_f32_e32 v100, v100
	s_nop 0
	v_mul_f32_e32 v97, v97, v100
	v_cvt_pk_bf16_f32 v95, v96, v97
	global_store_dwordx2 v[98:99], v[94:95], off
	v_mul_f32_e32 v94, 0x3d372713, v90
	v_mul_f32_e32 v94, v90, v94
	v_fma_f32 v94, v90, v94, v90
	v_mul_f32_e32 v94, 0xbfcc422a, v94
	v_mul_f32_e32 v94, 0x3fb8aa3b, v94
	v_exp_f32_e32 v94, v94
	s_nop 0
	v_add_f32_e32 v94, 1.0, v94
	v_rcp_f32_e32 v94, v94
	s_nop 0
	v_mul_f32_e32 v90, v90, v94
	v_mul_f32_e32 v94, 0x3d372713, v91
	v_mul_f32_e32 v94, v91, v94
	v_fma_f32 v94, v91, v94, v91
	v_mul_f32_e32 v94, 0xbfcc422a, v94
	v_mul_f32_e32 v94, 0x3fb8aa3b, v94
	v_exp_f32_e32 v94, v94
	s_nop 0
	v_add_f32_e32 v94, 1.0, v94
	v_rcp_f32_e32 v94, v94
	s_nop 0
	v_mul_f32_e32 v91, v91, v94
	v_mul_f32_e32 v94, 0x3d372713, v92
	v_mul_f32_e32 v94, v92, v94
	v_fma_f32 v94, v92, v94, v92
	v_mul_f32_e32 v94, 0xbfcc422a, v94
	v_mul_f32_e32 v94, 0x3fb8aa3b, v94
	v_exp_f32_e32 v94, v94
	v_cvt_pk_bf16_f32 v90, v90, v91
	v_add_f32_e32 v94, 1.0, v94
	v_rcp_f32_e32 v94, v94
	s_nop 0
	v_mul_f32_e32 v92, v92, v94
	v_mul_f32_e32 v94, 0x3d372713, v93
	v_mul_f32_e32 v94, v93, v94
	v_fma_f32 v94, v93, v94, v93
	v_mul_f32_e32 v94, 0xbfcc422a, v94
	v_mul_f32_e32 v94, 0x3fb8aa3b, v94
	v_exp_f32_e32 v94, v94
	s_nop 0
	v_add_f32_e32 v94, 1.0, v94
	v_rcp_f32_e32 v94, v94
	s_nop 0
	v_mul_f32_e32 v93, v93, v94
	v_cvt_pk_bf16_f32 v91, v92, v93
	global_store_dwordx2 v[98:99], v[90:91], off offset:32
	v_mul_f32_e32 v90, 0x3d372713, v86
	v_mul_f32_e32 v90, v86, v90
	v_fma_f32 v90, v86, v90, v86
; __device__ __forceinline__ float frcp(float x) { return __builtin_amdgcn_rcpf(x); }
; __device__ __forceinline__ float fexp(float x) { return __builtin_amdgcn_exp2f(x * 1.4426950408889634f); }
; __device__ __forceinline__ float gelu_tanh(float x) {
;     float u = 1.5957691216057308f * (x + 0.044715f * x * x * x);
;     return x * frcp(1.0f + fexp(-u));
; }
;     __device__ __forceinline__ void operator()(Acc& acc, int pm, int pn, int wr, int wc, int fr, int fq) const {
;     ...
;         for (int ai = 0; ai < 2; ++ai)
; #pragma unroll
;             for (int m = 0; m < 4; ++m) {
;                 const size_t ro = (size_t)(pm * 256 + ai * 128 + wr * 64 + m * 16 + fr) * DRNN + cb;
; #pragma unroll
;                 for (int bj = 0; bj < 2; ++bj)
; #pragma unroll
;                     for (int n = 0; n < 2; ++n) {
;                         f32x4 v = acc[ai][bj][m][n];
;                         if (isg) { v[0] = gelu_tanh(v[0]); v[1] = gelu_tanh(v[1]); v[2] = gelu_tanh(v[2]); v[3] = gelu_tanh(v[3]); }
;                         u32x2 o = {pack2(v[0], v[1]), pack2(v[2], v[3])};
;                         *reinterpret_cast<u32x2*>(base + ro + bj * 128 + n * 16) = o;
;                     }
	v_mul_f32_e32 v90, 0xbfcc422a, v90
	v_mul_f32_e32 v90, 0x3fb8aa3b, v90
	v_exp_f32_e32 v90, v90
	s_nop 0
	v_add_f32_e32 v90, 1.0, v90
	v_rcp_f32_e32 v90, v90
	s_nop 0
	v_mul_f32_e32 v86, v86, v90
	v_mul_f32_e32 v90, 0x3d372713, v87
	v_mul_f32_e32 v90, v87, v90
	v_fma_f32 v90, v87, v90, v87
	v_mul_f32_e32 v90, 0xbfcc422a, v90
	v_mul_f32_e32 v90, 0x3fb8aa3b, v90
	v_exp_f32_e32 v90, v90
	s_nop 0
	v_add_f32_e32 v90, 1.0, v90
	v_rcp_f32_e32 v90, v90
	s_nop 0
	v_mul_f32_e32 v87, v87, v90
	v_mul_f32_e32 v90, 0x3d372713, v88
	v_mul_f32_e32 v90, v88, v90
	v_fma_f32 v90, v88, v90, v88
	v_mul_f32_e32 v90, 0xbfcc422a, v90
	v_mul_f32_e32 v90, 0x3fb8aa3b, v90
	v_exp_f32_e32 v90, v90
	v_cvt_pk_bf16_f32 v86, v86, v87
	v_add_f32_e32 v90, 1.0, v90
	v_rcp_f32_e32 v90, v90
	s_nop 0
	v_mul_f32_e32 v88, v88, v90
	v_mul_f32_e32 v90, 0x3d372713, v89
	v_mul_f32_e32 v90, v89, v90
	v_fma_f32 v90, v89, v90, v89
	v_mul_f32_e32 v90, 0xbfcc422a, v90
	v_mul_f32_e32 v90, 0x3fb8aa3b, v90
	v_exp_f32_e32 v90, v90
	s_nop 0
	v_add_f32_e32 v90, 1.0, v90
	v_rcp_f32_e32 v90, v90
	s_nop 0
	v_mul_f32_e32 v89, v89, v90
	v_cvt_pk_bf16_f32 v87, v88, v89
	global_store_dwordx2 v[98:99], v[86:87], off offset:256
	v_mul_f32_e32 v86, 0x3d372713, v82
	v_mul_f32_e32 v86, v82, v86
	v_fma_f32 v86, v82, v86, v82
	v_mul_f32_e32 v86, 0xbfcc422a, v86
	v_mul_f32_e32 v86, 0x3fb8aa3b, v86
	v_exp_f32_e32 v86, v86
	s_nop 0
	v_add_f32_e32 v86, 1.0, v86
	v_rcp_f32_e32 v86, v86
	s_nop 0
	v_mul_f32_e32 v82, v82, v86
	v_mul_f32_e32 v86, 0x3d372713, v83
	v_mul_f32_e32 v86, v83, v86
	v_fma_f32 v86, v83, v86, v83
	v_mul_f32_e32 v86, 0xbfcc422a, v86
	v_mul_f32_e32 v86, 0x3fb8aa3b, v86
	v_exp_f32_e32 v86, v86
	s_nop 0
	v_add_f32_e32 v86, 1.0, v86
	v_rcp_f32_e32 v86, v86
	s_nop 0
	v_mul_f32_e32 v83, v83, v86
	v_mul_f32_e32 v86, 0x3d372713, v84
	v_mul_f32_e32 v86, v84, v86
	v_fma_f32 v86, v84, v86, v84
	v_mul_f32_e32 v86, 0xbfcc422a, v86
	v_mul_f32_e32 v86, 0x3fb8aa3b, v86
	v_exp_f32_e32 v86, v86
	v_cvt_pk_bf16_f32 v82, v82, v83
	v_add_f32_e32 v86, 1.0, v86
	v_rcp_f32_e32 v86, v86
	s_nop 0
	v_mul_f32_e32 v84, v84, v86
	v_mul_f32_e32 v86, 0x3d372713, v85
	v_mul_f32_e32 v86, v85, v86
	v_fma_f32 v86, v85, v86, v85
	v_mul_f32_e32 v86, 0xbfcc422a, v86
	v_mul_f32_e32 v86, 0x3fb8aa3b, v86
	v_exp_f32_e32 v86, v86
	s_nop 0
	v_add_f32_e32 v86, 1.0, v86
	v_rcp_f32_e32 v86, v86
	s_nop 0
	v_mul_f32_e32 v85, v85, v86
	v_cvt_pk_bf16_f32 v83, v84, v85
	v_mul_f32_e32 v84, 0x3d372713, v78
	v_mul_f32_e32 v84, v78, v84
	v_fma_f32 v84, v78, v84, v78
	v_mul_f32_e32 v84, 0xbfcc422a, v84
	v_mul_f32_e32 v84, 0x3fb8aa3b, v84
	v_exp_f32_e32 v84, v84
	global_store_dwordx2 v[98:99], v[82:83], off offset:288
	v_or_b32_e32 v82, 48, v161
	v_mad_i64_i32 v[82:83], s[10:11], v82, s73, v[154:155]
	v_add_f32_e32 v84, 1.0, v84
	v_rcp_f32_e32 v84, v84
	s_nop 0
	v_mul_f32_e32 v78, v78, v84
	v_mul_f32_e32 v84, 0x3d372713, v79
	v_mul_f32_e32 v84, v79, v84
	v_fma_f32 v84, v79, v84, v79
	v_mul_f32_e32 v84, 0xbfcc422a, v84
	v_mul_f32_e32 v84, 0x3fb8aa3b, v84
	v_exp_f32_e32 v84, v84
	s_nop 0
	v_add_f32_e32 v84, 1.0, v84
	v_rcp_f32_e32 v84, v84
	s_nop 0
	v_mul_f32_e32 v79, v79, v84
	v_mul_f32_e32 v84, 0x3d372713, v80
	v_mul_f32_e32 v84, v80, v84
	v_fma_f32 v84, v80, v84, v80
	v_mul_f32_e32 v84, 0xbfcc422a, v84
	v_mul_f32_e32 v84, 0x3fb8aa3b, v84
	v_exp_f32_e32 v84, v84
	v_cvt_pk_bf16_f32 v78, v78, v79
	v_add_f32_e32 v84, 1.0, v84
	v_rcp_f32_e32 v84, v84
	s_nop 0
	v_mul_f32_e32 v80, v80, v84
	v_mul_f32_e32 v84, 0x3d372713, v81
	v_mul_f32_e32 v84, v81, v84
	v_fma_f32 v84, v81, v84, v81
	v_mul_f32_e32 v84, 0xbfcc422a, v84
	v_mul_f32_e32 v84, 0x3fb8aa3b, v84
	v_exp_f32_e32 v84, v84
	s_nop 0
	v_add_f32_e32 v84, 1.0, v84
	v_rcp_f32_e32 v84, v84
	s_nop 0
	v_mul_f32_e32 v81, v81, v84
	v_cvt_pk_bf16_f32 v79, v80, v81
	global_store_dwordx2 v[82:83], v[78:79], off
	v_mul_f32_e32 v78, 0x3d372713, v74
	v_mul_f32_e32 v78, v74, v78
	v_fma_f32 v78, v74, v78, v74
	v_mul_f32_e32 v78, 0xbfcc422a, v78
	v_mul_f32_e32 v78, 0x3fb8aa3b, v78
	v_exp_f32_e32 v78, v78
	s_nop 0
	v_add_f32_e32 v78, 1.0, v78
	v_rcp_f32_e32 v78, v78
	s_nop 0
	v_mul_f32_e32 v74, v74, v78
	v_mul_f32_e32 v78, 0x3d372713, v75
	v_mul_f32_e32 v78, v75, v78
	v_fma_f32 v78, v75, v78, v75
	v_mul_f32_e32 v78, 0xbfcc422a, v78
	v_mul_f32_e32 v78, 0x3fb8aa3b, v78
	v_exp_f32_e32 v78, v78
	s_nop 0
	v_add_f32_e32 v78, 1.0, v78
	v_rcp_f32_e32 v78, v78
	s_nop 0
	v_mul_f32_e32 v75, v75, v78
	v_mul_f32_e32 v78, 0x3d372713, v76
	v_mul_f32_e32 v78, v76, v78
	v_fma_f32 v78, v76, v78, v76
	v_mul_f32_e32 v78, 0xbfcc422a, v78
	v_mul_f32_e32 v78, 0x3fb8aa3b, v78
	v_exp_f32_e32 v78, v78
	v_cvt_pk_bf16_f32 v74, v74, v75
	v_add_f32_e32 v78, 1.0, v78
	v_rcp_f32_e32 v78, v78
	s_nop 0
	v_mul_f32_e32 v76, v76, v78
	v_mul_f32_e32 v78, 0x3d372713, v77
	v_mul_f32_e32 v78, v77, v78
	v_fma_f32 v78, v77, v78, v77
	v_mul_f32_e32 v78, 0xbfcc422a, v78
	v_mul_f32_e32 v78, 0x3fb8aa3b, v78
	v_exp_f32_e32 v78, v78
	s_nop 0
	v_add_f32_e32 v78, 1.0, v78
	v_rcp_f32_e32 v78, v78
	s_nop 0
	v_mul_f32_e32 v77, v77, v78
	v_cvt_pk_bf16_f32 v75, v76, v77
	global_store_dwordx2 v[82:83], v[74:75], off offset:32
	v_mul_f32_e32 v74, 0x3d372713, v70
	v_mul_f32_e32 v74, v70, v74
	v_fma_f32 v74, v70, v74, v70
	v_mul_f32_e32 v74, 0xbfcc422a, v74
	v_mul_f32_e32 v74, 0x3fb8aa3b, v74
	v_exp_f32_e32 v74, v74
	s_nop 0
	v_add_f32_e32 v74, 1.0, v74
	v_rcp_f32_e32 v74, v74
	s_nop 0
	v_mul_f32_e32 v70, v70, v74
	v_mul_f32_e32 v74, 0x3d372713, v71
	v_mul_f32_e32 v74, v71, v74
	v_fma_f32 v74, v71, v74, v71
	v_mul_f32_e32 v74, 0xbfcc422a, v74
	v_mul_f32_e32 v74, 0x3fb8aa3b, v74
	v_exp_f32_e32 v74, v74
	s_nop 0
	v_add_f32_e32 v74, 1.0, v74
	v_rcp_f32_e32 v74, v74
	s_nop 0
; __device__ __forceinline__ float frcp(float x) { return __builtin_amdgcn_rcpf(x); }
; __device__ __forceinline__ float fexp(float x) { return __builtin_amdgcn_exp2f(x * 1.4426950408889634f); }
; __device__ __forceinline__ float gelu_tanh(float x) {
;     float u = 1.5957691216057308f * (x + 0.044715f * x * x * x);
;     return x * frcp(1.0f + fexp(-u));
; }
;     __device__ __forceinline__ void operator()(Acc& acc, int pm, int pn, int wr, int wc, int fr, int fq) const {
;     ...
;         for (int ai = 0; ai < 2; ++ai)
; #pragma unroll
;             for (int m = 0; m < 4; ++m) {
;                 const size_t ro = (size_t)(pm * 256 + ai * 128 + wr * 64 + m * 16 + fr) * DRNN + cb;
; #pragma unroll
;                 for (int bj = 0; bj < 2; ++bj)
; #pragma unroll
;                     for (int n = 0; n < 2; ++n) {
;                         f32x4 v = acc[ai][bj][m][n];
;                         if (isg) { v[0] = gelu_tanh(v[0]); v[1] = gelu_tanh(v[1]); v[2] = gelu_tanh(v[2]); v[3] = gelu_tanh(v[3]); }
;                         u32x2 o = {pack2(v[0], v[1]), pack2(v[2], v[3])};
;                         *reinterpret_cast<u32x2*>(base + ro + bj * 128 + n * 16) = o;
;                     }
	v_mul_f32_e32 v71, v71, v74
	v_mul_f32_e32 v74, 0x3d372713, v72
	v_mul_f32_e32 v74, v72, v74
	v_fma_f32 v74, v72, v74, v72
	v_mul_f32_e32 v74, 0xbfcc422a, v74
	v_mul_f32_e32 v74, 0x3fb8aa3b, v74
	v_exp_f32_e32 v74, v74
	v_cvt_pk_bf16_f32 v70, v70, v71
	v_add_f32_e32 v74, 1.0, v74
	v_rcp_f32_e32 v74, v74
	s_nop 0
	v_mul_f32_e32 v72, v72, v74
	v_mul_f32_e32 v74, 0x3d372713, v73
	v_mul_f32_e32 v74, v73, v74
	v_fma_f32 v74, v73, v74, v73
	v_mul_f32_e32 v74, 0xbfcc422a, v74
	v_mul_f32_e32 v74, 0x3fb8aa3b, v74
	v_exp_f32_e32 v74, v74
	s_nop 0
	v_add_f32_e32 v74, 1.0, v74
	v_rcp_f32_e32 v74, v74
	s_nop 0
	v_mul_f32_e32 v73, v73, v74
	v_cvt_pk_bf16_f32 v71, v72, v73
	global_store_dwordx2 v[82:83], v[70:71], off offset:256
	v_mul_f32_e32 v70, 0x3d372713, v66
	v_mul_f32_e32 v70, v66, v70
	v_fma_f32 v70, v66, v70, v66
	v_mul_f32_e32 v70, 0xbfcc422a, v70
	v_mul_f32_e32 v70, 0x3fb8aa3b, v70
	v_exp_f32_e32 v70, v70
	s_nop 0
	v_add_f32_e32 v70, 1.0, v70
	v_rcp_f32_e32 v70, v70
	s_nop 0
	v_mul_f32_e32 v66, v66, v70
	v_mul_f32_e32 v70, 0x3d372713, v67
	v_mul_f32_e32 v70, v67, v70
	v_fma_f32 v70, v67, v70, v67
	v_mul_f32_e32 v70, 0xbfcc422a, v70
	v_mul_f32_e32 v70, 0x3fb8aa3b, v70
	v_exp_f32_e32 v70, v70
	s_nop 0
	v_add_f32_e32 v70, 1.0, v70
	v_rcp_f32_e32 v70, v70
	s_nop 0
	v_mul_f32_e32 v67, v67, v70
	v_mul_f32_e32 v70, 0x3d372713, v68
	v_mul_f32_e32 v70, v68, v70
	v_fma_f32 v70, v68, v70, v68
	v_mul_f32_e32 v70, 0xbfcc422a, v70
	v_mul_f32_e32 v70, 0x3fb8aa3b, v70
	v_exp_f32_e32 v70, v70
	v_cvt_pk_bf16_f32 v66, v66, v67
	v_add_f32_e32 v70, 1.0, v70
	v_rcp_f32_e32 v70, v70
	s_nop 0
	v_mul_f32_e32 v68, v68, v70
	v_mul_f32_e32 v70, 0x3d372713, v69
	v_mul_f32_e32 v70, v69, v70
	v_fma_f32 v70, v69, v70, v69
	v_mul_f32_e32 v70, 0xbfcc422a, v70
	v_mul_f32_e32 v70, 0x3fb8aa3b, v70
	v_exp_f32_e32 v70, v70
	s_nop 0
	v_add_f32_e32 v70, 1.0, v70
	v_rcp_f32_e32 v70, v70
	s_nop 0
	v_mul_f32_e32 v69, v69, v70
	v_cvt_pk_bf16_f32 v67, v68, v69
	v_mul_f32_e32 v68, 0x3d372713, v62
	v_mul_f32_e32 v68, v62, v68
	v_fma_f32 v68, v62, v68, v62
	v_mul_f32_e32 v68, 0xbfcc422a, v68
	v_mul_f32_e32 v68, 0x3fb8aa3b, v68
	v_exp_f32_e32 v68, v68
	global_store_dwordx2 v[82:83], v[66:67], off offset:288
	v_add_u32_e32 v66, 0x80, v161
	v_mad_i64_i32 v[66:67], s[10:11], v66, s73, v[154:155]
	v_add_f32_e32 v68, 1.0, v68
	v_rcp_f32_e32 v68, v68
	s_nop 0
	v_mul_f32_e32 v62, v62, v68
	v_mul_f32_e32 v68, 0x3d372713, v63
	v_mul_f32_e32 v68, v63, v68
	v_fma_f32 v68, v63, v68, v63
	v_mul_f32_e32 v68, 0xbfcc422a, v68
	v_mul_f32_e32 v68, 0x3fb8aa3b, v68
	v_exp_f32_e32 v68, v68
	s_nop 0
	v_add_f32_e32 v68, 1.0, v68
	v_rcp_f32_e32 v68, v68
	s_nop 0
	v_mul_f32_e32 v63, v63, v68
	v_mul_f32_e32 v68, 0x3d372713, v64
	v_mul_f32_e32 v68, v64, v68
	v_fma_f32 v68, v64, v68, v64
	v_mul_f32_e32 v68, 0xbfcc422a, v68
	v_mul_f32_e32 v68, 0x3fb8aa3b, v68
	v_exp_f32_e32 v68, v68
	v_cvt_pk_bf16_f32 v62, v62, v63
	v_add_f32_e32 v68, 1.0, v68
	v_rcp_f32_e32 v68, v68
	s_nop 0
	v_mul_f32_e32 v64, v64, v68
	v_mul_f32_e32 v68, 0x3d372713, v65
	v_mul_f32_e32 v68, v65, v68
	v_fma_f32 v68, v65, v68, v65
	v_mul_f32_e32 v68, 0xbfcc422a, v68
	v_mul_f32_e32 v68, 0x3fb8aa3b, v68
	v_exp_f32_e32 v68, v68
	s_nop 0
	v_add_f32_e32 v68, 1.0, v68
	v_rcp_f32_e32 v68, v68
	s_nop 0
	v_mul_f32_e32 v65, v65, v68
	v_cvt_pk_bf16_f32 v63, v64, v65
	global_store_dwordx2 v[66:67], v[62:63], off
	v_mul_f32_e32 v62, 0x3d372713, v58
	v_mul_f32_e32 v62, v58, v62
	v_fma_f32 v62, v58, v62, v58
	v_mul_f32_e32 v62, 0xbfcc422a, v62
	v_mul_f32_e32 v62, 0x3fb8aa3b, v62
	v_exp_f32_e32 v62, v62
	s_nop 0
	v_add_f32_e32 v62, 1.0, v62
	v_rcp_f32_e32 v62, v62
	s_nop 0
	v_mul_f32_e32 v58, v58, v62
	v_mul_f32_e32 v62, 0x3d372713, v59
	v_mul_f32_e32 v62, v59, v62
	v_fma_f32 v62, v59, v62, v59
	v_mul_f32_e32 v62, 0xbfcc422a, v62
	v_mul_f32_e32 v62, 0x3fb8aa3b, v62
	v_exp_f32_e32 v62, v62
	s_nop 0
	v_add_f32_e32 v62, 1.0, v62
	v_rcp_f32_e32 v62, v62
	s_nop 0
	v_mul_f32_e32 v59, v59, v62
	v_mul_f32_e32 v62, 0x3d372713, v60
	v_mul_f32_e32 v62, v60, v62
	v_fma_f32 v62, v60, v62, v60
	v_mul_f32_e32 v62, 0xbfcc422a, v62
	v_mul_f32_e32 v62, 0x3fb8aa3b, v62
	v_exp_f32_e32 v62, v62
	v_cvt_pk_bf16_f32 v58, v58, v59
	v_add_f32_e32 v62, 1.0, v62
	v_rcp_f32_e32 v62, v62
	s_nop 0
	v_mul_f32_e32 v60, v60, v62
	v_mul_f32_e32 v62, 0x3d372713, v61
	v_mul_f32_e32 v62, v61, v62
	v_fma_f32 v62, v61, v62, v61
	v_mul_f32_e32 v62, 0xbfcc422a, v62
	v_mul_f32_e32 v62, 0x3fb8aa3b, v62
	v_exp_f32_e32 v62, v62
	s_nop 0
	v_add_f32_e32 v62, 1.0, v62
	v_rcp_f32_e32 v62, v62
	s_nop 0
	v_mul_f32_e32 v61, v61, v62
	v_cvt_pk_bf16_f32 v59, v60, v61
	global_store_dwordx2 v[66:67], v[58:59], off offset:32
	v_mul_f32_e32 v58, 0x3d372713, v54
	v_mul_f32_e32 v58, v54, v58
	v_fma_f32 v58, v54, v58, v54
	v_mul_f32_e32 v58, 0xbfcc422a, v58
	v_mul_f32_e32 v58, 0x3fb8aa3b, v58
	v_exp_f32_e32 v58, v58
	s_nop 0
	v_add_f32_e32 v58, 1.0, v58
	v_rcp_f32_e32 v58, v58
	s_nop 0
	v_mul_f32_e32 v54, v54, v58
	v_mul_f32_e32 v58, 0x3d372713, v55
	v_mul_f32_e32 v58, v55, v58
	v_fma_f32 v58, v55, v58, v55
	v_mul_f32_e32 v58, 0xbfcc422a, v58
	v_mul_f32_e32 v58, 0x3fb8aa3b, v58
	v_exp_f32_e32 v58, v58
	s_nop 0
	v_add_f32_e32 v58, 1.0, v58
	v_rcp_f32_e32 v58, v58
	s_nop 0
	v_mul_f32_e32 v55, v55, v58
	v_mul_f32_e32 v58, 0x3d372713, v56
	v_mul_f32_e32 v58, v56, v58
	v_fma_f32 v58, v56, v58, v56
	v_mul_f32_e32 v58, 0xbfcc422a, v58
	v_mul_f32_e32 v58, 0x3fb8aa3b, v58
	v_exp_f32_e32 v58, v58
	v_cvt_pk_bf16_f32 v54, v54, v55
	v_add_f32_e32 v58, 1.0, v58
	v_rcp_f32_e32 v58, v58
	s_nop 0
	v_mul_f32_e32 v56, v56, v58
	v_mul_f32_e32 v58, 0x3d372713, v57
	v_mul_f32_e32 v58, v57, v58
	v_fma_f32 v58, v57, v58, v57
	v_mul_f32_e32 v58, 0xbfcc422a, v58
; __device__ __forceinline__ float frcp(float x) { return __builtin_amdgcn_rcpf(x); }
; __device__ __forceinline__ float fexp(float x) { return __builtin_amdgcn_exp2f(x * 1.4426950408889634f); }
; __device__ __forceinline__ float gelu_tanh(float x) {
;     float u = 1.5957691216057308f * (x + 0.044715f * x * x * x);
;     return x * frcp(1.0f + fexp(-u));
; }
;     __device__ __forceinline__ void operator()(Acc& acc, int pm, int pn, int wr, int wc, int fr, int fq) const {
;     ...
;         for (int ai = 0; ai < 2; ++ai)
; #pragma unroll
;             for (int m = 0; m < 4; ++m) {
;                 const size_t ro = (size_t)(pm * 256 + ai * 128 + wr * 64 + m * 16 + fr) * DRNN + cb;
; #pragma unroll
;                 for (int bj = 0; bj < 2; ++bj)
; #pragma unroll
;                     for (int n = 0; n < 2; ++n) {
;                         f32x4 v = acc[ai][bj][m][n];
;                         if (isg) { v[0] = gelu_tanh(v[0]); v[1] = gelu_tanh(v[1]); v[2] = gelu_tanh(v[2]); v[3] = gelu_tanh(v[3]); }
;                         u32x2 o = {pack2(v[0], v[1]), pack2(v[2], v[3])};
;                         *reinterpret_cast<u32x2*>(base + ro + bj * 128 + n * 16) = o;
;                     }
	v_mul_f32_e32 v58, 0x3fb8aa3b, v58
	v_exp_f32_e32 v58, v58
	s_nop 0
	v_add_f32_e32 v58, 1.0, v58
	v_rcp_f32_e32 v58, v58
	s_nop 0
	v_mul_f32_e32 v57, v57, v58
	v_cvt_pk_bf16_f32 v55, v56, v57
	global_store_dwordx2 v[66:67], v[54:55], off offset:256
	v_mul_f32_e32 v54, 0x3d372713, v50
	v_mul_f32_e32 v54, v50, v54
	v_fma_f32 v54, v50, v54, v50
	v_mul_f32_e32 v54, 0xbfcc422a, v54
	v_mul_f32_e32 v54, 0x3fb8aa3b, v54
	v_exp_f32_e32 v54, v54
	s_nop 0
	v_add_f32_e32 v54, 1.0, v54
	v_rcp_f32_e32 v54, v54
	s_nop 0
	v_mul_f32_e32 v50, v50, v54
	v_mul_f32_e32 v54, 0x3d372713, v51
	v_mul_f32_e32 v54, v51, v54
	v_fma_f32 v54, v51, v54, v51
	v_mul_f32_e32 v54, 0xbfcc422a, v54
	v_mul_f32_e32 v54, 0x3fb8aa3b, v54
	v_exp_f32_e32 v54, v54
	s_nop 0
	v_add_f32_e32 v54, 1.0, v54
	v_rcp_f32_e32 v54, v54
	s_nop 0
	v_mul_f32_e32 v51, v51, v54
	v_mul_f32_e32 v54, 0x3d372713, v52
	v_mul_f32_e32 v54, v52, v54
	v_fma_f32 v54, v52, v54, v52
	v_mul_f32_e32 v54, 0xbfcc422a, v54
	v_mul_f32_e32 v54, 0x3fb8aa3b, v54
	v_exp_f32_e32 v54, v54
	v_cvt_pk_bf16_f32 v50, v50, v51
	v_add_f32_e32 v54, 1.0, v54
	v_rcp_f32_e32 v54, v54
	s_nop 0
	v_mul_f32_e32 v52, v52, v54
	v_mul_f32_e32 v54, 0x3d372713, v53
	v_mul_f32_e32 v54, v53, v54
	v_fma_f32 v54, v53, v54, v53
	v_mul_f32_e32 v54, 0xbfcc422a, v54
	v_mul_f32_e32 v54, 0x3fb8aa3b, v54
	v_exp_f32_e32 v54, v54
	s_nop 0
	v_add_f32_e32 v54, 1.0, v54
	v_rcp_f32_e32 v54, v54
	s_nop 0
	v_mul_f32_e32 v53, v53, v54
	v_cvt_pk_bf16_f32 v51, v52, v53
	v_mul_f32_e32 v52, 0x3d372713, v46
	v_mul_f32_e32 v52, v46, v52
	v_fma_f32 v52, v46, v52, v46
	v_mul_f32_e32 v52, 0xbfcc422a, v52
	v_mul_f32_e32 v52, 0x3fb8aa3b, v52
	v_exp_f32_e32 v52, v52
	global_store_dwordx2 v[66:67], v[50:51], off offset:288
	v_add_u32_e32 v50, 0x90, v161
	v_mad_i64_i32 v[50:51], s[10:11], v50, s73, v[154:155]
	v_add_f32_e32 v52, 1.0, v52
	v_rcp_f32_e32 v52, v52
	s_nop 0
	v_mul_f32_e32 v46, v46, v52
	v_mul_f32_e32 v52, 0x3d372713, v47
	v_mul_f32_e32 v52, v47, v52
	v_fma_f32 v52, v47, v52, v47
	v_mul_f32_e32 v52, 0xbfcc422a, v52
	v_mul_f32_e32 v52, 0x3fb8aa3b, v52
	v_exp_f32_e32 v52, v52
	s_nop 0
	v_add_f32_e32 v52, 1.0, v52
	v_rcp_f32_e32 v52, v52
	s_nop 0
	v_mul_f32_e32 v47, v47, v52
	v_mul_f32_e32 v52, 0x3d372713, v48
	v_mul_f32_e32 v52, v48, v52
	v_fma_f32 v52, v48, v52, v48
	v_mul_f32_e32 v52, 0xbfcc422a, v52
	v_mul_f32_e32 v52, 0x3fb8aa3b, v52
	v_exp_f32_e32 v52, v52
	v_cvt_pk_bf16_f32 v46, v46, v47
	v_add_f32_e32 v52, 1.0, v52
	v_rcp_f32_e32 v52, v52
	s_nop 0
	v_mul_f32_e32 v48, v48, v52
	v_mul_f32_e32 v52, 0x3d372713, v49
	v_mul_f32_e32 v52, v49, v52
	v_fma_f32 v52, v49, v52, v49
	v_mul_f32_e32 v52, 0xbfcc422a, v52
	v_mul_f32_e32 v52, 0x3fb8aa3b, v52
	v_exp_f32_e32 v52, v52
	s_nop 0
	v_add_f32_e32 v52, 1.0, v52
	v_rcp_f32_e32 v52, v52
	s_nop 0
	v_mul_f32_e32 v49, v49, v52
	v_cvt_pk_bf16_f32 v47, v48, v49
	global_store_dwordx2 v[50:51], v[46:47], off
	v_mul_f32_e32 v46, 0x3d372713, v42
	v_mul_f32_e32 v46, v42, v46
	v_fma_f32 v46, v42, v46, v42
	v_mul_f32_e32 v46, 0xbfcc422a, v46
	v_mul_f32_e32 v46, 0x3fb8aa3b, v46
	v_exp_f32_e32 v46, v46
	s_nop 0
	v_add_f32_e32 v46, 1.0, v46
	v_rcp_f32_e32 v46, v46
	s_nop 0
	v_mul_f32_e32 v42, v42, v46
	v_mul_f32_e32 v46, 0x3d372713, v43
	v_mul_f32_e32 v46, v43, v46
	v_fma_f32 v46, v43, v46, v43
	v_mul_f32_e32 v46, 0xbfcc422a, v46
	v_mul_f32_e32 v46, 0x3fb8aa3b, v46
	v_exp_f32_e32 v46, v46
	s_nop 0
	v_add_f32_e32 v46, 1.0, v46
	v_rcp_f32_e32 v46, v46
	s_nop 0
	v_mul_f32_e32 v43, v43, v46
	v_mul_f32_e32 v46, 0x3d372713, v44
	v_mul_f32_e32 v46, v44, v46
	v_fma_f32 v46, v44, v46, v44
	v_mul_f32_e32 v46, 0xbfcc422a, v46
	v_mul_f32_e32 v46, 0x3fb8aa3b, v46
	v_exp_f32_e32 v46, v46
	v_cvt_pk_bf16_f32 v42, v42, v43
	v_add_f32_e32 v46, 1.0, v46
	v_rcp_f32_e32 v46, v46
	s_nop 0
	v_mul_f32_e32 v44, v44, v46
	v_mul_f32_e32 v46, 0x3d372713, v45
	v_mul_f32_e32 v46, v45, v46
	v_fma_f32 v46, v45, v46, v45
	v_mul_f32_e32 v46, 0xbfcc422a, v46
	v_mul_f32_e32 v46, 0x3fb8aa3b, v46
	v_exp_f32_e32 v46, v46
	s_nop 0
	v_add_f32_e32 v46, 1.0, v46
	v_rcp_f32_e32 v46, v46
	s_nop 0
	v_mul_f32_e32 v45, v45, v46
	v_cvt_pk_bf16_f32 v43, v44, v45
	global_store_dwordx2 v[50:51], v[42:43], off offset:32
	v_mul_f32_e32 v42, 0x3d372713, v38
	v_mul_f32_e32 v42, v38, v42
	v_fma_f32 v42, v38, v42, v38
	v_mul_f32_e32 v42, 0xbfcc422a, v42
	v_mul_f32_e32 v42, 0x3fb8aa3b, v42
	v_exp_f32_e32 v42, v42
	s_nop 0
	v_add_f32_e32 v42, 1.0, v42
	v_rcp_f32_e32 v42, v42
	s_nop 0
	v_mul_f32_e32 v38, v38, v42
	v_mul_f32_e32 v42, 0x3d372713, v39
	v_mul_f32_e32 v42, v39, v42
	v_fma_f32 v42, v39, v42, v39
	v_mul_f32_e32 v42, 0xbfcc422a, v42
	v_mul_f32_e32 v42, 0x3fb8aa3b, v42
	v_exp_f32_e32 v42, v42
	s_nop 0
	v_add_f32_e32 v42, 1.0, v42
	v_rcp_f32_e32 v42, v42
	s_nop 0
	v_mul_f32_e32 v39, v39, v42
	v_mul_f32_e32 v42, 0x3d372713, v40
	v_mul_f32_e32 v42, v40, v42
	v_fma_f32 v42, v40, v42, v40
	v_mul_f32_e32 v42, 0xbfcc422a, v42
	v_mul_f32_e32 v42, 0x3fb8aa3b, v42
	v_exp_f32_e32 v42, v42
	v_cvt_pk_bf16_f32 v38, v38, v39
	v_add_f32_e32 v42, 1.0, v42
	v_rcp_f32_e32 v42, v42
	s_nop 0
	v_mul_f32_e32 v40, v40, v42
	v_mul_f32_e32 v42, 0x3d372713, v41
	v_mul_f32_e32 v42, v41, v42
	v_fma_f32 v42, v41, v42, v41
	v_mul_f32_e32 v42, 0xbfcc422a, v42
	v_mul_f32_e32 v42, 0x3fb8aa3b, v42
	v_exp_f32_e32 v42, v42
	s_nop 0
	v_add_f32_e32 v42, 1.0, v42
	v_rcp_f32_e32 v42, v42
	s_nop 0
	v_mul_f32_e32 v41, v41, v42
	v_cvt_pk_bf16_f32 v39, v40, v41
	global_store_dwordx2 v[50:51], v[38:39], off offset:256
	v_mul_f32_e32 v38, 0x3d372713, v34
	v_mul_f32_e32 v38, v34, v38
	v_fma_f32 v38, v34, v38, v34
	v_mul_f32_e32 v38, 0xbfcc422a, v38
	v_mul_f32_e32 v38, 0x3fb8aa3b, v38
	v_exp_f32_e32 v38, v38
	s_nop 0
; __device__ __forceinline__ float frcp(float x) { return __builtin_amdgcn_rcpf(x); }
; __device__ __forceinline__ float fexp(float x) { return __builtin_amdgcn_exp2f(x * 1.4426950408889634f); }
; __device__ __forceinline__ float gelu_tanh(float x) {
;     float u = 1.5957691216057308f * (x + 0.044715f * x * x * x);
;     return x * frcp(1.0f + fexp(-u));
; }
;     __device__ __forceinline__ void operator()(Acc& acc, int pm, int pn, int wr, int wc, int fr, int fq) const {
;     ...
;         for (int ai = 0; ai < 2; ++ai)
; #pragma unroll
;             for (int m = 0; m < 4; ++m) {
;                 const size_t ro = (size_t)(pm * 256 + ai * 128 + wr * 64 + m * 16 + fr) * DRNN + cb;
; #pragma unroll
;                 for (int bj = 0; bj < 2; ++bj)
; #pragma unroll
;                     for (int n = 0; n < 2; ++n) {
;                         f32x4 v = acc[ai][bj][m][n];
;                         if (isg) { v[0] = gelu_tanh(v[0]); v[1] = gelu_tanh(v[1]); v[2] = gelu_tanh(v[2]); v[3] = gelu_tanh(v[3]); }
;                         u32x2 o = {pack2(v[0], v[1]), pack2(v[2], v[3])};
;                         *reinterpret_cast<u32x2*>(base + ro + bj * 128 + n * 16) = o;
;                     }
	v_add_f32_e32 v38, 1.0, v38
	v_rcp_f32_e32 v38, v38
	s_nop 0
	v_mul_f32_e32 v34, v34, v38
	v_mul_f32_e32 v38, 0x3d372713, v35
	v_mul_f32_e32 v38, v35, v38
	v_fma_f32 v38, v35, v38, v35
	v_mul_f32_e32 v38, 0xbfcc422a, v38
	v_mul_f32_e32 v38, 0x3fb8aa3b, v38
	v_exp_f32_e32 v38, v38
	s_nop 0
	v_add_f32_e32 v38, 1.0, v38
	v_rcp_f32_e32 v38, v38
	s_nop 0
	v_mul_f32_e32 v35, v35, v38
	v_mul_f32_e32 v38, 0x3d372713, v36
	v_mul_f32_e32 v38, v36, v38
	v_fma_f32 v38, v36, v38, v36
	v_mul_f32_e32 v38, 0xbfcc422a, v38
	v_mul_f32_e32 v38, 0x3fb8aa3b, v38
	v_exp_f32_e32 v38, v38
	v_cvt_pk_bf16_f32 v34, v34, v35
	v_add_f32_e32 v38, 1.0, v38
	v_rcp_f32_e32 v38, v38
	s_nop 0
	v_mul_f32_e32 v36, v36, v38
	v_mul_f32_e32 v38, 0x3d372713, v37
	v_mul_f32_e32 v38, v37, v38
	v_fma_f32 v38, v37, v38, v37
	v_mul_f32_e32 v38, 0xbfcc422a, v38
	v_mul_f32_e32 v38, 0x3fb8aa3b, v38
	v_exp_f32_e32 v38, v38
	s_nop 0
	v_add_f32_e32 v38, 1.0, v38
	v_rcp_f32_e32 v38, v38
	s_nop 0
	v_mul_f32_e32 v37, v37, v38
	v_cvt_pk_bf16_f32 v35, v36, v37
	v_mul_f32_e32 v36, 0x3d372713, v30
	v_mul_f32_e32 v36, v30, v36
	v_fma_f32 v36, v30, v36, v30
	v_mul_f32_e32 v36, 0xbfcc422a, v36
	v_mul_f32_e32 v36, 0x3fb8aa3b, v36
	v_exp_f32_e32 v36, v36
	global_store_dwordx2 v[50:51], v[34:35], off offset:288
	v_add_u32_e32 v34, 0xa0, v161
	v_mad_i64_i32 v[34:35], s[10:11], v34, s73, v[154:155]
	v_add_f32_e32 v36, 1.0, v36
	v_rcp_f32_e32 v36, v36
	s_nop 0
	v_mul_f32_e32 v30, v30, v36
	v_mul_f32_e32 v36, 0x3d372713, v31
	v_mul_f32_e32 v36, v31, v36
	v_fma_f32 v36, v31, v36, v31
	v_mul_f32_e32 v36, 0xbfcc422a, v36
	v_mul_f32_e32 v36, 0x3fb8aa3b, v36
	v_exp_f32_e32 v36, v36
	s_nop 0
	v_add_f32_e32 v36, 1.0, v36
	v_rcp_f32_e32 v36, v36
	s_nop 0
	v_mul_f32_e32 v31, v31, v36
	v_mul_f32_e32 v36, 0x3d372713, v32
	v_mul_f32_e32 v36, v32, v36
	v_fma_f32 v36, v32, v36, v32
	v_mul_f32_e32 v36, 0xbfcc422a, v36
	v_mul_f32_e32 v36, 0x3fb8aa3b, v36
	v_exp_f32_e32 v36, v36
	v_cvt_pk_bf16_f32 v30, v30, v31
	v_add_f32_e32 v36, 1.0, v36
	v_rcp_f32_e32 v36, v36
	s_nop 0
	v_mul_f32_e32 v32, v32, v36
	v_mul_f32_e32 v36, 0x3d372713, v33
	v_mul_f32_e32 v36, v33, v36
	v_fma_f32 v36, v33, v36, v33
	v_mul_f32_e32 v36, 0xbfcc422a, v36
	v_mul_f32_e32 v36, 0x3fb8aa3b, v36
	v_exp_f32_e32 v36, v36
	s_nop 0
	v_add_f32_e32 v36, 1.0, v36
	v_rcp_f32_e32 v36, v36
	s_nop 0
	v_mul_f32_e32 v33, v33, v36
	v_cvt_pk_bf16_f32 v31, v32, v33
	global_store_dwordx2 v[34:35], v[30:31], off
	v_mul_f32_e32 v30, 0x3d372713, v26
	v_mul_f32_e32 v30, v26, v30
	v_fma_f32 v30, v26, v30, v26
	v_mul_f32_e32 v30, 0xbfcc422a, v30
	v_mul_f32_e32 v30, 0x3fb8aa3b, v30
	v_exp_f32_e32 v30, v30
	s_nop 0
	v_add_f32_e32 v30, 1.0, v30
	v_rcp_f32_e32 v30, v30
	s_nop 0
	v_mul_f32_e32 v26, v26, v30
	v_mul_f32_e32 v30, 0x3d372713, v27
	v_mul_f32_e32 v30, v27, v30
	v_fma_f32 v30, v27, v30, v27
	v_mul_f32_e32 v30, 0xbfcc422a, v30
	v_mul_f32_e32 v30, 0x3fb8aa3b, v30
	v_exp_f32_e32 v30, v30
	s_nop 0
	v_add_f32_e32 v30, 1.0, v30
	v_rcp_f32_e32 v30, v30
	s_nop 0
	v_mul_f32_e32 v27, v27, v30
	v_mul_f32_e32 v30, 0x3d372713, v28
	v_mul_f32_e32 v30, v28, v30
	v_fma_f32 v30, v28, v30, v28
	v_mul_f32_e32 v30, 0xbfcc422a, v30
	v_mul_f32_e32 v30, 0x3fb8aa3b, v30
	v_exp_f32_e32 v30, v30
	v_cvt_pk_bf16_f32 v26, v26, v27
	v_add_f32_e32 v30, 1.0, v30
	v_rcp_f32_e32 v30, v30
	s_nop 0
	v_mul_f32_e32 v28, v28, v30
	v_mul_f32_e32 v30, 0x3d372713, v29
	v_mul_f32_e32 v30, v29, v30
	v_fma_f32 v30, v29, v30, v29
	v_mul_f32_e32 v30, 0xbfcc422a, v30
	v_mul_f32_e32 v30, 0x3fb8aa3b, v30
	v_exp_f32_e32 v30, v30
	s_nop 0
	v_add_f32_e32 v30, 1.0, v30
	v_rcp_f32_e32 v30, v30
	s_nop 0
	v_mul_f32_e32 v29, v29, v30
	v_cvt_pk_bf16_f32 v27, v28, v29
	global_store_dwordx2 v[34:35], v[26:27], off offset:32
	v_mul_f32_e32 v26, 0x3d372713, v22
	v_mul_f32_e32 v26, v22, v26
	v_fma_f32 v26, v22, v26, v22
	v_mul_f32_e32 v26, 0xbfcc422a, v26
	v_mul_f32_e32 v26, 0x3fb8aa3b, v26
	v_exp_f32_e32 v26, v26
	s_nop 0
	v_add_f32_e32 v26, 1.0, v26
	v_rcp_f32_e32 v26, v26
	s_nop 0
	v_mul_f32_e32 v22, v22, v26
	v_mul_f32_e32 v26, 0x3d372713, v23
	v_mul_f32_e32 v26, v23, v26
	v_fma_f32 v26, v23, v26, v23
	v_mul_f32_e32 v26, 0xbfcc422a, v26
	v_mul_f32_e32 v26, 0x3fb8aa3b, v26
	v_exp_f32_e32 v26, v26
	s_nop 0
	v_add_f32_e32 v26, 1.0, v26
	v_rcp_f32_e32 v26, v26
	s_nop 0
	v_mul_f32_e32 v23, v23, v26
	v_mul_f32_e32 v26, 0x3d372713, v24
	v_mul_f32_e32 v26, v24, v26
	v_fma_f32 v26, v24, v26, v24
	v_mul_f32_e32 v26, 0xbfcc422a, v26
	v_mul_f32_e32 v26, 0x3fb8aa3b, v26
	v_exp_f32_e32 v26, v26
	v_cvt_pk_bf16_f32 v22, v22, v23
	v_add_f32_e32 v26, 1.0, v26
	v_rcp_f32_e32 v26, v26
	s_nop 0
	v_mul_f32_e32 v24, v24, v26
	v_mul_f32_e32 v26, 0x3d372713, v25
	v_mul_f32_e32 v26, v25, v26
	v_fma_f32 v26, v25, v26, v25
	v_mul_f32_e32 v26, 0xbfcc422a, v26
	v_mul_f32_e32 v26, 0x3fb8aa3b, v26
	v_exp_f32_e32 v26, v26
	s_nop 0
	v_add_f32_e32 v26, 1.0, v26
	v_rcp_f32_e32 v26, v26
	s_nop 0
	v_mul_f32_e32 v25, v25, v26
	v_cvt_pk_bf16_f32 v23, v24, v25
	global_store_dwordx2 v[34:35], v[22:23], off offset:256
	v_mul_f32_e32 v22, 0x3d372713, v18
	v_mul_f32_e32 v22, v18, v22
	v_fma_f32 v22, v18, v22, v18
	v_mul_f32_e32 v22, 0xbfcc422a, v22
	v_mul_f32_e32 v22, 0x3fb8aa3b, v22
	v_exp_f32_e32 v22, v22
	s_nop 0
	v_add_f32_e32 v22, 1.0, v22
	v_rcp_f32_e32 v22, v22
	s_nop 0
	v_mul_f32_e32 v18, v18, v22
	v_mul_f32_e32 v22, 0x3d372713, v19
	v_mul_f32_e32 v22, v19, v22
	v_fma_f32 v22, v19, v22, v19
	v_mul_f32_e32 v22, 0xbfcc422a, v22
	v_mul_f32_e32 v22, 0x3fb8aa3b, v22
	v_exp_f32_e32 v22, v22
	s_nop 0
	v_add_f32_e32 v22, 1.0, v22
	v_rcp_f32_e32 v22, v22
	s_nop 0
	v_mul_f32_e32 v19, v19, v22
	v_mul_f32_e32 v22, 0x3d372713, v20
	v_mul_f32_e32 v22, v20, v22
; #define PG8_WAIT_V(n) asm volatile("s_waitcnt vmcnt(" #n ")" ::: "memory")
; #define PG8_BAR __builtin_amdgcn_s_barrier()
;     ...
;     PG8_WAIT_V(0);
;     if (wr == 0) PG8_BAR;
;     PG8_BAR;
;     __device__ __forceinline__ void operator()(Acc& acc, int pm, int pn, int wr, int wc, int fr, int fq) const {
;     ...
;         for (int ai = 0; ai < 2; ++ai)
; #pragma unroll
;             for (int m = 0; m < 4; ++m) {
;                 const size_t ro = (size_t)(pm * 256 + ai * 128 + wr * 64 + m * 16 + fr) * DRNN + cb;
; #pragma unroll
;                 for (int bj = 0; bj < 2; ++bj)
; #pragma unroll
;                     for (int n = 0; n < 2; ++n) {
;                         f32x4 v = acc[ai][bj][m][n];
;                         if (isg) { v[0] = gelu_tanh(v[0]); v[1] = gelu_tanh(v[1]); v[2] = gelu_tanh(v[2]); v[3] = gelu_tanh(v[3]); }
;                         u32x2 o = {pack2(v[0], v[1]), pack2(v[2], v[3])};
;                         *reinterpret_cast<u32x2*>(base + ro + bj * 128 + n * 16) = o;
;                     }
	v_fma_f32 v22, v20, v22, v20
	v_mul_f32_e32 v22, 0xbfcc422a, v22
	v_mul_f32_e32 v22, 0x3fb8aa3b, v22
	v_exp_f32_e32 v22, v22
	v_cvt_pk_bf16_f32 v18, v18, v19
	v_add_f32_e32 v22, 1.0, v22
	v_rcp_f32_e32 v22, v22
	s_nop 0
	v_mul_f32_e32 v20, v20, v22
	v_mul_f32_e32 v22, 0x3d372713, v21
	v_mul_f32_e32 v22, v21, v22
	v_fma_f32 v22, v21, v22, v21
	v_mul_f32_e32 v22, 0xbfcc422a, v22
	v_mul_f32_e32 v22, 0x3fb8aa3b, v22
	v_exp_f32_e32 v22, v22
	s_nop 0
	v_add_f32_e32 v22, 1.0, v22
	v_rcp_f32_e32 v22, v22
	s_nop 0
	v_mul_f32_e32 v21, v21, v22
	v_cvt_pk_bf16_f32 v19, v20, v21
	v_mul_f32_e32 v20, 0x3d372713, v14
	v_mul_f32_e32 v20, v14, v20
	v_fma_f32 v20, v14, v20, v14
	v_mul_f32_e32 v20, 0xbfcc422a, v20
	v_mul_f32_e32 v20, 0x3fb8aa3b, v20
	v_exp_f32_e32 v20, v20
	global_store_dwordx2 v[34:35], v[18:19], off offset:288
	v_add_u32_e32 v18, 0xb0, v161
	v_mad_i64_i32 v[18:19], s[10:11], v18, s73, v[154:155]
	v_add_f32_e32 v20, 1.0, v20
	v_rcp_f32_e32 v20, v20
	s_mov_b64 s[10:11], s[62:63]
	v_mul_f32_e32 v14, v14, v20
	v_mul_f32_e32 v20, 0x3d372713, v15
	v_mul_f32_e32 v20, v15, v20
	v_fma_f32 v20, v15, v20, v15
	v_mul_f32_e32 v20, 0xbfcc422a, v20
	v_mul_f32_e32 v20, 0x3fb8aa3b, v20
	v_exp_f32_e32 v20, v20
	s_nop 0
	v_add_f32_e32 v20, 1.0, v20
	v_rcp_f32_e32 v20, v20
	s_nop 0
	v_mul_f32_e32 v15, v15, v20
	v_mul_f32_e32 v20, 0x3d372713, v16
	v_mul_f32_e32 v20, v16, v20
	v_fma_f32 v20, v16, v20, v16
	v_mul_f32_e32 v20, 0xbfcc422a, v20
	v_mul_f32_e32 v20, 0x3fb8aa3b, v20
	v_exp_f32_e32 v20, v20
	v_cvt_pk_bf16_f32 v14, v14, v15
	v_add_f32_e32 v20, 1.0, v20
	v_rcp_f32_e32 v20, v20
	s_nop 0
	v_mul_f32_e32 v16, v16, v20
	v_mul_f32_e32 v20, 0x3d372713, v17
	v_mul_f32_e32 v20, v17, v20
	v_fma_f32 v20, v17, v20, v17
	v_mul_f32_e32 v20, 0xbfcc422a, v20
	v_mul_f32_e32 v20, 0x3fb8aa3b, v20
	v_exp_f32_e32 v20, v20
	s_nop 0
	v_add_f32_e32 v20, 1.0, v20
	v_rcp_f32_e32 v20, v20
	s_nop 0
	v_mul_f32_e32 v17, v17, v20
	v_cvt_pk_bf16_f32 v15, v16, v17
	global_store_dwordx2 v[18:19], v[14:15], off
	v_mul_f32_e32 v14, 0x3d372713, v10
	v_mul_f32_e32 v14, v10, v14
	v_fma_f32 v14, v10, v14, v10
	v_mul_f32_e32 v14, 0xbfcc422a, v14
	v_mul_f32_e32 v14, 0x3fb8aa3b, v14
	v_exp_f32_e32 v14, v14
	s_nop 0
	v_add_f32_e32 v14, 1.0, v14
	v_rcp_f32_e32 v14, v14
	s_nop 0
	v_mul_f32_e32 v10, v10, v14
	v_mul_f32_e32 v14, 0x3d372713, v11
	v_mul_f32_e32 v14, v11, v14
	v_fma_f32 v14, v11, v14, v11
	v_mul_f32_e32 v14, 0xbfcc422a, v14
	v_mul_f32_e32 v14, 0x3fb8aa3b, v14
	v_exp_f32_e32 v14, v14
	s_nop 0
	v_add_f32_e32 v14, 1.0, v14
	v_rcp_f32_e32 v14, v14
	s_nop 0
	v_mul_f32_e32 v11, v11, v14
	v_mul_f32_e32 v14, 0x3d372713, v12
	v_mul_f32_e32 v14, v12, v14
	v_fma_f32 v14, v12, v14, v12
	v_mul_f32_e32 v14, 0xbfcc422a, v14
	v_mul_f32_e32 v14, 0x3fb8aa3b, v14
	v_exp_f32_e32 v14, v14
	v_cvt_pk_bf16_f32 v10, v10, v11
	v_add_f32_e32 v14, 1.0, v14
	v_rcp_f32_e32 v14, v14
	s_nop 0
	v_mul_f32_e32 v12, v12, v14
	v_mul_f32_e32 v14, 0x3d372713, v13
	v_mul_f32_e32 v14, v13, v14
	v_fma_f32 v14, v13, v14, v13
	v_mul_f32_e32 v14, 0xbfcc422a, v14
	v_mul_f32_e32 v14, 0x3fb8aa3b, v14
	v_exp_f32_e32 v14, v14
	s_nop 0
	v_add_f32_e32 v14, 1.0, v14
	v_rcp_f32_e32 v14, v14
	s_nop 0
	v_mul_f32_e32 v13, v13, v14
	v_cvt_pk_bf16_f32 v11, v12, v13
	global_store_dwordx2 v[18:19], v[10:11], off offset:32
	v_mul_f32_e32 v10, 0x3d372713, v6
	v_mul_f32_e32 v10, v6, v10
	v_fma_f32 v10, v6, v10, v6
	v_mul_f32_e32 v10, 0xbfcc422a, v10
	v_mul_f32_e32 v10, 0x3fb8aa3b, v10
	v_exp_f32_e32 v10, v10
	s_nop 0
	v_add_f32_e32 v10, 1.0, v10
	v_rcp_f32_e32 v10, v10
	s_nop 0
	v_mul_f32_e32 v6, v6, v10
	v_mul_f32_e32 v10, 0x3d372713, v7
	v_mul_f32_e32 v10, v7, v10
	v_fma_f32 v10, v7, v10, v7
	v_mul_f32_e32 v10, 0xbfcc422a, v10
	v_mul_f32_e32 v10, 0x3fb8aa3b, v10
	v_exp_f32_e32 v10, v10
	s_nop 0
	v_add_f32_e32 v10, 1.0, v10
	v_rcp_f32_e32 v10, v10
	s_nop 0
	v_mul_f32_e32 v7, v7, v10
	v_mul_f32_e32 v10, 0x3d372713, v8
	v_mul_f32_e32 v10, v8, v10
	v_fma_f32 v10, v8, v10, v8
	v_mul_f32_e32 v10, 0xbfcc422a, v10
	v_mul_f32_e32 v10, 0x3fb8aa3b, v10
	v_exp_f32_e32 v10, v10
	v_cvt_pk_bf16_f32 v6, v6, v7
	v_add_f32_e32 v10, 1.0, v10
	v_rcp_f32_e32 v10, v10
	s_nop 0
	v_mul_f32_e32 v8, v8, v10
	v_mul_f32_e32 v10, 0x3d372713, v9
	v_mul_f32_e32 v10, v9, v10
	v_fma_f32 v10, v9, v10, v9
	v_mul_f32_e32 v10, 0xbfcc422a, v10
	v_mul_f32_e32 v10, 0x3fb8aa3b, v10
	v_exp_f32_e32 v10, v10
	s_nop 0
	v_add_f32_e32 v10, 1.0, v10
	v_rcp_f32_e32 v10, v10
	s_nop 0
	v_mul_f32_e32 v9, v9, v10
	v_cvt_pk_bf16_f32 v7, v8, v9
	global_store_dwordx2 v[18:19], v[6:7], off offset:256
	v_mul_f32_e32 v6, 0x3d372713, v2
	v_mul_f32_e32 v6, v2, v6
	v_fma_f32 v6, v2, v6, v2
	v_mul_f32_e32 v6, 0xbfcc422a, v6
	v_mul_f32_e32 v6, 0x3fb8aa3b, v6
	v_exp_f32_e32 v6, v6
	s_nop 0
	v_add_f32_e32 v6, 1.0, v6
	v_rcp_f32_e32 v6, v6
	s_nop 0
	v_mul_f32_e32 v2, v2, v6
	v_mul_f32_e32 v6, 0x3d372713, v3
	v_mul_f32_e32 v6, v3, v6
	v_fma_f32 v6, v3, v6, v3
	v_mul_f32_e32 v6, 0xbfcc422a, v6
	v_mul_f32_e32 v6, 0x3fb8aa3b, v6
	v_exp_f32_e32 v6, v6
	s_nop 0
	v_add_f32_e32 v6, 1.0, v6
	v_rcp_f32_e32 v6, v6
	s_nop 0
	v_mul_f32_e32 v3, v3, v6
	v_mul_f32_e32 v6, 0x3d372713, v4
	v_mul_f32_e32 v6, v4, v6
	v_fma_f32 v6, v4, v6, v4
	v_mul_f32_e32 v6, 0xbfcc422a, v6
	v_mul_f32_e32 v6, 0x3fb8aa3b, v6
	v_exp_f32_e32 v6, v6
	v_cvt_pk_bf16_f32 v2, v2, v3
	v_add_f32_e32 v6, 1.0, v6
	v_rcp_f32_e32 v6, v6
	s_nop 0
	v_mul_f32_e32 v4, v4, v6
	v_mul_f32_e32 v6, 0x3d372713, v5
	v_mul_f32_e32 v6, v5, v6
	v_fma_f32 v6, v5, v6, v5
	v_mul_f32_e32 v6, 0xbfcc422a, v6
	v_mul_f32_e32 v6, 0x3fb8aa3b, v6
	v_exp_f32_e32 v6, v6
	s_nop 0
	v_add_f32_e32 v6, 1.0, v6
	v_rcp_f32_e32 v6, v6
	s_nop 0
	v_mul_f32_e32 v5, v5, v6
	v_cvt_pk_bf16_f32 v3, v4, v5
	global_store_dwordx2 v[18:19], v[2:3], off offset:288
	s_cbranch_vccz .LBB0_1048
	s_waitcnt vmcnt(0)
	s_cmpk_gt_u32 s5, 0xff
	s_cbranch_scc1 .LBB0_1055
	s_barrier

; #define PG8_STAGE(bufoff, gbase) do { _Pragma("unroll") for (int _i = 0; _i < 2; ++_i) \
;         __builtin_amdgcn_global_load_lds((const unsigned*)((const char*)(gbase) + voff[_i]), (LAS unsigned*)(lds + (bufoff) + ldsw + _i * 8192), 16, 0, 0); } while (0)
; #define PG8_LDA(dst, b, h) do { _Pragma("unroll") for (int m = 0; m < 4; ++m) _Pragma("unroll") for (int k = 0; k < 2; ++k) dst[m][k] = *(const LAS bf16x8*)(lds + PG8_SA(b, h) + aoff + m * 2048 + k * 1024); } while (0)
; #define PG8_LDB(dst, b, h) do { _Pragma("unroll") for (int n = 0; n < 2; ++n) _Pragma("unroll") for (int k = 0; k < 2; ++k) dst[n][k] = *(const LAS bf16x8*)(lds + PG8_SB(b, h) + boff + n * 2048 + k * 1024); } while (0)
; #define PG8_WAIT_V(n) asm volatile("s_waitcnt vmcnt(" #n ")" ::: "memory")
; #define PG8_WAIT_L(n) asm volatile("s_waitcnt lgkmcnt(" #n ")" ::: "memory")
; #define PG8_BAR __builtin_amdgcn_s_barrier()
; #define PG8_SCHED __builtin_amdgcn_sched_barrier(0)
;     ...
;             PG8_LDB(B0, 0, 0); PG8_SCHED; PG8_LDA(At, 0, 0); PG8_STAGE(PG8_SA(1, 1), a1 + hstep);
;             PG8_WAIT_L(8); PG8_BAR; PG8_WAIT_L(0); PG8_MMA(0, 0, At, B0); PG8_BAR; PG8_SCHED;
;             PG8_LDB(B1, 0, 1); PG8_STAGE(PG8_SB(0, 0), b2);
;             PG8_BAR; PG8_WAIT_L(0); PG8_MMA(0, 1, At, B1); PG8_BAR;
;             PG8_LDA(At, 0, 1); PG8_STAGE(PG8_SA(0, 0), a2);
;             PG8_BAR; PG8_WAIT_L(0); PG8_MMA(1, 0, At, B0); PG8_BAR; PG8_SCHED;
;             PG8_STAGE(PG8_SB(0, 1), b2 + hstep);
;             PG8_WAIT_V(6); PG8_BAR; PG8_MMA(1, 1, At, B1); PG8_BAR;
;             PG8_LDB(B0, 1, 0); PG8_SCHED; PG8_LDA(At, 1, 0); PG8_STAGE(PG8_SA(0, 1), a2 + hstep);
;             PG8_WAIT_L(8); PG8_BAR; PG8_WAIT_L(0); PG8_MMA(0, 0, At, B0); PG8_BAR; PG8_SCHED;
;             PG8_LDB(B1, 1, 1); PG8_STAGE(PG8_SB(1, 0), b3);
;             PG8_BAR; PG8_WAIT_L(0); PG8_MMA(0, 1, At, B1); PG8_BAR;
;             PG8_LDA(At, 1, 1); PG8_STAGE(PG8_SA(1, 0), a3);
;             PG8_BAR; PG8_WAIT_L(0); PG8_MMA(1, 0, At, B0); PG8_BAR; PG8_SCHED;
;             PG8_STAGE(PG8_SB(1, 1), b3 + hstep);
;             PG8_WAIT_V(6); PG8_BAR; PG8_MMA(1, 1, At, B1); PG8_BAR;
.LBB0_1245:
	s_add_i32 s67, s46, 2
	s_add_u32 s0, s40, 0x80
	s_addc_u32 s1, s41, 0
	s_add_i32 s68, 0, 0x10000
	v_add_u32_e32 v169, s68, v166
	ds_read_b128 v[130:133], v169
	ds_read_b128 v[158:161], v169 offset:1024
	ds_read_b128 v[162:165], v169 offset:2048
	ds_read_b128 v[170:173], v169 offset:3072
	s_cmp_eq_u32 s30, s46
	s_cselect_b32 s46, s12, s0
	s_cselect_b32 s47, s13, s1
	s_cselect_b32 s49, s15, s59
	s_cselect_b32 s48, s14, s58
	v_lshl_add_u64 v[174:175], s[40:41], 0, v[154:155]
	s_add_i32 m0, s23, 0xc000
	ds_read_b128 v[194:197], v168
	ds_read_b128 v[198:201], v168 offset:1024
	ds_read_b128 v[202:205], v168 offset:2048
	ds_read_b128 v[206:209], v168 offset:3072
	ds_read_b128 v[210:213], v168 offset:4096
	ds_read_b128 v[214:217], v168 offset:5120
	ds_read_b128 v[218:221], v168 offset:6144
	ds_read_b128 v[222:225], v168 offset:7168
	global_load_lds_dwordx4 v[174:175], off
	v_lshl_add_u64 v[174:175], s[40:41], 0, v[156:157]
	s_add_i32 m0, s23, 0xe000
	s_nop 0
	global_load_lds_dwordx4 v[174:175], off
	s_waitcnt lgkmcnt(8)
	s_barrier
	s_waitcnt lgkmcnt(0)
	s_setprio 1
	v_mfma_f32_16x16x32_bf16 v[126:129], v[130:133], v[194:197], v[126:129]
	v_mfma_f32_16x16x32_bf16 v[98:101], v[162:165], v[194:197], v[98:101]
	v_mfma_f32_16x16x32_bf16 v[122:125], v[130:133], v[202:205], v[122:125]
	v_mfma_f32_16x16x32_bf16 v[94:97], v[162:165], v[202:205], v[94:97]
	v_mfma_f32_16x16x32_bf16 v[118:121], v[130:133], v[210:213], v[118:121]
	v_mfma_f32_16x16x32_bf16 v[90:93], v[162:165], v[210:213], v[90:93]
	v_mfma_f32_16x16x32_bf16 v[114:117], v[130:133], v[218:221], v[114:117]
	v_mfma_f32_16x16x32_bf16 v[82:85], v[162:165], v[218:221], v[82:85]
	v_mfma_f32_16x16x32_bf16 v[126:129], v[158:161], v[198:201], v[126:129]
	v_mfma_f32_16x16x32_bf16 v[98:101], v[170:173], v[198:201], v[98:101]
	v_mfma_f32_16x16x32_bf16 v[122:125], v[158:161], v[206:209], v[122:125]
	v_mfma_f32_16x16x32_bf16 v[94:97], v[170:173], v[206:209], v[94:97]
	v_mfma_f32_16x16x32_bf16 v[118:121], v[158:161], v[214:217], v[118:121]
	v_mfma_f32_16x16x32_bf16 v[90:93], v[170:173], v[214:217], v[90:93]
	v_mfma_f32_16x16x32_bf16 v[114:117], v[158:161], v[222:225], v[114:117]
	v_mfma_f32_16x16x32_bf16 v[82:85], v[170:173], v[222:225], v[82:85]
	s_setprio 0
	s_barrier
	s_add_i32 s69, 0, 0x14000
	s_add_i32 s0, s68, s18
	v_add_u32_e32 v169, s69, v166
	v_lshl_add_u64 v[174:175], s[48:49], 0, v[152:153]
	s_mov_b32 m0, s0
	ds_read_b128 v[226:229], v169
	ds_read_b128 v[230:233], v169 offset:1024
	ds_read_b128 v[234:237], v169 offset:2048
	ds_read_b128 v[238:241], v169 offset:3072
	global_load_lds_dwordx4 v[174:175], off
	v_lshl_add_u64 v[192:193], s[48:49], 0, v[150:151]
	s_add_i32 m0, s0, 0x2000
	s_nop 0
	global_load_lds_dwordx4 v[192:193], off
	s_barrier
	s_waitcnt lgkmcnt(0)
	s_setprio 1
	v_mfma_f32_16x16x32_bf16 v[74:77], v[226:229], v[194:197], v[74:77]
	v_mfma_f32_16x16x32_bf16 v[46:49], v[234:237], v[194:197], v[46:49]
	v_mfma_f32_16x16x32_bf16 v[66:69], v[226:229], v[202:205], v[66:69]
	v_mfma_f32_16x16x32_bf16 v[38:41], v[234:237], v[202:205], v[38:41]
	v_mfma_f32_16x16x32_bf16 v[58:61], v[226:229], v[210:213], v[58:61]
	v_mfma_f32_16x16x32_bf16 v[30:33], v[234:237], v[210:213], v[30:33]
	v_mfma_f32_16x16x32_bf16 v[50:53], v[226:229], v[218:221], v[50:53]
	v_mfma_f32_16x16x32_bf16 v[22:25], v[234:237], v[218:221], v[22:25]
	v_mfma_f32_16x16x32_bf16 v[74:77], v[230:233], v[198:201], v[74:77]
	v_mfma_f32_16x16x32_bf16 v[46:49], v[238:241], v[198:201], v[46:49]
	v_mfma_f32_16x16x32_bf16 v[66:69], v[230:233], v[206:209], v[66:69]
	v_mfma_f32_16x16x32_bf16 v[38:41], v[238:241], v[206:209], v[38:41]
	v_mfma_f32_16x16x32_bf16 v[58:61], v[230:233], v[214:217], v[58:61]
	v_mfma_f32_16x16x32_bf16 v[30:33], v[238:241], v[214:217], v[30:33]
	v_mfma_f32_16x16x32_bf16 v[50:53], v[230:233], v[222:225], v[50:53]
	v_mfma_f32_16x16x32_bf16 v[22:25], v[238:241], v[222:225], v[22:25]
	s_setprio 0
	s_mov_b32 m0, s23
	v_lshl_add_u64 v[242:243], s[46:47], 0, v[152:153]
	s_barrier
	ds_read_b128 v[194:197], v168 offset:16384
	ds_read_b128 v[198:201], v168 offset:17408
	ds_read_b128 v[202:205], v168 offset:18432
	ds_read_b128 v[206:209], v168 offset:19456
	ds_read_b128 v[210:213], v168 offset:20480
	ds_read_b128 v[214:217], v168 offset:21504
	ds_read_b128 v[218:221], v168 offset:22528
	ds_read_b128 v[222:225], v168 offset:23552
	global_load_lds_dwordx4 v[242:243], off
	v_lshl_add_u64 v[244:245], s[46:47], 0, v[150:151]
	s_mov_b32 m0, s36
	s_nop 0
	global_load_lds_dwordx4 v[244:245], off
	s_barrier
	s_waitcnt lgkmcnt(0)
	s_setprio 1
	v_mfma_f32_16x16x32_bf16 v[110:113], v[130:133], v[194:197], v[110:113]
	v_mfma_f32_16x16x32_bf16 v[78:81], v[162:165], v[194:197], v[78:81]
	v_mfma_f32_16x16x32_bf16 v[106:109], v[130:133], v[202:205], v[106:109]
	v_mfma_f32_16x16x32_bf16 v[70:73], v[162:165], v[202:205], v[70:73]
	v_mfma_f32_16x16x32_bf16 v[102:105], v[130:133], v[210:213], v[102:105]
	v_mfma_f32_16x16x32_bf16 v[62:65], v[162:165], v[210:213], v[62:65]
	v_mfma_f32_16x16x32_bf16 v[86:89], v[130:133], v[218:221], v[86:89]
	v_mfma_f32_16x16x32_bf16 v[54:57], v[162:165], v[218:221], v[54:57]
	v_mfma_f32_16x16x32_bf16 v[110:113], v[158:161], v[198:201], v[110:113]
	v_mfma_f32_16x16x32_bf16 v[78:81], v[170:173], v[198:201], v[78:81]
	v_mfma_f32_16x16x32_bf16 v[106:109], v[158:161], v[206:209], v[106:109]
	v_mfma_f32_16x16x32_bf16 v[70:73], v[170:173], v[206:209], v[70:73]
	v_mfma_f32_16x16x32_bf16 v[102:105], v[158:161], v[214:217], v[102:105]
	v_mfma_f32_16x16x32_bf16 v[62:65], v[170:173], v[214:217], v[62:65]
	v_mfma_f32_16x16x32_bf16 v[86:89], v[158:161], v[222:225], v[86:89]
	v_mfma_f32_16x16x32_bf16 v[54:57], v[170:173], v[222:225], v[54:57]
	s_setprio 0
	s_barrier
; #define PG8_STAGE(bufoff, gbase) do { _Pragma("unroll") for (int _i = 0; _i < 2; ++_i) \
;         __builtin_amdgcn_global_load_lds((const unsigned*)((const char*)(gbase) + voff[_i]), (LAS unsigned*)(lds + (bufoff) + ldsw + _i * 8192), 16, 0, 0); } while (0)
; #define PG8_LDA(dst, b, h) do { _Pragma("unroll") for (int m = 0; m < 4; ++m) _Pragma("unroll") for (int k = 0; k < 2; ++k) dst[m][k] = *(const LAS bf16x8*)(lds + PG8_SA(b, h) + aoff + m * 2048 + k * 1024); } while (0)
; #define PG8_LDB(dst, b, h) do { _Pragma("unroll") for (int n = 0; n < 2; ++n) _Pragma("unroll") for (int k = 0; k < 2; ++k) dst[n][k] = *(const LAS bf16x8*)(lds + PG8_SB(b, h) + boff + n * 2048 + k * 1024); } while (0)
; #define PG8_WAIT_V(n) asm volatile("s_waitcnt vmcnt(" #n ")" ::: "memory")
; #define PG8_WAIT_L(n) asm volatile("s_waitcnt lgkmcnt(" #n ")" ::: "memory")
; #define PG8_BAR __builtin_amdgcn_s_barrier()
; #define PG8_SCHED __builtin_amdgcn_sched_barrier(0)
;     ...
;             PG8_LDB(B0, 0, 0); PG8_SCHED; PG8_LDA(At, 0, 0); PG8_STAGE(PG8_SA(1, 1), a1 + hstep);
;             PG8_WAIT_L(8); PG8_BAR; PG8_WAIT_L(0); PG8_MMA(0, 0, At, B0); PG8_BAR; PG8_SCHED;
;             PG8_LDB(B1, 0, 1); PG8_STAGE(PG8_SB(0, 0), b2);
;             PG8_BAR; PG8_WAIT_L(0); PG8_MMA(0, 1, At, B1); PG8_BAR;
;             PG8_LDA(At, 0, 1); PG8_STAGE(PG8_SA(0, 0), a2);
;             PG8_BAR; PG8_WAIT_L(0); PG8_MMA(1, 0, At, B0); PG8_BAR; PG8_SCHED;
;             PG8_STAGE(PG8_SB(0, 1), b2 + hstep);
;             PG8_WAIT_V(6); PG8_BAR; PG8_MMA(1, 1, At, B1); PG8_BAR;
;             PG8_LDB(B0, 1, 0); PG8_SCHED; PG8_LDA(At, 1, 0); PG8_STAGE(PG8_SA(0, 1), a2 + hstep);
;             PG8_WAIT_L(8); PG8_BAR; PG8_WAIT_L(0); PG8_MMA(0, 0, At, B0); PG8_BAR; PG8_SCHED;
;             PG8_LDB(B1, 1, 1); PG8_STAGE(PG8_SB(1, 0), b3);
;             PG8_BAR; PG8_WAIT_L(0); PG8_MMA(0, 1, At, B1); PG8_BAR;
;             PG8_LDA(At, 1, 1); PG8_STAGE(PG8_SA(1, 0), a3);
;             PG8_BAR; PG8_WAIT_L(0); PG8_MMA(1, 0, At, B0); PG8_BAR; PG8_SCHED;
;             PG8_STAGE(PG8_SB(1, 1), b3 + hstep);
;             PG8_WAIT_V(6); PG8_BAR; PG8_MMA(1, 1, At, B1); PG8_BAR;
	s_add_u32 s0, s48, s20
	s_addc_u32 s1, s49, 0
	s_add_i32 s48, s69, s18
	v_lshl_add_u64 v[246:247], s[0:1], 0, v[152:153]
	s_mov_b32 m0, s48
	v_lshl_add_u64 v[248:249], s[0:1], 0, v[150:151]
	global_load_lds_dwordx4 v[246:247], off
	s_add_i32 m0, s48, 0x2000
	s_nop 0
	global_load_lds_dwordx4 v[248:249], off
	s_waitcnt vmcnt(6)
	s_barrier
	s_setprio 1
	v_mfma_f32_16x16x32_bf16 v[42:45], v[226:229], v[194:197], v[42:45]
	v_mfma_f32_16x16x32_bf16 v[14:17], v[234:237], v[194:197], v[14:17]
	v_mfma_f32_16x16x32_bf16 v[34:37], v[226:229], v[202:205], v[34:37]
	v_mfma_f32_16x16x32_bf16 v[10:13], v[234:237], v[202:205], v[10:13]
	v_mfma_f32_16x16x32_bf16 v[26:29], v[226:229], v[210:213], v[26:29]
	v_mfma_f32_16x16x32_bf16 v[6:9], v[234:237], v[210:213], v[6:9]
	v_mfma_f32_16x16x32_bf16 v[18:21], v[226:229], v[218:221], v[18:21]
	v_mfma_f32_16x16x32_bf16 v[2:5], v[234:237], v[218:221], v[2:5]
	v_mfma_f32_16x16x32_bf16 v[42:45], v[230:233], v[198:201], v[42:45]
	v_mfma_f32_16x16x32_bf16 v[14:17], v[238:241], v[198:201], v[14:17]
	v_mfma_f32_16x16x32_bf16 v[34:37], v[230:233], v[206:209], v[34:37]
	v_mfma_f32_16x16x32_bf16 v[10:13], v[238:241], v[206:209], v[10:13]
	v_mfma_f32_16x16x32_bf16 v[26:29], v[230:233], v[214:217], v[26:29]
	v_mfma_f32_16x16x32_bf16 v[6:9], v[238:241], v[214:217], v[6:9]
	v_mfma_f32_16x16x32_bf16 v[18:21], v[230:233], v[222:225], v[18:21]
	v_mfma_f32_16x16x32_bf16 v[2:5], v[238:241], v[222:225], v[2:5]
	s_setprio 0
	s_add_i32 s48, 0, 0x18000
	v_add_u32_e32 v169, s48, v166
	s_barrier
	ds_read_b128 v[130:133], v169
	ds_read_b128 v[158:161], v169 offset:1024
	ds_read_b128 v[162:165], v169 offset:2048
	ds_read_b128 v[170:173], v169 offset:3072
	s_add_u32 s0, s46, s20
	s_addc_u32 s1, s47, 0
	s_mov_b32 m0, s60
	v_lshl_add_u64 v[226:227], s[0:1], 0, v[152:153]
	ds_read_b128 v[194:197], v168 offset:32768
	ds_read_b128 v[198:201], v168 offset:33792
	ds_read_b128 v[202:205], v168 offset:34816
	ds_read_b128 v[206:209], v168 offset:35840
	ds_read_b128 v[210:213], v168 offset:36864
	ds_read_b128 v[214:217], v168 offset:37888
	ds_read_b128 v[218:221], v168 offset:38912
	ds_read_b128 v[222:225], v168 offset:39936
	global_load_lds_dwordx4 v[226:227], off
	v_lshl_add_u64 v[226:227], s[0:1], 0, v[150:151]
	s_mov_b32 m0, s61
	s_nop 0
	global_load_lds_dwordx4 v[226:227], off
	s_waitcnt lgkmcnt(8)
	s_barrier
	s_waitcnt lgkmcnt(0)
	s_setprio 1
	v_mfma_f32_16x16x32_bf16 v[126:129], v[130:133], v[194:197], v[126:129]
	v_mfma_f32_16x16x32_bf16 v[98:101], v[162:165], v[194:197], v[98:101]
	v_mfma_f32_16x16x32_bf16 v[122:125], v[130:133], v[202:205], v[122:125]
	v_mfma_f32_16x16x32_bf16 v[94:97], v[162:165], v[202:205], v[94:97]
	v_mfma_f32_16x16x32_bf16 v[118:121], v[130:133], v[210:213], v[118:121]
	v_mfma_f32_16x16x32_bf16 v[90:93], v[162:165], v[210:213], v[90:93]
	v_mfma_f32_16x16x32_bf16 v[114:117], v[130:133], v[218:221], v[114:117]
	v_mfma_f32_16x16x32_bf16 v[82:85], v[162:165], v[218:221], v[82:85]
	v_mfma_f32_16x16x32_bf16 v[126:129], v[158:161], v[198:201], v[126:129]
	v_mfma_f32_16x16x32_bf16 v[98:101], v[170:173], v[198:201], v[98:101]
	v_mfma_f32_16x16x32_bf16 v[122:125], v[158:161], v[206:209], v[122:125]
	v_mfma_f32_16x16x32_bf16 v[94:97], v[170:173], v[206:209], v[94:97]
	v_mfma_f32_16x16x32_bf16 v[118:121], v[158:161], v[214:217], v[118:121]
	v_mfma_f32_16x16x32_bf16 v[90:93], v[170:173], v[214:217], v[90:93]
	v_mfma_f32_16x16x32_bf16 v[114:117], v[158:161], v[222:225], v[114:117]
	v_mfma_f32_16x16x32_bf16 v[82:85], v[170:173], v[222:225], v[82:85]
	s_setprio 0
	s_barrier
	s_add_i32 s0, 0, 0x1c000
	s_add_i32 s1, s48, s18
	v_add_u32_e32 v169, s0, v166
	v_lshl_add_u64 v[174:175], v[174:175], 0, s[88:89]
	s_mov_b32 m0, s1
	ds_read_b128 v[226:229], v169
	ds_read_b128 v[230:233], v169 offset:1024
	ds_read_b128 v[234:237], v169 offset:2048
	ds_read_b128 v[238:241], v169 offset:3072
	global_load_lds_dwordx4 v[174:175], off
	v_lshl_add_u64 v[174:175], v[192:193], 0, s[88:89]
	s_add_i32 m0, s1, 0x2000
	s_nop 0
	global_load_lds_dwordx4 v[174:175], off
	s_barrier
	s_waitcnt lgkmcnt(0)
	s_setprio 1
	v_mfma_f32_16x16x32_bf16 v[74:77], v[226:229], v[194:197], v[74:77]
	v_mfma_f32_16x16x32_bf16 v[46:49], v[234:237], v[194:197], v[46:49]
	v_mfma_f32_16x16x32_bf16 v[66:69], v[226:229], v[202:205], v[66:69]
	v_mfma_f32_16x16x32_bf16 v[38:41], v[234:237], v[202:205], v[38:41]
	v_mfma_f32_16x16x32_bf16 v[58:61], v[226:229], v[210:213], v[58:61]
	v_mfma_f32_16x16x32_bf16 v[30:33], v[234:237], v[210:213], v[30:33]
	v_mfma_f32_16x16x32_bf16 v[50:53], v[226:229], v[218:221], v[50:53]
	v_mfma_f32_16x16x32_bf16 v[22:25], v[234:237], v[218:221], v[22:25]
	v_mfma_f32_16x16x32_bf16 v[74:77], v[230:233], v[198:201], v[74:77]
	v_mfma_f32_16x16x32_bf16 v[46:49], v[238:241], v[198:201], v[46:49]
	v_mfma_f32_16x16x32_bf16 v[66:69], v[230:233], v[206:209], v[66:69]
	v_mfma_f32_16x16x32_bf16 v[38:41], v[238:241], v[206:209], v[38:41]
	v_mfma_f32_16x16x32_bf16 v[58:61], v[230:233], v[214:217], v[58:61]
	v_mfma_f32_16x16x32_bf16 v[30:33], v[238:241], v[214:217], v[30:33]
	v_mfma_f32_16x16x32_bf16 v[50:53], v[230:233], v[222:225], v[50:53]
	v_mfma_f32_16x16x32_bf16 v[22:25], v[238:241], v[222:225], v[22:25]
	s_setprio 0
	s_mov_b32 m0, s28
	v_lshl_add_u64 v[174:175], v[242:243], 0, s[88:89]
	s_barrier
	ds_read_b128 v[194:197], v168 offset:49152
	ds_read_b128 v[198:201], v168 offset:50176
	ds_read_b128 v[202:205], v168 offset:51200
	ds_read_b128 v[206:209], v168 offset:52224
	ds_read_b128 v[210:213], v168 offset:53248
	ds_read_b128 v[214:217], v168 offset:54272
	ds_read_b128 v[218:221], v168 offset:55296
	ds_read_b128 v[222:225], v168 offset:56320
	global_load_lds_dwordx4 v[174:175], off
	v_lshl_add_u64 v[174:175], v[244:245], 0, s[88:89]
	s_mov_b32 m0, s29
	s_nop 0
	global_load_lds_dwordx4 v[174:175], off
	s_barrier
; #define PG8_STAGE(bufoff, gbase) do { _Pragma("unroll") for (int _i = 0; _i < 2; ++_i) \
;         __builtin_amdgcn_global_load_lds((const unsigned*)((const char*)(gbase) + voff[_i]), (LAS unsigned*)(lds + (bufoff) + ldsw + _i * 8192), 16, 0, 0); } while (0)
; #define PG8_LDA(dst, b, h) do { _Pragma("unroll") for (int m = 0; m < 4; ++m) _Pragma("unroll") for (int k = 0; k < 2; ++k) dst[m][k] = *(const LAS bf16x8*)(lds + PG8_SA(b, h) + aoff + m * 2048 + k * 1024); } while (0)
; #define PG8_WAIT_V(n) asm volatile("s_waitcnt vmcnt(" #n ")" ::: "memory")
; #define PG8_WAIT_L(n) asm volatile("s_waitcnt lgkmcnt(" #n ")" ::: "memory")
; #define PG8_BAR __builtin_amdgcn_s_barrier()
;     ...
;             PG8_BAR; PG8_WAIT_L(0); PG8_MMA(0, 1, At, B1); PG8_BAR;
;             PG8_LDA(At, 1, 1); PG8_STAGE(PG8_SA(1, 0), a3);
;             PG8_BAR; PG8_WAIT_L(0); PG8_MMA(1, 0, At, B0); PG8_BAR; PG8_SCHED;
;             PG8_STAGE(PG8_SB(1, 1), b3 + hstep);
;             PG8_WAIT_V(6); PG8_BAR; PG8_MMA(1, 1, At, B1); PG8_BAR;
;     __device__ __forceinline__ void operator()(Acc& acc, int pm, int pn, int wr, int wc, int fr, int fq) const {
;         const int brow = pm * 256;
;         const bool lat = brow < T_LAT;
;         const float* xin = lat ? xin_lat : xin_ctx;
;         float* xout = lat ? xout_lat : xout_ctx;
;         const int rsub = lat ? 0 : T_LAT;
;         const int mi = lat ? (brow >> 12) : 8;
;         const int c0 = pn * 256 + wc * 32 + fq * 4;
;         const float* gp = modv_l + (size_t)mi * 6144 + gate_i * 1024 + c0;
; #pragma unroll
;         for (int bj = 0; bj < 2; ++bj)
; #pragma unroll
;             for (int n = 0; n < 2; ++n) {
;                 const f32x4 gv = *reinterpret_cast<const f32x4*>(gp + bj * 128 + n * 16);
; #pragma unroll
;                 for (int ai = 0; ai < 2; ++ai)
; #pragma unroll
;                     for (int m = 0; m < 4; ++m) {
;                         const size_t o = (size_t)(brow + ai * 128 + wr * 64 + m * 16 + fr - rsub) * DM + c0 + bj * 128 + n * 16;
;                         const f32x4 xi = *reinterpret_cast<const f32x4*>(xin + o);
;                         const f32x4 a = acc[ai][bj][m][n];
;                         f32x4 r = {xi[0] + gv[0] * a[0], xi[1] + gv[1] * a[1], xi[2] + gv[2] * a[2], xi[3] + gv[3] * a[3]};
;                         *reinterpret_cast<f32x4*>(xout + o) = r;
;                     }
;             }
	s_waitcnt lgkmcnt(0)
	s_setprio 1
	v_mfma_f32_16x16x32_bf16 v[110:113], v[130:133], v[194:197], v[110:113]
	v_mfma_f32_16x16x32_bf16 v[78:81], v[162:165], v[194:197], v[78:81]
	v_mfma_f32_16x16x32_bf16 v[106:109], v[130:133], v[202:205], v[106:109]
	v_mfma_f32_16x16x32_bf16 v[70:73], v[162:165], v[202:205], v[70:73]
	v_mfma_f32_16x16x32_bf16 v[102:105], v[130:133], v[210:213], v[102:105]
	v_mfma_f32_16x16x32_bf16 v[62:65], v[162:165], v[210:213], v[62:65]
	v_mfma_f32_16x16x32_bf16 v[86:89], v[130:133], v[218:221], v[86:89]
	v_mfma_f32_16x16x32_bf16 v[54:57], v[162:165], v[218:221], v[54:57]
	v_mfma_f32_16x16x32_bf16 v[110:113], v[158:161], v[198:201], v[110:113]
	v_mfma_f32_16x16x32_bf16 v[78:81], v[170:173], v[198:201], v[78:81]
	v_mfma_f32_16x16x32_bf16 v[106:109], v[158:161], v[206:209], v[106:109]
	v_mfma_f32_16x16x32_bf16 v[70:73], v[170:173], v[206:209], v[70:73]
	v_mfma_f32_16x16x32_bf16 v[102:105], v[158:161], v[214:217], v[102:105]
	v_mfma_f32_16x16x32_bf16 v[62:65], v[170:173], v[214:217], v[62:65]
	v_mfma_f32_16x16x32_bf16 v[86:89], v[158:161], v[222:225], v[86:89]
	v_mfma_f32_16x16x32_bf16 v[54:57], v[170:173], v[222:225], v[54:57]
	s_setprio 0
	s_barrier
	s_add_i32 s0, s0, s18
	v_lshl_add_u64 v[130:131], v[246:247], 0, s[88:89]
	s_mov_b32 m0, s0
	s_nop 0
	global_load_lds_dwordx4 v[130:131], off
	v_lshl_add_u64 v[130:131], v[248:249], 0, s[88:89]
	s_add_i32 m0, s0, 0x2000
	s_nop 0
	global_load_lds_dwordx4 v[130:131], off
	s_waitcnt vmcnt(6)
	s_barrier
	s_setprio 1
	v_mfma_f32_16x16x32_bf16 v[42:45], v[226:229], v[194:197], v[42:45]
	v_mfma_f32_16x16x32_bf16 v[14:17], v[234:237], v[194:197], v[14:17]
	v_mfma_f32_16x16x32_bf16 v[34:37], v[226:229], v[202:205], v[34:37]
	v_mfma_f32_16x16x32_bf16 v[10:13], v[234:237], v[202:205], v[10:13]
	v_mfma_f32_16x16x32_bf16 v[26:29], v[226:229], v[210:213], v[26:29]
	v_mfma_f32_16x16x32_bf16 v[6:9], v[234:237], v[210:213], v[6:9]
	v_mfma_f32_16x16x32_bf16 v[18:21], v[226:229], v[218:221], v[18:21]
	v_mfma_f32_16x16x32_bf16 v[2:5], v[234:237], v[218:221], v[2:5]
	v_mfma_f32_16x16x32_bf16 v[42:45], v[230:233], v[198:201], v[42:45]
	v_mfma_f32_16x16x32_bf16 v[14:17], v[238:241], v[198:201], v[14:17]
	v_mfma_f32_16x16x32_bf16 v[34:37], v[230:233], v[206:209], v[34:37]
	v_mfma_f32_16x16x32_bf16 v[10:13], v[238:241], v[206:209], v[10:13]
	v_mfma_f32_16x16x32_bf16 v[26:29], v[230:233], v[214:217], v[26:29]
	v_mfma_f32_16x16x32_bf16 v[6:9], v[238:241], v[214:217], v[6:9]
	v_mfma_f32_16x16x32_bf16 v[18:21], v[230:233], v[222:225], v[18:21]
	v_mfma_f32_16x16x32_bf16 v[2:5], v[238:241], v[222:225], v[2:5]
	s_setprio 0
	s_add_u32 s40, s40, 0x100
	s_addc_u32 s41, s41, 0
	s_add_u32 s58, s58, 0x100
	s_addc_u32 s59, s59, 0
	s_cmp_ge_u32 s67, s7
	s_mov_b32 s46, s67
	s_barrier
	s_cbranch_scc0 .LBB0_1245
	s_lshl_b32 s48, s65, 8
	v_readlane_b32 s0, v255, 26
	v_readlane_b32 s40, v255, 24
	v_readlane_b32 s68, v254, 6
	s_cmpk_lt_i32 s65, 0x80
	v_readlane_b32 s1, v255, 27
	v_readlane_b32 s41, v255, 25
	v_readlane_b32 s70, v254, 8
	v_readlane_b32 s71, v254, 9
	v_readlane_b32 s72, v254, 10
	v_readlane_b32 s73, v254, 11
	s_cselect_b32 s47, s41, s1
	s_cselect_b32 s46, s40, s0
	s_cselect_b32 s49, 0, 0xffff8000
	s_cselect_b32 s41, s71, s73
	s_cselect_b32 s40, s70, s72
	s_min_i32 s0, s65, 0x80
	s_ashr_i32 s0, s0, 4
	s_mul_hi_i32 s1, s0, 0x6000
	s_mulk_i32 s0, 0x6000
	s_add_u32 s0, s50, s0
	s_addc_u32 s1, s51, s1
	s_add_i32 s49, s49, s48
	s_add_u32 s0, s0, 0x2000
	s_addc_u32 s1, s1, 0
	v_lshl_or_b32 v162, s66, 8, v167
	v_add_u32_e32 v164, s49, v1
	v_ashrrev_i32_e32 v163, 31, v162
	v_lshl_add_u64 v[174:175], v[162:163], 2, s[0:1]
	global_load_dwordx4 v[130:133], v[174:175], off
	global_load_dwordx4 v[158:161], v[174:175], off offset:64
	global_load_dwordx4 v[170:173], v[174:175], off offset:512
	global_load_dwordx4 v[192:195], v[174:175], off offset:576
	v_lshl_add_u32 v165, v164, 10, v162
	v_lshlrev_b32_e32 v165, 2, v165
	v_add_u32_e32 v169, 0x10000, v165
	v_add_u32_e32 v248, 0x20000, v165
	v_add_u32_e32 v162, 0x30000, v165
	v_add_u32_e32 v163, 0x80000, v165
	v_add_u32_e32 v164, 0x90000, v165
	v_add_u32_e32 v174, 0xa0000, v165
	v_add_u32_e32 v175, 0xb0000, v165
	global_load_dwordx4 v[196:199], v165, s[46:47]
	global_load_dwordx4 v[200:203], v165, s[46:47] offset:64
	global_load_dwordx4 v[204:207], v169, s[46:47]
	global_load_dwordx4 v[208:211], v169, s[46:47] offset:64
	global_load_dwordx4 v[212:215], v248, s[46:47]
	global_load_dwordx4 v[216:219], v248, s[46:47] offset:64
	global_load_dwordx4 v[220:223], v162, s[46:47]
	global_load_dwordx4 v[224:227], v162, s[46:47] offset:64
	global_load_dwordx4 v[228:231], v163, s[46:47]
	global_load_dwordx4 v[232:235], v163, s[46:47] offset:64
	global_load_dwordx4 v[236:239], v164, s[46:47]
	global_load_dwordx4 v[240:243], v164, s[46:47] offset:64
	global_load_dwordx4 v[244:247], v174, s[46:47]
	v_readlane_b32 s74, v254, 12
	v_readlane_b32 s75, v254, 13
	v_readlane_b32 s74, v255, 22
	s_and_b64 vcc, exec, s[44:45]
	s_mov_b32 s66, s62
	s_mov_b32 s65, s64
	s_mov_b64 s[58:59], s[14:15]
	s_mov_b32 s94, 0x87ff
	v_readlane_b32 s75, v255, 23
	v_readlane_b32 s69, v254, 7
	s_waitcnt vmcnt(12)
	v_pk_fma_f32 v[126:127], v[126:127], v[130:131], v[196:197]
	v_pk_fma_f32 v[128:129], v[128:129], v[132:133], v[198:199]
	global_store_dwordx4 v165, v[126:129], s[40:41] sc1
	global_load_dwordx4 v[196:199], v174, s[46:47] offset:64
	s_waitcnt vmcnt(13)
	v_pk_fma_f32 v[98:99], v[98:99], v[158:159], v[200:201]
	v_pk_fma_f32 v[100:101], v[100:101], v[160:161], v[202:203]
	global_store_dwordx4 v165, v[98:101], s[40:41] offset:64 sc1
	global_load_dwordx4 v[200:203], v175, s[46:47]
	s_waitcnt vmcnt(14)
; #define PG8_WAIT_V(n) asm volatile("s_waitcnt vmcnt(" #n ")" ::: "memory")
; #define PG8_BAR __builtin_amdgcn_s_barrier()
;     ...
;     PG8_WAIT_V(0);
;     if (wr == 0) PG8_BAR;
;     PG8_BAR;
;     __device__ __forceinline__ void operator()(Acc& acc, int pm, int pn, int wr, int wc, int fr, int fq) const {
;     ...
;         for (int bj = 0; bj < 2; ++bj)
; #pragma unroll
;             for (int n = 0; n < 2; ++n) {
;                 const f32x4 gv = *reinterpret_cast<const f32x4*>(gp + bj * 128 + n * 16);
; #pragma unroll
;                 for (int ai = 0; ai < 2; ++ai)
; #pragma unroll
;                     for (int m = 0; m < 4; ++m) {
;                         const size_t o = (size_t)(brow + ai * 128 + wr * 64 + m * 16 + fr - rsub) * DM + c0 + bj * 128 + n * 16;
;                         const f32x4 xi = *reinterpret_cast<const f32x4*>(xin + o);
;                         const f32x4 a = acc[ai][bj][m][n];
;                         f32x4 r = {xi[0] + gv[0] * a[0], xi[1] + gv[1] * a[1], xi[2] + gv[2] * a[2], xi[3] + gv[3] * a[3]};
;                         *reinterpret_cast<f32x4*>(xout + o) = r;
;                     }
;             }
	v_pk_fma_f32 v[122:123], v[122:123], v[130:131], v[204:205]
	v_pk_fma_f32 v[124:125], v[124:125], v[132:133], v[206:207]
	global_store_dwordx4 v169, v[122:125], s[40:41] sc1
	global_load_dwordx4 v[204:207], v175, s[46:47] offset:64
	s_waitcnt vmcnt(15)
	v_pk_fma_f32 v[94:95], v[94:95], v[158:159], v[208:209]
	v_pk_fma_f32 v[96:97], v[96:97], v[160:161], v[210:211]
	global_store_dwordx4 v169, v[94:97], s[40:41] offset:64 sc1
	global_load_dwordx4 v[208:211], v165, s[46:47] offset:512
	s_waitcnt vmcnt(16)
	v_pk_fma_f32 v[118:119], v[118:119], v[130:131], v[212:213]
	v_pk_fma_f32 v[120:121], v[120:121], v[132:133], v[214:215]
	global_store_dwordx4 v248, v[118:121], s[40:41] sc1
	global_load_dwordx4 v[212:215], v165, s[46:47] offset:576
	s_waitcnt vmcnt(17)
	v_pk_fma_f32 v[90:91], v[90:91], v[158:159], v[216:217]
	v_pk_fma_f32 v[92:93], v[92:93], v[160:161], v[218:219]
	global_store_dwordx4 v248, v[90:93], s[40:41] offset:64 sc1
	global_load_dwordx4 v[216:219], v169, s[46:47] offset:512
	s_waitcnt vmcnt(18)
	v_pk_fma_f32 v[114:115], v[114:115], v[130:131], v[220:221]
	v_pk_fma_f32 v[116:117], v[116:117], v[132:133], v[222:223]
	global_store_dwordx4 v162, v[114:117], s[40:41] sc1
	global_load_dwordx4 v[220:223], v169, s[46:47] offset:576
	s_waitcnt vmcnt(19)
	v_pk_fma_f32 v[82:83], v[82:83], v[158:159], v[224:225]
	v_pk_fma_f32 v[84:85], v[84:85], v[160:161], v[226:227]
	global_store_dwordx4 v162, v[82:85], s[40:41] offset:64 sc1
	global_load_dwordx4 v[224:227], v248, s[46:47] offset:512
	s_waitcnt vmcnt(20)
	v_pk_fma_f32 v[110:111], v[110:111], v[130:131], v[228:229]
	v_pk_fma_f32 v[112:113], v[112:113], v[132:133], v[230:231]
	global_store_dwordx4 v163, v[110:113], s[40:41] sc1
	global_load_dwordx4 v[228:231], v248, s[46:47] offset:576
	s_waitcnt vmcnt(21)
	v_pk_fma_f32 v[78:79], v[78:79], v[158:159], v[232:233]
	v_pk_fma_f32 v[80:81], v[80:81], v[160:161], v[234:235]
	global_store_dwordx4 v163, v[78:81], s[40:41] offset:64 sc1
	global_load_dwordx4 v[232:235], v162, s[46:47] offset:512
	s_waitcnt vmcnt(22)
	v_pk_fma_f32 v[106:107], v[106:107], v[130:131], v[236:237]
	v_pk_fma_f32 v[108:109], v[108:109], v[132:133], v[238:239]
	global_store_dwordx4 v164, v[106:109], s[40:41] sc1
	global_load_dwordx4 v[236:239], v162, s[46:47] offset:576
	s_waitcnt vmcnt(23)
	v_pk_fma_f32 v[70:71], v[70:71], v[158:159], v[240:241]
	v_pk_fma_f32 v[72:73], v[72:73], v[160:161], v[242:243]
	global_store_dwordx4 v164, v[70:73], s[40:41] offset:64 sc1
	global_load_dwordx4 v[240:243], v163, s[46:47] offset:512
	s_waitcnt vmcnt(24)
	v_pk_fma_f32 v[102:103], v[102:103], v[130:131], v[244:245]
	v_pk_fma_f32 v[104:105], v[104:105], v[132:133], v[246:247]
	global_store_dwordx4 v174, v[102:105], s[40:41] sc1
	global_load_dwordx4 v[244:247], v163, s[46:47] offset:576
	s_waitcnt vmcnt(24)
	v_pk_fma_f32 v[62:63], v[62:63], v[158:159], v[196:197]
	v_pk_fma_f32 v[64:65], v[64:65], v[160:161], v[198:199]
	global_store_dwordx4 v174, v[62:65], s[40:41] offset:64 sc1
	global_load_dwordx4 v[196:199], v164, s[46:47] offset:512
	s_waitcnt vmcnt(24)
	v_pk_fma_f32 v[86:87], v[86:87], v[130:131], v[200:201]
	v_pk_fma_f32 v[88:89], v[88:89], v[132:133], v[202:203]
	global_store_dwordx4 v175, v[86:89], s[40:41] sc1
	global_load_dwordx4 v[200:203], v164, s[46:47] offset:576
	s_waitcnt vmcnt(24)
	v_pk_fma_f32 v[54:55], v[54:55], v[158:159], v[204:205]
	v_pk_fma_f32 v[56:57], v[56:57], v[160:161], v[206:207]
	global_store_dwordx4 v175, v[54:57], s[40:41] offset:64 sc1
	global_load_dwordx4 v[204:207], v174, s[46:47] offset:512
	s_waitcnt vmcnt(24)
	v_pk_fma_f32 v[74:75], v[74:75], v[170:171], v[208:209]
	v_pk_fma_f32 v[76:77], v[76:77], v[172:173], v[210:211]
	global_store_dwordx4 v165, v[74:77], s[40:41] offset:512 sc1
	global_load_dwordx4 v[208:211], v174, s[46:47] offset:576
	s_waitcnt vmcnt(24)
	v_pk_fma_f32 v[46:47], v[46:47], v[192:193], v[212:213]
	v_pk_fma_f32 v[48:49], v[48:49], v[194:195], v[214:215]
	global_store_dwordx4 v165, v[46:49], s[40:41] offset:576 sc1
	global_load_dwordx4 v[212:215], v175, s[46:47] offset:512
	s_waitcnt vmcnt(24)
	v_pk_fma_f32 v[66:67], v[66:67], v[170:171], v[216:217]
	v_pk_fma_f32 v[68:69], v[68:69], v[172:173], v[218:219]
	global_store_dwordx4 v169, v[66:69], s[40:41] offset:512 sc1
	global_load_dwordx4 v[216:219], v175, s[46:47] offset:576
	s_waitcnt vmcnt(24)
	v_pk_fma_f32 v[38:39], v[38:39], v[192:193], v[220:221]
	v_pk_fma_f32 v[40:41], v[40:41], v[194:195], v[222:223]
	global_store_dwordx4 v169, v[38:41], s[40:41] offset:576 sc1
	s_waitcnt vmcnt(23)
	v_pk_fma_f32 v[58:59], v[58:59], v[170:171], v[224:225]
	v_pk_fma_f32 v[60:61], v[60:61], v[172:173], v[226:227]
	global_store_dwordx4 v248, v[58:61], s[40:41] offset:512 sc1
	s_waitcnt vmcnt(22)
	v_pk_fma_f32 v[30:31], v[30:31], v[192:193], v[228:229]
	v_pk_fma_f32 v[32:33], v[32:33], v[194:195], v[230:231]
	global_store_dwordx4 v248, v[30:33], s[40:41] offset:576 sc1
	s_waitcnt vmcnt(21)
	v_pk_fma_f32 v[50:51], v[50:51], v[170:171], v[232:233]
	v_pk_fma_f32 v[52:53], v[52:53], v[172:173], v[234:235]
	global_store_dwordx4 v162, v[50:53], s[40:41] offset:512 sc1
	s_waitcnt vmcnt(20)
	v_pk_fma_f32 v[22:23], v[22:23], v[192:193], v[236:237]
	v_pk_fma_f32 v[24:25], v[24:25], v[194:195], v[238:239]
	global_store_dwordx4 v162, v[22:25], s[40:41] offset:576 sc1
	s_waitcnt vmcnt(19)
	v_pk_fma_f32 v[42:43], v[42:43], v[170:171], v[240:241]
	v_pk_fma_f32 v[44:45], v[44:45], v[172:173], v[242:243]
	global_store_dwordx4 v163, v[42:45], s[40:41] offset:512 sc1
	s_waitcnt vmcnt(18)
	v_pk_fma_f32 v[14:15], v[14:15], v[192:193], v[244:245]
	v_pk_fma_f32 v[16:17], v[16:17], v[194:195], v[246:247]
	global_store_dwordx4 v163, v[14:17], s[40:41] offset:576 sc1
	s_waitcnt vmcnt(17)
	v_pk_fma_f32 v[34:35], v[34:35], v[170:171], v[196:197]
	v_pk_fma_f32 v[36:37], v[36:37], v[172:173], v[198:199]
	global_store_dwordx4 v164, v[34:37], s[40:41] offset:512 sc1
	s_waitcnt vmcnt(16)
	v_pk_fma_f32 v[10:11], v[10:11], v[192:193], v[200:201]
	v_pk_fma_f32 v[12:13], v[12:13], v[194:195], v[202:203]
	global_store_dwordx4 v164, v[10:13], s[40:41] offset:576 sc1
	s_waitcnt vmcnt(15)
	v_pk_fma_f32 v[26:27], v[26:27], v[170:171], v[204:205]
	v_pk_fma_f32 v[28:29], v[28:29], v[172:173], v[206:207]
	global_store_dwordx4 v174, v[26:29], s[40:41] offset:512 sc1
	s_waitcnt vmcnt(14)
	v_pk_fma_f32 v[6:7], v[6:7], v[192:193], v[208:209]
	v_pk_fma_f32 v[8:9], v[8:9], v[194:195], v[210:211]
	global_store_dwordx4 v174, v[6:9], s[40:41] offset:576 sc1
	s_waitcnt vmcnt(13)
	v_pk_fma_f32 v[18:19], v[18:19], v[170:171], v[212:213]
	v_pk_fma_f32 v[20:21], v[20:21], v[172:173], v[214:215]
	global_store_dwordx4 v175, v[18:21], s[40:41] offset:512 sc1
	s_waitcnt vmcnt(12)
	v_pk_fma_f32 v[2:3], v[2:3], v[192:193], v[216:217]
	v_pk_fma_f32 v[4:5], v[4:5], v[194:195], v[218:219]
	global_store_dwordx4 v175, v[2:5], s[40:41] offset:576 sc1
	s_mov_b64 s[40:41], s[12:13]
	s_mov_b64 s[0:1], 0x2000
	s_cbranch_vccz .LBB0_1238
	s_waitcnt vmcnt(0)
	s_cmpk_gt_u32 s4, 0xff
	s_cbranch_scc1 .LBB0_1249
	s_barrier

; #define PG8_STAGE(bufoff, gbase) do { _Pragma("unroll") for (int _i = 0; _i < 2; ++_i) \
;         __builtin_amdgcn_global_load_lds((const unsigned*)((const char*)(gbase) + voff[_i]), (LAS unsigned*)(lds + (bufoff) + ldsw + _i * 8192), 16, 0, 0); } while (0)
; #define PG8_LDA(dst, b, h) do { _Pragma("unroll") for (int m = 0; m < 4; ++m) _Pragma("unroll") for (int k = 0; k < 2; ++k) dst[m][k] = *(const LAS bf16x8*)(lds + PG8_SA(b, h) + aoff + m * 2048 + k * 1024); } while (0)
; #define PG8_LDB(dst, b, h) do { _Pragma("unroll") for (int n = 0; n < 2; ++n) _Pragma("unroll") for (int k = 0; k < 2; ++k) dst[n][k] = *(const LAS bf16x8*)(lds + PG8_SB(b, h) + boff + n * 2048 + k * 1024); } while (0)
; #define PG8_WAIT_V(n) asm volatile("s_waitcnt vmcnt(" #n ")" ::: "memory")
; #define PG8_WAIT_L(n) asm volatile("s_waitcnt lgkmcnt(" #n ")" ::: "memory")
; #define PG8_BAR __builtin_amdgcn_s_barrier()
; #define PG8_SCHED __builtin_amdgcn_sched_barrier(0)
;     ...
;             PG8_LDB(B0, 0, 0); PG8_SCHED; PG8_LDA(At, 0, 0); PG8_STAGE(PG8_SA(1, 1), a1 + hstep);
;             PG8_WAIT_L(8); PG8_BAR; PG8_WAIT_L(0); PG8_MMA(0, 0, At, B0); PG8_BAR; PG8_SCHED;
;             PG8_LDB(B1, 0, 1); PG8_STAGE(PG8_SB(0, 0), b2);
;             PG8_BAR; PG8_WAIT_L(0); PG8_MMA(0, 1, At, B1); PG8_BAR;
;             PG8_LDA(At, 0, 1); PG8_STAGE(PG8_SA(0, 0), a2);
;             PG8_BAR; PG8_WAIT_L(0); PG8_MMA(1, 0, At, B0); PG8_BAR; PG8_SCHED;
;             PG8_STAGE(PG8_SB(0, 1), b2 + hstep);
;             PG8_WAIT_V(6); PG8_BAR; PG8_MMA(1, 1, At, B1); PG8_BAR;
;             PG8_LDB(B0, 1, 0); PG8_SCHED; PG8_LDA(At, 1, 0); PG8_STAGE(PG8_SA(0, 1), a2 + hstep);
;             PG8_WAIT_L(8); PG8_BAR; PG8_WAIT_L(0); PG8_MMA(0, 0, At, B0); PG8_BAR; PG8_SCHED;
;             PG8_LDB(B1, 1, 1); PG8_STAGE(PG8_SB(1, 0), b3);
;             PG8_BAR; PG8_WAIT_L(0); PG8_MMA(0, 1, At, B1); PG8_BAR;
;             PG8_LDA(At, 1, 1); PG8_STAGE(PG8_SA(1, 0), a3);
;             PG8_BAR; PG8_WAIT_L(0); PG8_MMA(1, 0, At, B0); PG8_BAR; PG8_SCHED;
;             PG8_STAGE(PG8_SB(1, 1), b3 + hstep);
;             PG8_WAIT_V(6); PG8_BAR; PG8_MMA(1, 1, At, B1); PG8_BAR;
.LBB0_1408:
	s_add_i32 s31, s5, 2
	s_add_u32 s0, s14, 0x80
	s_addc_u32 s1, s15, 0
	s_cmp_lg_u32 s30, s5
	s_cselect_b32 s0, s0, 0
	s_cselect_b32 s1, s1, 0
	s_add_u32 s40, s12, s0
	s_addc_u32 s41, s13, s1
	s_add_i32 s5, 0, 0x10000
	v_add_u32_e32 v157, s5, v155
	ds_read_b128 v[158:161], v157
	ds_read_b128 v[162:165], v157 offset:1024
	ds_read_b128 v[166:169], v157 offset:2048
	ds_read_b128 v[170:173], v157 offset:3072
	s_add_u32 s44, s10, s0
	s_addc_u32 s45, s11, s1
	v_lshl_add_u64 v[174:175], v[150:151], 0, s[14:15]
	s_add_i32 m0, s17, 0xc000
	ds_read_b128 v[194:197], v156
	ds_read_b128 v[198:201], v156 offset:1024
	ds_read_b128 v[202:205], v156 offset:2048
	ds_read_b128 v[206:209], v156 offset:3072
	ds_read_b128 v[210:213], v156 offset:4096
	ds_read_b128 v[214:217], v156 offset:5120
	ds_read_b128 v[218:221], v156 offset:6144
	ds_read_b128 v[222:225], v156 offset:7168
	global_load_lds_dwordx4 v[174:175], off
	v_lshl_add_u64 v[174:175], v[152:153], 0, s[14:15]
	s_add_i32 m0, s17, 0xe000
	s_nop 0
	global_load_lds_dwordx4 v[174:175], off
	s_waitcnt lgkmcnt(8)
	s_barrier
	s_waitcnt lgkmcnt(0)
	s_setprio 1
	v_mfma_f32_16x16x32_bf16 v[126:129], v[158:161], v[194:197], v[126:129]
	v_mfma_f32_16x16x32_bf16 v[98:101], v[166:169], v[194:197], v[98:101]
	v_mfma_f32_16x16x32_bf16 v[122:125], v[158:161], v[202:205], v[122:125]
	v_mfma_f32_16x16x32_bf16 v[94:97], v[166:169], v[202:205], v[94:97]
	v_mfma_f32_16x16x32_bf16 v[118:121], v[158:161], v[210:213], v[118:121]
	v_mfma_f32_16x16x32_bf16 v[90:93], v[166:169], v[210:213], v[90:93]
	v_mfma_f32_16x16x32_bf16 v[114:117], v[158:161], v[218:221], v[114:117]
	v_mfma_f32_16x16x32_bf16 v[82:85], v[166:169], v[218:221], v[82:85]
	v_mfma_f32_16x16x32_bf16 v[126:129], v[162:165], v[198:201], v[126:129]
	v_mfma_f32_16x16x32_bf16 v[98:101], v[170:173], v[198:201], v[98:101]
	v_mfma_f32_16x16x32_bf16 v[122:125], v[162:165], v[206:209], v[122:125]
	v_mfma_f32_16x16x32_bf16 v[94:97], v[170:173], v[206:209], v[94:97]
	v_mfma_f32_16x16x32_bf16 v[118:121], v[162:165], v[214:217], v[118:121]
	v_mfma_f32_16x16x32_bf16 v[90:93], v[170:173], v[214:217], v[90:93]
	v_mfma_f32_16x16x32_bf16 v[114:117], v[162:165], v[222:225], v[114:117]
	v_mfma_f32_16x16x32_bf16 v[82:85], v[170:173], v[222:225], v[82:85]
	s_setprio 0
	s_barrier
	s_add_i32 s36, 0, 0x14000
	s_add_i32 s0, s5, s16
	v_add_u32_e32 v157, s36, v155
	v_lshl_add_u64 v[174:175], s[44:45], 0, v[130:131]
	s_mov_b32 m0, s0
	ds_read_b128 v[226:229], v157
	ds_read_b128 v[230:233], v157 offset:1024
	ds_read_b128 v[234:237], v157 offset:2048
	ds_read_b128 v[238:241], v157 offset:3072
	global_load_lds_dwordx4 v[174:175], off
	v_lshl_add_u64 v[192:193], s[44:45], 0, v[132:133]
	s_add_i32 m0, s0, 0x2000
	s_nop 0
	global_load_lds_dwordx4 v[192:193], off
	s_barrier
	s_waitcnt lgkmcnt(0)
	s_setprio 1
	v_mfma_f32_16x16x32_bf16 v[74:77], v[226:229], v[194:197], v[74:77]
	v_mfma_f32_16x16x32_bf16 v[46:49], v[234:237], v[194:197], v[46:49]
	v_mfma_f32_16x16x32_bf16 v[66:69], v[226:229], v[202:205], v[66:69]
	v_mfma_f32_16x16x32_bf16 v[38:41], v[234:237], v[202:205], v[38:41]
	v_mfma_f32_16x16x32_bf16 v[58:61], v[226:229], v[210:213], v[58:61]
	v_mfma_f32_16x16x32_bf16 v[30:33], v[234:237], v[210:213], v[30:33]
	v_mfma_f32_16x16x32_bf16 v[50:53], v[226:229], v[218:221], v[50:53]
	v_mfma_f32_16x16x32_bf16 v[22:25], v[234:237], v[218:221], v[22:25]
	v_mfma_f32_16x16x32_bf16 v[74:77], v[230:233], v[198:201], v[74:77]
	v_mfma_f32_16x16x32_bf16 v[46:49], v[238:241], v[198:201], v[46:49]
	v_mfma_f32_16x16x32_bf16 v[66:69], v[230:233], v[206:209], v[66:69]
	v_mfma_f32_16x16x32_bf16 v[38:41], v[238:241], v[206:209], v[38:41]
	v_mfma_f32_16x16x32_bf16 v[58:61], v[230:233], v[214:217], v[58:61]
	v_mfma_f32_16x16x32_bf16 v[30:33], v[238:241], v[214:217], v[30:33]
	v_mfma_f32_16x16x32_bf16 v[50:53], v[230:233], v[222:225], v[50:53]
	v_mfma_f32_16x16x32_bf16 v[22:25], v[238:241], v[222:225], v[22:25]
	s_setprio 0
	s_mov_b32 m0, s17
	v_lshl_add_u64 v[242:243], s[40:41], 0, v[130:131]
	s_barrier
	ds_read_b128 v[194:197], v156 offset:16384
	ds_read_b128 v[198:201], v156 offset:17408
	ds_read_b128 v[202:205], v156 offset:18432
	ds_read_b128 v[206:209], v156 offset:19456
	ds_read_b128 v[210:213], v156 offset:20480
	ds_read_b128 v[214:217], v156 offset:21504
	ds_read_b128 v[218:221], v156 offset:22528
	ds_read_b128 v[222:225], v156 offset:23552
	global_load_lds_dwordx4 v[242:243], off
	v_lshl_add_u64 v[244:245], s[40:41], 0, v[132:133]
	s_mov_b32 m0, s18
	s_nop 0
	global_load_lds_dwordx4 v[244:245], off
	s_barrier
	s_waitcnt lgkmcnt(0)
	s_setprio 1
	v_mfma_f32_16x16x32_bf16 v[110:113], v[158:161], v[194:197], v[110:113]
	v_mfma_f32_16x16x32_bf16 v[78:81], v[166:169], v[194:197], v[78:81]
	v_mfma_f32_16x16x32_bf16 v[106:109], v[158:161], v[202:205], v[106:109]
	v_mfma_f32_16x16x32_bf16 v[70:73], v[166:169], v[202:205], v[70:73]
	v_mfma_f32_16x16x32_bf16 v[102:105], v[158:161], v[210:213], v[102:105]
	v_mfma_f32_16x16x32_bf16 v[62:65], v[166:169], v[210:213], v[62:65]
	v_mfma_f32_16x16x32_bf16 v[86:89], v[158:161], v[218:221], v[86:89]
	v_mfma_f32_16x16x32_bf16 v[54:57], v[166:169], v[218:221], v[54:57]
	v_mfma_f32_16x16x32_bf16 v[110:113], v[162:165], v[198:201], v[110:113]
	v_mfma_f32_16x16x32_bf16 v[78:81], v[170:173], v[198:201], v[78:81]
	v_mfma_f32_16x16x32_bf16 v[106:109], v[162:165], v[206:209], v[106:109]
	v_mfma_f32_16x16x32_bf16 v[70:73], v[170:173], v[206:209], v[70:73]
	v_mfma_f32_16x16x32_bf16 v[102:105], v[162:165], v[214:217], v[102:105]
	v_mfma_f32_16x16x32_bf16 v[62:65], v[170:173], v[214:217], v[62:65]
	v_mfma_f32_16x16x32_bf16 v[86:89], v[162:165], v[222:225], v[86:89]
	v_mfma_f32_16x16x32_bf16 v[54:57], v[170:173], v[222:225], v[54:57]
	s_setprio 0
	s_barrier
; #define PG8_STAGE(bufoff, gbase) do { _Pragma("unroll") for (int _i = 0; _i < 2; ++_i) \
;         __builtin_amdgcn_global_load_lds((const unsigned*)((const char*)(gbase) + voff[_i]), (LAS unsigned*)(lds + (bufoff) + ldsw + _i * 8192), 16, 0, 0); } while (0)
; #define PG8_LDA(dst, b, h) do { _Pragma("unroll") for (int m = 0; m < 4; ++m) _Pragma("unroll") for (int k = 0; k < 2; ++k) dst[m][k] = *(const LAS bf16x8*)(lds + PG8_SA(b, h) + aoff + m * 2048 + k * 1024); } while (0)
; #define PG8_LDB(dst, b, h) do { _Pragma("unroll") for (int n = 0; n < 2; ++n) _Pragma("unroll") for (int k = 0; k < 2; ++k) dst[n][k] = *(const LAS bf16x8*)(lds + PG8_SB(b, h) + boff + n * 2048 + k * 1024); } while (0)
; #define PG8_WAIT_V(n) asm volatile("s_waitcnt vmcnt(" #n ")" ::: "memory")
; #define PG8_WAIT_L(n) asm volatile("s_waitcnt lgkmcnt(" #n ")" ::: "memory")
; #define PG8_BAR __builtin_amdgcn_s_barrier()
; #define PG8_SCHED __builtin_amdgcn_sched_barrier(0)
;     ...
;             PG8_LDB(B0, 0, 0); PG8_SCHED; PG8_LDA(At, 0, 0); PG8_STAGE(PG8_SA(1, 1), a1 + hstep);
;             PG8_WAIT_L(8); PG8_BAR; PG8_WAIT_L(0); PG8_MMA(0, 0, At, B0); PG8_BAR; PG8_SCHED;
;             PG8_LDB(B1, 0, 1); PG8_STAGE(PG8_SB(0, 0), b2);
;             PG8_BAR; PG8_WAIT_L(0); PG8_MMA(0, 1, At, B1); PG8_BAR;
;             PG8_LDA(At, 0, 1); PG8_STAGE(PG8_SA(0, 0), a2);
;             PG8_BAR; PG8_WAIT_L(0); PG8_MMA(1, 0, At, B0); PG8_BAR; PG8_SCHED;
;             PG8_STAGE(PG8_SB(0, 1), b2 + hstep);
;             PG8_WAIT_V(6); PG8_BAR; PG8_MMA(1, 1, At, B1); PG8_BAR;
;             PG8_LDB(B0, 1, 0); PG8_SCHED; PG8_LDA(At, 1, 0); PG8_STAGE(PG8_SA(0, 1), a2 + hstep);
;             PG8_WAIT_L(8); PG8_BAR; PG8_WAIT_L(0); PG8_MMA(0, 0, At, B0); PG8_BAR; PG8_SCHED;
;             PG8_LDB(B1, 1, 1); PG8_STAGE(PG8_SB(1, 0), b3);
;             PG8_BAR; PG8_WAIT_L(0); PG8_MMA(0, 1, At, B1); PG8_BAR;
;             PG8_LDA(At, 1, 1); PG8_STAGE(PG8_SA(1, 0), a3);
;             PG8_BAR; PG8_WAIT_L(0); PG8_MMA(1, 0, At, B0); PG8_BAR; PG8_SCHED;
;             PG8_STAGE(PG8_SB(1, 1), b3 + hstep);
;             PG8_WAIT_V(6); PG8_BAR; PG8_MMA(1, 1, At, B1); PG8_BAR;
	s_add_u32 s0, s44, s7
	s_addc_u32 s1, s45, 0
	s_add_i32 s5, s36, s16
	v_lshl_add_u64 v[246:247], s[0:1], 0, v[130:131]
	s_mov_b32 m0, s5
	v_lshl_add_u64 v[248:249], s[0:1], 0, v[132:133]
	global_load_lds_dwordx4 v[246:247], off
	s_add_i32 m0, s5, 0x2000
	s_nop 0
	global_load_lds_dwordx4 v[248:249], off
	s_waitcnt vmcnt(6)
	s_barrier
	s_setprio 1
	v_mfma_f32_16x16x32_bf16 v[42:45], v[226:229], v[194:197], v[42:45]
	v_mfma_f32_16x16x32_bf16 v[14:17], v[234:237], v[194:197], v[14:17]
	v_mfma_f32_16x16x32_bf16 v[34:37], v[226:229], v[202:205], v[34:37]
	v_mfma_f32_16x16x32_bf16 v[10:13], v[234:237], v[202:205], v[10:13]
	v_mfma_f32_16x16x32_bf16 v[26:29], v[226:229], v[210:213], v[26:29]
	v_mfma_f32_16x16x32_bf16 v[6:9], v[234:237], v[210:213], v[6:9]
	v_mfma_f32_16x16x32_bf16 v[18:21], v[226:229], v[218:221], v[18:21]
	v_mfma_f32_16x16x32_bf16 v[2:5], v[234:237], v[218:221], v[2:5]
	v_mfma_f32_16x16x32_bf16 v[42:45], v[230:233], v[198:201], v[42:45]
	v_mfma_f32_16x16x32_bf16 v[14:17], v[238:241], v[198:201], v[14:17]
	v_mfma_f32_16x16x32_bf16 v[34:37], v[230:233], v[206:209], v[34:37]
	v_mfma_f32_16x16x32_bf16 v[10:13], v[238:241], v[206:209], v[10:13]
	v_mfma_f32_16x16x32_bf16 v[26:29], v[230:233], v[214:217], v[26:29]
	v_mfma_f32_16x16x32_bf16 v[6:9], v[238:241], v[214:217], v[6:9]
	v_mfma_f32_16x16x32_bf16 v[18:21], v[230:233], v[222:225], v[18:21]
	v_mfma_f32_16x16x32_bf16 v[2:5], v[238:241], v[222:225], v[2:5]
	s_setprio 0
	s_add_i32 s5, 0, 0x18000
	v_add_u32_e32 v157, s5, v155
	s_barrier
	ds_read_b128 v[158:161], v157
	ds_read_b128 v[162:165], v157 offset:1024
	ds_read_b128 v[166:169], v157 offset:2048
	ds_read_b128 v[170:173], v157 offset:3072
	s_add_u32 s0, s40, s7
	s_addc_u32 s1, s41, 0
	s_mov_b32 m0, s19
	v_lshl_add_u64 v[226:227], s[0:1], 0, v[130:131]
	ds_read_b128 v[194:197], v156 offset:32768
	ds_read_b128 v[198:201], v156 offset:33792
	ds_read_b128 v[202:205], v156 offset:34816
	ds_read_b128 v[206:209], v156 offset:35840
	ds_read_b128 v[210:213], v156 offset:36864
	ds_read_b128 v[214:217], v156 offset:37888
	ds_read_b128 v[218:221], v156 offset:38912
	ds_read_b128 v[222:225], v156 offset:39936
	global_load_lds_dwordx4 v[226:227], off
	v_lshl_add_u64 v[226:227], s[0:1], 0, v[132:133]
	s_mov_b32 m0, s20
	s_nop 0
	global_load_lds_dwordx4 v[226:227], off
	s_waitcnt lgkmcnt(8)
	s_barrier
	s_waitcnt lgkmcnt(0)
	s_setprio 1
	v_mfma_f32_16x16x32_bf16 v[126:129], v[158:161], v[194:197], v[126:129]
	v_mfma_f32_16x16x32_bf16 v[98:101], v[166:169], v[194:197], v[98:101]
	v_mfma_f32_16x16x32_bf16 v[122:125], v[158:161], v[202:205], v[122:125]
	v_mfma_f32_16x16x32_bf16 v[94:97], v[166:169], v[202:205], v[94:97]
	v_mfma_f32_16x16x32_bf16 v[118:121], v[158:161], v[210:213], v[118:121]
	v_mfma_f32_16x16x32_bf16 v[90:93], v[166:169], v[210:213], v[90:93]
	v_mfma_f32_16x16x32_bf16 v[114:117], v[158:161], v[218:221], v[114:117]
	v_mfma_f32_16x16x32_bf16 v[82:85], v[166:169], v[218:221], v[82:85]
	v_mfma_f32_16x16x32_bf16 v[126:129], v[162:165], v[198:201], v[126:129]
	v_mfma_f32_16x16x32_bf16 v[98:101], v[170:173], v[198:201], v[98:101]
	v_mfma_f32_16x16x32_bf16 v[122:125], v[162:165], v[206:209], v[122:125]
	v_mfma_f32_16x16x32_bf16 v[94:97], v[170:173], v[206:209], v[94:97]
	v_mfma_f32_16x16x32_bf16 v[118:121], v[162:165], v[214:217], v[118:121]
	v_mfma_f32_16x16x32_bf16 v[90:93], v[170:173], v[214:217], v[90:93]
	v_mfma_f32_16x16x32_bf16 v[114:117], v[162:165], v[222:225], v[114:117]
	v_mfma_f32_16x16x32_bf16 v[82:85], v[170:173], v[222:225], v[82:85]
	s_setprio 0
	s_barrier
	s_add_i32 s0, 0, 0x1c000
	s_add_i32 s1, s5, s16
	v_add_u32_e32 v157, s0, v155
	v_lshl_add_u64 v[174:175], v[174:175], 0, s[88:89]
	s_mov_b32 m0, s1
	ds_read_b128 v[226:229], v157
	ds_read_b128 v[230:233], v157 offset:1024
	ds_read_b128 v[234:237], v157 offset:2048
	ds_read_b128 v[238:241], v157 offset:3072
	global_load_lds_dwordx4 v[174:175], off
	v_lshl_add_u64 v[174:175], v[192:193], 0, s[88:89]
	s_add_i32 m0, s1, 0x2000
	s_nop 0
	global_load_lds_dwordx4 v[174:175], off
	s_barrier
	s_waitcnt lgkmcnt(0)
	s_setprio 1
	v_mfma_f32_16x16x32_bf16 v[74:77], v[226:229], v[194:197], v[74:77]
	v_mfma_f32_16x16x32_bf16 v[46:49], v[234:237], v[194:197], v[46:49]
	v_mfma_f32_16x16x32_bf16 v[66:69], v[226:229], v[202:205], v[66:69]
	v_mfma_f32_16x16x32_bf16 v[38:41], v[234:237], v[202:205], v[38:41]
	v_mfma_f32_16x16x32_bf16 v[58:61], v[226:229], v[210:213], v[58:61]
	v_mfma_f32_16x16x32_bf16 v[30:33], v[234:237], v[210:213], v[30:33]
	v_mfma_f32_16x16x32_bf16 v[50:53], v[226:229], v[218:221], v[50:53]
	v_mfma_f32_16x16x32_bf16 v[22:25], v[234:237], v[218:221], v[22:25]
	v_mfma_f32_16x16x32_bf16 v[74:77], v[230:233], v[198:201], v[74:77]
	v_mfma_f32_16x16x32_bf16 v[46:49], v[238:241], v[198:201], v[46:49]
	v_mfma_f32_16x16x32_bf16 v[66:69], v[230:233], v[206:209], v[66:69]
	v_mfma_f32_16x16x32_bf16 v[38:41], v[238:241], v[206:209], v[38:41]
	v_mfma_f32_16x16x32_bf16 v[58:61], v[230:233], v[214:217], v[58:61]
	v_mfma_f32_16x16x32_bf16 v[30:33], v[238:241], v[214:217], v[30:33]
	v_mfma_f32_16x16x32_bf16 v[50:53], v[230:233], v[222:225], v[50:53]
	v_mfma_f32_16x16x32_bf16 v[22:25], v[238:241], v[222:225], v[22:25]
	s_setprio 0
	s_mov_b32 m0, s28
	v_lshl_add_u64 v[174:175], v[242:243], 0, s[88:89]
	s_barrier
	ds_read_b128 v[194:197], v156 offset:49152
	ds_read_b128 v[198:201], v156 offset:50176
	ds_read_b128 v[202:205], v156 offset:51200
	ds_read_b128 v[206:209], v156 offset:52224
	ds_read_b128 v[210:213], v156 offset:53248
	ds_read_b128 v[214:217], v156 offset:54272
	ds_read_b128 v[218:221], v156 offset:55296
	ds_read_b128 v[222:225], v156 offset:56320
	global_load_lds_dwordx4 v[174:175], off
	v_lshl_add_u64 v[174:175], v[244:245], 0, s[88:89]
	s_mov_b32 m0, s29
	s_nop 0
	global_load_lds_dwordx4 v[174:175], off
	s_barrier
; #define PG8_STAGE(bufoff, gbase) do { _Pragma("unroll") for (int _i = 0; _i < 2; ++_i) \
;         __builtin_amdgcn_global_load_lds((const unsigned*)((const char*)(gbase) + voff[_i]), (LAS unsigned*)(lds + (bufoff) + ldsw + _i * 8192), 16, 0, 0); } while (0)
; #define PG8_LDA(dst, b, h) do { _Pragma("unroll") for (int m = 0; m < 4; ++m) _Pragma("unroll") for (int k = 0; k < 2; ++k) dst[m][k] = *(const LAS bf16x8*)(lds + PG8_SA(b, h) + aoff + m * 2048 + k * 1024); } while (0)
; #define PG8_WAIT_V(n) asm volatile("s_waitcnt vmcnt(" #n ")" ::: "memory")
; #define PG8_WAIT_L(n) asm volatile("s_waitcnt lgkmcnt(" #n ")" ::: "memory")
; #define PG8_BAR __builtin_amdgcn_s_barrier()
;     ...
;             PG8_BAR; PG8_WAIT_L(0); PG8_MMA(0, 1, At, B1); PG8_BAR;
;             PG8_LDA(At, 1, 1); PG8_STAGE(PG8_SA(1, 0), a3);
;             PG8_BAR; PG8_WAIT_L(0); PG8_MMA(1, 0, At, B0); PG8_BAR; PG8_SCHED;
;             PG8_STAGE(PG8_SB(1, 1), b3 + hstep);
;             PG8_WAIT_V(6); PG8_BAR; PG8_MMA(1, 1, At, B1); PG8_BAR;
;     __device__ __forceinline__ void operator()(Acc& acc, int pm, int pn, int wr, int wc, int fr, int fq) const {
;         const int brow = pm * 256;
;         const bool lat = brow < T_LAT;
;         const float* xin = lat ? xin_lat : xin_ctx;
;         float* xout = lat ? xout_lat : xout_ctx;
;         const int rsub = lat ? 0 : T_LAT;
;         const int mi = lat ? (brow >> 12) : 8;
;         const int c0 = pn * 256 + wc * 32 + fq * 4;
;         const float* gp = modv_l + (size_t)mi * 6144 + gate_i * 1024 + c0;
; #pragma unroll
;         for (int bj = 0; bj < 2; ++bj)
; #pragma unroll
;             for (int n = 0; n < 2; ++n) {
;                 const f32x4 gv = *reinterpret_cast<const f32x4*>(gp + bj * 128 + n * 16);
; #pragma unroll
;                 for (int ai = 0; ai < 2; ++ai)
; #pragma unroll
;                     for (int m = 0; m < 4; ++m) {
;                         const size_t o = (size_t)(brow + ai * 128 + wr * 64 + m * 16 + fr - rsub) * DM + c0 + bj * 128 + n * 16;
;                         const f32x4 xi = *reinterpret_cast<const f32x4*>(xin + o);
;                         const f32x4 a = acc[ai][bj][m][n];
;                         f32x4 r = {xi[0] + gv[0] * a[0], xi[1] + gv[1] * a[1], xi[2] + gv[2] * a[2], xi[3] + gv[3] * a[3]};
;                         *reinterpret_cast<f32x4*>(xout + o) = r;
;                     }
;             }
	s_waitcnt lgkmcnt(0)
	s_setprio 1
	v_mfma_f32_16x16x32_bf16 v[110:113], v[158:161], v[194:197], v[110:113]
	v_mfma_f32_16x16x32_bf16 v[78:81], v[166:169], v[194:197], v[78:81]
	v_mfma_f32_16x16x32_bf16 v[106:109], v[158:161], v[202:205], v[106:109]
	v_mfma_f32_16x16x32_bf16 v[70:73], v[166:169], v[202:205], v[70:73]
	v_mfma_f32_16x16x32_bf16 v[102:105], v[158:161], v[210:213], v[102:105]
	v_mfma_f32_16x16x32_bf16 v[62:65], v[166:169], v[210:213], v[62:65]
	v_mfma_f32_16x16x32_bf16 v[86:89], v[158:161], v[218:221], v[86:89]
	v_mfma_f32_16x16x32_bf16 v[54:57], v[166:169], v[218:221], v[54:57]
	v_mfma_f32_16x16x32_bf16 v[110:113], v[162:165], v[198:201], v[110:113]
	v_mfma_f32_16x16x32_bf16 v[78:81], v[170:173], v[198:201], v[78:81]
	v_mfma_f32_16x16x32_bf16 v[106:109], v[162:165], v[206:209], v[106:109]
	v_mfma_f32_16x16x32_bf16 v[70:73], v[170:173], v[206:209], v[70:73]
	v_mfma_f32_16x16x32_bf16 v[102:105], v[162:165], v[214:217], v[102:105]
	v_mfma_f32_16x16x32_bf16 v[62:65], v[170:173], v[214:217], v[62:65]
	v_mfma_f32_16x16x32_bf16 v[86:89], v[162:165], v[222:225], v[86:89]
	v_mfma_f32_16x16x32_bf16 v[54:57], v[170:173], v[222:225], v[54:57]
	s_setprio 0
	s_barrier
	s_add_i32 s0, s0, s16
	v_lshl_add_u64 v[158:159], v[246:247], 0, s[88:89]
	s_mov_b32 m0, s0
	s_nop 0
	global_load_lds_dwordx4 v[158:159], off
	v_lshl_add_u64 v[158:159], v[248:249], 0, s[88:89]
	s_add_i32 m0, s0, 0x2000
	s_nop 0
	global_load_lds_dwordx4 v[158:159], off
	s_waitcnt vmcnt(6)
	s_barrier
	s_setprio 1
	v_mfma_f32_16x16x32_bf16 v[42:45], v[226:229], v[194:197], v[42:45]
	v_mfma_f32_16x16x32_bf16 v[14:17], v[234:237], v[194:197], v[14:17]
	v_mfma_f32_16x16x32_bf16 v[34:37], v[226:229], v[202:205], v[34:37]
	v_mfma_f32_16x16x32_bf16 v[10:13], v[234:237], v[202:205], v[10:13]
	v_mfma_f32_16x16x32_bf16 v[26:29], v[226:229], v[210:213], v[26:29]
	v_mfma_f32_16x16x32_bf16 v[6:9], v[234:237], v[210:213], v[6:9]
	v_mfma_f32_16x16x32_bf16 v[18:21], v[226:229], v[218:221], v[18:21]
	v_mfma_f32_16x16x32_bf16 v[2:5], v[234:237], v[218:221], v[2:5]
	v_mfma_f32_16x16x32_bf16 v[42:45], v[230:233], v[198:201], v[42:45]
	v_mfma_f32_16x16x32_bf16 v[14:17], v[238:241], v[198:201], v[14:17]
	v_mfma_f32_16x16x32_bf16 v[34:37], v[230:233], v[206:209], v[34:37]
	v_mfma_f32_16x16x32_bf16 v[10:13], v[238:241], v[206:209], v[10:13]
	v_mfma_f32_16x16x32_bf16 v[26:29], v[230:233], v[214:217], v[26:29]
	v_mfma_f32_16x16x32_bf16 v[6:9], v[238:241], v[214:217], v[6:9]
	v_mfma_f32_16x16x32_bf16 v[18:21], v[230:233], v[222:225], v[18:21]
	v_mfma_f32_16x16x32_bf16 v[2:5], v[238:241], v[222:225], v[2:5]
	s_setprio 0
	s_add_u32 s14, s14, 0x100
	s_addc_u32 s15, s15, 0
	s_cmp_ge_u32 s31, s22
	s_mov_b32 s5, s31
	s_barrier
	s_cbranch_scc0 .LBB0_1408
	v_readlane_b32 s0, v253, 63
	v_readlane_b32 s10, v255, 26
	v_readlane_b32 s11, v255, 27
	v_readlane_b32 s12, v254, 6
	v_readlane_b32 s16, v254, 10
	v_readlane_b32 s17, v254, 11
	v_readlane_b32 s13, v254, 7
	v_readlane_b32 s14, v254, 8
	v_readlane_b32 s15, v254, 9
	v_readlane_b32 s18, v254, 12
	v_readlane_b32 s19, v254, 13
	v_mov_b32_e32 v161, v0
	v_lshl_or_b32 v157, v154, 2, s0
	v_or_b32_e32 v157, s23, v157
	v_lshlrev_b32_e32 v160, 2, v157
	v_readlane_b32 s0, v253, 61
	s_nop 1
	v_lshl_add_u64 v[158:159], s[50:51], 0, v[160:161]
	v_add_u32_e32 v162, s0, v1
	s_mov_b64 s[0:1], 0x32000
	v_lshl_add_u64 v[158:159], v[158:159], 0, s[0:1]
	global_load_dwordx4 v[192:195], v[158:159], off
	global_load_dwordx4 v[196:199], v[158:159], off offset:64
	global_load_dwordx4 v[200:203], v[158:159], off offset:512
	global_load_dwordx4 v[204:207], v[158:159], off offset:576
	v_add_u32_e32 v163, 0xffff8000, v162
	v_lshl_or_b32 v164, v163, 12, v160
	v_add_u32_e32 v165, 0x10000, v164
	v_add_u32_e32 v166, 0x20000, v164
	v_add_u32_e32 v167, 0x30000, v164
	v_add_u32_e32 v168, 0x80000, v164
	v_add_u32_e32 v169, 0x90000, v164
	v_add_u32_e32 v170, 0xa0000, v164
	v_add_u32_e32 v171, 0xb0000, v164
	global_load_dwordx4 v[208:211], v164, s[10:11]
	global_load_dwordx4 v[212:215], v164, s[10:11] offset:64
	global_load_dwordx4 v[216:219], v165, s[10:11]
	global_load_dwordx4 v[220:223], v165, s[10:11] offset:64
	global_load_dwordx4 v[224:227], v166, s[10:11]
	global_load_dwordx4 v[228:231], v166, s[10:11] offset:64
	global_load_dwordx4 v[232:235], v167, s[10:11]
	global_load_dwordx4 v[236:239], v167, s[10:11] offset:64
	global_load_dwordx4 v[240:243], v168, s[10:11]
	global_load_dwordx4 v[244:247], v168, s[10:11] offset:64
	s_cmpk_lt_u32 s4, 0x100
	s_waitcnt vmcnt(9)
	v_pk_fma_f32 v[126:127], v[126:127], v[192:193], v[208:209]
	v_pk_fma_f32 v[128:129], v[128:129], v[194:195], v[210:211]
	global_store_dwordx4 v164, v[126:129], s[16:17] sc1
	global_load_dwordx4 v[208:211], v169, s[10:11]
	s_waitcnt vmcnt(10)
	v_pk_fma_f32 v[98:99], v[98:99], v[196:197], v[212:213]
	v_pk_fma_f32 v[100:101], v[100:101], v[198:199], v[214:215]
	global_store_dwordx4 v164, v[98:101], s[16:17] offset:64 sc1
	global_load_dwordx4 v[212:215], v169, s[10:11] offset:64
	s_waitcnt vmcnt(11)
	v_pk_fma_f32 v[122:123], v[122:123], v[192:193], v[216:217]
	v_pk_fma_f32 v[124:125], v[124:125], v[194:195], v[218:219]
	global_store_dwordx4 v165, v[122:125], s[16:17] sc1
	global_load_dwordx4 v[216:219], v170, s[10:11]
	s_waitcnt vmcnt(12)
	v_pk_fma_f32 v[94:95], v[94:95], v[196:197], v[220:221]
	v_pk_fma_f32 v[96:97], v[96:97], v[198:199], v[222:223]
	global_store_dwordx4 v165, v[94:97], s[16:17] offset:64 sc1
	global_load_dwordx4 v[220:223], v170, s[10:11] offset:64
	s_waitcnt vmcnt(13)
	v_pk_fma_f32 v[118:119], v[118:119], v[192:193], v[224:225]
	v_pk_fma_f32 v[120:121], v[120:121], v[194:195], v[226:227]
	global_store_dwordx4 v166, v[118:121], s[16:17] sc1
	global_load_dwordx4 v[224:227], v171, s[10:11]
	s_waitcnt vmcnt(14)
; #define PG8_WAIT_V(n) asm volatile("s_waitcnt vmcnt(" #n ")" ::: "memory")
; #define PG8_BAR __builtin_amdgcn_s_barrier()
;     ...
;     PG8_WAIT_V(0);
;     if (wr == 0) PG8_BAR;
;     PG8_BAR;
;     __device__ __forceinline__ void operator()(Acc& acc, int pm, int pn, int wr, int wc, int fr, int fq) const {
;     ...
;         for (int bj = 0; bj < 2; ++bj)
; #pragma unroll
;             for (int n = 0; n < 2; ++n) {
;                 const f32x4 gv = *reinterpret_cast<const f32x4*>(gp + bj * 128 + n * 16);
; #pragma unroll
;                 for (int ai = 0; ai < 2; ++ai)
; #pragma unroll
;                     for (int m = 0; m < 4; ++m) {
;                         const size_t o = (size_t)(brow + ai * 128 + wr * 64 + m * 16 + fr - rsub) * DM + c0 + bj * 128 + n * 16;
;                         const f32x4 xi = *reinterpret_cast<const f32x4*>(xin + o);
;                         const f32x4 a = acc[ai][bj][m][n];
;                         f32x4 r = {xi[0] + gv[0] * a[0], xi[1] + gv[1] * a[1], xi[2] + gv[2] * a[2], xi[3] + gv[3] * a[3]};
;                         *reinterpret_cast<f32x4*>(xout + o) = r;
;                     }
;             }
	v_pk_fma_f32 v[90:91], v[90:91], v[196:197], v[228:229]
	v_pk_fma_f32 v[92:93], v[92:93], v[198:199], v[230:231]
	global_store_dwordx4 v166, v[90:93], s[16:17] offset:64 sc1
	global_load_dwordx4 v[228:231], v171, s[10:11] offset:64
	s_waitcnt vmcnt(15)
	v_pk_fma_f32 v[114:115], v[114:115], v[192:193], v[232:233]
	v_pk_fma_f32 v[116:117], v[116:117], v[194:195], v[234:235]
	global_store_dwordx4 v167, v[114:117], s[16:17] sc1
	global_load_dwordx4 v[232:235], v164, s[10:11] offset:512
	s_waitcnt vmcnt(16)
	v_pk_fma_f32 v[82:83], v[82:83], v[196:197], v[236:237]
	v_pk_fma_f32 v[84:85], v[84:85], v[198:199], v[238:239]
	global_store_dwordx4 v167, v[82:85], s[16:17] offset:64 sc1
	global_load_dwordx4 v[236:239], v164, s[10:11] offset:576
	s_waitcnt vmcnt(17)
	v_pk_fma_f32 v[110:111], v[110:111], v[192:193], v[240:241]
	v_pk_fma_f32 v[112:113], v[112:113], v[194:195], v[242:243]
	global_store_dwordx4 v168, v[110:113], s[16:17] sc1
	global_load_dwordx4 v[240:243], v165, s[10:11] offset:512
	s_waitcnt vmcnt(18)
	v_pk_fma_f32 v[78:79], v[78:79], v[196:197], v[244:245]
	v_pk_fma_f32 v[80:81], v[80:81], v[198:199], v[246:247]
	global_store_dwordx4 v168, v[78:81], s[16:17] offset:64 sc1
	global_load_dwordx4 v[244:247], v165, s[10:11] offset:576
	s_waitcnt vmcnt(18)
	v_pk_fma_f32 v[106:107], v[106:107], v[192:193], v[208:209]
	v_pk_fma_f32 v[108:109], v[108:109], v[194:195], v[210:211]
	global_store_dwordx4 v169, v[106:109], s[16:17] sc1
	global_load_dwordx4 v[208:211], v166, s[10:11] offset:512
	s_waitcnt vmcnt(18)
	v_pk_fma_f32 v[70:71], v[70:71], v[196:197], v[212:213]
	v_pk_fma_f32 v[72:73], v[72:73], v[198:199], v[214:215]
	global_store_dwordx4 v169, v[70:73], s[16:17] offset:64 sc1
	global_load_dwordx4 v[212:215], v166, s[10:11] offset:576
	s_waitcnt vmcnt(18)
	v_pk_fma_f32 v[102:103], v[102:103], v[192:193], v[216:217]
	v_pk_fma_f32 v[104:105], v[104:105], v[194:195], v[218:219]
	global_store_dwordx4 v170, v[102:105], s[16:17] sc1
	global_load_dwordx4 v[216:219], v167, s[10:11] offset:512
	s_waitcnt vmcnt(18)
	v_pk_fma_f32 v[62:63], v[62:63], v[196:197], v[220:221]
	v_pk_fma_f32 v[64:65], v[64:65], v[198:199], v[222:223]
	global_store_dwordx4 v170, v[62:65], s[16:17] offset:64 sc1
	global_load_dwordx4 v[220:223], v167, s[10:11] offset:576
	s_waitcnt vmcnt(18)
	v_pk_fma_f32 v[86:87], v[86:87], v[192:193], v[224:225]
	v_pk_fma_f32 v[88:89], v[88:89], v[194:195], v[226:227]
	global_store_dwordx4 v171, v[86:89], s[16:17] sc1
	global_load_dwordx4 v[224:227], v168, s[10:11] offset:512
	s_waitcnt vmcnt(18)
	v_pk_fma_f32 v[54:55], v[54:55], v[196:197], v[228:229]
	v_pk_fma_f32 v[56:57], v[56:57], v[198:199], v[230:231]
	global_store_dwordx4 v171, v[54:57], s[16:17] offset:64 sc1
	global_load_dwordx4 v[228:231], v168, s[10:11] offset:576
	s_waitcnt vmcnt(18)
	v_pk_fma_f32 v[74:75], v[74:75], v[200:201], v[232:233]
	v_pk_fma_f32 v[76:77], v[76:77], v[202:203], v[234:235]
	global_store_dwordx4 v164, v[74:77], s[16:17] offset:512 sc1
	global_load_dwordx4 v[232:235], v169, s[10:11] offset:512
	s_waitcnt vmcnt(18)
	v_pk_fma_f32 v[46:47], v[46:47], v[204:205], v[236:237]
	v_pk_fma_f32 v[48:49], v[48:49], v[206:207], v[238:239]
	global_store_dwordx4 v164, v[46:49], s[16:17] offset:576 sc1
	global_load_dwordx4 v[236:239], v169, s[10:11] offset:576
	s_waitcnt vmcnt(18)
	v_pk_fma_f32 v[66:67], v[66:67], v[200:201], v[240:241]
	v_pk_fma_f32 v[68:69], v[68:69], v[202:203], v[242:243]
	global_store_dwordx4 v165, v[66:69], s[16:17] offset:512 sc1
	global_load_dwordx4 v[240:243], v170, s[10:11] offset:512
	s_waitcnt vmcnt(18)
	v_pk_fma_f32 v[38:39], v[38:39], v[204:205], v[244:245]
	v_pk_fma_f32 v[40:41], v[40:41], v[206:207], v[246:247]
	global_store_dwordx4 v165, v[38:41], s[16:17] offset:576 sc1
	global_load_dwordx4 v[244:247], v170, s[10:11] offset:576
	s_waitcnt vmcnt(18)
	v_pk_fma_f32 v[58:59], v[58:59], v[200:201], v[208:209]
	v_pk_fma_f32 v[60:61], v[60:61], v[202:203], v[210:211]
	global_store_dwordx4 v166, v[58:61], s[16:17] offset:512 sc1
	global_load_dwordx4 v[208:211], v171, s[10:11] offset:512
	s_waitcnt vmcnt(18)
	v_pk_fma_f32 v[30:31], v[30:31], v[204:205], v[212:213]
	v_pk_fma_f32 v[32:33], v[32:33], v[206:207], v[214:215]
	global_store_dwordx4 v166, v[30:33], s[16:17] offset:576 sc1
	global_load_dwordx4 v[212:215], v171, s[10:11] offset:576
	s_waitcnt vmcnt(18)
	v_pk_fma_f32 v[50:51], v[50:51], v[200:201], v[216:217]
	v_pk_fma_f32 v[52:53], v[52:53], v[202:203], v[218:219]
	global_store_dwordx4 v167, v[50:53], s[16:17] offset:512 sc1
	s_waitcnt vmcnt(17)
	v_pk_fma_f32 v[22:23], v[22:23], v[204:205], v[220:221]
	v_pk_fma_f32 v[24:25], v[24:25], v[206:207], v[222:223]
	global_store_dwordx4 v167, v[22:25], s[16:17] offset:576 sc1
	s_waitcnt vmcnt(16)
	v_pk_fma_f32 v[42:43], v[42:43], v[200:201], v[224:225]
	v_pk_fma_f32 v[44:45], v[44:45], v[202:203], v[226:227]
	global_store_dwordx4 v168, v[42:45], s[16:17] offset:512 sc1
	s_waitcnt vmcnt(15)
	v_pk_fma_f32 v[14:15], v[14:15], v[204:205], v[228:229]
	v_pk_fma_f32 v[16:17], v[16:17], v[206:207], v[230:231]
	global_store_dwordx4 v168, v[14:17], s[16:17] offset:576 sc1
	s_waitcnt vmcnt(14)
	v_pk_fma_f32 v[34:35], v[34:35], v[200:201], v[232:233]
	v_pk_fma_f32 v[36:37], v[36:37], v[202:203], v[234:235]
	global_store_dwordx4 v169, v[34:37], s[16:17] offset:512 sc1
	s_waitcnt vmcnt(13)
	v_pk_fma_f32 v[10:11], v[10:11], v[204:205], v[236:237]
	v_pk_fma_f32 v[12:13], v[12:13], v[206:207], v[238:239]
	global_store_dwordx4 v169, v[10:13], s[16:17] offset:576 sc1
	s_waitcnt vmcnt(12)
	v_pk_fma_f32 v[26:27], v[26:27], v[200:201], v[240:241]
	v_pk_fma_f32 v[28:29], v[28:29], v[202:203], v[242:243]
	global_store_dwordx4 v170, v[26:29], s[16:17] offset:512 sc1
	s_waitcnt vmcnt(11)
	v_pk_fma_f32 v[6:7], v[6:7], v[204:205], v[244:245]
	v_pk_fma_f32 v[8:9], v[8:9], v[206:207], v[246:247]
	global_store_dwordx4 v170, v[6:9], s[16:17] offset:576 sc1
	s_waitcnt vmcnt(10)
	v_pk_fma_f32 v[18:19], v[18:19], v[200:201], v[208:209]
	v_pk_fma_f32 v[20:21], v[20:21], v[202:203], v[210:211]
	global_store_dwordx4 v171, v[18:21], s[16:17] offset:512 sc1
	s_waitcnt vmcnt(9)
	v_pk_fma_f32 v[2:3], v[2:3], v[204:205], v[212:213]
	v_pk_fma_f32 v[4:5], v[4:5], v[206:207], v[214:215]
	global_store_dwordx4 v171, v[2:5], s[16:17] offset:576 sc1
	s_mov_b32 s0, 0xf80b0000
	s_mov_b32 s1, -1
	s_waitcnt vmcnt(0)
	s_cbranch_scc0 .LBB0_1411
	s_barrier

; #define PG8_STAGE(bufoff, gbase) do { _Pragma("unroll") for (int _i = 0; _i < 2; ++_i) \
;         __builtin_amdgcn_global_load_lds((const unsigned*)((const char*)(gbase) + voff[_i]), (LAS unsigned*)(lds + (bufoff) + ldsw + _i * 8192), 16, 0, 0); } while (0)
; #define PG8_LDA(dst, b, h) do { _Pragma("unroll") for (int m = 0; m < 4; ++m) _Pragma("unroll") for (int k = 0; k < 2; ++k) dst[m][k] = *(const LAS bf16x8*)(lds + PG8_SA(b, h) + aoff + m * 2048 + k * 1024); } while (0)
; #define PG8_LDB(dst, b, h) do { _Pragma("unroll") for (int n = 0; n < 2; ++n) _Pragma("unroll") for (int k = 0; k < 2; ++k) dst[n][k] = *(const LAS bf16x8*)(lds + PG8_SB(b, h) + boff + n * 2048 + k * 1024); } while (0)
; #define PG8_WAIT_V(n) asm volatile("s_waitcnt vmcnt(" #n ")" ::: "memory")
; #define PG8_WAIT_L(n) asm volatile("s_waitcnt lgkmcnt(" #n ")" ::: "memory")
; #define PG8_BAR __builtin_amdgcn_s_barrier()
; #define PG8_SCHED __builtin_amdgcn_sched_barrier(0)
;     ...
;             PG8_LDB(B0, 0, 0); PG8_SCHED; PG8_LDA(At, 0, 0); PG8_STAGE(PG8_SA(1, 1), a1 + hstep);
;             PG8_WAIT_L(8); PG8_BAR; PG8_WAIT_L(0); PG8_MMA(0, 0, At, B0); PG8_BAR; PG8_SCHED;
;             PG8_LDB(B1, 0, 1); PG8_STAGE(PG8_SB(0, 0), b2);
;             PG8_BAR; PG8_WAIT_L(0); PG8_MMA(0, 1, At, B1); PG8_BAR;
;             PG8_LDA(At, 0, 1); PG8_STAGE(PG8_SA(0, 0), a2);
;             PG8_BAR; PG8_WAIT_L(0); PG8_MMA(1, 0, At, B0); PG8_BAR; PG8_SCHED;
;             PG8_STAGE(PG8_SB(0, 1), b2 + hstep);
;             PG8_WAIT_V(6); PG8_BAR; PG8_MMA(1, 1, At, B1); PG8_BAR;
;             PG8_LDB(B0, 1, 0); PG8_SCHED; PG8_LDA(At, 1, 0); PG8_STAGE(PG8_SA(0, 1), a2 + hstep);
;             PG8_WAIT_L(8); PG8_BAR; PG8_WAIT_L(0); PG8_MMA(0, 0, At, B0); PG8_BAR; PG8_SCHED;
;             PG8_LDB(B1, 1, 1); PG8_STAGE(PG8_SB(1, 0), b3);
;             PG8_BAR; PG8_WAIT_L(0); PG8_MMA(0, 1, At, B1); PG8_BAR;
;             PG8_LDA(At, 1, 1); PG8_STAGE(PG8_SA(1, 0), a3);
;             PG8_BAR; PG8_WAIT_L(0); PG8_MMA(1, 0, At, B0); PG8_BAR; PG8_SCHED;
;             PG8_STAGE(PG8_SB(1, 1), b3 + hstep);
;             PG8_WAIT_V(6); PG8_BAR; PG8_MMA(1, 1, At, B1); PG8_BAR;
.LBB0_1563:
	s_add_u32 s0, s12, 0xfffc0080
	s_addc_u32 s1, s13, -1
	s_add_i32 s30, 0, 0x10000
	v_add_u32_e32 v157, s30, v154
	ds_read_b128 v[158:161], v157
	ds_read_b128 v[162:165], v157 offset:1024
	ds_read_b128 v[166:169], v157 offset:2048
	ds_read_b128 v[170:173], v157 offset:3072
	s_cmp_eq_u32 s29, 12
	s_cselect_b32 s59, s7, s1
	s_cselect_b32 s58, s18, s0
	s_cselect_b32 s15, s19, s28
	s_cselect_b32 s14, s22, s23
	v_lshl_add_u64 v[174:175], s[12:13], 0, v[150:151]
	s_add_i32 m0, s11, 0xc000
	ds_read_b128 v[194:197], v156
	ds_read_b128 v[198:201], v156 offset:1024
	ds_read_b128 v[202:205], v156 offset:2048
	ds_read_b128 v[206:209], v156 offset:3072
	ds_read_b128 v[210:213], v156 offset:4096
	ds_read_b128 v[214:217], v156 offset:5120
	ds_read_b128 v[218:221], v156 offset:6144
	ds_read_b128 v[222:225], v156 offset:7168
	global_load_lds_dwordx4 v[174:175], off
	v_lshl_add_u64 v[174:175], s[12:13], 0, v[152:153]
	s_add_i32 m0, s11, 0xe000
	s_nop 0
	global_load_lds_dwordx4 v[174:175], off
	s_waitcnt lgkmcnt(8)
	s_barrier
	s_waitcnt lgkmcnt(0)
	s_setprio 1
	v_mfma_f32_16x16x32_bf16 v[126:129], v[158:161], v[194:197], v[126:129]
	v_mfma_f32_16x16x32_bf16 v[118:121], v[166:169], v[194:197], v[118:121]
	v_mfma_f32_16x16x32_bf16 v[110:113], v[158:161], v[202:205], v[110:113]
	v_mfma_f32_16x16x32_bf16 v[102:105], v[166:169], v[202:205], v[102:105]
	v_mfma_f32_16x16x32_bf16 v[94:97], v[158:161], v[210:213], v[94:97]
	v_mfma_f32_16x16x32_bf16 v[86:89], v[166:169], v[210:213], v[86:89]
	v_mfma_f32_16x16x32_bf16 v[78:81], v[158:161], v[218:221], v[78:81]
	v_mfma_f32_16x16x32_bf16 v[70:73], v[166:169], v[218:221], v[70:73]
	v_mfma_f32_16x16x32_bf16 v[126:129], v[162:165], v[198:201], v[126:129]
	v_mfma_f32_16x16x32_bf16 v[118:121], v[170:173], v[198:201], v[118:121]
	v_mfma_f32_16x16x32_bf16 v[110:113], v[162:165], v[206:209], v[110:113]
	v_mfma_f32_16x16x32_bf16 v[102:105], v[170:173], v[206:209], v[102:105]
	v_mfma_f32_16x16x32_bf16 v[94:97], v[162:165], v[214:217], v[94:97]
	v_mfma_f32_16x16x32_bf16 v[86:89], v[170:173], v[214:217], v[86:89]
	v_mfma_f32_16x16x32_bf16 v[78:81], v[162:165], v[222:225], v[78:81]
	v_mfma_f32_16x16x32_bf16 v[70:73], v[170:173], v[222:225], v[70:73]
	s_setprio 0
	s_barrier
	s_add_i32 s31, 0, 0x14000
	s_add_i32 s0, s30, s17
	v_add_u32_e32 v157, s31, v154
	v_lshl_add_u64 v[174:175], s[14:15], 0, v[132:133]
	s_mov_b32 m0, s0
	ds_read_b128 v[226:229], v157
	ds_read_b128 v[230:233], v157 offset:1024
	ds_read_b128 v[234:237], v157 offset:2048
	ds_read_b128 v[238:241], v157 offset:3072
	global_load_lds_dwordx4 v[174:175], off
	v_lshl_add_u64 v[192:193], s[14:15], 0, v[130:131]
	s_add_i32 m0, s0, 0x2000
	s_nop 0
	global_load_lds_dwordx4 v[192:193], off
	s_barrier
	s_waitcnt lgkmcnt(0)
	s_setprio 1
	v_mfma_f32_16x16x32_bf16 v[122:125], v[226:229], v[194:197], v[122:125]
	v_mfma_f32_16x16x32_bf16 v[114:117], v[234:237], v[194:197], v[114:117]
	v_mfma_f32_16x16x32_bf16 v[106:109], v[226:229], v[202:205], v[106:109]
	v_mfma_f32_16x16x32_bf16 v[98:101], v[234:237], v[202:205], v[98:101]
	v_mfma_f32_16x16x32_bf16 v[90:93], v[226:229], v[210:213], v[90:93]
	v_mfma_f32_16x16x32_bf16 v[82:85], v[234:237], v[210:213], v[82:85]
	v_mfma_f32_16x16x32_bf16 v[74:77], v[226:229], v[218:221], v[74:77]
	v_mfma_f32_16x16x32_bf16 v[66:69], v[234:237], v[218:221], v[66:69]
	v_mfma_f32_16x16x32_bf16 v[122:125], v[230:233], v[198:201], v[122:125]
	v_mfma_f32_16x16x32_bf16 v[114:117], v[238:241], v[198:201], v[114:117]
	v_mfma_f32_16x16x32_bf16 v[106:109], v[230:233], v[206:209], v[106:109]
	v_mfma_f32_16x16x32_bf16 v[98:101], v[238:241], v[206:209], v[98:101]
	v_mfma_f32_16x16x32_bf16 v[90:93], v[230:233], v[214:217], v[90:93]
	v_mfma_f32_16x16x32_bf16 v[82:85], v[238:241], v[214:217], v[82:85]
	v_mfma_f32_16x16x32_bf16 v[74:77], v[230:233], v[222:225], v[74:77]
	v_mfma_f32_16x16x32_bf16 v[66:69], v[238:241], v[222:225], v[66:69]
	s_setprio 0
	s_mov_b32 m0, s11
	v_lshl_add_u64 v[242:243], s[58:59], 0, v[132:133]
	s_barrier
	ds_read_b128 v[194:197], v156 offset:16384
	ds_read_b128 v[198:201], v156 offset:17408
	ds_read_b128 v[202:205], v156 offset:18432
	ds_read_b128 v[206:209], v156 offset:19456
	ds_read_b128 v[210:213], v156 offset:20480
	ds_read_b128 v[214:217], v156 offset:21504
	ds_read_b128 v[218:221], v156 offset:22528
	ds_read_b128 v[222:225], v156 offset:23552
	global_load_lds_dwordx4 v[242:243], off
	v_lshl_add_u64 v[244:245], s[58:59], 0, v[130:131]
	s_mov_b32 m0, s36
	s_nop 0
	global_load_lds_dwordx4 v[244:245], off
	s_barrier
	s_waitcnt lgkmcnt(0)
	s_setprio 1
	v_mfma_f32_16x16x32_bf16 v[62:65], v[158:161], v[194:197], v[62:65]
	v_mfma_f32_16x16x32_bf16 v[54:57], v[166:169], v[194:197], v[54:57]
	v_mfma_f32_16x16x32_bf16 v[46:49], v[158:161], v[202:205], v[46:49]
	v_mfma_f32_16x16x32_bf16 v[38:41], v[166:169], v[202:205], v[38:41]
	v_mfma_f32_16x16x32_bf16 v[30:33], v[158:161], v[210:213], v[30:33]
	v_mfma_f32_16x16x32_bf16 v[22:25], v[166:169], v[210:213], v[22:25]
	v_mfma_f32_16x16x32_bf16 v[14:17], v[158:161], v[218:221], v[14:17]
	v_mfma_f32_16x16x32_bf16 v[6:9], v[166:169], v[218:221], v[6:9]
	v_mfma_f32_16x16x32_bf16 v[62:65], v[162:165], v[198:201], v[62:65]
	v_mfma_f32_16x16x32_bf16 v[54:57], v[170:173], v[198:201], v[54:57]
	v_mfma_f32_16x16x32_bf16 v[46:49], v[162:165], v[206:209], v[46:49]
	v_mfma_f32_16x16x32_bf16 v[38:41], v[170:173], v[206:209], v[38:41]
	v_mfma_f32_16x16x32_bf16 v[30:33], v[162:165], v[214:217], v[30:33]
	v_mfma_f32_16x16x32_bf16 v[22:25], v[170:173], v[214:217], v[22:25]
	v_mfma_f32_16x16x32_bf16 v[14:17], v[162:165], v[222:225], v[14:17]
	v_mfma_f32_16x16x32_bf16 v[6:9], v[170:173], v[222:225], v[6:9]
	s_setprio 0
	s_barrier
; #define PG8_STAGE(bufoff, gbase) do { _Pragma("unroll") for (int _i = 0; _i < 2; ++_i) \
;         __builtin_amdgcn_global_load_lds((const unsigned*)((const char*)(gbase) + voff[_i]), (LAS unsigned*)(lds + (bufoff) + ldsw + _i * 8192), 16, 0, 0); } while (0)
; #define PG8_LDA(dst, b, h) do { _Pragma("unroll") for (int m = 0; m < 4; ++m) _Pragma("unroll") for (int k = 0; k < 2; ++k) dst[m][k] = *(const LAS bf16x8*)(lds + PG8_SA(b, h) + aoff + m * 2048 + k * 1024); } while (0)
; #define PG8_LDB(dst, b, h) do { _Pragma("unroll") for (int n = 0; n < 2; ++n) _Pragma("unroll") for (int k = 0; k < 2; ++k) dst[n][k] = *(const LAS bf16x8*)(lds + PG8_SB(b, h) + boff + n * 2048 + k * 1024); } while (0)
; #define PG8_WAIT_V(n) asm volatile("s_waitcnt vmcnt(" #n ")" ::: "memory")
; #define PG8_WAIT_L(n) asm volatile("s_waitcnt lgkmcnt(" #n ")" ::: "memory")
; #define PG8_BAR __builtin_amdgcn_s_barrier()
; #define PG8_SCHED __builtin_amdgcn_sched_barrier(0)
;     ...
;             PG8_LDB(B0, 0, 0); PG8_SCHED; PG8_LDA(At, 0, 0); PG8_STAGE(PG8_SA(1, 1), a1 + hstep);
;             PG8_WAIT_L(8); PG8_BAR; PG8_WAIT_L(0); PG8_MMA(0, 0, At, B0); PG8_BAR; PG8_SCHED;
;             PG8_LDB(B1, 0, 1); PG8_STAGE(PG8_SB(0, 0), b2);
;             PG8_BAR; PG8_WAIT_L(0); PG8_MMA(0, 1, At, B1); PG8_BAR;
;             PG8_LDA(At, 0, 1); PG8_STAGE(PG8_SA(0, 0), a2);
;             PG8_BAR; PG8_WAIT_L(0); PG8_MMA(1, 0, At, B0); PG8_BAR; PG8_SCHED;
;             PG8_STAGE(PG8_SB(0, 1), b2 + hstep);
;             PG8_WAIT_V(6); PG8_BAR; PG8_MMA(1, 1, At, B1); PG8_BAR;
;             PG8_LDB(B0, 1, 0); PG8_SCHED; PG8_LDA(At, 1, 0); PG8_STAGE(PG8_SA(0, 1), a2 + hstep);
;             PG8_WAIT_L(8); PG8_BAR; PG8_WAIT_L(0); PG8_MMA(0, 0, At, B0); PG8_BAR; PG8_SCHED;
;             PG8_LDB(B1, 1, 1); PG8_STAGE(PG8_SB(1, 0), b3);
;             PG8_BAR; PG8_WAIT_L(0); PG8_MMA(0, 1, At, B1); PG8_BAR;
;             PG8_LDA(At, 1, 1); PG8_STAGE(PG8_SA(1, 0), a3);
;             PG8_BAR; PG8_WAIT_L(0); PG8_MMA(1, 0, At, B0); PG8_BAR; PG8_SCHED;
;             PG8_STAGE(PG8_SB(1, 1), b3 + hstep);
;             PG8_WAIT_V(6); PG8_BAR; PG8_MMA(1, 1, At, B1); PG8_BAR;
	s_add_u32 s0, s14, 0x40000
	s_addc_u32 s1, s15, 0
	s_add_i32 s30, s31, s17
	v_lshl_add_u64 v[158:159], s[0:1], 0, v[132:133]
	s_mov_b32 m0, s30
	s_nop 0
	global_load_lds_dwordx4 v[158:159], off
	v_lshl_add_u64 v[158:159], s[0:1], 0, v[130:131]
	s_add_i32 m0, s30, 0x2000
	s_nop 0
	global_load_lds_dwordx4 v[158:159], off
	s_waitcnt vmcnt(6)
	s_barrier
	s_setprio 1
	v_mfma_f32_16x16x32_bf16 v[58:61], v[226:229], v[194:197], v[58:61]
	v_mfma_f32_16x16x32_bf16 v[50:53], v[234:237], v[194:197], v[50:53]
	v_mfma_f32_16x16x32_bf16 v[42:45], v[226:229], v[202:205], v[42:45]
	v_mfma_f32_16x16x32_bf16 v[34:37], v[234:237], v[202:205], v[34:37]
	v_mfma_f32_16x16x32_bf16 v[26:29], v[226:229], v[210:213], v[26:29]
	v_mfma_f32_16x16x32_bf16 v[18:21], v[234:237], v[210:213], v[18:21]
	v_mfma_f32_16x16x32_bf16 v[10:13], v[226:229], v[218:221], v[10:13]
	v_mfma_f32_16x16x32_bf16 v[2:5], v[234:237], v[218:221], v[2:5]
	v_mfma_f32_16x16x32_bf16 v[58:61], v[230:233], v[198:201], v[58:61]
	v_mfma_f32_16x16x32_bf16 v[50:53], v[238:241], v[198:201], v[50:53]
	v_mfma_f32_16x16x32_bf16 v[42:45], v[230:233], v[206:209], v[42:45]
	v_mfma_f32_16x16x32_bf16 v[34:37], v[238:241], v[206:209], v[34:37]
	v_mfma_f32_16x16x32_bf16 v[26:29], v[230:233], v[214:217], v[26:29]
	v_mfma_f32_16x16x32_bf16 v[18:21], v[238:241], v[214:217], v[18:21]
	v_mfma_f32_16x16x32_bf16 v[10:13], v[230:233], v[222:225], v[10:13]
	v_mfma_f32_16x16x32_bf16 v[2:5], v[238:241], v[222:225], v[2:5]
	s_setprio 0
	s_add_i32 s30, 0, 0x18000
	v_add_u32_e32 v157, s30, v154
	s_barrier
	ds_read_b128 v[158:161], v157
	ds_read_b128 v[162:165], v157 offset:1024
	ds_read_b128 v[166:169], v157 offset:2048
	ds_read_b128 v[170:173], v157 offset:3072
	s_add_u32 s0, s58, 0x40000
	s_addc_u32 s1, s59, 0
	s_mov_b32 m0, s63
	v_lshl_add_u64 v[226:227], s[0:1], 0, v[132:133]
	ds_read_b128 v[194:197], v156 offset:32768
	ds_read_b128 v[198:201], v156 offset:33792
	ds_read_b128 v[202:205], v156 offset:34816
	ds_read_b128 v[206:209], v156 offset:35840
	ds_read_b128 v[210:213], v156 offset:36864
	ds_read_b128 v[214:217], v156 offset:37888
	ds_read_b128 v[218:221], v156 offset:38912
	ds_read_b128 v[222:225], v156 offset:39936
	global_load_lds_dwordx4 v[226:227], off
	v_lshl_add_u64 v[226:227], s[0:1], 0, v[130:131]
	s_mov_b32 m0, s64
	s_nop 0
	global_load_lds_dwordx4 v[226:227], off
	s_waitcnt lgkmcnt(8)
	s_barrier
	s_waitcnt lgkmcnt(0)
	s_setprio 1
	v_mfma_f32_16x16x32_bf16 v[126:129], v[158:161], v[194:197], v[126:129]
	v_mfma_f32_16x16x32_bf16 v[118:121], v[166:169], v[194:197], v[118:121]
	v_mfma_f32_16x16x32_bf16 v[110:113], v[158:161], v[202:205], v[110:113]
	v_mfma_f32_16x16x32_bf16 v[102:105], v[166:169], v[202:205], v[102:105]
	v_mfma_f32_16x16x32_bf16 v[94:97], v[158:161], v[210:213], v[94:97]
	v_mfma_f32_16x16x32_bf16 v[86:89], v[166:169], v[210:213], v[86:89]
	v_mfma_f32_16x16x32_bf16 v[78:81], v[158:161], v[218:221], v[78:81]
	v_mfma_f32_16x16x32_bf16 v[70:73], v[166:169], v[218:221], v[70:73]
	v_mfma_f32_16x16x32_bf16 v[126:129], v[162:165], v[198:201], v[126:129]
	v_mfma_f32_16x16x32_bf16 v[118:121], v[170:173], v[198:201], v[118:121]
	v_mfma_f32_16x16x32_bf16 v[110:113], v[162:165], v[206:209], v[110:113]
	v_mfma_f32_16x16x32_bf16 v[102:105], v[170:173], v[206:209], v[102:105]
	v_mfma_f32_16x16x32_bf16 v[94:97], v[162:165], v[214:217], v[94:97]
	v_mfma_f32_16x16x32_bf16 v[86:89], v[170:173], v[214:217], v[86:89]
	v_mfma_f32_16x16x32_bf16 v[78:81], v[162:165], v[222:225], v[78:81]
	v_mfma_f32_16x16x32_bf16 v[70:73], v[170:173], v[222:225], v[70:73]
	s_setprio 0
	s_barrier
	s_add_i32 s31, 0, 0x1c000
	s_add_i32 s0, s30, s17
	v_add_u32_e32 v157, s31, v154
	v_lshl_add_u64 v[174:175], v[174:175], 0, s[88:89]
	s_mov_b32 m0, s0
	ds_read_b128 v[226:229], v157
	ds_read_b128 v[230:233], v157 offset:1024
	ds_read_b128 v[234:237], v157 offset:2048
	ds_read_b128 v[238:241], v157 offset:3072
	global_load_lds_dwordx4 v[174:175], off
	v_lshl_add_u64 v[174:175], v[192:193], 0, s[88:89]
	s_add_i32 m0, s0, 0x2000
	s_nop 0
	global_load_lds_dwordx4 v[174:175], off
	s_barrier
	s_waitcnt lgkmcnt(0)
	s_setprio 1
	v_mfma_f32_16x16x32_bf16 v[122:125], v[226:229], v[194:197], v[122:125]
	v_mfma_f32_16x16x32_bf16 v[114:117], v[234:237], v[194:197], v[114:117]
	v_mfma_f32_16x16x32_bf16 v[106:109], v[226:229], v[202:205], v[106:109]
	v_mfma_f32_16x16x32_bf16 v[98:101], v[234:237], v[202:205], v[98:101]
	v_mfma_f32_16x16x32_bf16 v[90:93], v[226:229], v[210:213], v[90:93]
	v_mfma_f32_16x16x32_bf16 v[82:85], v[234:237], v[210:213], v[82:85]
	v_mfma_f32_16x16x32_bf16 v[74:77], v[226:229], v[218:221], v[74:77]
	v_mfma_f32_16x16x32_bf16 v[66:69], v[234:237], v[218:221], v[66:69]
	v_mfma_f32_16x16x32_bf16 v[122:125], v[230:233], v[198:201], v[122:125]
	v_mfma_f32_16x16x32_bf16 v[114:117], v[238:241], v[198:201], v[114:117]
	v_mfma_f32_16x16x32_bf16 v[106:109], v[230:233], v[206:209], v[106:109]
	v_mfma_f32_16x16x32_bf16 v[98:101], v[238:241], v[206:209], v[98:101]
	v_mfma_f32_16x16x32_bf16 v[90:93], v[230:233], v[214:217], v[90:93]
	v_mfma_f32_16x16x32_bf16 v[82:85], v[238:241], v[214:217], v[82:85]
	v_mfma_f32_16x16x32_bf16 v[74:77], v[230:233], v[222:225], v[74:77]
	v_mfma_f32_16x16x32_bf16 v[66:69], v[238:241], v[222:225], v[66:69]
	s_setprio 0
	s_mov_b32 m0, s65
	v_lshl_add_u64 v[174:175], v[242:243], 0, s[88:89]
	s_barrier
	ds_read_b128 v[194:197], v156 offset:49152
	ds_read_b128 v[198:201], v156 offset:50176
	ds_read_b128 v[202:205], v156 offset:51200
	ds_read_b128 v[206:209], v156 offset:52224
	ds_read_b128 v[210:213], v156 offset:53248
	ds_read_b128 v[214:217], v156 offset:54272
	ds_read_b128 v[218:221], v156 offset:55296
	ds_read_b128 v[222:225], v156 offset:56320
	global_load_lds_dwordx4 v[174:175], off
	v_lshl_add_u64 v[174:175], v[244:245], 0, s[88:89]
	s_mov_b32 m0, s66
	s_nop 0
	global_load_lds_dwordx4 v[174:175], off
	s_barrier
; __device__ __forceinline__ float siluf_(float x) { return x * frcp(1.0f + fexp(-x)); }
; #define PG8_STAGE(bufoff, gbase) do { _Pragma("unroll") for (int _i = 0; _i < 2; ++_i) \
;         __builtin_amdgcn_global_load_lds((const unsigned*)((const char*)(gbase) + voff[_i]), (LAS unsigned*)(lds + (bufoff) + ldsw + _i * 8192), 16, 0, 0); } while (0)
; #define PG8_LDA(dst, b, h) do { _Pragma("unroll") for (int m = 0; m < 4; ++m) _Pragma("unroll") for (int k = 0; k < 2; ++k) dst[m][k] = *(const LAS bf16x8*)(lds + PG8_SA(b, h) + aoff + m * 2048 + k * 1024); } while (0)
; #define PG8_WAIT_V(n) asm volatile("s_waitcnt vmcnt(" #n ")" ::: "memory")
; #define PG8_WAIT_L(n) asm volatile("s_waitcnt lgkmcnt(" #n ")" ::: "memory")
; #define PG8_BAR __builtin_amdgcn_s_barrier()
; #define PG8_SCHED __builtin_amdgcn_sched_barrier(0)
;     ...
;             PG8_BAR; PG8_WAIT_L(0); PG8_MMA(0, 1, At, B1); PG8_BAR;
;             PG8_LDA(At, 1, 1); PG8_STAGE(PG8_SA(1, 0), a3);
;             PG8_BAR; PG8_WAIT_L(0); PG8_MMA(1, 0, At, B0); PG8_BAR; PG8_SCHED;
;             PG8_STAGE(PG8_SB(1, 1), b3 + hstep);
;             PG8_WAIT_V(6); PG8_BAR; PG8_MMA(1, 1, At, B1); PG8_BAR;
;     __device__ __forceinline__ void operator()(Acc& acc, int pm, int pn, int wr, int wc, int fr, int fq) const {
;         const int hb = pn * 128 + wc * 32 + fq * 4;
; #pragma unroll
;         for (int ai = 0; ai < 2; ++ai)
; #pragma unroll
;             for (int m = 0; m < 4; ++m) {
;                 const size_t ro = (size_t)(pm * 256 + ai * 128 + wr * 64 + m * 16 + fr) * DFF + hb;
; #pragma unroll
;                 for (int n = 0; n < 2; ++n) {
;                     const f32x4 a = acc[ai][0][m][n], b = acc[ai][1][m][n];
;                     u32x2 o = {pack2(siluf_(a[0]) * b[0], siluf_(a[1]) * b[1]), pack2(siluf_(a[2]) * b[2], siluf_(a[3]) * b[3])};
;                     *reinterpret_cast<u32x2*>(ffh + ro + n * 16) = o;
;                 }
;             }
;     }
	s_waitcnt lgkmcnt(0)
	s_setprio 1
	v_mfma_f32_16x16x32_bf16 v[62:65], v[158:161], v[194:197], v[62:65]
	v_mfma_f32_16x16x32_bf16 v[54:57], v[166:169], v[194:197], v[54:57]
	v_mfma_f32_16x16x32_bf16 v[46:49], v[158:161], v[202:205], v[46:49]
	v_mfma_f32_16x16x32_bf16 v[38:41], v[166:169], v[202:205], v[38:41]
	v_mfma_f32_16x16x32_bf16 v[30:33], v[158:161], v[210:213], v[30:33]
	v_mfma_f32_16x16x32_bf16 v[22:25], v[166:169], v[210:213], v[22:25]
	v_mfma_f32_16x16x32_bf16 v[14:17], v[158:161], v[218:221], v[14:17]
	v_mfma_f32_16x16x32_bf16 v[6:9], v[166:169], v[218:221], v[6:9]
	v_mfma_f32_16x16x32_bf16 v[62:65], v[162:165], v[198:201], v[62:65]
	v_mfma_f32_16x16x32_bf16 v[54:57], v[170:173], v[198:201], v[54:57]
	v_mfma_f32_16x16x32_bf16 v[46:49], v[162:165], v[206:209], v[46:49]
	v_mfma_f32_16x16x32_bf16 v[38:41], v[170:173], v[206:209], v[38:41]
	v_mfma_f32_16x16x32_bf16 v[30:33], v[162:165], v[214:217], v[30:33]
	v_mfma_f32_16x16x32_bf16 v[22:25], v[170:173], v[214:217], v[22:25]
	v_mfma_f32_16x16x32_bf16 v[14:17], v[162:165], v[222:225], v[14:17]
	v_mfma_f32_16x16x32_bf16 v[6:9], v[170:173], v[222:225], v[6:9]
	s_setprio 0
	s_barrier
	s_add_u32 s0, s14, 0x40080
	s_addc_u32 s1, s15, 0
	s_add_i32 s14, s31, s17
	v_lshl_add_u64 v[158:159], s[0:1], 0, v[132:133]
	s_mov_b32 m0, s14
	s_nop 0
	global_load_lds_dwordx4 v[158:159], off
	v_lshl_add_u64 v[158:159], s[0:1], 0, v[130:131]
	s_add_i32 m0, s14, 0x2000
	s_nop 0
	global_load_lds_dwordx4 v[158:159], off
	s_waitcnt vmcnt(6)
	s_barrier
	s_setprio 1
	v_mfma_f32_16x16x32_bf16 v[58:61], v[226:229], v[194:197], v[58:61]
	v_mfma_f32_16x16x32_bf16 v[50:53], v[234:237], v[194:197], v[50:53]
	v_mfma_f32_16x16x32_bf16 v[42:45], v[226:229], v[202:205], v[42:45]
	v_mfma_f32_16x16x32_bf16 v[34:37], v[234:237], v[202:205], v[34:37]
	v_mfma_f32_16x16x32_bf16 v[26:29], v[226:229], v[210:213], v[26:29]
	v_mfma_f32_16x16x32_bf16 v[18:21], v[234:237], v[210:213], v[18:21]
	v_mfma_f32_16x16x32_bf16 v[10:13], v[226:229], v[218:221], v[10:13]
	v_mfma_f32_16x16x32_bf16 v[2:5], v[234:237], v[218:221], v[2:5]
	v_mfma_f32_16x16x32_bf16 v[58:61], v[230:233], v[198:201], v[58:61]
	v_mfma_f32_16x16x32_bf16 v[50:53], v[238:241], v[198:201], v[50:53]
	v_mfma_f32_16x16x32_bf16 v[42:45], v[230:233], v[206:209], v[42:45]
	v_mfma_f32_16x16x32_bf16 v[34:37], v[238:241], v[206:209], v[34:37]
	v_mfma_f32_16x16x32_bf16 v[26:29], v[230:233], v[214:217], v[26:29]
	v_mfma_f32_16x16x32_bf16 v[18:21], v[238:241], v[214:217], v[18:21]
	v_mfma_f32_16x16x32_bf16 v[10:13], v[230:233], v[222:225], v[10:13]
	v_mfma_f32_16x16x32_bf16 v[2:5], v[238:241], v[222:225], v[2:5]
	s_setprio 0
	s_add_i32 s29, s29, 2
	s_add_u32 s12, s12, 0x100
	s_addc_u32 s13, s13, 0
	s_add_u32 s23, s23, 0x100
	s_addc_u32 s28, s28, 0
	s_cmp_gt_u32 s29, 13
	s_barrier
	s_cbranch_scc0 .LBB0_1563
	v_mul_f32_e32 v160, 0xbfb8aa3b, v126
	v_mul_f32_e32 v161, 0xbfb8aa3b, v127
	v_exp_f32_e32 v160, v160
	v_exp_f32_e32 v161, v161
	v_lshl_or_b32 v158, s4, 7, v155
	v_lshl_add_u32 v157, s10, 8, v1
	v_add_f32_e32 v160, 1.0, v160
	v_add_f32_e32 v161, 1.0, v161
	v_rcp_f32_e32 v160, v160
	v_rcp_f32_e32 v161, v161
	v_ashrrev_i32_e32 v159, 31, v158
	s_and_b64 vcc, exec, s[44:45]
	s_mov_b32 s4, s40
	v_pk_mul_f32 v[126:127], v[126:127], v[160:161]
	s_mov_b32 s10, s48
	v_pk_mul_f32 v[122:123], v[126:127], v[122:123]
	s_mov_b64 s[14:15], s[56:57]
	v_cvt_pk_bf16_f32 v126, v122, v123
	v_mul_f32_e32 v122, 0xbfb8aa3b, v128
	v_mul_f32_e32 v123, 0xbfb8aa3b, v129
	v_exp_f32_e32 v122, v122
	v_exp_f32_e32 v123, v123
	s_mov_b64 s[12:13], s[52:53]
	v_add_f32_e32 v122, 1.0, v122
	v_add_f32_e32 v123, 1.0, v123
	v_rcp_f32_e32 v122, v122
	v_rcp_f32_e32 v123, v123
	s_nop 0
	v_pk_mul_f32 v[122:123], v[128:129], v[122:123]
	s_nop 0
	v_pk_mul_f32 v[122:123], v[122:123], v[124:125]
	v_lshlrev_b64 v[124:125], 1, v[158:159]
	v_cvt_pk_bf16_f32 v127, v122, v123
	v_mov_b64_e32 v[122:123], s[26:27]
	v_mad_i64_i32 v[128:129], s[0:1], v157, s68, v[122:123]
	v_lshl_add_u64 v[128:129], v[128:129], 0, v[124:125]
	global_store_dwordx2 v[128:129], v[126:127], off
	v_mul_f32_e32 v126, 0xbfb8aa3b, v118
	v_mul_f32_e32 v127, 0xbfb8aa3b, v119
	v_exp_f32_e32 v126, v126
	v_exp_f32_e32 v127, v127
	v_add_f32_e32 v126, 1.0, v126
	v_add_f32_e32 v127, 1.0, v127
	v_rcp_f32_e32 v126, v126
	v_rcp_f32_e32 v127, v127
	s_nop 0
	v_pk_mul_f32 v[118:119], v[118:119], v[126:127]
	s_nop 0
	v_pk_mul_f32 v[114:115], v[118:119], v[114:115]
	s_nop 0
	v_cvt_pk_bf16_f32 v114, v114, v115
	v_mul_f32_e32 v115, 0xbfb8aa3b, v120
	v_exp_f32_e32 v115, v115
	s_nop 0
	v_add_f32_e32 v115, 1.0, v115
	v_rcp_f32_e32 v118, v115
	v_mul_f32_e32 v115, 0xbfb8aa3b, v121
	v_exp_f32_e32 v115, v115
	s_nop 0
	v_add_f32_e32 v115, 1.0, v115
	v_rcp_f32_e32 v119, v115
	s_nop 0
	v_pk_mul_f32 v[118:119], v[120:121], v[118:119]
	s_nop 0
	v_pk_mul_f32 v[116:117], v[118:119], v[116:117]
	s_nop 0
	v_cvt_pk_bf16_f32 v115, v116, v117
	global_store_dwordx2 v[128:129], v[114:115], off offset:32
	v_mul_f32_e32 v114, 0xbfb8aa3b, v110
	v_mul_f32_e32 v115, 0xbfb8aa3b, v111
	v_exp_f32_e32 v114, v114
	v_exp_f32_e32 v115, v115
	v_or_b32_e32 v116, 16, v157
	v_add_f32_e32 v114, 1.0, v114
	v_add_f32_e32 v115, 1.0, v115
	v_rcp_f32_e32 v114, v114
	v_rcp_f32_e32 v115, v115
	s_nop 0
	v_pk_mul_f32 v[110:111], v[110:111], v[114:115]
	s_nop 0
	v_pk_mul_f32 v[106:107], v[110:111], v[106:107]
	s_nop 0
	v_cvt_pk_bf16_f32 v106, v106, v107
	v_mul_f32_e32 v107, 0xbfb8aa3b, v112
	v_exp_f32_e32 v107, v107
	s_nop 0
	v_add_f32_e32 v107, 1.0, v107
	v_rcp_f32_e32 v110, v107
	v_mul_f32_e32 v107, 0xbfb8aa3b, v113
	v_exp_f32_e32 v107, v107
	s_nop 0
	v_add_f32_e32 v107, 1.0, v107
	v_rcp_f32_e32 v111, v107
	s_nop 0
; __device__ __forceinline__ float siluf_(float x) { return x * frcp(1.0f + fexp(-x)); }
;     __device__ __forceinline__ void operator()(Acc& acc, int pm, int pn, int wr, int wc, int fr, int fq) const {
;         const int hb = pn * 128 + wc * 32 + fq * 4;
; #pragma unroll
;         for (int ai = 0; ai < 2; ++ai)
; #pragma unroll
;             for (int m = 0; m < 4; ++m) {
;                 const size_t ro = (size_t)(pm * 256 + ai * 128 + wr * 64 + m * 16 + fr) * DFF + hb;
; #pragma unroll
;                 for (int n = 0; n < 2; ++n) {
;                     const f32x4 a = acc[ai][0][m][n], b = acc[ai][1][m][n];
;                     u32x2 o = {pack2(siluf_(a[0]) * b[0], siluf_(a[1]) * b[1]), pack2(siluf_(a[2]) * b[2], siluf_(a[3]) * b[3])};
;                     *reinterpret_cast<u32x2*>(ffh + ro + n * 16) = o;
;                 }
;             }
;     }
	v_pk_mul_f32 v[110:111], v[112:113], v[110:111]
	s_nop 0
	v_pk_mul_f32 v[108:109], v[110:111], v[108:109]
	s_nop 0
	v_cvt_pk_bf16_f32 v107, v108, v109
	v_mad_i64_i32 v[108:109], s[0:1], v116, s68, v[122:123]
	v_lshl_add_u64 v[108:109], v[108:109], 0, v[124:125]
	global_store_dwordx2 v[108:109], v[106:107], off
	v_mul_f32_e32 v106, 0xbfb8aa3b, v102
	v_mul_f32_e32 v107, 0xbfb8aa3b, v103
	v_exp_f32_e32 v106, v106
	v_exp_f32_e32 v107, v107
	v_add_f32_e32 v106, 1.0, v106
	v_add_f32_e32 v107, 1.0, v107
	v_rcp_f32_e32 v106, v106
	v_rcp_f32_e32 v107, v107
	s_nop 0
	v_pk_mul_f32 v[102:103], v[102:103], v[106:107]
	s_nop 0
	v_pk_mul_f32 v[98:99], v[102:103], v[98:99]
	s_nop 0
	v_cvt_pk_bf16_f32 v98, v98, v99
	v_mul_f32_e32 v99, 0xbfb8aa3b, v104
	v_exp_f32_e32 v99, v99
	s_nop 0
	v_add_f32_e32 v99, 1.0, v99
	v_rcp_f32_e32 v102, v99
	v_mul_f32_e32 v99, 0xbfb8aa3b, v105
	v_exp_f32_e32 v99, v99
	s_nop 0
	v_add_f32_e32 v99, 1.0, v99
	v_rcp_f32_e32 v103, v99
	s_nop 0
	v_pk_mul_f32 v[102:103], v[104:105], v[102:103]
	s_nop 0
	v_pk_mul_f32 v[100:101], v[102:103], v[100:101]
	s_nop 0
	v_cvt_pk_bf16_f32 v99, v100, v101
	global_store_dwordx2 v[108:109], v[98:99], off offset:32
	v_mul_f32_e32 v98, 0xbfb8aa3b, v94
	v_mul_f32_e32 v99, 0xbfb8aa3b, v95
	v_exp_f32_e32 v98, v98
	v_exp_f32_e32 v99, v99
	v_or_b32_e32 v100, 32, v157
	v_add_f32_e32 v98, 1.0, v98
	v_add_f32_e32 v99, 1.0, v99
	v_rcp_f32_e32 v98, v98
	v_rcp_f32_e32 v99, v99
	s_nop 0
	v_pk_mul_f32 v[94:95], v[94:95], v[98:99]
	s_nop 0
	v_pk_mul_f32 v[90:91], v[94:95], v[90:91]
	s_nop 0
	v_cvt_pk_bf16_f32 v90, v90, v91
	v_mul_f32_e32 v91, 0xbfb8aa3b, v96
	v_exp_f32_e32 v91, v91
	s_nop 0
	v_add_f32_e32 v91, 1.0, v91
	v_rcp_f32_e32 v94, v91
	v_mul_f32_e32 v91, 0xbfb8aa3b, v97
	v_exp_f32_e32 v91, v91
	s_nop 0
	v_add_f32_e32 v91, 1.0, v91
	v_rcp_f32_e32 v95, v91
	s_nop 0
	v_pk_mul_f32 v[94:95], v[96:97], v[94:95]
	s_nop 0
	v_pk_mul_f32 v[92:93], v[94:95], v[92:93]
	s_nop 0
	v_cvt_pk_bf16_f32 v91, v92, v93
	v_mad_i64_i32 v[92:93], s[0:1], v100, s68, v[122:123]
	v_lshl_add_u64 v[92:93], v[92:93], 0, v[124:125]
	global_store_dwordx2 v[92:93], v[90:91], off
	v_mul_f32_e32 v90, 0xbfb8aa3b, v86
	v_mul_f32_e32 v91, 0xbfb8aa3b, v87
	v_exp_f32_e32 v90, v90
	v_exp_f32_e32 v91, v91
	v_add_f32_e32 v90, 1.0, v90
	v_add_f32_e32 v91, 1.0, v91
	v_rcp_f32_e32 v90, v90
	v_rcp_f32_e32 v91, v91
	s_nop 0
	v_pk_mul_f32 v[86:87], v[86:87], v[90:91]
	s_nop 0
	v_pk_mul_f32 v[82:83], v[86:87], v[82:83]
	s_nop 0
	v_cvt_pk_bf16_f32 v82, v82, v83
	v_mul_f32_e32 v83, 0xbfb8aa3b, v88
	v_exp_f32_e32 v83, v83
	s_nop 0
	v_add_f32_e32 v83, 1.0, v83
	v_rcp_f32_e32 v86, v83
	v_mul_f32_e32 v83, 0xbfb8aa3b, v89
	v_exp_f32_e32 v83, v83
	s_nop 0
	v_add_f32_e32 v83, 1.0, v83
	v_rcp_f32_e32 v87, v83
	s_nop 0
	v_pk_mul_f32 v[86:87], v[88:89], v[86:87]
	s_nop 0
	v_pk_mul_f32 v[84:85], v[86:87], v[84:85]
	s_nop 0
	v_cvt_pk_bf16_f32 v83, v84, v85
	global_store_dwordx2 v[92:93], v[82:83], off offset:32
	v_mul_f32_e32 v82, 0xbfb8aa3b, v78
	v_mul_f32_e32 v83, 0xbfb8aa3b, v79
	v_exp_f32_e32 v82, v82
	v_exp_f32_e32 v83, v83
	v_or_b32_e32 v84, 48, v157
	v_add_f32_e32 v82, 1.0, v82
	v_add_f32_e32 v83, 1.0, v83
	v_rcp_f32_e32 v82, v82
	v_rcp_f32_e32 v83, v83
	s_nop 0
	v_pk_mul_f32 v[78:79], v[78:79], v[82:83]
	s_nop 0
	v_pk_mul_f32 v[74:75], v[78:79], v[74:75]
	s_nop 0
	v_cvt_pk_bf16_f32 v74, v74, v75
	v_mul_f32_e32 v75, 0xbfb8aa3b, v80
	v_exp_f32_e32 v75, v75
	s_nop 0
	v_add_f32_e32 v75, 1.0, v75
	v_rcp_f32_e32 v78, v75
	v_mul_f32_e32 v75, 0xbfb8aa3b, v81
	v_exp_f32_e32 v75, v75
	s_nop 0
	v_add_f32_e32 v75, 1.0, v75
	v_rcp_f32_e32 v79, v75
	s_nop 0
	v_pk_mul_f32 v[78:79], v[80:81], v[78:79]
	s_nop 0
	v_pk_mul_f32 v[76:77], v[78:79], v[76:77]
	s_nop 0
	v_cvt_pk_bf16_f32 v75, v76, v77
	v_mad_i64_i32 v[76:77], s[0:1], v84, s68, v[122:123]
	v_lshl_add_u64 v[76:77], v[76:77], 0, v[124:125]
	global_store_dwordx2 v[76:77], v[74:75], off
	v_mul_f32_e32 v74, 0xbfb8aa3b, v70
	v_mul_f32_e32 v75, 0xbfb8aa3b, v71
	v_exp_f32_e32 v74, v74
	v_exp_f32_e32 v75, v75
	v_add_f32_e32 v74, 1.0, v74
	v_add_f32_e32 v75, 1.0, v75
	v_rcp_f32_e32 v74, v74
	v_rcp_f32_e32 v75, v75
	s_nop 0
	v_pk_mul_f32 v[70:71], v[70:71], v[74:75]
	s_nop 0
	v_pk_mul_f32 v[66:67], v[70:71], v[66:67]
	s_nop 0
	v_cvt_pk_bf16_f32 v66, v66, v67
	v_mul_f32_e32 v67, 0xbfb8aa3b, v72
	v_exp_f32_e32 v67, v67
	s_nop 0
	v_add_f32_e32 v67, 1.0, v67
	v_rcp_f32_e32 v70, v67
	v_mul_f32_e32 v67, 0xbfb8aa3b, v73
	v_exp_f32_e32 v67, v67
	s_nop 0
	v_add_f32_e32 v67, 1.0, v67
	v_rcp_f32_e32 v71, v67
	s_nop 0
	v_pk_mul_f32 v[70:71], v[72:73], v[70:71]
	s_nop 0
	v_pk_mul_f32 v[68:69], v[70:71], v[68:69]
	s_nop 0
	v_cvt_pk_bf16_f32 v67, v68, v69
	global_store_dwordx2 v[76:77], v[66:67], off offset:32
	v_mul_f32_e32 v66, 0xbfb8aa3b, v62
	v_mul_f32_e32 v67, 0xbfb8aa3b, v63
	v_exp_f32_e32 v66, v66
	v_exp_f32_e32 v67, v67
	v_add_u32_e32 v68, 0x80, v157
	v_add_f32_e32 v66, 1.0, v66
	v_add_f32_e32 v67, 1.0, v67
	v_rcp_f32_e32 v66, v66
	v_rcp_f32_e32 v67, v67
	s_nop 0
	v_pk_mul_f32 v[62:63], v[62:63], v[66:67]
	s_nop 0
	v_pk_mul_f32 v[58:59], v[62:63], v[58:59]
	s_nop 0
	v_cvt_pk_bf16_f32 v58, v58, v59
	v_mul_f32_e32 v59, 0xbfb8aa3b, v64
	v_exp_f32_e32 v59, v59
	s_nop 0
	v_add_f32_e32 v59, 1.0, v59
	v_rcp_f32_e32 v62, v59
	v_mul_f32_e32 v59, 0xbfb8aa3b, v65
	v_exp_f32_e32 v59, v59
	s_nop 0
	v_add_f32_e32 v59, 1.0, v59
	v_rcp_f32_e32 v63, v59
	s_nop 0
	v_pk_mul_f32 v[62:63], v[64:65], v[62:63]
	s_nop 0
	v_pk_mul_f32 v[60:61], v[62:63], v[60:61]
	s_nop 0
	v_cvt_pk_bf16_f32 v59, v60, v61
	v_mad_i64_i32 v[60:61], s[0:1], v68, s68, v[122:123]
	v_lshl_add_u64 v[60:61], v[60:61], 0, v[124:125]
	global_store_dwordx2 v[60:61], v[58:59], off
; __device__ __forceinline__ float siluf_(float x) { return x * frcp(1.0f + fexp(-x)); }
; #define PG8_WAIT_V(n) asm volatile("s_waitcnt vmcnt(" #n ")" ::: "memory")
; #define PG8_BAR __builtin_amdgcn_s_barrier()
;     ...
;         E(acc, cur.pm + pm0, cur.pn, wr, wc, fr, fq);
;         if (!has_next) break;
; #pragma unroll
;         for (int a = 0; a < 2; ++a)
; #pragma unroll
;             for (int b = 0; b < 2; ++b)
; #pragma unroll
;                 for (int m = 0; m < 4; ++m)
; #pragma unroll
;                     for (int n = 0; n < 2; ++n) acc[a][b][m][n] = (f32x4){0.f, 0.f, 0.f, 0.f};
;         cur = nxt; cA = nA; cB = nB; ++ui;
;     }
;     PG8_WAIT_V(0);
;     if (wr == 0) PG8_BAR;
;     PG8_BAR;
;     __device__ __forceinline__ void operator()(Acc& acc, int pm, int pn, int wr, int wc, int fr, int fq) const {
;         const int hb = pn * 128 + wc * 32 + fq * 4;
; #pragma unroll
;         for (int ai = 0; ai < 2; ++ai)
; #pragma unroll
;             for (int m = 0; m < 4; ++m) {
;                 const size_t ro = (size_t)(pm * 256 + ai * 128 + wr * 64 + m * 16 + fr) * DFF + hb;
; #pragma unroll
;                 for (int n = 0; n < 2; ++n) {
;                     const f32x4 a = acc[ai][0][m][n], b = acc[ai][1][m][n];
;                     u32x2 o = {pack2(siluf_(a[0]) * b[0], siluf_(a[1]) * b[1]), pack2(siluf_(a[2]) * b[2], siluf_(a[3]) * b[3])};
;                     *reinterpret_cast<u32x2*>(ffh + ro + n * 16) = o;
;                 }
;             }
;     }
	v_mul_f32_e32 v58, 0xbfb8aa3b, v54
	v_mul_f32_e32 v59, 0xbfb8aa3b, v55
	v_exp_f32_e32 v58, v58
	v_exp_f32_e32 v59, v59
	v_add_f32_e32 v58, 1.0, v58
	v_add_f32_e32 v59, 1.0, v59
	v_rcp_f32_e32 v58, v58
	v_rcp_f32_e32 v59, v59
	s_nop 0
	v_pk_mul_f32 v[54:55], v[54:55], v[58:59]
	s_nop 0
	v_pk_mul_f32 v[50:51], v[54:55], v[50:51]
	s_nop 0
	v_cvt_pk_bf16_f32 v50, v50, v51
	v_mul_f32_e32 v51, 0xbfb8aa3b, v56
	v_exp_f32_e32 v51, v51
	s_nop 0
	v_add_f32_e32 v51, 1.0, v51
	v_rcp_f32_e32 v54, v51
	v_mul_f32_e32 v51, 0xbfb8aa3b, v57
	v_exp_f32_e32 v51, v51
	s_nop 0
	v_add_f32_e32 v51, 1.0, v51
	v_rcp_f32_e32 v55, v51
	s_nop 0
	v_pk_mul_f32 v[54:55], v[56:57], v[54:55]
	s_nop 0
	v_pk_mul_f32 v[52:53], v[54:55], v[52:53]
	s_nop 0
	v_cvt_pk_bf16_f32 v51, v52, v53
	global_store_dwordx2 v[60:61], v[50:51], off offset:32
	v_mul_f32_e32 v50, 0xbfb8aa3b, v46
	v_mul_f32_e32 v51, 0xbfb8aa3b, v47
	v_exp_f32_e32 v50, v50
	v_exp_f32_e32 v51, v51
	v_add_u32_e32 v52, 0x90, v157
	v_add_f32_e32 v50, 1.0, v50
	v_add_f32_e32 v51, 1.0, v51
	v_rcp_f32_e32 v50, v50
	v_rcp_f32_e32 v51, v51
	s_nop 0
	v_pk_mul_f32 v[46:47], v[46:47], v[50:51]
	s_nop 0
	v_pk_mul_f32 v[42:43], v[46:47], v[42:43]
	s_nop 0
	v_cvt_pk_bf16_f32 v42, v42, v43
	v_mul_f32_e32 v43, 0xbfb8aa3b, v48
	v_exp_f32_e32 v43, v43
	s_nop 0
	v_add_f32_e32 v43, 1.0, v43
	v_rcp_f32_e32 v46, v43
	v_mul_f32_e32 v43, 0xbfb8aa3b, v49
	v_exp_f32_e32 v43, v43
	s_nop 0
	v_add_f32_e32 v43, 1.0, v43
	v_rcp_f32_e32 v47, v43
	s_nop 0
	v_pk_mul_f32 v[46:47], v[48:49], v[46:47]
	s_nop 0
	v_pk_mul_f32 v[44:45], v[46:47], v[44:45]
	s_nop 0
	v_cvt_pk_bf16_f32 v43, v44, v45
	v_mad_i64_i32 v[44:45], s[0:1], v52, s68, v[122:123]
	v_lshl_add_u64 v[44:45], v[44:45], 0, v[124:125]
	global_store_dwordx2 v[44:45], v[42:43], off
	v_mul_f32_e32 v42, 0xbfb8aa3b, v38
	v_mul_f32_e32 v43, 0xbfb8aa3b, v39
	v_exp_f32_e32 v42, v42
	v_exp_f32_e32 v43, v43
	v_add_f32_e32 v42, 1.0, v42
	v_add_f32_e32 v43, 1.0, v43
	v_rcp_f32_e32 v42, v42
	v_rcp_f32_e32 v43, v43
	s_nop 0
	v_pk_mul_f32 v[38:39], v[38:39], v[42:43]
	s_nop 0
	v_pk_mul_f32 v[34:35], v[38:39], v[34:35]
	s_nop 0
	v_cvt_pk_bf16_f32 v34, v34, v35
	v_mul_f32_e32 v35, 0xbfb8aa3b, v40
	v_exp_f32_e32 v35, v35
	s_nop 0
	v_add_f32_e32 v35, 1.0, v35
	v_rcp_f32_e32 v38, v35
	v_mul_f32_e32 v35, 0xbfb8aa3b, v41
	v_exp_f32_e32 v35, v35
	s_nop 0
	v_add_f32_e32 v35, 1.0, v35
	v_rcp_f32_e32 v39, v35
	s_nop 0
	v_pk_mul_f32 v[38:39], v[40:41], v[38:39]
	s_nop 0
	v_pk_mul_f32 v[36:37], v[38:39], v[36:37]
	s_nop 0
	v_cvt_pk_bf16_f32 v35, v36, v37
	global_store_dwordx2 v[44:45], v[34:35], off offset:32
	v_mul_f32_e32 v34, 0xbfb8aa3b, v30
	v_mul_f32_e32 v35, 0xbfb8aa3b, v31
	v_exp_f32_e32 v34, v34
	v_exp_f32_e32 v35, v35
	v_add_u32_e32 v36, 0xa0, v157
	v_add_f32_e32 v34, 1.0, v34
	v_add_f32_e32 v35, 1.0, v35
	v_rcp_f32_e32 v34, v34
	v_rcp_f32_e32 v35, v35
	s_nop 0
	v_pk_mul_f32 v[30:31], v[30:31], v[34:35]
	s_nop 0
	v_pk_mul_f32 v[26:27], v[30:31], v[26:27]
	s_nop 0
	v_cvt_pk_bf16_f32 v26, v26, v27
	v_mul_f32_e32 v27, 0xbfb8aa3b, v32
	v_exp_f32_e32 v27, v27
	s_nop 0
	v_add_f32_e32 v27, 1.0, v27
	v_rcp_f32_e32 v30, v27
	v_mul_f32_e32 v27, 0xbfb8aa3b, v33
	v_exp_f32_e32 v27, v27
	s_nop 0
	v_add_f32_e32 v27, 1.0, v27
	v_rcp_f32_e32 v31, v27
	s_nop 0
	v_pk_mul_f32 v[30:31], v[32:33], v[30:31]
	s_nop 0
	v_pk_mul_f32 v[28:29], v[30:31], v[28:29]
	s_nop 0
	v_cvt_pk_bf16_f32 v27, v28, v29
	v_mad_i64_i32 v[28:29], s[0:1], v36, s68, v[122:123]
	v_lshl_add_u64 v[28:29], v[28:29], 0, v[124:125]
	global_store_dwordx2 v[28:29], v[26:27], off
	v_mul_f32_e32 v26, 0xbfb8aa3b, v22
	v_mul_f32_e32 v27, 0xbfb8aa3b, v23
	v_exp_f32_e32 v26, v26
	v_exp_f32_e32 v27, v27
	v_add_f32_e32 v26, 1.0, v26
	v_add_f32_e32 v27, 1.0, v27
	v_rcp_f32_e32 v26, v26
	v_rcp_f32_e32 v27, v27
	s_nop 0
	v_pk_mul_f32 v[22:23], v[22:23], v[26:27]
	s_nop 0
	v_pk_mul_f32 v[18:19], v[22:23], v[18:19]
	s_nop 0
	v_cvt_pk_bf16_f32 v18, v18, v19
	v_mul_f32_e32 v19, 0xbfb8aa3b, v24
	v_exp_f32_e32 v19, v19
	s_nop 0
	v_add_f32_e32 v19, 1.0, v19
	v_rcp_f32_e32 v22, v19
	v_mul_f32_e32 v19, 0xbfb8aa3b, v25
	v_exp_f32_e32 v19, v19
	s_nop 0
	v_add_f32_e32 v19, 1.0, v19
	v_rcp_f32_e32 v23, v19
	s_nop 0
	v_pk_mul_f32 v[22:23], v[24:25], v[22:23]
	s_nop 0
	v_pk_mul_f32 v[20:21], v[22:23], v[20:21]
	s_nop 0
	v_cvt_pk_bf16_f32 v19, v20, v21
	global_store_dwordx2 v[28:29], v[18:19], off offset:32
	v_mul_f32_e32 v18, 0xbfb8aa3b, v14
	v_mul_f32_e32 v19, 0xbfb8aa3b, v15
	v_exp_f32_e32 v18, v18
	v_exp_f32_e32 v19, v19
	v_add_u32_e32 v20, 0xb0, v157
	v_add_f32_e32 v18, 1.0, v18
	v_add_f32_e32 v19, 1.0, v19
	v_rcp_f32_e32 v18, v18
	v_rcp_f32_e32 v19, v19
	s_nop 0
	v_pk_mul_f32 v[14:15], v[14:15], v[18:19]
	s_nop 0
	v_pk_mul_f32 v[10:11], v[14:15], v[10:11]
	s_nop 0
	v_cvt_pk_bf16_f32 v10, v10, v11
	v_mul_f32_e32 v11, 0xbfb8aa3b, v16
	v_exp_f32_e32 v11, v11
	s_nop 0
	v_add_f32_e32 v11, 1.0, v11
	v_rcp_f32_e32 v14, v11
	v_mul_f32_e32 v11, 0xbfb8aa3b, v17
	v_exp_f32_e32 v11, v11
	s_nop 0
	v_add_f32_e32 v11, 1.0, v11
	v_rcp_f32_e32 v15, v11
	s_nop 0
	v_pk_mul_f32 v[14:15], v[16:17], v[14:15]
	s_nop 0
	v_pk_mul_f32 v[12:13], v[14:15], v[12:13]
	s_nop 0
	v_cvt_pk_bf16_f32 v11, v12, v13
	v_mad_i64_i32 v[12:13], s[0:1], v20, s68, v[122:123]
	v_lshl_add_u64 v[12:13], v[12:13], 0, v[124:125]
	global_store_dwordx2 v[12:13], v[10:11], off
	v_mul_f32_e32 v10, 0xbfb8aa3b, v6
	v_mul_f32_e32 v11, 0xbfb8aa3b, v7
	v_exp_f32_e32 v10, v10
	v_exp_f32_e32 v11, v11
	v_add_f32_e32 v10, 1.0, v10
	v_add_f32_e32 v11, 1.0, v11
	v_rcp_f32_e32 v10, v10
	v_rcp_f32_e32 v11, v11
	s_nop 0
	v_pk_mul_f32 v[6:7], v[6:7], v[10:11]
	s_nop 0
	v_pk_mul_f32 v[2:3], v[6:7], v[2:3]
	s_nop 0
	v_cvt_pk_bf16_f32 v2, v2, v3
	v_mul_f32_e32 v3, 0xbfb8aa3b, v8
	v_exp_f32_e32 v3, v3
	s_nop 0
	v_add_f32_e32 v3, 1.0, v3
	v_rcp_f32_e32 v6, v3
	v_mul_f32_e32 v3, 0xbfb8aa3b, v9
	v_exp_f32_e32 v3, v3
	s_nop 0
	v_add_f32_e32 v3, 1.0, v3
	v_rcp_f32_e32 v7, v3
	s_nop 0
	v_pk_mul_f32 v[6:7], v[8:9], v[6:7]
	s_nop 0
	v_pk_mul_f32 v[4:5], v[6:7], v[4:5]
	s_nop 0
	v_cvt_pk_bf16_f32 v3, v4, v5
	global_store_dwordx2 v[12:13], v[2:3], off offset:32
	s_cbranch_vccz .LBB0_1560
	s_waitcnt vmcnt(0)
	s_cmpk_gt_u32 s16, 0xff
	s_cbranch_scc1 .LBB0_1567
	s_barrier

; #define PG8_STAGE(bufoff, gbase) do { _Pragma("unroll") for (int _i = 0; _i < 2; ++_i) \
;         __builtin_amdgcn_global_load_lds((const unsigned*)((const char*)(gbase) + voff[_i]), (LAS unsigned*)(lds + (bufoff) + ldsw + _i * 8192), 16, 0, 0); } while (0)
; #define PG8_LDA(dst, b, h) do { _Pragma("unroll") for (int m = 0; m < 4; ++m) _Pragma("unroll") for (int k = 0; k < 2; ++k) dst[m][k] = *(const LAS bf16x8*)(lds + PG8_SA(b, h) + aoff + m * 2048 + k * 1024); } while (0)
; #define PG8_LDB(dst, b, h) do { _Pragma("unroll") for (int n = 0; n < 2; ++n) _Pragma("unroll") for (int k = 0; k < 2; ++k) dst[n][k] = *(const LAS bf16x8*)(lds + PG8_SB(b, h) + boff + n * 2048 + k * 1024); } while (0)
; #define PG8_WAIT_V(n) asm volatile("s_waitcnt vmcnt(" #n ")" ::: "memory")
; #define PG8_WAIT_L(n) asm volatile("s_waitcnt lgkmcnt(" #n ")" ::: "memory")
; #define PG8_BAR __builtin_amdgcn_s_barrier()
; #define PG8_SCHED __builtin_amdgcn_sched_barrier(0)
;     ...
;             PG8_LDB(B0, 0, 0); PG8_SCHED; PG8_LDA(At, 0, 0); PG8_STAGE(PG8_SA(1, 1), a1 + hstep);
;             PG8_WAIT_L(8); PG8_BAR; PG8_WAIT_L(0); PG8_MMA(0, 0, At, B0); PG8_BAR; PG8_SCHED;
;             PG8_LDB(B1, 0, 1); PG8_STAGE(PG8_SB(0, 0), b2);
;             PG8_BAR; PG8_WAIT_L(0); PG8_MMA(0, 1, At, B1); PG8_BAR;
;             PG8_LDA(At, 0, 1); PG8_STAGE(PG8_SA(0, 0), a2);
;             PG8_BAR; PG8_WAIT_L(0); PG8_MMA(1, 0, At, B0); PG8_BAR; PG8_SCHED;
;             PG8_STAGE(PG8_SB(0, 1), b2 + hstep);
;             PG8_WAIT_V(6); PG8_BAR; PG8_MMA(1, 1, At, B1); PG8_BAR;
;             PG8_LDB(B0, 1, 0); PG8_SCHED; PG8_LDA(At, 1, 0); PG8_STAGE(PG8_SA(0, 1), a2 + hstep);
;             PG8_WAIT_L(8); PG8_BAR; PG8_WAIT_L(0); PG8_MMA(0, 0, At, B0); PG8_BAR; PG8_SCHED;
;             PG8_LDB(B1, 1, 1); PG8_STAGE(PG8_SB(1, 0), b3);
;             PG8_BAR; PG8_WAIT_L(0); PG8_MMA(0, 1, At, B1); PG8_BAR;
;             PG8_LDA(At, 1, 1); PG8_STAGE(PG8_SA(1, 0), a3);
;             PG8_BAR; PG8_WAIT_L(0); PG8_MMA(1, 0, At, B0); PG8_BAR; PG8_SCHED;
;             PG8_STAGE(PG8_SB(1, 1), b3 + hstep);
;             PG8_WAIT_V(6); PG8_BAR; PG8_MMA(1, 1, At, B1); PG8_BAR;
.LBB0_1649:
	s_add_u32 s46, s14, 0x100
	s_addc_u32 s47, s15, 0
	s_add_i32 s0, 0, 0x10000
	v_add_u32_e32 v161, s0, v158
	ds_read_b128 v[154:157], v161
	ds_read_b128 v[162:165], v161 offset:1024
	ds_read_b128 v[166:169], v161 offset:2048
	ds_read_b128 v[170:173], v161 offset:3072
	s_cmp_eq_u32 s28, 40
	s_cselect_b32 s53, s11, s47
	s_cselect_b32 s52, s10, s46
	s_cselect_b32 s49, s13, s23
	s_cselect_b32 s48, s12, s22
	v_lshl_add_u64 v[174:175], s[14:15], 0, v[150:151]
	s_add_i32 m0, s56, 0xc000
	ds_read_b128 v[194:197], v160
	ds_read_b128 v[198:201], v160 offset:1024
	ds_read_b128 v[202:205], v160 offset:2048
	ds_read_b128 v[206:209], v160 offset:3072
	ds_read_b128 v[210:213], v160 offset:4096
	ds_read_b128 v[214:217], v160 offset:5120
	ds_read_b128 v[218:221], v160 offset:6144
	ds_read_b128 v[222:225], v160 offset:7168
	global_load_lds_dwordx4 v[174:175], off
	v_lshl_add_u64 v[174:175], s[14:15], 0, v[152:153]
	s_add_i32 m0, s56, 0xe000
	s_nop 0
	global_load_lds_dwordx4 v[174:175], off
	s_waitcnt lgkmcnt(8)
	s_barrier
	s_waitcnt lgkmcnt(0)
	s_setprio 1
	v_mfma_f32_16x16x32_bf16 v[126:129], v[154:157], v[194:197], v[126:129]
	v_mfma_f32_16x16x32_bf16 v[102:105], v[166:169], v[194:197], v[102:105]
	v_mfma_f32_16x16x32_bf16 v[122:125], v[154:157], v[202:205], v[122:125]
	v_mfma_f32_16x16x32_bf16 v[90:93], v[166:169], v[202:205], v[90:93]
	v_mfma_f32_16x16x32_bf16 v[118:121], v[154:157], v[210:213], v[118:121]
	v_mfma_f32_16x16x32_bf16 v[86:89], v[166:169], v[210:213], v[86:89]
	v_mfma_f32_16x16x32_bf16 v[114:117], v[154:157], v[218:221], v[114:117]
	v_mfma_f32_16x16x32_bf16 v[82:85], v[166:169], v[218:221], v[82:85]
	v_mfma_f32_16x16x32_bf16 v[126:129], v[162:165], v[198:201], v[126:129]
	v_mfma_f32_16x16x32_bf16 v[102:105], v[170:173], v[198:201], v[102:105]
	v_mfma_f32_16x16x32_bf16 v[122:125], v[162:165], v[206:209], v[122:125]
	v_mfma_f32_16x16x32_bf16 v[90:93], v[170:173], v[206:209], v[90:93]
	v_mfma_f32_16x16x32_bf16 v[118:121], v[162:165], v[214:217], v[118:121]
	v_mfma_f32_16x16x32_bf16 v[86:89], v[170:173], v[214:217], v[86:89]
	v_mfma_f32_16x16x32_bf16 v[114:117], v[162:165], v[222:225], v[114:117]
	v_mfma_f32_16x16x32_bf16 v[82:85], v[170:173], v[222:225], v[82:85]
	s_setprio 0
	s_barrier
	s_add_i32 s14, 0, 0x14000
	s_add_i32 s0, s0, s36
	v_add_u32_e32 v161, s14, v158
	v_lshl_add_u64 v[174:175], s[48:49], 0, v[132:133]
	s_mov_b32 m0, s0
	ds_read_b128 v[226:229], v161
	ds_read_b128 v[230:233], v161 offset:1024
	ds_read_b128 v[234:237], v161 offset:2048
	ds_read_b128 v[238:241], v161 offset:3072
	global_load_lds_dwordx4 v[174:175], off
	v_lshl_add_u64 v[192:193], s[48:49], 0, v[130:131]
	s_add_i32 m0, s0, 0x2000
	s_nop 0
	global_load_lds_dwordx4 v[192:193], off
	s_barrier
	s_waitcnt lgkmcnt(0)
	s_setprio 1
	v_mfma_f32_16x16x32_bf16 v[66:69], v[226:229], v[194:197], v[66:69]
	v_mfma_f32_16x16x32_bf16 v[38:41], v[234:237], v[194:197], v[38:41]
	v_mfma_f32_16x16x32_bf16 v[58:61], v[226:229], v[202:205], v[58:61]
	v_mfma_f32_16x16x32_bf16 v[26:29], v[234:237], v[202:205], v[26:29]
	v_mfma_f32_16x16x32_bf16 v[54:57], v[226:229], v[210:213], v[54:57]
	v_mfma_f32_16x16x32_bf16 v[22:25], v[234:237], v[210:213], v[22:25]
	v_mfma_f32_16x16x32_bf16 v[50:53], v[226:229], v[218:221], v[50:53]
	v_mfma_f32_16x16x32_bf16 v[18:21], v[234:237], v[218:221], v[18:21]
	v_mfma_f32_16x16x32_bf16 v[66:69], v[230:233], v[198:201], v[66:69]
	v_mfma_f32_16x16x32_bf16 v[38:41], v[238:241], v[198:201], v[38:41]
	v_mfma_f32_16x16x32_bf16 v[58:61], v[230:233], v[206:209], v[58:61]
	v_mfma_f32_16x16x32_bf16 v[26:29], v[238:241], v[206:209], v[26:29]
	v_mfma_f32_16x16x32_bf16 v[54:57], v[230:233], v[214:217], v[54:57]
	v_mfma_f32_16x16x32_bf16 v[22:25], v[238:241], v[214:217], v[22:25]
	v_mfma_f32_16x16x32_bf16 v[50:53], v[230:233], v[222:225], v[50:53]
	v_mfma_f32_16x16x32_bf16 v[18:21], v[238:241], v[222:225], v[18:21]
	s_setprio 0
	s_mov_b32 m0, s56
	v_lshl_add_u64 v[242:243], s[52:53], 0, v[132:133]
	s_barrier
	ds_read_b128 v[194:197], v160 offset:16384
	ds_read_b128 v[198:201], v160 offset:17408
	ds_read_b128 v[202:205], v160 offset:18432
	ds_read_b128 v[206:209], v160 offset:19456
	ds_read_b128 v[210:213], v160 offset:20480
	ds_read_b128 v[214:217], v160 offset:21504
	ds_read_b128 v[218:221], v160 offset:22528
	ds_read_b128 v[222:225], v160 offset:23552
	global_load_lds_dwordx4 v[242:243], off
	v_lshl_add_u64 v[244:245], s[52:53], 0, v[130:131]
	s_mov_b32 m0, s57
	s_nop 0
	global_load_lds_dwordx4 v[244:245], off
	s_barrier
	s_waitcnt lgkmcnt(0)
	s_setprio 1
	v_mfma_f32_16x16x32_bf16 v[110:113], v[154:157], v[194:197], v[110:113]
	v_mfma_f32_16x16x32_bf16 v[78:81], v[166:169], v[194:197], v[78:81]
	v_mfma_f32_16x16x32_bf16 v[106:109], v[154:157], v[202:205], v[106:109]
	v_mfma_f32_16x16x32_bf16 v[74:77], v[166:169], v[202:205], v[74:77]
	v_mfma_f32_16x16x32_bf16 v[98:101], v[154:157], v[210:213], v[98:101]
	v_mfma_f32_16x16x32_bf16 v[70:73], v[166:169], v[210:213], v[70:73]
	v_mfma_f32_16x16x32_bf16 v[94:97], v[154:157], v[218:221], v[94:97]
	v_mfma_f32_16x16x32_bf16 v[62:65], v[166:169], v[218:221], v[62:65]
	v_mfma_f32_16x16x32_bf16 v[110:113], v[162:165], v[198:201], v[110:113]
	v_mfma_f32_16x16x32_bf16 v[78:81], v[170:173], v[198:201], v[78:81]
	v_mfma_f32_16x16x32_bf16 v[106:109], v[162:165], v[206:209], v[106:109]
	v_mfma_f32_16x16x32_bf16 v[74:77], v[170:173], v[206:209], v[74:77]
	v_mfma_f32_16x16x32_bf16 v[98:101], v[162:165], v[214:217], v[98:101]
	v_mfma_f32_16x16x32_bf16 v[70:73], v[170:173], v[214:217], v[70:73]
	v_mfma_f32_16x16x32_bf16 v[94:97], v[162:165], v[222:225], v[94:97]
	v_mfma_f32_16x16x32_bf16 v[62:65], v[170:173], v[222:225], v[62:65]
	s_setprio 0
	s_barrier
; #define PG8_STAGE(bufoff, gbase) do { _Pragma("unroll") for (int _i = 0; _i < 2; ++_i) \
;         __builtin_amdgcn_global_load_lds((const unsigned*)((const char*)(gbase) + voff[_i]), (LAS unsigned*)(lds + (bufoff) + ldsw + _i * 8192), 16, 0, 0); } while (0)
; #define PG8_LDA(dst, b, h) do { _Pragma("unroll") for (int m = 0; m < 4; ++m) _Pragma("unroll") for (int k = 0; k < 2; ++k) dst[m][k] = *(const LAS bf16x8*)(lds + PG8_SA(b, h) + aoff + m * 2048 + k * 1024); } while (0)
; #define PG8_LDB(dst, b, h) do { _Pragma("unroll") for (int n = 0; n < 2; ++n) _Pragma("unroll") for (int k = 0; k < 2; ++k) dst[n][k] = *(const LAS bf16x8*)(lds + PG8_SB(b, h) + boff + n * 2048 + k * 1024); } while (0)
; #define PG8_WAIT_V(n) asm volatile("s_waitcnt vmcnt(" #n ")" ::: "memory")
; #define PG8_WAIT_L(n) asm volatile("s_waitcnt lgkmcnt(" #n ")" ::: "memory")
; #define PG8_BAR __builtin_amdgcn_s_barrier()
; #define PG8_SCHED __builtin_amdgcn_sched_barrier(0)
;     ...
;             PG8_LDB(B0, 0, 0); PG8_SCHED; PG8_LDA(At, 0, 0); PG8_STAGE(PG8_SA(1, 1), a1 + hstep);
;             PG8_WAIT_L(8); PG8_BAR; PG8_WAIT_L(0); PG8_MMA(0, 0, At, B0); PG8_BAR; PG8_SCHED;
;             PG8_LDB(B1, 0, 1); PG8_STAGE(PG8_SB(0, 0), b2);
;             PG8_BAR; PG8_WAIT_L(0); PG8_MMA(0, 1, At, B1); PG8_BAR;
;             PG8_LDA(At, 0, 1); PG8_STAGE(PG8_SA(0, 0), a2);
;             PG8_BAR; PG8_WAIT_L(0); PG8_MMA(1, 0, At, B0); PG8_BAR; PG8_SCHED;
;             PG8_STAGE(PG8_SB(0, 1), b2 + hstep);
;             PG8_WAIT_V(6); PG8_BAR; PG8_MMA(1, 1, At, B1); PG8_BAR;
;             PG8_LDB(B0, 1, 0); PG8_SCHED; PG8_LDA(At, 1, 0); PG8_STAGE(PG8_SA(0, 1), a2 + hstep);
;             PG8_WAIT_L(8); PG8_BAR; PG8_WAIT_L(0); PG8_MMA(0, 0, At, B0); PG8_BAR; PG8_SCHED;
;             PG8_LDB(B1, 1, 1); PG8_STAGE(PG8_SB(1, 0), b3);
;             PG8_BAR; PG8_WAIT_L(0); PG8_MMA(0, 1, At, B1); PG8_BAR;
;             PG8_LDA(At, 1, 1); PG8_STAGE(PG8_SA(1, 0), a3);
;             PG8_BAR; PG8_WAIT_L(0); PG8_MMA(1, 0, At, B0); PG8_BAR; PG8_SCHED;
;             PG8_STAGE(PG8_SB(1, 1), b3 + hstep);
;             PG8_WAIT_V(6); PG8_BAR; PG8_MMA(1, 1, At, B1); PG8_BAR;
	s_add_u32 s0, s48, 0xb0000
	s_addc_u32 s1, s49, 0
	s_add_i32 s14, s14, s36
	v_lshl_add_u64 v[154:155], s[0:1], 0, v[132:133]
	s_mov_b32 m0, s14
	s_nop 0
	global_load_lds_dwordx4 v[154:155], off
	v_lshl_add_u64 v[154:155], s[0:1], 0, v[130:131]
	s_add_i32 m0, s14, 0x2000
	s_nop 0
	global_load_lds_dwordx4 v[154:155], off
	s_waitcnt vmcnt(6)
	s_barrier
	s_setprio 1
	v_mfma_f32_16x16x32_bf16 v[46:49], v[226:229], v[194:197], v[46:49]
	v_mfma_f32_16x16x32_bf16 v[14:17], v[234:237], v[194:197], v[14:17]
	v_mfma_f32_16x16x32_bf16 v[42:45], v[226:229], v[202:205], v[42:45]
	v_mfma_f32_16x16x32_bf16 v[10:13], v[234:237], v[202:205], v[10:13]
	v_mfma_f32_16x16x32_bf16 v[34:37], v[226:229], v[210:213], v[34:37]
	v_mfma_f32_16x16x32_bf16 v[6:9], v[234:237], v[210:213], v[6:9]
	v_mfma_f32_16x16x32_bf16 v[30:33], v[226:229], v[218:221], v[30:33]
	v_mfma_f32_16x16x32_bf16 v[2:5], v[234:237], v[218:221], v[2:5]
	v_mfma_f32_16x16x32_bf16 v[46:49], v[230:233], v[198:201], v[46:49]
	v_mfma_f32_16x16x32_bf16 v[14:17], v[238:241], v[198:201], v[14:17]
	v_mfma_f32_16x16x32_bf16 v[42:45], v[230:233], v[206:209], v[42:45]
	v_mfma_f32_16x16x32_bf16 v[10:13], v[238:241], v[206:209], v[10:13]
	v_mfma_f32_16x16x32_bf16 v[34:37], v[230:233], v[214:217], v[34:37]
	v_mfma_f32_16x16x32_bf16 v[6:9], v[238:241], v[214:217], v[6:9]
	v_mfma_f32_16x16x32_bf16 v[30:33], v[230:233], v[222:225], v[30:33]
	v_mfma_f32_16x16x32_bf16 v[2:5], v[238:241], v[222:225], v[2:5]
	s_setprio 0
	s_add_i32 s14, 0, 0x18000
	v_add_u32_e32 v161, s14, v158
	s_barrier
	ds_read_b128 v[154:157], v161
	ds_read_b128 v[162:165], v161 offset:1024
	ds_read_b128 v[166:169], v161 offset:2048
	ds_read_b128 v[170:173], v161 offset:3072
	s_add_u32 s0, s52, 0xb0000
	s_addc_u32 s1, s53, 0
	s_mov_b32 m0, s58
	v_lshl_add_u64 v[226:227], s[0:1], 0, v[132:133]
	ds_read_b128 v[194:197], v160 offset:32768
	ds_read_b128 v[198:201], v160 offset:33792
	ds_read_b128 v[202:205], v160 offset:34816
	ds_read_b128 v[206:209], v160 offset:35840
	ds_read_b128 v[210:213], v160 offset:36864
	ds_read_b128 v[214:217], v160 offset:37888
	ds_read_b128 v[218:221], v160 offset:38912
	ds_read_b128 v[222:225], v160 offset:39936
	global_load_lds_dwordx4 v[226:227], off
	v_lshl_add_u64 v[226:227], s[0:1], 0, v[130:131]
	s_mov_b32 m0, s59
	s_nop 0
	global_load_lds_dwordx4 v[226:227], off
	s_waitcnt lgkmcnt(8)
	s_barrier
	s_waitcnt lgkmcnt(0)
	s_setprio 1
	v_mfma_f32_16x16x32_bf16 v[126:129], v[154:157], v[194:197], v[126:129]
	v_mfma_f32_16x16x32_bf16 v[102:105], v[166:169], v[194:197], v[102:105]
	v_mfma_f32_16x16x32_bf16 v[122:125], v[154:157], v[202:205], v[122:125]
	v_mfma_f32_16x16x32_bf16 v[90:93], v[166:169], v[202:205], v[90:93]
	v_mfma_f32_16x16x32_bf16 v[118:121], v[154:157], v[210:213], v[118:121]
	v_mfma_f32_16x16x32_bf16 v[86:89], v[166:169], v[210:213], v[86:89]
	v_mfma_f32_16x16x32_bf16 v[114:117], v[154:157], v[218:221], v[114:117]
	v_mfma_f32_16x16x32_bf16 v[82:85], v[166:169], v[218:221], v[82:85]
	v_mfma_f32_16x16x32_bf16 v[126:129], v[162:165], v[198:201], v[126:129]
	v_mfma_f32_16x16x32_bf16 v[102:105], v[170:173], v[198:201], v[102:105]
	v_mfma_f32_16x16x32_bf16 v[122:125], v[162:165], v[206:209], v[122:125]
	v_mfma_f32_16x16x32_bf16 v[90:93], v[170:173], v[206:209], v[90:93]
	v_mfma_f32_16x16x32_bf16 v[118:121], v[162:165], v[214:217], v[118:121]
	v_mfma_f32_16x16x32_bf16 v[86:89], v[170:173], v[214:217], v[86:89]
	v_mfma_f32_16x16x32_bf16 v[114:117], v[162:165], v[222:225], v[114:117]
	v_mfma_f32_16x16x32_bf16 v[82:85], v[170:173], v[222:225], v[82:85]
	s_setprio 0
	s_barrier
	s_add_i32 s15, 0, 0x1c000
	s_add_i32 s0, s14, s36
	v_add_u32_e32 v161, s15, v158
	v_lshl_add_u64 v[174:175], v[174:175], 0, s[88:89]
	s_mov_b32 m0, s0
	ds_read_b128 v[226:229], v161
	ds_read_b128 v[230:233], v161 offset:1024
	ds_read_b128 v[234:237], v161 offset:2048
	ds_read_b128 v[238:241], v161 offset:3072
	global_load_lds_dwordx4 v[174:175], off
	v_lshl_add_u64 v[174:175], v[192:193], 0, s[88:89]
	s_add_i32 m0, s0, 0x2000
	s_nop 0
	global_load_lds_dwordx4 v[174:175], off
	s_barrier
	s_waitcnt lgkmcnt(0)
	s_setprio 1
	v_mfma_f32_16x16x32_bf16 v[66:69], v[226:229], v[194:197], v[66:69]
	v_mfma_f32_16x16x32_bf16 v[38:41], v[234:237], v[194:197], v[38:41]
	v_mfma_f32_16x16x32_bf16 v[58:61], v[226:229], v[202:205], v[58:61]
	v_mfma_f32_16x16x32_bf16 v[26:29], v[234:237], v[202:205], v[26:29]
	v_mfma_f32_16x16x32_bf16 v[54:57], v[226:229], v[210:213], v[54:57]
	v_mfma_f32_16x16x32_bf16 v[22:25], v[234:237], v[210:213], v[22:25]
	v_mfma_f32_16x16x32_bf16 v[50:53], v[226:229], v[218:221], v[50:53]
	v_mfma_f32_16x16x32_bf16 v[18:21], v[234:237], v[218:221], v[18:21]
	v_mfma_f32_16x16x32_bf16 v[66:69], v[230:233], v[198:201], v[66:69]
	v_mfma_f32_16x16x32_bf16 v[38:41], v[238:241], v[198:201], v[38:41]
	v_mfma_f32_16x16x32_bf16 v[58:61], v[230:233], v[206:209], v[58:61]
	v_mfma_f32_16x16x32_bf16 v[26:29], v[238:241], v[206:209], v[26:29]
	v_mfma_f32_16x16x32_bf16 v[54:57], v[230:233], v[214:217], v[54:57]
	v_mfma_f32_16x16x32_bf16 v[22:25], v[238:241], v[214:217], v[22:25]
	v_mfma_f32_16x16x32_bf16 v[50:53], v[230:233], v[222:225], v[50:53]
	v_mfma_f32_16x16x32_bf16 v[18:21], v[238:241], v[222:225], v[18:21]
	s_setprio 0
	s_mov_b32 m0, s60
	v_lshl_add_u64 v[174:175], v[242:243], 0, s[88:89]
	s_barrier
	ds_read_b128 v[194:197], v160 offset:49152
	ds_read_b128 v[198:201], v160 offset:50176
	ds_read_b128 v[202:205], v160 offset:51200
	ds_read_b128 v[206:209], v160 offset:52224
	ds_read_b128 v[210:213], v160 offset:53248
	ds_read_b128 v[214:217], v160 offset:54272
	ds_read_b128 v[218:221], v160 offset:55296
	ds_read_b128 v[222:225], v160 offset:56320
	global_load_lds_dwordx4 v[174:175], off
	v_lshl_add_u64 v[174:175], v[244:245], 0, s[88:89]
	s_mov_b32 m0, s61
	s_nop 0
	global_load_lds_dwordx4 v[174:175], off
	s_barrier
; #define PG8_STAGE(bufoff, gbase) do { _Pragma("unroll") for (int _i = 0; _i < 2; ++_i) \
;         __builtin_amdgcn_global_load_lds((const unsigned*)((const char*)(gbase) + voff[_i]), (LAS unsigned*)(lds + (bufoff) + ldsw + _i * 8192), 16, 0, 0); } while (0)
; #define PG8_WAIT_V(n) asm volatile("s_waitcnt vmcnt(" #n ")" ::: "memory")
; #define PG8_WAIT_L(n) asm volatile("s_waitcnt lgkmcnt(" #n ")" ::: "memory")
; #define PG8_BAR __builtin_amdgcn_s_barrier()
; #define PG8_SCHED __builtin_amdgcn_sched_barrier(0)
;     ...
;             PG8_BAR; PG8_WAIT_L(0); PG8_MMA(1, 0, At, B0); PG8_BAR; PG8_SCHED;
;             PG8_STAGE(PG8_SB(1, 1), b3 + hstep);
;             PG8_WAIT_V(6); PG8_BAR; PG8_MMA(1, 1, At, B1); PG8_BAR;
;         }
;         E(acc, cur.pm + pm0, cur.pn, wr, wc, fr, fq);
;     __device__ __forceinline__ void operator()(Acc& acc, int pm, int pn, int wr, int wc, int fr, int fq) const {
;         const int brow = pm * 256;
;         const bool lat = brow < T_LAT;
;         const float* xin = lat ? xin_lat : xin_ctx;
;         float* xout = lat ? xout_lat : xout_ctx;
;         const int rsub = lat ? 0 : T_LAT;
;         const int mi = lat ? (brow >> 12) : 8;
;         const int c0 = pn * 256 + wc * 32 + fq * 4;
;         const float* gp = modv_l + (size_t)mi * 6144 + gate_i * 1024 + c0;
; #pragma unroll
;         for (int bj = 0; bj < 2; ++bj)
; #pragma unroll
;             for (int n = 0; n < 2; ++n) {
;                 const f32x4 gv = *reinterpret_cast<const f32x4*>(gp + bj * 128 + n * 16);
; #pragma unroll
;                 for (int ai = 0; ai < 2; ++ai)
; #pragma unroll
;                     for (int m = 0; m < 4; ++m) {
;                         const size_t o = (size_t)(brow + ai * 128 + wr * 64 + m * 16 + fr - rsub) * DM + c0 + bj * 128 + n * 16;
;                         const f32x4 xi = *reinterpret_cast<const f32x4*>(xin + o);
;                         const f32x4 a = acc[ai][bj][m][n];
;                         f32x4 r = {xi[0] + gv[0] * a[0], xi[1] + gv[1] * a[1], xi[2] + gv[2] * a[2], xi[3] + gv[3] * a[3]};
;                         *reinterpret_cast<f32x4*>(xout + o) = r;
;                     }
	s_waitcnt lgkmcnt(0)
	s_setprio 1
	v_mfma_f32_16x16x32_bf16 v[110:113], v[154:157], v[194:197], v[110:113]
	v_mfma_f32_16x16x32_bf16 v[78:81], v[166:169], v[194:197], v[78:81]
	v_mfma_f32_16x16x32_bf16 v[106:109], v[154:157], v[202:205], v[106:109]
	v_mfma_f32_16x16x32_bf16 v[74:77], v[166:169], v[202:205], v[74:77]
	v_mfma_f32_16x16x32_bf16 v[98:101], v[154:157], v[210:213], v[98:101]
	v_mfma_f32_16x16x32_bf16 v[70:73], v[166:169], v[210:213], v[70:73]
	v_mfma_f32_16x16x32_bf16 v[94:97], v[154:157], v[218:221], v[94:97]
	v_mfma_f32_16x16x32_bf16 v[62:65], v[166:169], v[218:221], v[62:65]
	v_mfma_f32_16x16x32_bf16 v[110:113], v[162:165], v[198:201], v[110:113]
	v_mfma_f32_16x16x32_bf16 v[78:81], v[170:173], v[198:201], v[78:81]
	v_mfma_f32_16x16x32_bf16 v[106:109], v[162:165], v[206:209], v[106:109]
	v_mfma_f32_16x16x32_bf16 v[74:77], v[170:173], v[206:209], v[74:77]
	v_mfma_f32_16x16x32_bf16 v[98:101], v[162:165], v[214:217], v[98:101]
	v_mfma_f32_16x16x32_bf16 v[70:73], v[170:173], v[214:217], v[70:73]
	v_mfma_f32_16x16x32_bf16 v[94:97], v[162:165], v[222:225], v[94:97]
	v_mfma_f32_16x16x32_bf16 v[62:65], v[170:173], v[222:225], v[62:65]
	s_setprio 0
	s_barrier
	s_add_u32 s0, s48, 0xb0080
	s_addc_u32 s1, s49, 0
	s_add_i32 s14, s15, s36
	v_lshl_add_u64 v[154:155], s[0:1], 0, v[132:133]
	s_mov_b32 m0, s14
	s_nop 0
	global_load_lds_dwordx4 v[154:155], off
	v_lshl_add_u64 v[154:155], s[0:1], 0, v[130:131]
	s_add_i32 m0, s14, 0x2000
	s_nop 0
	global_load_lds_dwordx4 v[154:155], off
	s_waitcnt vmcnt(6)
	s_barrier
	s_setprio 1
	v_mfma_f32_16x16x32_bf16 v[46:49], v[226:229], v[194:197], v[46:49]
	v_mfma_f32_16x16x32_bf16 v[14:17], v[234:237], v[194:197], v[14:17]
	v_mfma_f32_16x16x32_bf16 v[42:45], v[226:229], v[202:205], v[42:45]
	v_mfma_f32_16x16x32_bf16 v[10:13], v[234:237], v[202:205], v[10:13]
	v_mfma_f32_16x16x32_bf16 v[34:37], v[226:229], v[210:213], v[34:37]
	v_mfma_f32_16x16x32_bf16 v[6:9], v[234:237], v[210:213], v[6:9]
	v_mfma_f32_16x16x32_bf16 v[30:33], v[226:229], v[218:221], v[30:33]
	v_mfma_f32_16x16x32_bf16 v[2:5], v[234:237], v[218:221], v[2:5]
	v_mfma_f32_16x16x32_bf16 v[46:49], v[230:233], v[198:201], v[46:49]
	v_mfma_f32_16x16x32_bf16 v[14:17], v[238:241], v[198:201], v[14:17]
	v_mfma_f32_16x16x32_bf16 v[42:45], v[230:233], v[206:209], v[42:45]
	v_mfma_f32_16x16x32_bf16 v[10:13], v[238:241], v[206:209], v[10:13]
	v_mfma_f32_16x16x32_bf16 v[34:37], v[230:233], v[214:217], v[34:37]
	v_mfma_f32_16x16x32_bf16 v[6:9], v[238:241], v[214:217], v[6:9]
	v_mfma_f32_16x16x32_bf16 v[30:33], v[230:233], v[222:225], v[30:33]
	v_mfma_f32_16x16x32_bf16 v[2:5], v[238:241], v[222:225], v[2:5]
	s_setprio 0
	s_add_i32 s28, s28, 2
	s_add_u32 s22, s22, 0x100
	s_addc_u32 s23, s23, 0
	s_cmp_gt_u32 s28, 41
	s_mov_b64 s[14:15], s[46:47]
	s_barrier
	s_cbranch_scc0 .LBB0_1649
	s_lshl_b32 s22, s4, 8
	v_readlane_b32 s64, v254, 6
	s_cmpk_lt_i32 s4, 0x80
	v_readlane_b32 s66, v254, 8
	v_readlane_b32 s67, v254, 9
	v_readlane_b32 s68, v254, 10
	v_readlane_b32 s69, v254, 11
	s_cselect_b32 s15, s67, s69
	s_cselect_b32 s14, s66, s68
	s_cselect_b32 s23, 0, 0xffff8000
	s_min_i32 s0, s4, 0x80
	s_ashr_i32 s0, s0, 4
	s_mul_hi_i32 s1, s0, 0x6000
	s_mulk_i32 s0, 0x6000
	s_add_u32 s0, s50, s0
	s_addc_u32 s1, s51, s1
	s_add_i32 s23, s23, s22
	s_add_u32 s0, s0, 0x5000
	s_addc_u32 s1, s1, 0
	v_lshl_or_b32 v154, s7, 8, v159
	v_add_u32_e32 v172, s23, v1
	v_ashrrev_i32_e32 v155, 31, v154
	v_lshl_add_u64 v[156:157], v[154:155], 2, s[0:1]
	global_load_dwordx4 v[162:165], v[156:157], off
	global_load_dwordx4 v[166:169], v[156:157], off offset:64
	global_load_dwordx4 v[192:195], v[156:157], off offset:512
	global_load_dwordx4 v[196:199], v[156:157], off offset:576
	v_lshl_add_u32 v161, v172, 10, v154
	v_lshlrev_b32_e32 v161, 2, v161
	v_add_u32_e32 v170, 0x10000, v161
	v_add_u32_e32 v171, 0x20000, v161
	v_add_u32_e32 v154, 0x30000, v161
	v_add_u32_e32 v155, 0x80000, v161
	v_add_u32_e32 v172, 0x90000, v161
	v_add_u32_e32 v156, 0xa0000, v161
	v_add_u32_e32 v157, 0xb0000, v161
	global_load_dwordx4 v[200:203], v161, s[14:15]
	global_load_dwordx4 v[204:207], v161, s[14:15] offset:64
	global_load_dwordx4 v[208:211], v170, s[14:15]
	global_load_dwordx4 v[212:215], v170, s[14:15] offset:64
	global_load_dwordx4 v[216:219], v171, s[14:15]
	global_load_dwordx4 v[220:223], v171, s[14:15] offset:64
	global_load_dwordx4 v[224:227], v154, s[14:15]
	global_load_dwordx4 v[228:231], v154, s[14:15] offset:64
	global_load_dwordx4 v[232:235], v155, s[14:15]
	global_load_dwordx4 v[236:239], v155, s[14:15] offset:64
	global_load_dwordx4 v[240:243], v172, s[14:15]
	s_and_b64 vcc, exec, s[44:45]
	s_mov_b32 s7, s18
	s_mov_b32 s4, s19
	s_mov_b64 s[52:53], s[12:13]
	v_readlane_b32 s65, v254, 7
	v_readlane_b32 s70, v254, 12
	v_readlane_b32 s71, v254, 13
	s_waitcnt vmcnt(10)
	v_pk_fma_f32 v[126:127], v[126:127], v[162:163], v[200:201]
	v_pk_fma_f32 v[128:129], v[128:129], v[164:165], v[202:203]
	global_store_dwordx4 v161, v[126:129], s[14:15] sc1
	global_load_dwordx4 v[200:203], v172, s[14:15] offset:64
	s_waitcnt vmcnt(11)
	v_pk_fma_f32 v[102:103], v[102:103], v[166:167], v[204:205]
	v_pk_fma_f32 v[104:105], v[104:105], v[168:169], v[206:207]
	global_store_dwordx4 v161, v[102:105], s[14:15] offset:64 sc1
	global_load_dwordx4 v[204:207], v156, s[14:15]
	s_waitcnt vmcnt(12)
	v_pk_fma_f32 v[122:123], v[122:123], v[162:163], v[208:209]
	v_pk_fma_f32 v[124:125], v[124:125], v[164:165], v[210:211]
	global_store_dwordx4 v170, v[122:125], s[14:15] sc1
	global_load_dwordx4 v[208:211], v156, s[14:15] offset:64
	s_waitcnt vmcnt(13)
; #define PG8_WAIT_V(n) asm volatile("s_waitcnt vmcnt(" #n ")" ::: "memory")
; #define PG8_BAR __builtin_amdgcn_s_barrier()
;     ...
;         if (!has_next) break;
;     ...
;     PG8_WAIT_V(0);
;     if (wr == 0) PG8_BAR;
;     PG8_BAR;
;     __device__ __forceinline__ void operator()(Acc& acc, int pm, int pn, int wr, int wc, int fr, int fq) const {
;     ...
; #pragma unroll
;         for (int bj = 0; bj < 2; ++bj)
; #pragma unroll
;             for (int n = 0; n < 2; ++n) {
;                 const f32x4 gv = *reinterpret_cast<const f32x4*>(gp + bj * 128 + n * 16);
; #pragma unroll
;                 for (int ai = 0; ai < 2; ++ai)
; #pragma unroll
;                     for (int m = 0; m < 4; ++m) {
;                         const size_t o = (size_t)(brow + ai * 128 + wr * 64 + m * 16 + fr - rsub) * DM + c0 + bj * 128 + n * 16;
;                         const f32x4 xi = *reinterpret_cast<const f32x4*>(xin + o);
;                         const f32x4 a = acc[ai][bj][m][n];
;                         f32x4 r = {xi[0] + gv[0] * a[0], xi[1] + gv[1] * a[1], xi[2] + gv[2] * a[2], xi[3] + gv[3] * a[3]};
;                         *reinterpret_cast<f32x4*>(xout + o) = r;
;                     }
;             }
	v_pk_fma_f32 v[90:91], v[90:91], v[166:167], v[212:213]
	v_pk_fma_f32 v[92:93], v[92:93], v[168:169], v[214:215]
	global_store_dwordx4 v170, v[90:93], s[14:15] offset:64 sc1
	global_load_dwordx4 v[212:215], v157, s[14:15]
	s_waitcnt vmcnt(14)
	v_pk_fma_f32 v[118:119], v[118:119], v[162:163], v[216:217]
	v_pk_fma_f32 v[120:121], v[120:121], v[164:165], v[218:219]
	global_store_dwordx4 v171, v[118:121], s[14:15] sc1
	global_load_dwordx4 v[216:219], v157, s[14:15] offset:64
	s_waitcnt vmcnt(15)
	v_pk_fma_f32 v[86:87], v[86:87], v[166:167], v[220:221]
	v_pk_fma_f32 v[88:89], v[88:89], v[168:169], v[222:223]
	global_store_dwordx4 v171, v[86:89], s[14:15] offset:64 sc1
	global_load_dwordx4 v[220:223], v161, s[14:15] offset:512
	s_waitcnt vmcnt(16)
	v_pk_fma_f32 v[114:115], v[114:115], v[162:163], v[224:225]
	v_pk_fma_f32 v[116:117], v[116:117], v[164:165], v[226:227]
	global_store_dwordx4 v154, v[114:117], s[14:15] sc1
	global_load_dwordx4 v[224:227], v161, s[14:15] offset:576
	s_waitcnt vmcnt(17)
	v_pk_fma_f32 v[82:83], v[82:83], v[166:167], v[228:229]
	v_pk_fma_f32 v[84:85], v[84:85], v[168:169], v[230:231]
	global_store_dwordx4 v154, v[82:85], s[14:15] offset:64 sc1
	global_load_dwordx4 v[228:231], v170, s[14:15] offset:512
	s_waitcnt vmcnt(18)
	v_pk_fma_f32 v[110:111], v[110:111], v[162:163], v[232:233]
	v_pk_fma_f32 v[112:113], v[112:113], v[164:165], v[234:235]
	global_store_dwordx4 v155, v[110:113], s[14:15] sc1
	global_load_dwordx4 v[232:235], v170, s[14:15] offset:576
	s_waitcnt vmcnt(19)
	v_pk_fma_f32 v[78:79], v[78:79], v[166:167], v[236:237]
	v_pk_fma_f32 v[80:81], v[80:81], v[168:169], v[238:239]
	global_store_dwordx4 v155, v[78:81], s[14:15] offset:64 sc1
	global_load_dwordx4 v[236:239], v171, s[14:15] offset:512
	s_waitcnt vmcnt(20)
	v_pk_fma_f32 v[106:107], v[106:107], v[162:163], v[240:241]
	v_pk_fma_f32 v[108:109], v[108:109], v[164:165], v[242:243]
	global_store_dwordx4 v172, v[106:109], s[14:15] sc1
	global_load_dwordx4 v[240:243], v171, s[14:15] offset:576
	s_waitcnt vmcnt(20)
	v_pk_fma_f32 v[74:75], v[74:75], v[166:167], v[200:201]
	v_pk_fma_f32 v[76:77], v[76:77], v[168:169], v[202:203]
	global_store_dwordx4 v172, v[74:77], s[14:15] offset:64 sc1
	global_load_dwordx4 v[200:203], v154, s[14:15] offset:512
	s_waitcnt vmcnt(20)
	v_pk_fma_f32 v[98:99], v[98:99], v[162:163], v[204:205]
	v_pk_fma_f32 v[100:101], v[100:101], v[164:165], v[206:207]
	global_store_dwordx4 v156, v[98:101], s[14:15] sc1
	global_load_dwordx4 v[204:207], v154, s[14:15] offset:576
	s_waitcnt vmcnt(20)
	v_pk_fma_f32 v[70:71], v[70:71], v[166:167], v[208:209]
	v_pk_fma_f32 v[72:73], v[72:73], v[168:169], v[210:211]
	global_store_dwordx4 v156, v[70:73], s[14:15] offset:64 sc1
	global_load_dwordx4 v[208:211], v155, s[14:15] offset:512
	s_waitcnt vmcnt(20)
	v_pk_fma_f32 v[94:95], v[94:95], v[162:163], v[212:213]
	v_pk_fma_f32 v[96:97], v[96:97], v[164:165], v[214:215]
	global_store_dwordx4 v157, v[94:97], s[14:15] sc1
	global_load_dwordx4 v[212:215], v155, s[14:15] offset:576
	s_waitcnt vmcnt(20)
	v_pk_fma_f32 v[62:63], v[62:63], v[166:167], v[216:217]
	v_pk_fma_f32 v[64:65], v[64:65], v[168:169], v[218:219]
	global_store_dwordx4 v157, v[62:65], s[14:15] offset:64 sc1
	global_load_dwordx4 v[216:219], v172, s[14:15] offset:512
	s_waitcnt vmcnt(20)
	v_pk_fma_f32 v[66:67], v[66:67], v[192:193], v[220:221]
	v_pk_fma_f32 v[68:69], v[68:69], v[194:195], v[222:223]
	global_store_dwordx4 v161, v[66:69], s[14:15] offset:512 sc1
	global_load_dwordx4 v[220:223], v172, s[14:15] offset:576
	s_waitcnt vmcnt(20)
	v_pk_fma_f32 v[38:39], v[38:39], v[196:197], v[224:225]
	v_pk_fma_f32 v[40:41], v[40:41], v[198:199], v[226:227]
	global_store_dwordx4 v161, v[38:41], s[14:15] offset:576 sc1
	global_load_dwordx4 v[224:227], v156, s[14:15] offset:512
	s_waitcnt vmcnt(20)
	v_pk_fma_f32 v[58:59], v[58:59], v[192:193], v[228:229]
	v_pk_fma_f32 v[60:61], v[60:61], v[194:195], v[230:231]
	global_store_dwordx4 v170, v[58:61], s[14:15] offset:512 sc1
	global_load_dwordx4 v[228:231], v156, s[14:15] offset:576
	s_waitcnt vmcnt(20)
	v_pk_fma_f32 v[26:27], v[26:27], v[196:197], v[232:233]
	v_pk_fma_f32 v[28:29], v[28:29], v[198:199], v[234:235]
	global_store_dwordx4 v170, v[26:29], s[14:15] offset:576 sc1
	global_load_dwordx4 v[232:235], v157, s[14:15] offset:512
	s_waitcnt vmcnt(20)
	v_pk_fma_f32 v[54:55], v[54:55], v[192:193], v[236:237]
	v_pk_fma_f32 v[56:57], v[56:57], v[194:195], v[238:239]
	global_store_dwordx4 v171, v[54:57], s[14:15] offset:512 sc1
	global_load_dwordx4 v[236:239], v157, s[14:15] offset:576
	s_waitcnt vmcnt(20)
	v_pk_fma_f32 v[22:23], v[22:23], v[196:197], v[240:241]
	v_pk_fma_f32 v[24:25], v[24:25], v[198:199], v[242:243]
	global_store_dwordx4 v171, v[22:25], s[14:15] offset:576 sc1
	s_waitcnt vmcnt(19)
	v_pk_fma_f32 v[50:51], v[50:51], v[192:193], v[200:201]
	v_pk_fma_f32 v[52:53], v[52:53], v[194:195], v[202:203]
	global_store_dwordx4 v154, v[50:53], s[14:15] offset:512 sc1
	s_waitcnt vmcnt(18)
	v_pk_fma_f32 v[18:19], v[18:19], v[196:197], v[204:205]
	v_pk_fma_f32 v[20:21], v[20:21], v[198:199], v[206:207]
	global_store_dwordx4 v154, v[18:21], s[14:15] offset:576 sc1
	s_waitcnt vmcnt(17)
	v_pk_fma_f32 v[46:47], v[46:47], v[192:193], v[208:209]
	v_pk_fma_f32 v[48:49], v[48:49], v[194:195], v[210:211]
	global_store_dwordx4 v155, v[46:49], s[14:15] offset:512 sc1
	s_waitcnt vmcnt(16)
	v_pk_fma_f32 v[14:15], v[14:15], v[196:197], v[212:213]
	v_pk_fma_f32 v[16:17], v[16:17], v[198:199], v[214:215]
	global_store_dwordx4 v155, v[14:17], s[14:15] offset:576 sc1
	s_waitcnt vmcnt(15)
	v_pk_fma_f32 v[42:43], v[42:43], v[192:193], v[216:217]
	v_pk_fma_f32 v[44:45], v[44:45], v[194:195], v[218:219]
	global_store_dwordx4 v172, v[42:45], s[14:15] offset:512 sc1
	s_waitcnt vmcnt(14)
	v_pk_fma_f32 v[10:11], v[10:11], v[196:197], v[220:221]
	v_pk_fma_f32 v[12:13], v[12:13], v[198:199], v[222:223]
	global_store_dwordx4 v172, v[10:13], s[14:15] offset:576 sc1
	s_waitcnt vmcnt(13)
	v_pk_fma_f32 v[34:35], v[34:35], v[192:193], v[224:225]
	v_pk_fma_f32 v[36:37], v[36:37], v[194:195], v[226:227]
	global_store_dwordx4 v156, v[34:37], s[14:15] offset:512 sc1
	s_waitcnt vmcnt(12)
	v_pk_fma_f32 v[6:7], v[6:7], v[196:197], v[228:229]
	v_pk_fma_f32 v[8:9], v[8:9], v[198:199], v[230:231]
	global_store_dwordx4 v156, v[6:9], s[14:15] offset:576 sc1
	s_waitcnt vmcnt(11)
	v_pk_fma_f32 v[30:31], v[30:31], v[192:193], v[232:233]
	v_pk_fma_f32 v[32:33], v[32:33], v[194:195], v[234:235]
	global_store_dwordx4 v157, v[30:33], s[14:15] offset:512 sc1
	s_waitcnt vmcnt(10)
	v_pk_fma_f32 v[2:3], v[2:3], v[196:197], v[236:237]
	v_pk_fma_f32 v[4:5], v[4:5], v[198:199], v[238:239]
	global_store_dwordx4 v157, v[2:5], s[14:15] offset:576 sc1
	s_mov_b64 s[14:15], s[10:11]
	s_mov_b64 s[0:1], 0x5000
	s_cbranch_vccz .LBB0_1642
	s_waitcnt vmcnt(0)
	s_cmpk_gt_u32 s16, 0xff
	s_cbranch_scc1 .LBB0_1653
	s_barrier

; #define PG8_STAGE(bufoff, gbase) do { _Pragma("unroll") for (int _i = 0; _i < 2; ++_i) \
;         __builtin_amdgcn_global_load_lds((const unsigned*)((const char*)(gbase) + voff[_i]), (LAS unsigned*)(lds + (bufoff) + ldsw + _i * 8192), 16, 0, 0); } while (0)
; #define PG8_LDA(dst, b, h) do { _Pragma("unroll") for (int m = 0; m < 4; ++m) _Pragma("unroll") for (int k = 0; k < 2; ++k) dst[m][k] = *(const LAS bf16x8*)(lds + PG8_SA(b, h) + aoff + m * 2048 + k * 1024); } while (0)
; #define PG8_LDB(dst, b, h) do { _Pragma("unroll") for (int n = 0; n < 2; ++n) _Pragma("unroll") for (int k = 0; k < 2; ++k) dst[n][k] = *(const LAS bf16x8*)(lds + PG8_SB(b, h) + boff + n * 2048 + k * 1024); } while (0)
; #define PG8_WAIT_L(n) asm volatile("s_waitcnt lgkmcnt(" #n ")" ::: "memory")
; #define PG8_BAR __builtin_amdgcn_s_barrier()
; #define PG8_SCHED __builtin_amdgcn_sched_barrier(0)
;     ...
;     for (;;) {
;         const bool has_next = S.next(ui + 1, nxt);
;         const char* nA = has_next ? (const char*)gA + (size_t)nxt.pm * tstep : cA; const char* nB = has_next ? (const char*)gBt + (size_t)nxt.pn * tstep : cB;
;         for (int t = 0; t < nt; t += 2) {
;             const bool last = (t == nt - 2);
;             const char* a1 = cA + (size_t)(t + 1) * kstep;
;             const char* a2 = last ? nA : cA + (size_t)(t + 2) * kstep; const char* b2 = last ? nB : cB + (size_t)(t + 2) * kstep;
;             const char* a3 = a2 + kstep; const char* b3 = b2 + kstep;
;             PG8_LDB(B0, 0, 0); PG8_SCHED; PG8_LDA(At, 0, 0); PG8_STAGE(PG8_SA(1, 1), a1 + hstep);
;             PG8_WAIT_L(8); PG8_BAR; PG8_WAIT_L(0); PG8_MMA(0, 0, At, B0); PG8_BAR; PG8_SCHED;
;             PG8_LDB(B1, 0, 1); PG8_STAGE(PG8_SB(0, 0), b2);
;             PG8_BAR; PG8_WAIT_L(0); PG8_MMA(0, 1, At, B1); PG8_BAR;
;             PG8_LDA(At, 0, 1); PG8_STAGE(PG8_SA(0, 0), a2);
;             PG8_BAR; PG8_WAIT_L(0); PG8_MMA(1, 0, At, B0); PG8_BAR; PG8_SCHED;
.LBB0_1832:
	s_add_u32 s0, s12, 0xf4f50080
	s_addc_u32 s1, s13, -1
	s_cmp_lg_u32 s28, 40
	s_cselect_b32 s0, s0, 0
	s_cselect_b32 s1, s1, 0
	s_add_u32 s40, s44, s0
	s_addc_u32 s41, s45, s1
	s_add_i32 s29, 0, 0x10000
	v_add_u32_e32 v157, s29, v155
	ds_read_b128 v[158:161], v157
	ds_read_b128 v[162:165], v157 offset:1024
	ds_read_b128 v[166:169], v157 offset:2048
	ds_read_b128 v[170:173], v157 offset:3072
	s_add_u32 s14, s10, s0
	s_addc_u32 s15, s11, s1
	v_lshl_add_u64 v[174:175], v[150:151], 0, s[12:13]
	s_add_i32 m0, s7, 0xc000
	ds_read_b128 v[194:197], v156
	ds_read_b128 v[198:201], v156 offset:1024
	ds_read_b128 v[202:205], v156 offset:2048
	ds_read_b128 v[206:209], v156 offset:3072
	ds_read_b128 v[210:213], v156 offset:4096
	ds_read_b128 v[214:217], v156 offset:5120
	ds_read_b128 v[218:221], v156 offset:6144
	ds_read_b128 v[222:225], v156 offset:7168
	global_load_lds_dwordx4 v[174:175], off
	v_lshl_add_u64 v[174:175], v[152:153], 0, s[12:13]
	s_add_i32 m0, s7, 0xe000
	s_nop 0
	global_load_lds_dwordx4 v[174:175], off
	s_waitcnt lgkmcnt(8)
	s_barrier
	s_waitcnt lgkmcnt(0)
	s_setprio 1
	v_mfma_f32_16x16x32_bf16 v[126:129], v[158:161], v[194:197], v[126:129]
	v_mfma_f32_16x16x32_bf16 v[102:105], v[166:169], v[194:197], v[102:105]
	v_mfma_f32_16x16x32_bf16 v[122:125], v[158:161], v[202:205], v[122:125]
	v_mfma_f32_16x16x32_bf16 v[90:93], v[166:169], v[202:205], v[90:93]
	v_mfma_f32_16x16x32_bf16 v[118:121], v[158:161], v[210:213], v[118:121]
	v_mfma_f32_16x16x32_bf16 v[86:89], v[166:169], v[210:213], v[86:89]
	v_mfma_f32_16x16x32_bf16 v[114:117], v[158:161], v[218:221], v[114:117]
	v_mfma_f32_16x16x32_bf16 v[82:85], v[166:169], v[218:221], v[82:85]
	v_mfma_f32_16x16x32_bf16 v[126:129], v[162:165], v[198:201], v[126:129]
	v_mfma_f32_16x16x32_bf16 v[102:105], v[170:173], v[198:201], v[102:105]
	v_mfma_f32_16x16x32_bf16 v[122:125], v[162:165], v[206:209], v[122:125]
	v_mfma_f32_16x16x32_bf16 v[90:93], v[170:173], v[206:209], v[90:93]
	v_mfma_f32_16x16x32_bf16 v[118:121], v[162:165], v[214:217], v[118:121]
	v_mfma_f32_16x16x32_bf16 v[86:89], v[170:173], v[214:217], v[86:89]
	v_mfma_f32_16x16x32_bf16 v[114:117], v[162:165], v[222:225], v[114:117]
	v_mfma_f32_16x16x32_bf16 v[82:85], v[170:173], v[222:225], v[82:85]
	s_setprio 0
	s_barrier
	s_add_i32 s30, 0, 0x14000
	s_add_i32 s0, s29, s4
	v_add_u32_e32 v157, s30, v155
	v_lshl_add_u64 v[174:175], s[14:15], 0, v[130:131]
	s_mov_b32 m0, s0
	ds_read_b128 v[226:229], v157
	ds_read_b128 v[230:233], v157 offset:1024
	ds_read_b128 v[234:237], v157 offset:2048
	ds_read_b128 v[238:241], v157 offset:3072
	global_load_lds_dwordx4 v[174:175], off
	v_lshl_add_u64 v[192:193], s[14:15], 0, v[132:133]
	s_add_i32 m0, s0, 0x2000
	s_nop 0
	global_load_lds_dwordx4 v[192:193], off
	s_barrier
	s_waitcnt lgkmcnt(0)
	s_setprio 1
	v_mfma_f32_16x16x32_bf16 v[78:81], v[226:229], v[194:197], v[78:81]
	v_mfma_f32_16x16x32_bf16 v[54:57], v[234:237], v[194:197], v[54:57]
	v_mfma_f32_16x16x32_bf16 v[74:77], v[226:229], v[202:205], v[74:77]
	v_mfma_f32_16x16x32_bf16 v[46:49], v[234:237], v[202:205], v[46:49]
	v_mfma_f32_16x16x32_bf16 v[66:69], v[226:229], v[210:213], v[66:69]
	v_mfma_f32_16x16x32_bf16 v[38:41], v[234:237], v[210:213], v[38:41]
	v_mfma_f32_16x16x32_bf16 v[58:61], v[226:229], v[218:221], v[58:61]
	v_mfma_f32_16x16x32_bf16 v[34:37], v[234:237], v[218:221], v[34:37]
	v_mfma_f32_16x16x32_bf16 v[78:81], v[230:233], v[198:201], v[78:81]
	v_mfma_f32_16x16x32_bf16 v[54:57], v[238:241], v[198:201], v[54:57]
	v_mfma_f32_16x16x32_bf16 v[74:77], v[230:233], v[206:209], v[74:77]
	v_mfma_f32_16x16x32_bf16 v[46:49], v[238:241], v[206:209], v[46:49]
	v_mfma_f32_16x16x32_bf16 v[66:69], v[230:233], v[214:217], v[66:69]
	v_mfma_f32_16x16x32_bf16 v[38:41], v[238:241], v[214:217], v[38:41]
	v_mfma_f32_16x16x32_bf16 v[58:61], v[230:233], v[222:225], v[58:61]
	v_mfma_f32_16x16x32_bf16 v[34:37], v[238:241], v[222:225], v[34:37]
	s_setprio 0
	s_mov_b32 m0, s7
	v_lshl_add_u64 v[242:243], s[40:41], 0, v[130:131]
	s_barrier
	ds_read_b128 v[194:197], v156 offset:16384
	ds_read_b128 v[198:201], v156 offset:17408
	ds_read_b128 v[202:205], v156 offset:18432
	ds_read_b128 v[206:209], v156 offset:19456
	ds_read_b128 v[210:213], v156 offset:20480
	ds_read_b128 v[214:217], v156 offset:21504
	ds_read_b128 v[218:221], v156 offset:22528
	ds_read_b128 v[222:225], v156 offset:23552
	global_load_lds_dwordx4 v[242:243], off
	v_lshl_add_u64 v[244:245], s[40:41], 0, v[132:133]
	s_mov_b32 m0, s17
	s_nop 0
	global_load_lds_dwordx4 v[244:245], off
	s_barrier
	s_waitcnt lgkmcnt(0)
	s_setprio 1
	v_mfma_f32_16x16x32_bf16 v[110:113], v[158:161], v[194:197], v[110:113]
	v_mfma_f32_16x16x32_bf16 v[70:73], v[166:169], v[194:197], v[70:73]
	v_mfma_f32_16x16x32_bf16 v[106:109], v[158:161], v[202:205], v[106:109]
	v_mfma_f32_16x16x32_bf16 v[62:65], v[166:169], v[202:205], v[62:65]
	v_mfma_f32_16x16x32_bf16 v[98:101], v[158:161], v[210:213], v[98:101]
	v_mfma_f32_16x16x32_bf16 v[50:53], v[166:169], v[210:213], v[50:53]
	v_mfma_f32_16x16x32_bf16 v[94:97], v[158:161], v[218:221], v[94:97]
	v_mfma_f32_16x16x32_bf16 v[42:45], v[166:169], v[218:221], v[42:45]
	v_mfma_f32_16x16x32_bf16 v[110:113], v[162:165], v[198:201], v[110:113]
	v_mfma_f32_16x16x32_bf16 v[70:73], v[170:173], v[198:201], v[70:73]
	v_mfma_f32_16x16x32_bf16 v[106:109], v[162:165], v[206:209], v[106:109]
	v_mfma_f32_16x16x32_bf16 v[62:65], v[170:173], v[206:209], v[62:65]
	v_mfma_f32_16x16x32_bf16 v[98:101], v[162:165], v[214:217], v[98:101]
	v_mfma_f32_16x16x32_bf16 v[50:53], v[170:173], v[214:217], v[50:53]
	v_mfma_f32_16x16x32_bf16 v[94:97], v[162:165], v[222:225], v[94:97]
	v_mfma_f32_16x16x32_bf16 v[42:45], v[170:173], v[222:225], v[42:45]
	s_setprio 0
	s_barrier
; #define PG8_STAGE(bufoff, gbase) do { _Pragma("unroll") for (int _i = 0; _i < 2; ++_i) \
;         __builtin_amdgcn_global_load_lds((const unsigned*)((const char*)(gbase) + voff[_i]), (LAS unsigned*)(lds + (bufoff) + ldsw + _i * 8192), 16, 0, 0); } while (0)
; #define PG8_LDA(dst, b, h) do { _Pragma("unroll") for (int m = 0; m < 4; ++m) _Pragma("unroll") for (int k = 0; k < 2; ++k) dst[m][k] = *(const LAS bf16x8*)(lds + PG8_SA(b, h) + aoff + m * 2048 + k * 1024); } while (0)
; #define PG8_LDB(dst, b, h) do { _Pragma("unroll") for (int n = 0; n < 2; ++n) _Pragma("unroll") for (int k = 0; k < 2; ++k) dst[n][k] = *(const LAS bf16x8*)(lds + PG8_SB(b, h) + boff + n * 2048 + k * 1024); } while (0)
; #define PG8_WAIT_V(n) asm volatile("s_waitcnt vmcnt(" #n ")" ::: "memory")
; #define PG8_WAIT_L(n) asm volatile("s_waitcnt lgkmcnt(" #n ")" ::: "memory")
; #define PG8_BAR __builtin_amdgcn_s_barrier()
; #define PG8_SCHED __builtin_amdgcn_sched_barrier(0)
;     ...
;             PG8_STAGE(PG8_SB(0, 1), b2 + hstep);
;             PG8_WAIT_V(6); PG8_BAR; PG8_MMA(1, 1, At, B1); PG8_BAR;
;             PG8_LDB(B0, 1, 0); PG8_SCHED; PG8_LDA(At, 1, 0); PG8_STAGE(PG8_SA(0, 1), a2 + hstep);
;             PG8_WAIT_L(8); PG8_BAR; PG8_WAIT_L(0); PG8_MMA(0, 0, At, B0); PG8_BAR; PG8_SCHED;
;             PG8_LDB(B1, 1, 1); PG8_STAGE(PG8_SB(1, 0), b3);
;             PG8_BAR; PG8_WAIT_L(0); PG8_MMA(0, 1, At, B1); PG8_BAR;
;             PG8_LDA(At, 1, 1); PG8_STAGE(PG8_SA(1, 0), a3);
;             PG8_BAR; PG8_WAIT_L(0); PG8_MMA(1, 0, At, B0); PG8_BAR; PG8_SCHED;
	s_add_u32 s0, s14, 0xb0000
	s_addc_u32 s1, s15, 0
	s_add_i32 s29, s30, s4
	v_lshl_add_u64 v[158:159], s[0:1], 0, v[130:131]
	s_mov_b32 m0, s29
	s_nop 0
	global_load_lds_dwordx4 v[158:159], off
	v_lshl_add_u64 v[158:159], s[0:1], 0, v[132:133]
	s_add_i32 m0, s29, 0x2000
	s_nop 0
	global_load_lds_dwordx4 v[158:159], off
	s_waitcnt vmcnt(6)
	s_barrier
	s_setprio 1
	v_mfma_f32_16x16x32_bf16 v[30:33], v[226:229], v[194:197], v[30:33]
	v_mfma_f32_16x16x32_bf16 v[14:17], v[234:237], v[194:197], v[14:17]
	v_mfma_f32_16x16x32_bf16 v[26:29], v[226:229], v[202:205], v[26:29]
	v_mfma_f32_16x16x32_bf16 v[10:13], v[234:237], v[202:205], v[10:13]
	v_mfma_f32_16x16x32_bf16 v[22:25], v[226:229], v[210:213], v[22:25]
	v_mfma_f32_16x16x32_bf16 v[6:9], v[234:237], v[210:213], v[6:9]
	v_mfma_f32_16x16x32_bf16 v[18:21], v[226:229], v[218:221], v[18:21]
	v_mfma_f32_16x16x32_bf16 v[2:5], v[234:237], v[218:221], v[2:5]
	v_mfma_f32_16x16x32_bf16 v[30:33], v[230:233], v[198:201], v[30:33]
	v_mfma_f32_16x16x32_bf16 v[14:17], v[238:241], v[198:201], v[14:17]
	v_mfma_f32_16x16x32_bf16 v[26:29], v[230:233], v[206:209], v[26:29]
	v_mfma_f32_16x16x32_bf16 v[10:13], v[238:241], v[206:209], v[10:13]
	v_mfma_f32_16x16x32_bf16 v[22:25], v[230:233], v[214:217], v[22:25]
	v_mfma_f32_16x16x32_bf16 v[6:9], v[238:241], v[214:217], v[6:9]
	v_mfma_f32_16x16x32_bf16 v[18:21], v[230:233], v[222:225], v[18:21]
	v_mfma_f32_16x16x32_bf16 v[2:5], v[238:241], v[222:225], v[2:5]
	s_setprio 0
	s_add_i32 s29, 0, 0x18000
	v_add_u32_e32 v157, s29, v155
	s_barrier
	ds_read_b128 v[158:161], v157
	ds_read_b128 v[162:165], v157 offset:1024
	ds_read_b128 v[166:169], v157 offset:2048
	ds_read_b128 v[170:173], v157 offset:3072
	s_add_u32 s0, s40, 0xb0000
	s_addc_u32 s1, s41, 0
	s_mov_b32 m0, s18
	v_lshl_add_u64 v[226:227], s[0:1], 0, v[130:131]
	ds_read_b128 v[194:197], v156 offset:32768
	ds_read_b128 v[198:201], v156 offset:33792
	ds_read_b128 v[202:205], v156 offset:34816
	ds_read_b128 v[206:209], v156 offset:35840
	ds_read_b128 v[210:213], v156 offset:36864
	ds_read_b128 v[214:217], v156 offset:37888
	ds_read_b128 v[218:221], v156 offset:38912
	ds_read_b128 v[222:225], v156 offset:39936
	global_load_lds_dwordx4 v[226:227], off
	v_lshl_add_u64 v[226:227], s[0:1], 0, v[132:133]
	s_mov_b32 m0, s19
	s_nop 0
	global_load_lds_dwordx4 v[226:227], off
	s_waitcnt lgkmcnt(8)
	s_barrier
	s_waitcnt lgkmcnt(0)
	s_setprio 1
	v_mfma_f32_16x16x32_bf16 v[126:129], v[158:161], v[194:197], v[126:129]
	v_mfma_f32_16x16x32_bf16 v[102:105], v[166:169], v[194:197], v[102:105]
	v_mfma_f32_16x16x32_bf16 v[122:125], v[158:161], v[202:205], v[122:125]
	v_mfma_f32_16x16x32_bf16 v[90:93], v[166:169], v[202:205], v[90:93]
	v_mfma_f32_16x16x32_bf16 v[118:121], v[158:161], v[210:213], v[118:121]
	v_mfma_f32_16x16x32_bf16 v[86:89], v[166:169], v[210:213], v[86:89]
	v_mfma_f32_16x16x32_bf16 v[114:117], v[158:161], v[218:221], v[114:117]
	v_mfma_f32_16x16x32_bf16 v[82:85], v[166:169], v[218:221], v[82:85]
	v_mfma_f32_16x16x32_bf16 v[126:129], v[162:165], v[198:201], v[126:129]
	v_mfma_f32_16x16x32_bf16 v[102:105], v[170:173], v[198:201], v[102:105]
	v_mfma_f32_16x16x32_bf16 v[122:125], v[162:165], v[206:209], v[122:125]
	v_mfma_f32_16x16x32_bf16 v[90:93], v[170:173], v[206:209], v[90:93]
	v_mfma_f32_16x16x32_bf16 v[118:121], v[162:165], v[214:217], v[118:121]
	v_mfma_f32_16x16x32_bf16 v[86:89], v[170:173], v[214:217], v[86:89]
	v_mfma_f32_16x16x32_bf16 v[114:117], v[162:165], v[222:225], v[114:117]
	v_mfma_f32_16x16x32_bf16 v[82:85], v[170:173], v[222:225], v[82:85]
	s_setprio 0
	s_barrier
	s_add_i32 s30, 0, 0x1c000
	s_add_i32 s0, s29, s4
	v_add_u32_e32 v157, s30, v155
	v_lshl_add_u64 v[174:175], v[174:175], 0, s[88:89]
	s_mov_b32 m0, s0
	ds_read_b128 v[226:229], v157
	ds_read_b128 v[230:233], v157 offset:1024
	ds_read_b128 v[234:237], v157 offset:2048
	ds_read_b128 v[238:241], v157 offset:3072
	global_load_lds_dwordx4 v[174:175], off
	v_lshl_add_u64 v[174:175], v[192:193], 0, s[88:89]
	s_add_i32 m0, s0, 0x2000
	s_nop 0
	global_load_lds_dwordx4 v[174:175], off
	s_barrier
	s_waitcnt lgkmcnt(0)
	s_setprio 1
	v_mfma_f32_16x16x32_bf16 v[78:81], v[226:229], v[194:197], v[78:81]
	v_mfma_f32_16x16x32_bf16 v[54:57], v[234:237], v[194:197], v[54:57]
	v_mfma_f32_16x16x32_bf16 v[74:77], v[226:229], v[202:205], v[74:77]
	v_mfma_f32_16x16x32_bf16 v[46:49], v[234:237], v[202:205], v[46:49]
	v_mfma_f32_16x16x32_bf16 v[66:69], v[226:229], v[210:213], v[66:69]
	v_mfma_f32_16x16x32_bf16 v[38:41], v[234:237], v[210:213], v[38:41]
	v_mfma_f32_16x16x32_bf16 v[58:61], v[226:229], v[218:221], v[58:61]
	v_mfma_f32_16x16x32_bf16 v[34:37], v[234:237], v[218:221], v[34:37]
	v_mfma_f32_16x16x32_bf16 v[78:81], v[230:233], v[198:201], v[78:81]
	v_mfma_f32_16x16x32_bf16 v[54:57], v[238:241], v[198:201], v[54:57]
	v_mfma_f32_16x16x32_bf16 v[74:77], v[230:233], v[206:209], v[74:77]
	v_mfma_f32_16x16x32_bf16 v[46:49], v[238:241], v[206:209], v[46:49]
	v_mfma_f32_16x16x32_bf16 v[66:69], v[230:233], v[214:217], v[66:69]
	v_mfma_f32_16x16x32_bf16 v[38:41], v[238:241], v[214:217], v[38:41]
	v_mfma_f32_16x16x32_bf16 v[58:61], v[230:233], v[222:225], v[58:61]
	v_mfma_f32_16x16x32_bf16 v[34:37], v[238:241], v[222:225], v[34:37]
	s_setprio 0
	s_mov_b32 m0, s22
	v_lshl_add_u64 v[174:175], v[242:243], 0, s[88:89]
	s_barrier
	ds_read_b128 v[194:197], v156 offset:49152
	ds_read_b128 v[198:201], v156 offset:50176
	ds_read_b128 v[202:205], v156 offset:51200
	ds_read_b128 v[206:209], v156 offset:52224
	ds_read_b128 v[210:213], v156 offset:53248
	ds_read_b128 v[214:217], v156 offset:54272
	ds_read_b128 v[218:221], v156 offset:55296
	ds_read_b128 v[222:225], v156 offset:56320
	global_load_lds_dwordx4 v[174:175], off
	v_lshl_add_u64 v[174:175], v[244:245], 0, s[88:89]
	s_mov_b32 m0, s23
	s_nop 0
	global_load_lds_dwordx4 v[174:175], off
	s_barrier
; #define PG8_STAGE(bufoff, gbase) do { _Pragma("unroll") for (int _i = 0; _i < 2; ++_i) \
;         __builtin_amdgcn_global_load_lds((const unsigned*)((const char*)(gbase) + voff[_i]), (LAS unsigned*)(lds + (bufoff) + ldsw + _i * 8192), 16, 0, 0); } while (0)
; #define PG8_WAIT_V(n) asm volatile("s_waitcnt vmcnt(" #n ")" ::: "memory")
; #define PG8_WAIT_L(n) asm volatile("s_waitcnt lgkmcnt(" #n ")" ::: "memory")
; #define PG8_BAR __builtin_amdgcn_s_barrier()
; #define PG8_SCHED __builtin_amdgcn_sched_barrier(0)
;     ...
;             PG8_BAR; PG8_WAIT_L(0); PG8_MMA(1, 0, At, B0); PG8_BAR; PG8_SCHED;
;             PG8_STAGE(PG8_SB(1, 1), b3 + hstep);
;             PG8_WAIT_V(6); PG8_BAR; PG8_MMA(1, 1, At, B1); PG8_BAR;
;         }
;         E(acc, cur.pm + pm0, cur.pn, wr, wc, fr, fq);
;     __device__ __forceinline__ void operator()(Acc& acc, int pm, int pn, int wr, int wc, int fr, int fq) const {
;         const int brow = pm * 256;
;         const bool lat = brow < T_LAT;
;         const float* xin = lat ? xin_lat : xin_ctx;
;         float* xout = lat ? xout_lat : xout_ctx;
;         const int rsub = lat ? 0 : T_LAT;
;         const int mi = lat ? (brow >> 12) : 8;
;         const int c0 = pn * 256 + wc * 32 + fq * 4;
;         const float* gp = modv_l + (size_t)mi * 6144 + gate_i * 1024 + c0;
; #pragma unroll
;         for (int bj = 0; bj < 2; ++bj)
; #pragma unroll
;             for (int n = 0; n < 2; ++n) {
;                 const f32x4 gv = *reinterpret_cast<const f32x4*>(gp + bj * 128 + n * 16);
; #pragma unroll
;                 for (int ai = 0; ai < 2; ++ai)
; #pragma unroll
;                     for (int m = 0; m < 4; ++m) {
;                         const size_t o = (size_t)(brow + ai * 128 + wr * 64 + m * 16 + fr - rsub) * DM + c0 + bj * 128 + n * 16;
;                         const f32x4 xi = *reinterpret_cast<const f32x4*>(xin + o);
;                         const f32x4 a = acc[ai][bj][m][n];
;                         f32x4 r = {xi[0] + gv[0] * a[0], xi[1] + gv[1] * a[1], xi[2] + gv[2] * a[2], xi[3] + gv[3] * a[3]};
;                         *reinterpret_cast<f32x4*>(xout + o) = r;
;                     }
	s_waitcnt lgkmcnt(0)
	s_setprio 1
	v_mfma_f32_16x16x32_bf16 v[110:113], v[158:161], v[194:197], v[110:113]
	v_mfma_f32_16x16x32_bf16 v[70:73], v[166:169], v[194:197], v[70:73]
	v_mfma_f32_16x16x32_bf16 v[106:109], v[158:161], v[202:205], v[106:109]
	v_mfma_f32_16x16x32_bf16 v[62:65], v[166:169], v[202:205], v[62:65]
	v_mfma_f32_16x16x32_bf16 v[98:101], v[158:161], v[210:213], v[98:101]
	v_mfma_f32_16x16x32_bf16 v[50:53], v[166:169], v[210:213], v[50:53]
	v_mfma_f32_16x16x32_bf16 v[94:97], v[158:161], v[218:221], v[94:97]
	v_mfma_f32_16x16x32_bf16 v[42:45], v[166:169], v[218:221], v[42:45]
	v_mfma_f32_16x16x32_bf16 v[110:113], v[162:165], v[198:201], v[110:113]
	v_mfma_f32_16x16x32_bf16 v[70:73], v[170:173], v[198:201], v[70:73]
	v_mfma_f32_16x16x32_bf16 v[106:109], v[162:165], v[206:209], v[106:109]
	v_mfma_f32_16x16x32_bf16 v[62:65], v[170:173], v[206:209], v[62:65]
	v_mfma_f32_16x16x32_bf16 v[98:101], v[162:165], v[214:217], v[98:101]
	v_mfma_f32_16x16x32_bf16 v[50:53], v[170:173], v[214:217], v[50:53]
	v_mfma_f32_16x16x32_bf16 v[94:97], v[162:165], v[222:225], v[94:97]
	v_mfma_f32_16x16x32_bf16 v[42:45], v[170:173], v[222:225], v[42:45]
	s_setprio 0
	s_barrier
	s_add_u32 s0, s14, 0xb0080
	s_addc_u32 s1, s15, 0
	s_add_i32 s14, s30, s4
	v_lshl_add_u64 v[158:159], s[0:1], 0, v[130:131]
	s_mov_b32 m0, s14
	s_nop 0
	global_load_lds_dwordx4 v[158:159], off
	v_lshl_add_u64 v[158:159], s[0:1], 0, v[132:133]
	s_add_i32 m0, s14, 0x2000
	s_nop 0
	global_load_lds_dwordx4 v[158:159], off
	s_waitcnt vmcnt(6)
	s_barrier
	s_setprio 1
	v_mfma_f32_16x16x32_bf16 v[30:33], v[226:229], v[194:197], v[30:33]
	v_mfma_f32_16x16x32_bf16 v[14:17], v[234:237], v[194:197], v[14:17]
	v_mfma_f32_16x16x32_bf16 v[26:29], v[226:229], v[202:205], v[26:29]
	v_mfma_f32_16x16x32_bf16 v[10:13], v[234:237], v[202:205], v[10:13]
	v_mfma_f32_16x16x32_bf16 v[22:25], v[226:229], v[210:213], v[22:25]
	v_mfma_f32_16x16x32_bf16 v[6:9], v[234:237], v[210:213], v[6:9]
	v_mfma_f32_16x16x32_bf16 v[18:21], v[226:229], v[218:221], v[18:21]
	v_mfma_f32_16x16x32_bf16 v[2:5], v[234:237], v[218:221], v[2:5]
	v_mfma_f32_16x16x32_bf16 v[30:33], v[230:233], v[198:201], v[30:33]
	v_mfma_f32_16x16x32_bf16 v[14:17], v[238:241], v[198:201], v[14:17]
	v_mfma_f32_16x16x32_bf16 v[26:29], v[230:233], v[206:209], v[26:29]
	v_mfma_f32_16x16x32_bf16 v[10:13], v[238:241], v[206:209], v[10:13]
	v_mfma_f32_16x16x32_bf16 v[22:25], v[230:233], v[214:217], v[22:25]
	v_mfma_f32_16x16x32_bf16 v[6:9], v[238:241], v[214:217], v[6:9]
	v_mfma_f32_16x16x32_bf16 v[18:21], v[230:233], v[222:225], v[18:21]
	v_mfma_f32_16x16x32_bf16 v[2:5], v[238:241], v[222:225], v[2:5]
	s_setprio 0
	s_add_i32 s28, s28, 2
	s_add_u32 s12, s12, 0x100
	s_addc_u32 s13, s13, 0
	s_cmp_gt_u32 s28, 41
	s_barrier
	s_cbranch_scc0 .LBB0_1832
	v_readlane_b32 s0, v253, 63
	v_readlane_b32 s64, v254, 6
	v_readlane_b32 s68, v254, 10
	v_readlane_b32 s69, v254, 11
	v_readlane_b32 s65, v254, 7
	v_readlane_b32 s66, v254, 8
	v_readlane_b32 s67, v254, 9
	v_readlane_b32 s70, v254, 12
	v_readlane_b32 s71, v254, 13
	v_mov_b32_e32 v161, v0
	v_lshl_or_b32 v157, v154, 2, s0
	v_or_b32_e32 v157, s20, v157
	v_lshlrev_b32_e32 v160, 2, v157
	v_readlane_b32 s0, v253, 61
	s_nop 1
	v_lshl_add_u64 v[158:159], s[50:51], 0, v[160:161]
	v_add_u32_e32 v162, s0, v1
	s_mov_b64 s[0:1], 0x35000
	v_lshl_add_u64 v[158:159], v[158:159], 0, s[0:1]
	global_load_dwordx4 v[192:195], v[158:159], off
	global_load_dwordx4 v[196:199], v[158:159], off offset:64
	global_load_dwordx4 v[200:203], v[158:159], off offset:512
	global_load_dwordx4 v[204:207], v[158:159], off offset:576
	v_add_u32_e32 v163, 0xffff8000, v162
	v_lshl_or_b32 v164, v163, 12, v160
	v_add_u32_e32 v165, 0x10000, v164
	v_add_u32_e32 v166, 0x20000, v164
	v_add_u32_e32 v167, 0x30000, v164
	v_add_u32_e32 v168, 0x80000, v164
	v_add_u32_e32 v169, 0x90000, v164
	v_add_u32_e32 v170, 0xa0000, v164
	v_add_u32_e32 v171, 0xb0000, v164
	global_load_dwordx4 v[208:211], v164, s[68:69]
	global_load_dwordx4 v[212:215], v164, s[68:69] offset:64
	global_load_dwordx4 v[216:219], v165, s[68:69]
	global_load_dwordx4 v[220:223], v165, s[68:69] offset:64
	global_load_dwordx4 v[224:227], v166, s[68:69]
	global_load_dwordx4 v[228:231], v166, s[68:69] offset:64
	global_load_dwordx4 v[232:235], v167, s[68:69]
	global_load_dwordx4 v[236:239], v167, s[68:69] offset:64
	global_load_dwordx4 v[240:243], v168, s[68:69]
	s_cmpk_lt_u32 s16, 0x100
	s_waitcnt vmcnt(8)
	v_pk_fma_f32 v[126:127], v[126:127], v[192:193], v[208:209]
	v_pk_fma_f32 v[128:129], v[128:129], v[194:195], v[210:211]
	global_store_dwordx4 v164, v[126:129], s[68:69] sc1
	global_load_dwordx4 v[208:211], v168, s[68:69] offset:64
	s_waitcnt vmcnt(9)
	v_pk_fma_f32 v[102:103], v[102:103], v[196:197], v[212:213]
	v_pk_fma_f32 v[104:105], v[104:105], v[198:199], v[214:215]
	global_store_dwordx4 v164, v[102:105], s[68:69] offset:64 sc1
	global_load_dwordx4 v[212:215], v169, s[68:69]
	s_waitcnt vmcnt(10)
	v_pk_fma_f32 v[122:123], v[122:123], v[192:193], v[216:217]
	v_pk_fma_f32 v[124:125], v[124:125], v[194:195], v[218:219]
	global_store_dwordx4 v165, v[122:125], s[68:69] sc1
	global_load_dwordx4 v[216:219], v169, s[68:69] offset:64
	s_waitcnt vmcnt(11)
	v_pk_fma_f32 v[90:91], v[90:91], v[196:197], v[220:221]
	v_pk_fma_f32 v[92:93], v[92:93], v[198:199], v[222:223]
	global_store_dwordx4 v165, v[90:93], s[68:69] offset:64 sc1
	global_load_dwordx4 v[220:223], v170, s[68:69]
	s_waitcnt vmcnt(12)
	v_pk_fma_f32 v[118:119], v[118:119], v[192:193], v[224:225]
	v_pk_fma_f32 v[120:121], v[120:121], v[194:195], v[226:227]
	global_store_dwordx4 v166, v[118:121], s[68:69] sc1
	global_load_dwordx4 v[224:227], v170, s[68:69] offset:64
	s_waitcnt vmcnt(13)
; #define PG8_WAIT_V(n) asm volatile("s_waitcnt vmcnt(" #n ")" ::: "memory")
; #define PG8_BAR __builtin_amdgcn_s_barrier()
;     ...
;     PG8_WAIT_V(0);
;     if (wr == 0) PG8_BAR;
;     PG8_BAR;
;     __device__ __forceinline__ void operator()(Acc& acc, int pm, int pn, int wr, int wc, int fr, int fq) const {
;     ...
; #pragma unroll
;         for (int bj = 0; bj < 2; ++bj)
; #pragma unroll
;             for (int n = 0; n < 2; ++n) {
;                 const f32x4 gv = *reinterpret_cast<const f32x4*>(gp + bj * 128 + n * 16);
; #pragma unroll
;                 for (int ai = 0; ai < 2; ++ai)
; #pragma unroll
;                     for (int m = 0; m < 4; ++m) {
;                         const size_t o = (size_t)(brow + ai * 128 + wr * 64 + m * 16 + fr - rsub) * DM + c0 + bj * 128 + n * 16;
;                         const f32x4 xi = *reinterpret_cast<const f32x4*>(xin + o);
;                         const f32x4 a = acc[ai][bj][m][n];
;                         f32x4 r = {xi[0] + gv[0] * a[0], xi[1] + gv[1] * a[1], xi[2] + gv[2] * a[2], xi[3] + gv[3] * a[3]};
;                         *reinterpret_cast<f32x4*>(xout + o) = r;
;                     }
;             }
	v_pk_fma_f32 v[86:87], v[86:87], v[196:197], v[228:229]
	v_pk_fma_f32 v[88:89], v[88:89], v[198:199], v[230:231]
	global_store_dwordx4 v166, v[86:89], s[68:69] offset:64 sc1
	global_load_dwordx4 v[228:231], v171, s[68:69]
	s_waitcnt vmcnt(14)
	v_pk_fma_f32 v[114:115], v[114:115], v[192:193], v[232:233]
	v_pk_fma_f32 v[116:117], v[116:117], v[194:195], v[234:235]
	global_store_dwordx4 v167, v[114:117], s[68:69] sc1
	global_load_dwordx4 v[232:235], v171, s[68:69] offset:64
	s_waitcnt vmcnt(15)
	v_pk_fma_f32 v[82:83], v[82:83], v[196:197], v[236:237]
	v_pk_fma_f32 v[84:85], v[84:85], v[198:199], v[238:239]
	global_store_dwordx4 v167, v[82:85], s[68:69] offset:64 sc1
	global_load_dwordx4 v[236:239], v164, s[68:69] offset:512
	s_waitcnt vmcnt(16)
	v_pk_fma_f32 v[110:111], v[110:111], v[192:193], v[240:241]
	v_pk_fma_f32 v[112:113], v[112:113], v[194:195], v[242:243]
	global_store_dwordx4 v168, v[110:113], s[68:69] sc1
	global_load_dwordx4 v[240:243], v164, s[68:69] offset:576
	s_waitcnt vmcnt(16)
	v_pk_fma_f32 v[70:71], v[70:71], v[196:197], v[208:209]
	v_pk_fma_f32 v[72:73], v[72:73], v[198:199], v[210:211]
	global_store_dwordx4 v168, v[70:73], s[68:69] offset:64 sc1
	global_load_dwordx4 v[208:211], v165, s[68:69] offset:512
	s_waitcnt vmcnt(16)
	v_pk_fma_f32 v[106:107], v[106:107], v[192:193], v[212:213]
	v_pk_fma_f32 v[108:109], v[108:109], v[194:195], v[214:215]
	global_store_dwordx4 v169, v[106:109], s[68:69] sc1
	global_load_dwordx4 v[212:215], v165, s[68:69] offset:576
	s_waitcnt vmcnt(16)
	v_pk_fma_f32 v[62:63], v[62:63], v[196:197], v[216:217]
	v_pk_fma_f32 v[64:65], v[64:65], v[198:199], v[218:219]
	global_store_dwordx4 v169, v[62:65], s[68:69] offset:64 sc1
	global_load_dwordx4 v[216:219], v166, s[68:69] offset:512
	s_waitcnt vmcnt(16)
	v_pk_fma_f32 v[98:99], v[98:99], v[192:193], v[220:221]
	v_pk_fma_f32 v[100:101], v[100:101], v[194:195], v[222:223]
	global_store_dwordx4 v170, v[98:101], s[68:69] sc1
	global_load_dwordx4 v[220:223], v166, s[68:69] offset:576
	s_waitcnt vmcnt(16)
	v_pk_fma_f32 v[50:51], v[50:51], v[196:197], v[224:225]
	v_pk_fma_f32 v[52:53], v[52:53], v[198:199], v[226:227]
	global_store_dwordx4 v170, v[50:53], s[68:69] offset:64 sc1
	global_load_dwordx4 v[224:227], v167, s[68:69] offset:512
	s_waitcnt vmcnt(16)
	v_pk_fma_f32 v[94:95], v[94:95], v[192:193], v[228:229]
	v_pk_fma_f32 v[96:97], v[96:97], v[194:195], v[230:231]
	global_store_dwordx4 v171, v[94:97], s[68:69] sc1
	global_load_dwordx4 v[228:231], v167, s[68:69] offset:576
	s_waitcnt vmcnt(16)
	v_pk_fma_f32 v[42:43], v[42:43], v[196:197], v[232:233]
	v_pk_fma_f32 v[44:45], v[44:45], v[198:199], v[234:235]
	global_store_dwordx4 v171, v[42:45], s[68:69] offset:64 sc1
	global_load_dwordx4 v[232:235], v168, s[68:69] offset:512
	s_waitcnt vmcnt(16)
	v_pk_fma_f32 v[78:79], v[78:79], v[200:201], v[236:237]
	v_pk_fma_f32 v[80:81], v[80:81], v[202:203], v[238:239]
	global_store_dwordx4 v164, v[78:81], s[68:69] offset:512 sc1
	global_load_dwordx4 v[236:239], v168, s[68:69] offset:576
	s_waitcnt vmcnt(16)
	v_pk_fma_f32 v[54:55], v[54:55], v[204:205], v[240:241]
	v_pk_fma_f32 v[56:57], v[56:57], v[206:207], v[242:243]
	global_store_dwordx4 v164, v[54:57], s[68:69] offset:576 sc1
	global_load_dwordx4 v[240:243], v169, s[68:69] offset:512
	s_waitcnt vmcnt(16)
	v_pk_fma_f32 v[74:75], v[74:75], v[200:201], v[208:209]
	v_pk_fma_f32 v[76:77], v[76:77], v[202:203], v[210:211]
	global_store_dwordx4 v165, v[74:77], s[68:69] offset:512 sc1
	global_load_dwordx4 v[208:211], v169, s[68:69] offset:576
	s_waitcnt vmcnt(16)
	v_pk_fma_f32 v[46:47], v[46:47], v[204:205], v[212:213]
	v_pk_fma_f32 v[48:49], v[48:49], v[206:207], v[214:215]
	global_store_dwordx4 v165, v[46:49], s[68:69] offset:576 sc1
	global_load_dwordx4 v[212:215], v170, s[68:69] offset:512
	s_waitcnt vmcnt(16)
	v_pk_fma_f32 v[66:67], v[66:67], v[200:201], v[216:217]
	v_pk_fma_f32 v[68:69], v[68:69], v[202:203], v[218:219]
	global_store_dwordx4 v166, v[66:69], s[68:69] offset:512 sc1
	global_load_dwordx4 v[216:219], v170, s[68:69] offset:576
	s_waitcnt vmcnt(16)
	v_pk_fma_f32 v[38:39], v[38:39], v[204:205], v[220:221]
	v_pk_fma_f32 v[40:41], v[40:41], v[206:207], v[222:223]
	global_store_dwordx4 v166, v[38:41], s[68:69] offset:576 sc1
	global_load_dwordx4 v[220:223], v171, s[68:69] offset:512
	s_waitcnt vmcnt(16)
	v_pk_fma_f32 v[58:59], v[58:59], v[200:201], v[224:225]
	v_pk_fma_f32 v[60:61], v[60:61], v[202:203], v[226:227]
	global_store_dwordx4 v167, v[58:61], s[68:69] offset:512 sc1
	global_load_dwordx4 v[224:227], v171, s[68:69] offset:576
	s_waitcnt vmcnt(16)
	v_pk_fma_f32 v[34:35], v[34:35], v[204:205], v[228:229]
	v_pk_fma_f32 v[36:37], v[36:37], v[206:207], v[230:231]
	global_store_dwordx4 v167, v[34:37], s[68:69] offset:576 sc1
	s_waitcnt vmcnt(15)
	v_pk_fma_f32 v[30:31], v[30:31], v[200:201], v[232:233]
	v_pk_fma_f32 v[32:33], v[32:33], v[202:203], v[234:235]
	global_store_dwordx4 v168, v[30:33], s[68:69] offset:512 sc1
	s_waitcnt vmcnt(14)
	v_pk_fma_f32 v[14:15], v[14:15], v[204:205], v[236:237]
	v_pk_fma_f32 v[16:17], v[16:17], v[206:207], v[238:239]
	global_store_dwordx4 v168, v[14:17], s[68:69] offset:576 sc1
	s_waitcnt vmcnt(13)
	v_pk_fma_f32 v[26:27], v[26:27], v[200:201], v[240:241]
	v_pk_fma_f32 v[28:29], v[28:29], v[202:203], v[242:243]
	global_store_dwordx4 v169, v[26:29], s[68:69] offset:512 sc1
	s_waitcnt vmcnt(12)
	v_pk_fma_f32 v[10:11], v[10:11], v[204:205], v[208:209]
	v_pk_fma_f32 v[12:13], v[12:13], v[206:207], v[210:211]
	global_store_dwordx4 v169, v[10:13], s[68:69] offset:576 sc1
	s_waitcnt vmcnt(11)
	v_pk_fma_f32 v[22:23], v[22:23], v[200:201], v[212:213]
	v_pk_fma_f32 v[24:25], v[24:25], v[202:203], v[214:215]
	global_store_dwordx4 v170, v[22:25], s[68:69] offset:512 sc1
	s_waitcnt vmcnt(10)
	v_pk_fma_f32 v[6:7], v[6:7], v[204:205], v[216:217]
	v_pk_fma_f32 v[8:9], v[8:9], v[206:207], v[218:219]
	global_store_dwordx4 v170, v[6:9], s[68:69] offset:576 sc1
	s_waitcnt vmcnt(9)
	v_pk_fma_f32 v[18:19], v[18:19], v[200:201], v[220:221]
	v_pk_fma_f32 v[20:21], v[20:21], v[202:203], v[222:223]
	global_store_dwordx4 v171, v[18:21], s[68:69] offset:512 sc1
	s_waitcnt vmcnt(8)
	v_pk_fma_f32 v[2:3], v[2:3], v[204:205], v[224:225]
	v_pk_fma_f32 v[4:5], v[4:5], v[206:207], v[226:227]
	global_store_dwordx4 v171, v[2:5], s[68:69] offset:576 sc1
	s_mov_b32 s0, 0xf80b0000
	s_mov_b32 s1, -1
	s_waitcnt vmcnt(0)
	s_cbranch_scc0 .LBB0_1835
	s_barrier
